# v27 + closing barrier of each MFMA burst moved up 3 MFMAs, prio 2
# baseline (speedup 1.0000x reference)
.LBB0_379:
	v_add_u32_e32 v14, s56, v140
	v_add_u32_e32 v30, s57, v140
	ds_read_b128 v[2:5], v14
	ds_read_b128 v[6:9], v14 offset:1024
	ds_read_b128 v[10:13], v14 offset:2048
	ds_read_b128 v[14:17], v14 offset:3072
	ds_read_b128 v[18:21], v30
	ds_read_b128 v[22:25], v30 offset:1024
	ds_read_b128 v[26:29], v30 offset:2048
	ds_read_b128 v[30:33], v30 offset:3072
	v_add_u32_e32 v141, 0, v1
	ds_read_b128 v[34:37], v141
	ds_read_b128 v[38:41], v141 offset:1024
	ds_read_b128 v[42:45], v141 offset:2048
	ds_read_b128 v[46:49], v141 offset:3072
	ds_read_b128 v[50:53], v141 offset:4096
	ds_read_b128 v[54:57], v141 offset:5120
	ds_read_b128 v[58:61], v141 offset:6144
	ds_read_b128 v[62:65], v141 offset:7168
	s_waitcnt vmcnt(8)
	s_waitcnt lgkmcnt(0)
	s_barrier
	s_setprio 1
	s_waitcnt lgkmcnt(0)
	v_mfma_f32_16x16x32_bf16 v[66:69], v[2:5], v[34:37], 0
	v_mfma_f32_16x16x32_bf16 v[66:69], v[6:9], v[38:41], v[66:69]
	v_mfma_f32_16x16x32_bf16 v[70:73], v[10:13], v[34:37], 0
	v_mfma_f32_16x16x32_bf16 v[70:73], v[14:17], v[38:41], v[70:73]
	v_mfma_f32_16x16x32_bf16 v[78:81], v[10:13], v[42:45], 0
	v_mfma_f32_16x16x32_bf16 v[78:81], v[14:17], v[46:49], v[78:81]
	v_mfma_f32_16x16x32_bf16 v[74:77], v[2:5], v[42:45], 0
	v_mfma_f32_16x16x32_bf16 v[74:77], v[6:9], v[46:49], v[74:77]
	v_mfma_f32_16x16x32_bf16 v[82:85], v[2:5], v[50:53], 0
	v_mfma_f32_16x16x32_bf16 v[82:85], v[6:9], v[54:57], v[82:85]
	v_mfma_f32_16x16x32_bf16 v[86:89], v[10:13], v[50:53], 0
	v_mfma_f32_16x16x32_bf16 v[86:89], v[14:17], v[54:57], v[86:89]
	v_mfma_f32_16x16x32_bf16 v[94:97], v[10:13], v[58:61], 0
	v_mfma_f32_16x16x32_bf16 v[94:97], v[14:17], v[62:65], v[94:97]
	v_mfma_f32_16x16x32_bf16 v[90:93], v[2:5], v[58:61], 0
	v_mfma_f32_16x16x32_bf16 v[90:93], v[6:9], v[62:65], v[90:93]
	s_setprio 0
	s_setprio 1
	v_mfma_f32_16x16x32_bf16 v[98:101], v[18:21], v[34:37], 0
	v_mfma_f32_16x16x32_bf16 v[34:37], v[26:29], v[34:37], 0
	v_mfma_f32_16x16x32_bf16 v[102:105], v[18:21], v[42:45], 0
	v_mfma_f32_16x16x32_bf16 v[42:45], v[26:29], v[42:45], 0
	v_mfma_f32_16x16x32_bf16 v[106:109], v[18:21], v[50:53], 0
	v_mfma_f32_16x16x32_bf16 v[50:53], v[26:29], v[50:53], 0
	v_mfma_f32_16x16x32_bf16 v[110:113], v[18:21], v[58:61], 0
	v_mfma_f32_16x16x32_bf16 v[58:61], v[26:29], v[58:61], 0
	v_mfma_f32_16x16x32_bf16 v[98:101], v[22:25], v[38:41], v[98:101]
	v_mfma_f32_16x16x32_bf16 v[38:41], v[30:33], v[38:41], v[34:37]
	v_mfma_f32_16x16x32_bf16 v[102:105], v[22:25], v[46:49], v[102:105]
	v_mfma_f32_16x16x32_bf16 v[46:49], v[30:33], v[46:49], v[42:45]
	v_mfma_f32_16x16x32_bf16 v[106:109], v[22:25], v[54:57], v[106:109]
	s_setprio 2
	s_barrier
	v_mfma_f32_16x16x32_bf16 v[54:57], v[30:33], v[54:57], v[50:53]
	v_mfma_f32_16x16x32_bf16 v[110:113], v[22:25], v[62:65], v[110:113]
	v_mfma_f32_16x16x32_bf16 v[62:65], v[30:33], v[62:65], v[58:61]
	s_setprio 0
	v_lshl_add_u64 v[136:137], s[38:39], 0, v[130:131]
	s_add_i32 s60, s56, s21
	v_mov_b32_e32 v135, v131
	v_lshl_add_u64 v[142:143], v[136:137], 0, s[10:11]
	s_mov_b32 m0, s60
	v_lshl_add_u64 v[244:245], s[38:39], 0, v[134:135]
	ds_read_b128 v[34:37], v141 offset:16384
	ds_read_b128 v[42:45], v141 offset:17408
	ds_read_b128 v[50:53], v141 offset:18432
	ds_read_b128 v[58:61], v141 offset:19456
	ds_read_b128 v[114:117], v141 offset:20480
	ds_read_b128 v[118:121], v141 offset:21504
	ds_read_b128 v[122:125], v141 offset:22528
	ds_read_b128 v[126:129], v141 offset:23552
	global_load_lds_dwordx4 v[142:143], off
	v_lshl_add_u64 v[142:143], v[244:245], 0, s[10:11]
	s_add_i32 m0, s60, 0x2000
	s_add_i32 s60, s57, s21
	global_load_lds_dwordx4 v[142:143], off
	s_mov_b32 m0, s60
	v_mov_b32_e32 v139, v131
	global_load_lds_dwordx4 v130, s[40:41]
	s_add_i32 m0, s60, 0x2000
	v_lshl_add_u64 v[246:247], s[36:37], 0, v[138:139]
	v_mov_b32_e32 v133, v131
	global_load_lds_dwordx4 v134, s[40:41]
	v_lshl_add_u64 v[142:143], v[246:247], 0, s[10:11]
	s_mov_b32 m0, s33
	v_lshl_add_u64 v[248:249], s[36:37], 0, v[132:133]
	global_load_lds_dwordx4 v[142:143], off
	v_lshl_add_u64 v[142:143], v[248:249], 0, s[10:11]
	s_mov_b32 m0, s46
	s_nop 0
	global_load_lds_dwordx4 v[142:143], off
	s_waitcnt vmcnt(8)
	s_waitcnt lgkmcnt(0)
	s_barrier
	s_setprio 1
	s_waitcnt lgkmcnt(0)
	v_mfma_f32_16x16x32_bf16 v[142:145], v[2:5], v[34:37], 0
	v_mfma_f32_16x16x32_bf16 v[148:151], v[10:13], v[34:37], 0
	v_mfma_f32_16x16x32_bf16 v[152:155], v[2:5], v[50:53], 0
	v_mfma_f32_16x16x32_bf16 v[156:159], v[10:13], v[50:53], 0
	v_mfma_f32_16x16x32_bf16 v[160:163], v[2:5], v[114:117], 0
	v_mfma_f32_16x16x32_bf16 v[164:167], v[10:13], v[114:117], 0
	v_mfma_f32_16x16x32_bf16 v[2:5], v[2:5], v[122:125], 0
	v_mfma_f32_16x16x32_bf16 v[10:13], v[10:13], v[122:125], 0
	v_mfma_f32_16x16x32_bf16 v[142:145], v[6:9], v[42:45], v[142:145]
	v_mfma_f32_16x16x32_bf16 v[148:151], v[14:17], v[42:45], v[148:151]
	v_mfma_f32_16x16x32_bf16 v[152:155], v[6:9], v[58:61], v[152:155]
	v_mfma_f32_16x16x32_bf16 v[156:159], v[14:17], v[58:61], v[156:159]
	v_mfma_f32_16x16x32_bf16 v[160:163], v[6:9], v[118:121], v[160:163]
	v_mfma_f32_16x16x32_bf16 v[164:167], v[14:17], v[118:121], v[164:167]
	v_mfma_f32_16x16x32_bf16 v[168:171], v[6:9], v[126:129], v[2:5]
	v_mfma_f32_16x16x32_bf16 v[172:175], v[14:17], v[126:129], v[10:13]
	s_setprio 0
	s_setprio 1
	v_mfma_f32_16x16x32_bf16 v[2:5], v[18:21], v[34:37], 0
	v_mfma_f32_16x16x32_bf16 v[6:9], v[26:29], v[34:37], 0
	v_mfma_f32_16x16x32_bf16 v[10:13], v[18:21], v[50:53], 0
	v_mfma_f32_16x16x32_bf16 v[14:17], v[26:29], v[50:53], 0
	v_mfma_f32_16x16x32_bf16 v[34:37], v[18:21], v[114:117], 0
	v_mfma_f32_16x16x32_bf16 v[50:53], v[26:29], v[114:117], 0
	v_mfma_f32_16x16x32_bf16 v[18:21], v[18:21], v[122:125], 0
	v_mfma_f32_16x16x32_bf16 v[26:29], v[26:29], v[122:125], 0
	v_mfma_f32_16x16x32_bf16 v[114:117], v[22:25], v[42:45], v[2:5]
	v_mfma_f32_16x16x32_bf16 v[188:191], v[22:25], v[118:121], v[34:37]
	v_mfma_f32_16x16x32_bf16 v[118:121], v[30:33], v[118:121], v[50:53]
	v_mfma_f32_16x16x32_bf16 v[176:179], v[30:33], v[42:45], v[6:9]
	v_mfma_f32_16x16x32_bf16 v[180:183], v[22:25], v[58:61], v[10:13]
	s_setprio 2
	s_barrier
	v_mfma_f32_16x16x32_bf16 v[184:187], v[30:33], v[58:61], v[14:17]
	v_mfma_f32_16x16x32_bf16 v[192:195], v[22:25], v[126:129], v[18:21]
	v_mfma_f32_16x16x32_bf16 v[196:199], v[30:33], v[126:129], v[26:29]
	s_setprio 0
	s_add_i32 s60, 0, 0x18000
	v_add_u32_e32 v2, s60, v140
	s_add_i32 s61, 0, 0x1c000
	ds_read_b128 v[200:203], v2
	ds_read_b128 v[204:207], v2 offset:1024
	ds_read_b128 v[208:211], v2 offset:2048
	ds_read_b128 v[212:215], v2 offset:3072
	v_add_u32_e32 v2, s61, v140
	ds_read_b128 v[216:219], v2
	ds_read_b128 v[220:223], v2 offset:1024
	ds_read_b128 v[224:227], v2 offset:2048
	ds_read_b128 v[228:231], v2 offset:3072
	s_mov_b32 m0, s47
	ds_read_b128 v[42:45], v141 offset:32768
	ds_read_b128 v[50:53], v141 offset:33792
	ds_read_b128 v[58:61], v141 offset:34816
	ds_read_b128 v[122:125], v141 offset:35840
	ds_read_b128 v[126:129], v141 offset:36864
	ds_read_b128 v[232:235], v141 offset:37888
	ds_read_b128 v[236:239], v141 offset:38912
	ds_read_b128 v[240:243], v141 offset:39936
	global_load_lds_dwordx4 v138, s[42:43]
	s_mov_b32 m0, s48
	s_nop 0
	global_load_lds_dwordx4 v132, s[42:43]
	s_waitcnt vmcnt(8)
	s_waitcnt lgkmcnt(0)
	s_barrier
	s_setprio 1
	s_waitcnt lgkmcnt(0)
	v_mfma_f32_16x16x32_bf16 v[2:5], v[200:203], v[42:45], v[66:69]
	v_mfma_f32_16x16x32_bf16 v[6:9], v[208:211], v[42:45], v[70:73]
	v_mfma_f32_16x16x32_bf16 v[10:13], v[200:203], v[58:61], v[74:77]
	v_mfma_f32_16x16x32_bf16 v[14:17], v[208:211], v[58:61], v[78:81]
	v_mfma_f32_16x16x32_bf16 v[18:21], v[200:203], v[126:129], v[82:85]
	v_mfma_f32_16x16x32_bf16 v[22:25], v[208:211], v[126:129], v[86:89]
	v_mfma_f32_16x16x32_bf16 v[26:29], v[200:203], v[236:239], v[90:93]
	v_mfma_f32_16x16x32_bf16 v[30:33], v[208:211], v[236:239], v[94:97]
	v_mfma_f32_16x16x32_bf16 v[2:5], v[204:207], v[50:53], v[2:5]
	v_mfma_f32_16x16x32_bf16 v[6:9], v[212:215], v[50:53], v[6:9]
	v_mfma_f32_16x16x32_bf16 v[10:13], v[204:207], v[122:125], v[10:13]
	v_mfma_f32_16x16x32_bf16 v[14:17], v[212:215], v[122:125], v[14:17]
	v_mfma_f32_16x16x32_bf16 v[18:21], v[204:207], v[232:235], v[18:21]
	v_mfma_f32_16x16x32_bf16 v[22:25], v[212:215], v[232:235], v[22:25]
	v_mfma_f32_16x16x32_bf16 v[26:29], v[204:207], v[240:243], v[26:29]
	v_mfma_f32_16x16x32_bf16 v[30:33], v[212:215], v[240:243], v[30:33]
	s_setprio 0
	s_setprio 1
	v_mfma_f32_16x16x32_bf16 v[34:37], v[216:219], v[42:45], v[98:101]
	v_mfma_f32_16x16x32_bf16 v[38:41], v[224:227], v[42:45], v[38:41]
	v_mfma_f32_16x16x32_bf16 v[34:37], v[220:223], v[50:53], v[34:37]
	v_mfma_f32_16x16x32_bf16 v[38:41], v[228:231], v[50:53], v[38:41]
	v_mfma_f32_16x16x32_bf16 v[42:45], v[216:219], v[58:61], v[102:105]
	v_mfma_f32_16x16x32_bf16 v[46:49], v[224:227], v[58:61], v[46:49]
	v_mfma_f32_16x16x32_bf16 v[50:53], v[216:219], v[126:129], v[106:109]
	v_mfma_f32_16x16x32_bf16 v[54:57], v[224:227], v[126:129], v[54:57]
	v_mfma_f32_16x16x32_bf16 v[58:61], v[216:219], v[236:239], v[110:113]
	v_mfma_f32_16x16x32_bf16 v[62:65], v[224:227], v[236:239], v[62:65]
	v_mfma_f32_16x16x32_bf16 v[42:45], v[220:223], v[122:125], v[42:45]
	v_mfma_f32_16x16x32_bf16 v[46:49], v[228:231], v[122:125], v[46:49]
	v_mfma_f32_16x16x32_bf16 v[50:53], v[220:223], v[232:235], v[50:53]
	s_setprio 2
	s_barrier
	v_mfma_f32_16x16x32_bf16 v[54:57], v[228:231], v[232:235], v[54:57]
	v_mfma_f32_16x16x32_bf16 v[58:61], v[220:223], v[240:243], v[58:61]
	v_mfma_f32_16x16x32_bf16 v[62:65], v[228:231], v[240:243], v[62:65]
	s_setprio 0
	s_add_i32 s60, s60, s21
	v_lshl_add_u64 v[66:67], v[136:137], 0, s[12:13]
	s_mov_b32 m0, s60
	ds_read_b128 v[94:97], v141 offset:49152
	ds_read_b128 v[98:101], v141 offset:50176
	ds_read_b128 v[102:105], v141 offset:51200
	ds_read_b128 v[106:109], v141 offset:52224
	ds_read_b128 v[110:113], v141 offset:53248
	ds_read_b128 v[232:235], v141 offset:54272
	ds_read_b128 v[236:239], v141 offset:55296
	ds_read_b128 v[240:243], v141 offset:56320
	global_load_lds_dwordx4 v[66:67], off
	v_lshl_add_u64 v[66:67], v[244:245], 0, s[12:13]
	s_add_i32 m0, s60, 0x2000
	s_add_i32 s60, s61, s21
	global_load_lds_dwordx4 v[66:67], off
	s_mov_b32 m0, s60
	v_lshl_add_u64 v[66:67], v[246:247], 0, s[12:13]
	global_load_lds_dwordx4 v130, s[44:45]
	s_add_i32 m0, s60, 0x2000
	s_nop 0
	global_load_lds_dwordx4 v134, s[44:45]
	s_mov_b32 m0, s52
	s_nop 0
	global_load_lds_dwordx4 v[66:67], off
	v_lshl_add_u64 v[66:67], v[248:249], 0, s[12:13]
	s_mov_b32 m0, s53
	s_nop 0
	global_load_lds_dwordx4 v[66:67], off
	s_waitcnt vmcnt(8)
	s_waitcnt lgkmcnt(0)
	s_barrier
	s_setprio 1
	s_waitcnt lgkmcnt(0)
	v_mfma_f32_16x16x32_bf16 v[66:69], v[200:203], v[94:97], v[142:145]
	v_mfma_f32_16x16x32_bf16 v[122:125], v[204:207], v[98:101], v[66:69]
	v_mfma_f32_16x16x32_bf16 v[66:69], v[208:211], v[94:97], v[148:151]
	v_mfma_f32_16x16x32_bf16 v[126:129], v[212:215], v[98:101], v[66:69]
	v_mfma_f32_16x16x32_bf16 v[66:69], v[200:203], v[102:105], v[152:155]
	v_mfma_f32_16x16x32_bf16 v[70:73], v[208:211], v[102:105], v[156:159]
	v_mfma_f32_16x16x32_bf16 v[74:77], v[200:203], v[110:113], v[160:163]
	v_mfma_f32_16x16x32_bf16 v[78:81], v[208:211], v[110:113], v[164:167]
	v_mfma_f32_16x16x32_bf16 v[82:85], v[200:203], v[236:239], v[168:171]
	v_mfma_f32_16x16x32_bf16 v[86:89], v[208:211], v[236:239], v[172:175]
	v_mfma_f32_16x16x32_bf16 v[66:69], v[204:207], v[106:109], v[66:69]
	v_mfma_f32_16x16x32_bf16 v[70:73], v[212:215], v[106:109], v[70:73]
	v_mfma_f32_16x16x32_bf16 v[74:77], v[204:207], v[232:235], v[74:77]
	v_mfma_f32_16x16x32_bf16 v[78:81], v[212:215], v[232:235], v[78:81]
	v_mfma_f32_16x16x32_bf16 v[82:85], v[204:207], v[240:243], v[82:85]
	v_mfma_f32_16x16x32_bf16 v[86:89], v[212:215], v[240:243], v[86:89]
	s_setprio 0
	s_setprio 1
	v_mfma_f32_16x16x32_bf16 v[90:93], v[216:219], v[94:97], v[114:117]
	v_mfma_f32_16x16x32_bf16 v[94:97], v[224:227], v[94:97], v[176:179]
	v_mfma_f32_16x16x32_bf16 v[90:93], v[220:223], v[98:101], v[90:93]
	v_mfma_f32_16x16x32_bf16 v[94:97], v[228:231], v[98:101], v[94:97]
	v_mfma_f32_16x16x32_bf16 v[98:101], v[216:219], v[102:105], v[180:183]
	v_mfma_f32_16x16x32_bf16 v[102:105], v[224:227], v[102:105], v[184:187]
	v_mfma_f32_16x16x32_bf16 v[98:101], v[220:223], v[106:109], v[98:101]
	v_mfma_f32_16x16x32_bf16 v[102:105], v[228:231], v[106:109], v[102:105]
	v_mfma_f32_16x16x32_bf16 v[106:109], v[216:219], v[110:113], v[188:191]
	v_mfma_f32_16x16x32_bf16 v[110:113], v[224:227], v[110:113], v[118:121]
	v_mfma_f32_16x16x32_bf16 v[114:117], v[216:219], v[236:239], v[192:195]
	v_mfma_f32_16x16x32_bf16 v[118:121], v[224:227], v[236:239], v[196:199]
	v_mfma_f32_16x16x32_bf16 v[106:109], v[220:223], v[232:235], v[106:109]
	s_setprio 2
	s_barrier
	v_mfma_f32_16x16x32_bf16 v[110:113], v[228:231], v[232:235], v[110:113]
	v_mfma_f32_16x16x32_bf16 v[114:117], v[220:223], v[240:243], v[114:117]
	v_mfma_f32_16x16x32_bf16 v[118:121], v[228:231], v[240:243], v[118:121]
	s_setprio 0
	s_add_i32 s59, s59, 2
	s_cmp_ge_i32 s59, s15
	s_cbranch_scc0 .LBB0_379
	v_mov_b32_e32 v136, v130
	s_branch .LBB0_382

.LBB0_383:
	v_add_u32_e32 v133, s56, v140
	ds_read_b128 v[142:145], v133
	ds_read_b128 v[148:151], v133 offset:1024
	ds_read_b128 v[152:155], v133 offset:2048
	ds_read_b128 v[156:159], v133 offset:3072
	v_add_u32_e32 v133, s57, v140
	ds_read_b128 v[160:163], v133
	ds_read_b128 v[164:167], v133 offset:1024
	ds_read_b128 v[168:171], v133 offset:2048
	ds_read_b128 v[172:175], v133 offset:3072
	s_add_u32 s38, s36, 0xfff80080
	s_addc_u32 s39, s37, -1
	s_cmp_eq_u32 s43, 28
	s_cselect_b32 s41, s31, s39
	s_cselect_b32 s40, s30, s38
	s_cselect_b32 s39, s35, s42
	s_cselect_b32 s38, s34, s15
	s_mov_b32 m0, s54
	v_add_u32_e32 v141, 0, v1
	ds_read_b128 v[176:179], v141
	ds_read_b128 v[180:183], v141 offset:1024
	ds_read_b128 v[184:187], v141 offset:2048
	ds_read_b128 v[188:191], v141 offset:3072
	ds_read_b128 v[192:195], v141 offset:4096
	ds_read_b128 v[196:199], v141 offset:5120
	ds_read_b128 v[200:203], v141 offset:6144
	ds_read_b128 v[204:207], v141 offset:7168
	global_load_lds_dwordx4 v130, s[36:37]
	s_mov_b32 m0, s55
	v_mov_b32_e32 v133, v131
	global_load_lds_dwordx4 v132, s[36:37]
	s_waitcnt vmcnt(8)
	s_waitcnt lgkmcnt(0)
	s_barrier
	s_setprio 1
	s_waitcnt lgkmcnt(0)
	v_mfma_f32_16x16x32_bf16 v[2:5], v[142:145], v[176:179], v[2:5]
	v_mfma_f32_16x16x32_bf16 v[2:5], v[148:151], v[180:183], v[2:5]
	v_mfma_f32_16x16x32_bf16 v[6:9], v[156:159], v[180:183], v[6:9]
	v_mfma_f32_16x16x32_bf16 v[6:9], v[152:155], v[176:179], v[6:9]
	v_mfma_f32_16x16x32_bf16 v[14:17], v[152:155], v[184:187], v[14:17]
	v_mfma_f32_16x16x32_bf16 v[14:17], v[156:159], v[188:191], v[14:17]
	v_mfma_f32_16x16x32_bf16 v[10:13], v[148:151], v[188:191], v[10:13]
	v_mfma_f32_16x16x32_bf16 v[10:13], v[142:145], v[184:187], v[10:13]
	v_mfma_f32_16x16x32_bf16 v[18:21], v[142:145], v[192:195], v[18:21]
	v_mfma_f32_16x16x32_bf16 v[18:21], v[148:151], v[196:199], v[18:21]
	v_mfma_f32_16x16x32_bf16 v[22:25], v[156:159], v[196:199], v[22:25]
	v_mfma_f32_16x16x32_bf16 v[22:25], v[152:155], v[192:195], v[22:25]
	v_mfma_f32_16x16x32_bf16 v[30:33], v[152:155], v[200:203], v[30:33]
	v_mfma_f32_16x16x32_bf16 v[30:33], v[156:159], v[204:207], v[30:33]
	v_mfma_f32_16x16x32_bf16 v[26:29], v[148:151], v[204:207], v[26:29]
	v_mfma_f32_16x16x32_bf16 v[26:29], v[142:145], v[200:203], v[26:29]
	s_setprio 0
	s_setprio 1
	v_mfma_f32_16x16x32_bf16 v[34:37], v[160:163], v[176:179], v[34:37]
	v_mfma_f32_16x16x32_bf16 v[34:37], v[164:167], v[180:183], v[34:37]
	v_mfma_f32_16x16x32_bf16 v[38:41], v[172:175], v[180:183], v[38:41]
	v_mfma_f32_16x16x32_bf16 v[38:41], v[168:171], v[176:179], v[38:41]
	v_mfma_f32_16x16x32_bf16 v[46:49], v[168:171], v[184:187], v[46:49]
	v_mfma_f32_16x16x32_bf16 v[46:49], v[172:175], v[188:191], v[46:49]
	v_mfma_f32_16x16x32_bf16 v[42:45], v[164:167], v[188:191], v[42:45]
	v_mfma_f32_16x16x32_bf16 v[42:45], v[160:163], v[184:187], v[42:45]
	v_mfma_f32_16x16x32_bf16 v[50:53], v[160:163], v[192:195], v[50:53]
	v_mfma_f32_16x16x32_bf16 v[50:53], v[164:167], v[196:199], v[50:53]
	v_mfma_f32_16x16x32_bf16 v[54:57], v[172:175], v[196:199], v[54:57]
	v_mfma_f32_16x16x32_bf16 v[54:57], v[168:171], v[192:195], v[54:57]
	v_mfma_f32_16x16x32_bf16 v[62:65], v[168:171], v[200:203], v[62:65]
	s_setprio 2
	s_barrier
	v_mfma_f32_16x16x32_bf16 v[62:65], v[172:175], v[204:207], v[62:65]
	v_mfma_f32_16x16x32_bf16 v[58:61], v[164:167], v[204:207], v[58:61]
	v_mfma_f32_16x16x32_bf16 v[58:61], v[160:163], v[200:203], v[58:61]
	s_setprio 0
	s_add_i32 s44, s56, s21
	s_mov_b32 m0, s44
	ds_read_b128 v[176:179], v141 offset:16384
	ds_read_b128 v[180:183], v141 offset:17408
	ds_read_b128 v[184:187], v141 offset:18432
	ds_read_b128 v[188:191], v141 offset:19456
	ds_read_b128 v[192:195], v141 offset:20480
	ds_read_b128 v[196:199], v141 offset:21504
	ds_read_b128 v[200:203], v141 offset:22528
	ds_read_b128 v[204:207], v141 offset:23552
	global_load_lds_dwordx4 v136, s[38:39]
	s_add_i32 m0, s44, 0x2000
	s_add_u32 s44, s38, 0x80000
	s_addc_u32 s45, s39, 0
	s_add_i32 s59, s57, s21
	global_load_lds_dwordx4 v134, s[38:39]
	s_mov_b32 m0, s59
	v_mov_b32_e32 v137, v131
	global_load_lds_dwordx4 v136, s[44:45]
	s_add_i32 m0, s59, 0x2000
	v_mov_b32_e32 v135, v131
	global_load_lds_dwordx4 v134, s[44:45]
	s_mov_b32 m0, s33
	v_lshl_add_u64 v[138:139], s[38:39], 0, v[136:137]
	global_load_lds_dwordx4 v130, s[40:41]
	s_mov_b32 m0, s46
	v_lshl_add_u64 v[208:209], s[38:39], 0, v[134:135]
	global_load_lds_dwordx4 v132, s[40:41]
	s_waitcnt vmcnt(8)
	s_waitcnt lgkmcnt(0)
	v_lshl_add_u64 v[210:211], s[40:41], 0, v[130:131]
	v_lshl_add_u64 v[212:213], s[40:41], 0, v[132:133]
	s_barrier
	s_setprio 1
	s_waitcnt lgkmcnt(0)
	v_mfma_f32_16x16x32_bf16 v[122:125], v[142:145], v[176:179], v[122:125]
	v_mfma_f32_16x16x32_bf16 v[122:125], v[148:151], v[180:183], v[122:125]
	v_mfma_f32_16x16x32_bf16 v[126:129], v[156:159], v[180:183], v[126:129]
	v_mfma_f32_16x16x32_bf16 v[126:129], v[152:155], v[176:179], v[126:129]
	v_mfma_f32_16x16x32_bf16 v[70:73], v[152:155], v[184:187], v[70:73]
	v_mfma_f32_16x16x32_bf16 v[70:73], v[156:159], v[188:191], v[70:73]
	v_mfma_f32_16x16x32_bf16 v[66:69], v[148:151], v[188:191], v[66:69]
	v_mfma_f32_16x16x32_bf16 v[66:69], v[142:145], v[184:187], v[66:69]
	v_mfma_f32_16x16x32_bf16 v[74:77], v[142:145], v[192:195], v[74:77]
	v_mfma_f32_16x16x32_bf16 v[74:77], v[148:151], v[196:199], v[74:77]
	v_mfma_f32_16x16x32_bf16 v[78:81], v[156:159], v[196:199], v[78:81]
	v_mfma_f32_16x16x32_bf16 v[78:81], v[152:155], v[192:195], v[78:81]
	v_mfma_f32_16x16x32_bf16 v[86:89], v[152:155], v[200:203], v[86:89]
	v_mfma_f32_16x16x32_bf16 v[86:89], v[156:159], v[204:207], v[86:89]
	v_mfma_f32_16x16x32_bf16 v[82:85], v[148:151], v[204:207], v[82:85]
	v_mfma_f32_16x16x32_bf16 v[82:85], v[142:145], v[200:203], v[82:85]
	s_setprio 0
	s_setprio 1
	v_mfma_f32_16x16x32_bf16 v[90:93], v[160:163], v[176:179], v[90:93]
	v_mfma_f32_16x16x32_bf16 v[90:93], v[164:167], v[180:183], v[90:93]
	v_mfma_f32_16x16x32_bf16 v[94:97], v[172:175], v[180:183], v[94:97]
	v_mfma_f32_16x16x32_bf16 v[94:97], v[168:171], v[176:179], v[94:97]
	v_mfma_f32_16x16x32_bf16 v[102:105], v[168:171], v[184:187], v[102:105]
	v_mfma_f32_16x16x32_bf16 v[102:105], v[172:175], v[188:191], v[102:105]
	v_mfma_f32_16x16x32_bf16 v[98:101], v[164:167], v[188:191], v[98:101]
	v_mfma_f32_16x16x32_bf16 v[98:101], v[160:163], v[184:187], v[98:101]
	v_mfma_f32_16x16x32_bf16 v[106:109], v[160:163], v[192:195], v[106:109]
	v_mfma_f32_16x16x32_bf16 v[106:109], v[164:167], v[196:199], v[106:109]
	v_mfma_f32_16x16x32_bf16 v[110:113], v[172:175], v[196:199], v[110:113]
	v_mfma_f32_16x16x32_bf16 v[110:113], v[168:171], v[192:195], v[110:113]
	v_mfma_f32_16x16x32_bf16 v[118:121], v[168:171], v[200:203], v[118:121]
	s_setprio 2
	s_barrier
	v_mfma_f32_16x16x32_bf16 v[118:121], v[172:175], v[204:207], v[118:121]
	v_mfma_f32_16x16x32_bf16 v[114:117], v[164:167], v[204:207], v[114:117]
	v_mfma_f32_16x16x32_bf16 v[114:117], v[160:163], v[200:203], v[114:117]
	s_setprio 0
	s_add_i32 s44, 0, 0x18000
	v_add_u32_e32 v135, s44, v140
	s_add_i32 s45, 0, 0x1c000
	ds_read_b128 v[142:145], v135
	ds_read_b128 v[148:151], v135 offset:1024
	ds_read_b128 v[152:155], v135 offset:2048
	ds_read_b128 v[156:159], v135 offset:3072
	v_add_u32_e32 v135, s45, v140
	ds_read_b128 v[160:163], v135
	ds_read_b128 v[164:167], v135 offset:1024
	ds_read_b128 v[168:171], v135 offset:2048
	ds_read_b128 v[172:175], v135 offset:3072
	s_add_u32 s40, s40, 0x80000
	s_addc_u32 s41, s41, 0
	s_mov_b32 m0, s47
	ds_read_b128 v[176:179], v141 offset:32768
	ds_read_b128 v[180:183], v141 offset:33792
	ds_read_b128 v[184:187], v141 offset:34816
	ds_read_b128 v[188:191], v141 offset:35840
	ds_read_b128 v[192:195], v141 offset:36864
	ds_read_b128 v[196:199], v141 offset:37888
	ds_read_b128 v[200:203], v141 offset:38912
	ds_read_b128 v[204:207], v141 offset:39936
	global_load_lds_dwordx4 v130, s[40:41]
	s_mov_b32 m0, s48
	s_nop 0
	global_load_lds_dwordx4 v132, s[40:41]
	s_waitcnt vmcnt(8)
	s_waitcnt lgkmcnt(0)
	s_barrier
	s_setprio 1
	s_waitcnt lgkmcnt(0)
	v_mfma_f32_16x16x32_bf16 v[2:5], v[142:145], v[176:179], v[2:5]
	v_mfma_f32_16x16x32_bf16 v[2:5], v[148:151], v[180:183], v[2:5]
	v_mfma_f32_16x16x32_bf16 v[6:9], v[156:159], v[180:183], v[6:9]
	v_mfma_f32_16x16x32_bf16 v[6:9], v[152:155], v[176:179], v[6:9]
	v_mfma_f32_16x16x32_bf16 v[14:17], v[152:155], v[184:187], v[14:17]
	v_mfma_f32_16x16x32_bf16 v[14:17], v[156:159], v[188:191], v[14:17]
	v_mfma_f32_16x16x32_bf16 v[10:13], v[148:151], v[188:191], v[10:13]
	v_mfma_f32_16x16x32_bf16 v[10:13], v[142:145], v[184:187], v[10:13]
	v_mfma_f32_16x16x32_bf16 v[18:21], v[142:145], v[192:195], v[18:21]
	v_mfma_f32_16x16x32_bf16 v[18:21], v[148:151], v[196:199], v[18:21]
	v_mfma_f32_16x16x32_bf16 v[22:25], v[156:159], v[196:199], v[22:25]
	v_mfma_f32_16x16x32_bf16 v[22:25], v[152:155], v[192:195], v[22:25]
	v_mfma_f32_16x16x32_bf16 v[30:33], v[152:155], v[200:203], v[30:33]
	v_mfma_f32_16x16x32_bf16 v[30:33], v[156:159], v[204:207], v[30:33]
	v_mfma_f32_16x16x32_bf16 v[26:29], v[148:151], v[204:207], v[26:29]
	v_mfma_f32_16x16x32_bf16 v[26:29], v[142:145], v[200:203], v[26:29]
	s_setprio 0
	s_setprio 1
	v_mfma_f32_16x16x32_bf16 v[34:37], v[160:163], v[176:179], v[34:37]
	v_mfma_f32_16x16x32_bf16 v[34:37], v[164:167], v[180:183], v[34:37]
	v_mfma_f32_16x16x32_bf16 v[38:41], v[172:175], v[180:183], v[38:41]
	v_mfma_f32_16x16x32_bf16 v[38:41], v[168:171], v[176:179], v[38:41]
	v_mfma_f32_16x16x32_bf16 v[46:49], v[168:171], v[184:187], v[46:49]
	v_mfma_f32_16x16x32_bf16 v[46:49], v[172:175], v[188:191], v[46:49]
	v_mfma_f32_16x16x32_bf16 v[42:45], v[164:167], v[188:191], v[42:45]
	v_mfma_f32_16x16x32_bf16 v[42:45], v[160:163], v[184:187], v[42:45]
	v_mfma_f32_16x16x32_bf16 v[50:53], v[160:163], v[192:195], v[50:53]
	v_mfma_f32_16x16x32_bf16 v[50:53], v[164:167], v[196:199], v[50:53]
	v_mfma_f32_16x16x32_bf16 v[54:57], v[172:175], v[196:199], v[54:57]
	v_mfma_f32_16x16x32_bf16 v[54:57], v[168:171], v[192:195], v[54:57]
	v_mfma_f32_16x16x32_bf16 v[62:65], v[168:171], v[200:203], v[62:65]
	s_setprio 2
	s_barrier
	v_mfma_f32_16x16x32_bf16 v[62:65], v[172:175], v[204:207], v[62:65]
	v_mfma_f32_16x16x32_bf16 v[58:61], v[164:167], v[204:207], v[58:61]
	v_mfma_f32_16x16x32_bf16 v[58:61], v[160:163], v[200:203], v[58:61]
	s_setprio 0
	s_add_i32 s40, s44, s21
	v_lshl_add_u64 v[138:139], v[138:139], 0, s[6:7]
	s_mov_b32 m0, s40
	ds_read_b128 v[176:179], v141 offset:49152
	ds_read_b128 v[180:183], v141 offset:50176
	ds_read_b128 v[184:187], v141 offset:51200
	ds_read_b128 v[188:191], v141 offset:52224
	ds_read_b128 v[192:195], v141 offset:53248
	ds_read_b128 v[196:199], v141 offset:54272
	ds_read_b128 v[200:203], v141 offset:55296
	ds_read_b128 v[204:207], v141 offset:56320
	global_load_lds_dwordx4 v[138:139], off
	s_add_i32 m0, s40, 0x2000
	s_add_u32 s38, s38, 0x80080
	v_lshl_add_u64 v[138:139], v[208:209], 0, s[6:7]
	s_addc_u32 s39, s39, 0
	s_add_i32 s40, s45, s21
	global_load_lds_dwordx4 v[138:139], off
	s_mov_b32 m0, s40
	v_lshl_add_u64 v[138:139], v[210:211], 0, s[6:7]
	global_load_lds_dwordx4 v136, s[38:39]
	s_add_i32 m0, s40, 0x2000
	s_nop 0
	global_load_lds_dwordx4 v134, s[38:39]
	s_mov_b32 m0, s52
	s_nop 0
	global_load_lds_dwordx4 v[138:139], off
	v_lshl_add_u64 v[138:139], v[212:213], 0, s[6:7]
	s_mov_b32 m0, s53
	s_nop 0
	global_load_lds_dwordx4 v[138:139], off
	s_waitcnt vmcnt(8)
	s_waitcnt lgkmcnt(0)
	s_barrier
	s_setprio 1
	s_waitcnt lgkmcnt(0)
	v_mfma_f32_16x16x32_bf16 v[122:125], v[142:145], v[176:179], v[122:125]
	v_mfma_f32_16x16x32_bf16 v[122:125], v[148:151], v[180:183], v[122:125]
	v_mfma_f32_16x16x32_bf16 v[126:129], v[156:159], v[180:183], v[126:129]
	v_mfma_f32_16x16x32_bf16 v[126:129], v[152:155], v[176:179], v[126:129]
	v_mfma_f32_16x16x32_bf16 v[70:73], v[152:155], v[184:187], v[70:73]
	v_mfma_f32_16x16x32_bf16 v[70:73], v[156:159], v[188:191], v[70:73]
	v_mfma_f32_16x16x32_bf16 v[66:69], v[148:151], v[188:191], v[66:69]
	v_mfma_f32_16x16x32_bf16 v[66:69], v[142:145], v[184:187], v[66:69]
	v_mfma_f32_16x16x32_bf16 v[74:77], v[142:145], v[192:195], v[74:77]
	v_mfma_f32_16x16x32_bf16 v[74:77], v[148:151], v[196:199], v[74:77]
	v_mfma_f32_16x16x32_bf16 v[78:81], v[156:159], v[196:199], v[78:81]
	v_mfma_f32_16x16x32_bf16 v[78:81], v[152:155], v[192:195], v[78:81]
	v_mfma_f32_16x16x32_bf16 v[86:89], v[152:155], v[200:203], v[86:89]
	v_mfma_f32_16x16x32_bf16 v[86:89], v[156:159], v[204:207], v[86:89]
	v_mfma_f32_16x16x32_bf16 v[82:85], v[148:151], v[204:207], v[82:85]
	v_mfma_f32_16x16x32_bf16 v[82:85], v[142:145], v[200:203], v[82:85]
	s_setprio 0
	s_setprio 1
	v_mfma_f32_16x16x32_bf16 v[90:93], v[160:163], v[176:179], v[90:93]
	v_mfma_f32_16x16x32_bf16 v[90:93], v[164:167], v[180:183], v[90:93]
	v_mfma_f32_16x16x32_bf16 v[94:97], v[172:175], v[180:183], v[94:97]
	v_mfma_f32_16x16x32_bf16 v[94:97], v[168:171], v[176:179], v[94:97]
	v_mfma_f32_16x16x32_bf16 v[102:105], v[168:171], v[184:187], v[102:105]
	v_mfma_f32_16x16x32_bf16 v[102:105], v[172:175], v[188:191], v[102:105]
	v_mfma_f32_16x16x32_bf16 v[98:101], v[164:167], v[188:191], v[98:101]
	v_mfma_f32_16x16x32_bf16 v[98:101], v[160:163], v[184:187], v[98:101]
	v_mfma_f32_16x16x32_bf16 v[106:109], v[160:163], v[192:195], v[106:109]
	v_mfma_f32_16x16x32_bf16 v[106:109], v[164:167], v[196:199], v[106:109]
	v_mfma_f32_16x16x32_bf16 v[110:113], v[172:175], v[196:199], v[110:113]
	v_mfma_f32_16x16x32_bf16 v[110:113], v[168:171], v[192:195], v[110:113]
	v_mfma_f32_16x16x32_bf16 v[118:121], v[168:171], v[200:203], v[118:121]
	s_setprio 2
	s_barrier
	v_mfma_f32_16x16x32_bf16 v[118:121], v[172:175], v[204:207], v[118:121]
	v_mfma_f32_16x16x32_bf16 v[114:117], v[164:167], v[204:207], v[114:117]
	v_mfma_f32_16x16x32_bf16 v[114:117], v[160:163], v[200:203], v[114:117]
	s_setprio 0
	s_add_i32 s43, s43, 2
	s_add_u32 s36, s36, 0x100
	s_addc_u32 s37, s37, 0
	s_add_u32 s15, s15, 0x100
	s_addc_u32 s42, s42, 0
	s_cmp_gt_u32 s43, 29
	s_cbranch_scc0 .LBB0_383
	s_and_b64 vcc, exec, s[8:9]
	s_cbranch_vccz .LBB0_386
	s_barrier

.LBB0_462:
	v_add_u32_e32 v14, s54, v140
	v_add_u32_e32 v30, s55, v140
	ds_read_b128 v[2:5], v14
	ds_read_b128 v[6:9], v14 offset:1024
	ds_read_b128 v[10:13], v14 offset:2048
	ds_read_b128 v[14:17], v14 offset:3072
	ds_read_b128 v[18:21], v30
	ds_read_b128 v[22:25], v30 offset:1024
	ds_read_b128 v[26:29], v30 offset:2048
	ds_read_b128 v[30:33], v30 offset:3072
	v_add_u32_e32 v141, 0, v1
	ds_read_b128 v[34:37], v141
	ds_read_b128 v[38:41], v141 offset:1024
	ds_read_b128 v[42:45], v141 offset:2048
	ds_read_b128 v[46:49], v141 offset:3072
	ds_read_b128 v[50:53], v141 offset:4096
	ds_read_b128 v[54:57], v141 offset:5120
	ds_read_b128 v[58:61], v141 offset:6144
	ds_read_b128 v[62:65], v141 offset:7168
	s_waitcnt vmcnt(8)
	s_waitcnt lgkmcnt(0)
	s_barrier
	s_setprio 1
	s_waitcnt lgkmcnt(0)
	v_mfma_f32_16x16x32_bf16 v[66:69], v[2:5], v[34:37], 0
	v_mfma_f32_16x16x32_bf16 v[66:69], v[6:9], v[38:41], v[66:69]
	v_mfma_f32_16x16x32_bf16 v[70:73], v[10:13], v[34:37], 0
	v_mfma_f32_16x16x32_bf16 v[70:73], v[14:17], v[38:41], v[70:73]
	v_mfma_f32_16x16x32_bf16 v[78:81], v[10:13], v[42:45], 0
	v_mfma_f32_16x16x32_bf16 v[78:81], v[14:17], v[46:49], v[78:81]
	v_mfma_f32_16x16x32_bf16 v[74:77], v[2:5], v[42:45], 0
	v_mfma_f32_16x16x32_bf16 v[74:77], v[6:9], v[46:49], v[74:77]
	v_mfma_f32_16x16x32_bf16 v[82:85], v[2:5], v[50:53], 0
	v_mfma_f32_16x16x32_bf16 v[82:85], v[6:9], v[54:57], v[82:85]
	v_mfma_f32_16x16x32_bf16 v[86:89], v[10:13], v[50:53], 0
	v_mfma_f32_16x16x32_bf16 v[86:89], v[14:17], v[54:57], v[86:89]
	v_mfma_f32_16x16x32_bf16 v[94:97], v[10:13], v[58:61], 0
	v_mfma_f32_16x16x32_bf16 v[94:97], v[14:17], v[62:65], v[94:97]
	v_mfma_f32_16x16x32_bf16 v[90:93], v[2:5], v[58:61], 0
	v_mfma_f32_16x16x32_bf16 v[90:93], v[6:9], v[62:65], v[90:93]
	s_setprio 0
	s_setprio 1
	v_mfma_f32_16x16x32_bf16 v[98:101], v[18:21], v[34:37], 0
	v_mfma_f32_16x16x32_bf16 v[34:37], v[26:29], v[34:37], 0
	v_mfma_f32_16x16x32_bf16 v[102:105], v[18:21], v[42:45], 0
	v_mfma_f32_16x16x32_bf16 v[42:45], v[26:29], v[42:45], 0
	v_mfma_f32_16x16x32_bf16 v[106:109], v[18:21], v[50:53], 0
	v_mfma_f32_16x16x32_bf16 v[50:53], v[26:29], v[50:53], 0
	v_mfma_f32_16x16x32_bf16 v[110:113], v[18:21], v[58:61], 0
	v_mfma_f32_16x16x32_bf16 v[58:61], v[26:29], v[58:61], 0
	v_mfma_f32_16x16x32_bf16 v[98:101], v[22:25], v[38:41], v[98:101]
	v_mfma_f32_16x16x32_bf16 v[38:41], v[30:33], v[38:41], v[34:37]
	v_mfma_f32_16x16x32_bf16 v[102:105], v[22:25], v[46:49], v[102:105]
	v_mfma_f32_16x16x32_bf16 v[46:49], v[30:33], v[46:49], v[42:45]
	v_mfma_f32_16x16x32_bf16 v[106:109], v[22:25], v[54:57], v[106:109]
	s_setprio 2
	s_barrier
	v_mfma_f32_16x16x32_bf16 v[54:57], v[30:33], v[54:57], v[50:53]
	v_mfma_f32_16x16x32_bf16 v[110:113], v[22:25], v[62:65], v[110:113]
	v_mfma_f32_16x16x32_bf16 v[62:65], v[30:33], v[62:65], v[58:61]
	s_setprio 0
	v_lshl_add_u64 v[136:137], s[36:37], 0, v[130:131]
	s_add_i32 s62, s54, s21
	v_mov_b32_e32 v135, v131
	v_lshl_add_u64 v[142:143], v[136:137], 0, s[12:13]
	s_mov_b32 m0, s62
	v_lshl_add_u64 v[244:245], s[36:37], 0, v[134:135]
	ds_read_b128 v[34:37], v141 offset:16384
	ds_read_b128 v[42:45], v141 offset:17408
	ds_read_b128 v[50:53], v141 offset:18432
	ds_read_b128 v[58:61], v141 offset:19456
	ds_read_b128 v[114:117], v141 offset:20480
	ds_read_b128 v[118:121], v141 offset:21504
	ds_read_b128 v[122:125], v141 offset:22528
	ds_read_b128 v[126:129], v141 offset:23552
	global_load_lds_dwordx4 v[142:143], off
	v_lshl_add_u64 v[142:143], v[244:245], 0, s[12:13]
	s_add_i32 m0, s62, 0x2000
	s_add_i32 s62, s55, s21
	global_load_lds_dwordx4 v[142:143], off
	s_mov_b32 m0, s62
	v_mov_b32_e32 v139, v131
	global_load_lds_dwordx4 v130, s[38:39]
	s_add_i32 m0, s62, 0x2000
	v_lshl_add_u64 v[246:247], s[34:35], 0, v[138:139]
	v_mov_b32_e32 v133, v131
	global_load_lds_dwordx4 v134, s[38:39]
	v_lshl_add_u64 v[142:143], v[246:247], 0, s[12:13]
	s_mov_b32 m0, s33
	v_lshl_add_u64 v[248:249], s[34:35], 0, v[132:133]
	global_load_lds_dwordx4 v[142:143], off
	v_lshl_add_u64 v[142:143], v[248:249], 0, s[12:13]
	s_mov_b32 m0, s44
	s_nop 0
	global_load_lds_dwordx4 v[142:143], off
	s_waitcnt vmcnt(8)
	s_waitcnt lgkmcnt(0)
	s_barrier
	s_setprio 1
	s_waitcnt lgkmcnt(0)
	v_mfma_f32_16x16x32_bf16 v[142:145], v[2:5], v[34:37], 0
	v_mfma_f32_16x16x32_bf16 v[148:151], v[10:13], v[34:37], 0
	v_mfma_f32_16x16x32_bf16 v[152:155], v[2:5], v[50:53], 0
	v_mfma_f32_16x16x32_bf16 v[156:159], v[10:13], v[50:53], 0
	v_mfma_f32_16x16x32_bf16 v[160:163], v[2:5], v[114:117], 0
	v_mfma_f32_16x16x32_bf16 v[164:167], v[10:13], v[114:117], 0
	v_mfma_f32_16x16x32_bf16 v[2:5], v[2:5], v[122:125], 0
	v_mfma_f32_16x16x32_bf16 v[10:13], v[10:13], v[122:125], 0
	v_mfma_f32_16x16x32_bf16 v[142:145], v[6:9], v[42:45], v[142:145]
	v_mfma_f32_16x16x32_bf16 v[148:151], v[14:17], v[42:45], v[148:151]
	v_mfma_f32_16x16x32_bf16 v[152:155], v[6:9], v[58:61], v[152:155]
	v_mfma_f32_16x16x32_bf16 v[156:159], v[14:17], v[58:61], v[156:159]
	v_mfma_f32_16x16x32_bf16 v[160:163], v[6:9], v[118:121], v[160:163]
	v_mfma_f32_16x16x32_bf16 v[164:167], v[14:17], v[118:121], v[164:167]
	v_mfma_f32_16x16x32_bf16 v[168:171], v[6:9], v[126:129], v[2:5]
	v_mfma_f32_16x16x32_bf16 v[172:175], v[14:17], v[126:129], v[10:13]
	s_setprio 0
	s_setprio 1
	v_mfma_f32_16x16x32_bf16 v[2:5], v[18:21], v[34:37], 0
	v_mfma_f32_16x16x32_bf16 v[6:9], v[26:29], v[34:37], 0
	v_mfma_f32_16x16x32_bf16 v[10:13], v[18:21], v[50:53], 0
	v_mfma_f32_16x16x32_bf16 v[14:17], v[26:29], v[50:53], 0
	v_mfma_f32_16x16x32_bf16 v[34:37], v[18:21], v[114:117], 0
	v_mfma_f32_16x16x32_bf16 v[50:53], v[26:29], v[114:117], 0
	v_mfma_f32_16x16x32_bf16 v[18:21], v[18:21], v[122:125], 0
	v_mfma_f32_16x16x32_bf16 v[26:29], v[26:29], v[122:125], 0
	v_mfma_f32_16x16x32_bf16 v[114:117], v[22:25], v[42:45], v[2:5]
	v_mfma_f32_16x16x32_bf16 v[122:125], v[30:33], v[42:45], v[6:9]
	v_mfma_f32_16x16x32_bf16 v[184:187], v[22:25], v[118:121], v[34:37]
	v_mfma_f32_16x16x32_bf16 v[118:121], v[30:33], v[118:121], v[50:53]
	v_mfma_f32_16x16x32_bf16 v[188:191], v[22:25], v[126:129], v[18:21]
	s_setprio 2
	s_barrier
	v_mfma_f32_16x16x32_bf16 v[126:129], v[30:33], v[126:129], v[26:29]
	v_mfma_f32_16x16x32_bf16 v[176:179], v[22:25], v[58:61], v[10:13]
	v_mfma_f32_16x16x32_bf16 v[180:183], v[30:33], v[58:61], v[14:17]
	s_setprio 0
	s_add_i32 s62, 0, 0x18000
	v_add_u32_e32 v2, s62, v140
	s_add_i32 s63, 0, 0x1c000
	ds_read_b128 v[192:195], v2
	ds_read_b128 v[196:199], v2 offset:1024
	ds_read_b128 v[200:203], v2 offset:2048
	ds_read_b128 v[204:207], v2 offset:3072
	v_add_u32_e32 v2, s63, v140
	ds_read_b128 v[208:211], v2
	ds_read_b128 v[212:215], v2 offset:1024
	ds_read_b128 v[216:219], v2 offset:2048
	ds_read_b128 v[220:223], v2 offset:3072
	s_mov_b32 m0, s45
	ds_read_b128 v[42:45], v141 offset:32768
	ds_read_b128 v[50:53], v141 offset:33792
	ds_read_b128 v[58:61], v141 offset:34816
	ds_read_b128 v[224:227], v141 offset:35840
	ds_read_b128 v[228:231], v141 offset:36864
	ds_read_b128 v[232:235], v141 offset:37888
	ds_read_b128 v[236:239], v141 offset:38912
	ds_read_b128 v[240:243], v141 offset:39936
	global_load_lds_dwordx4 v138, s[40:41]
	s_mov_b32 m0, s46
	s_nop 0
	global_load_lds_dwordx4 v132, s[40:41]
	s_waitcnt vmcnt(8)
	s_waitcnt lgkmcnt(0)
	s_barrier
	s_setprio 1
	s_waitcnt lgkmcnt(0)
	v_mfma_f32_16x16x32_bf16 v[2:5], v[192:195], v[42:45], v[66:69]
	v_mfma_f32_16x16x32_bf16 v[6:9], v[200:203], v[42:45], v[70:73]
	v_mfma_f32_16x16x32_bf16 v[10:13], v[192:195], v[58:61], v[74:77]
	v_mfma_f32_16x16x32_bf16 v[14:17], v[200:203], v[58:61], v[78:81]
	v_mfma_f32_16x16x32_bf16 v[18:21], v[192:195], v[228:231], v[82:85]
	v_mfma_f32_16x16x32_bf16 v[22:25], v[200:203], v[228:231], v[86:89]
	v_mfma_f32_16x16x32_bf16 v[26:29], v[192:195], v[236:239], v[90:93]
	v_mfma_f32_16x16x32_bf16 v[30:33], v[200:203], v[236:239], v[94:97]
	v_mfma_f32_16x16x32_bf16 v[2:5], v[196:199], v[50:53], v[2:5]
	v_mfma_f32_16x16x32_bf16 v[6:9], v[204:207], v[50:53], v[6:9]
	v_mfma_f32_16x16x32_bf16 v[10:13], v[196:199], v[224:227], v[10:13]
	v_mfma_f32_16x16x32_bf16 v[14:17], v[204:207], v[224:227], v[14:17]
	v_mfma_f32_16x16x32_bf16 v[18:21], v[196:199], v[232:235], v[18:21]
	v_mfma_f32_16x16x32_bf16 v[22:25], v[204:207], v[232:235], v[22:25]
	v_mfma_f32_16x16x32_bf16 v[26:29], v[196:199], v[240:243], v[26:29]
	v_mfma_f32_16x16x32_bf16 v[30:33], v[204:207], v[240:243], v[30:33]
	s_setprio 0
	s_setprio 1
	v_mfma_f32_16x16x32_bf16 v[34:37], v[208:211], v[42:45], v[98:101]
	v_mfma_f32_16x16x32_bf16 v[38:41], v[216:219], v[42:45], v[38:41]
	v_mfma_f32_16x16x32_bf16 v[34:37], v[212:215], v[50:53], v[34:37]
	v_mfma_f32_16x16x32_bf16 v[38:41], v[220:223], v[50:53], v[38:41]
	v_mfma_f32_16x16x32_bf16 v[42:45], v[208:211], v[58:61], v[102:105]
	v_mfma_f32_16x16x32_bf16 v[46:49], v[216:219], v[58:61], v[46:49]
	v_mfma_f32_16x16x32_bf16 v[50:53], v[208:211], v[228:231], v[106:109]
	v_mfma_f32_16x16x32_bf16 v[54:57], v[216:219], v[228:231], v[54:57]
	v_mfma_f32_16x16x32_bf16 v[58:61], v[208:211], v[236:239], v[110:113]
	v_mfma_f32_16x16x32_bf16 v[62:65], v[216:219], v[236:239], v[62:65]
	v_mfma_f32_16x16x32_bf16 v[42:45], v[212:215], v[224:227], v[42:45]
	v_mfma_f32_16x16x32_bf16 v[46:49], v[220:223], v[224:227], v[46:49]
	v_mfma_f32_16x16x32_bf16 v[50:53], v[212:215], v[232:235], v[50:53]
	s_setprio 2
	s_barrier
	v_mfma_f32_16x16x32_bf16 v[54:57], v[220:223], v[232:235], v[54:57]
	v_mfma_f32_16x16x32_bf16 v[58:61], v[212:215], v[240:243], v[58:61]
	v_mfma_f32_16x16x32_bf16 v[62:65], v[220:223], v[240:243], v[62:65]
	s_setprio 0
	s_add_i32 s62, s62, s21
	v_lshl_add_u64 v[66:67], v[136:137], 0, s[14:15]
	s_mov_b32 m0, s62
	ds_read_b128 v[102:105], v141 offset:49152
	ds_read_b128 v[106:109], v141 offset:50176
	ds_read_b128 v[110:113], v141 offset:51200
	ds_read_b128 v[224:227], v141 offset:52224
	ds_read_b128 v[228:231], v141 offset:53248
	ds_read_b128 v[232:235], v141 offset:54272
	ds_read_b128 v[236:239], v141 offset:55296
	ds_read_b128 v[240:243], v141 offset:56320
	global_load_lds_dwordx4 v[66:67], off
	v_lshl_add_u64 v[66:67], v[244:245], 0, s[14:15]
	s_add_i32 m0, s62, 0x2000
	s_add_i32 s62, s63, s21
	global_load_lds_dwordx4 v[66:67], off
	s_mov_b32 m0, s62
	v_lshl_add_u64 v[66:67], v[246:247], 0, s[14:15]
	global_load_lds_dwordx4 v130, s[42:43]
	s_add_i32 m0, s62, 0x2000
	s_nop 0
	global_load_lds_dwordx4 v134, s[42:43]
	s_mov_b32 m0, s50
	s_nop 0
	global_load_lds_dwordx4 v[66:67], off
	v_lshl_add_u64 v[66:67], v[248:249], 0, s[14:15]
	s_mov_b32 m0, s51
	s_nop 0
	global_load_lds_dwordx4 v[66:67], off
	s_waitcnt vmcnt(8)
	s_waitcnt lgkmcnt(0)
	s_barrier
	s_setprio 1
	s_waitcnt lgkmcnt(0)
	v_mfma_f32_16x16x32_bf16 v[66:69], v[192:195], v[102:105], v[142:145]
	v_mfma_f32_16x16x32_bf16 v[70:73], v[200:203], v[102:105], v[148:151]
	v_mfma_f32_16x16x32_bf16 v[74:77], v[192:195], v[110:113], v[152:155]
	v_mfma_f32_16x16x32_bf16 v[78:81], v[200:203], v[110:113], v[156:159]
	v_mfma_f32_16x16x32_bf16 v[82:85], v[192:195], v[228:231], v[160:163]
	v_mfma_f32_16x16x32_bf16 v[86:89], v[200:203], v[228:231], v[164:167]
	v_mfma_f32_16x16x32_bf16 v[90:93], v[192:195], v[236:239], v[168:171]
	v_mfma_f32_16x16x32_bf16 v[94:97], v[200:203], v[236:239], v[172:175]
	v_mfma_f32_16x16x32_bf16 v[66:69], v[196:199], v[106:109], v[66:69]
	v_mfma_f32_16x16x32_bf16 v[70:73], v[204:207], v[106:109], v[70:73]
	v_mfma_f32_16x16x32_bf16 v[74:77], v[196:199], v[224:227], v[74:77]
	v_mfma_f32_16x16x32_bf16 v[78:81], v[204:207], v[224:227], v[78:81]
	v_mfma_f32_16x16x32_bf16 v[82:85], v[196:199], v[232:235], v[82:85]
	v_mfma_f32_16x16x32_bf16 v[86:89], v[204:207], v[232:235], v[86:89]
	v_mfma_f32_16x16x32_bf16 v[90:93], v[196:199], v[240:243], v[90:93]
	v_mfma_f32_16x16x32_bf16 v[94:97], v[204:207], v[240:243], v[94:97]
	s_setprio 0
	s_setprio 1
	v_mfma_f32_16x16x32_bf16 v[98:101], v[208:211], v[102:105], v[114:117]
	v_mfma_f32_16x16x32_bf16 v[102:105], v[216:219], v[102:105], v[122:125]
	v_mfma_f32_16x16x32_bf16 v[98:101], v[212:215], v[106:109], v[98:101]
	v_mfma_f32_16x16x32_bf16 v[102:105], v[220:223], v[106:109], v[102:105]
	v_mfma_f32_16x16x32_bf16 v[106:109], v[208:211], v[110:113], v[176:179]
	v_mfma_f32_16x16x32_bf16 v[110:113], v[216:219], v[110:113], v[180:183]
	v_mfma_f32_16x16x32_bf16 v[114:117], v[208:211], v[228:231], v[184:187]
	v_mfma_f32_16x16x32_bf16 v[118:121], v[216:219], v[228:231], v[118:121]
	v_mfma_f32_16x16x32_bf16 v[122:125], v[208:211], v[236:239], v[188:191]
	v_mfma_f32_16x16x32_bf16 v[126:129], v[216:219], v[236:239], v[126:129]
	v_mfma_f32_16x16x32_bf16 v[106:109], v[212:215], v[224:227], v[106:109]
	v_mfma_f32_16x16x32_bf16 v[110:113], v[220:223], v[224:227], v[110:113]
	v_mfma_f32_16x16x32_bf16 v[114:117], v[212:215], v[232:235], v[114:117]
	s_setprio 2
	s_barrier
	v_mfma_f32_16x16x32_bf16 v[118:121], v[220:223], v[232:235], v[118:121]
	v_mfma_f32_16x16x32_bf16 v[122:125], v[212:215], v[240:243], v[122:125]
	v_mfma_f32_16x16x32_bf16 v[126:129], v[220:223], v[240:243], v[126:129]
	s_setprio 0
	s_add_i32 s61, s61, 2
	s_cmp_ge_i32 s61, s60
	s_cbranch_scc0 .LBB0_462
	v_mov_b32_e32 v136, v130
	s_branch .LBB0_465

.LBB0_466:
	v_add_u32_e32 v133, s54, v140
	ds_read_b128 v[142:145], v133
	ds_read_b128 v[148:151], v133 offset:1024
	ds_read_b128 v[152:155], v133 offset:2048
	ds_read_b128 v[156:159], v133 offset:3072
	v_add_u32_e32 v133, s55, v140
	ds_read_b128 v[160:163], v133
	ds_read_b128 v[164:167], v133 offset:1024
	ds_read_b128 v[168:171], v133 offset:2048
	ds_read_b128 v[172:175], v133 offset:3072
	s_add_u32 s36, s34, 0xffc00080
	s_addc_u32 s37, s35, -1
	s_cmp_eq_u32 s42, 4
	s_cselect_b32 s39, s29, s37
	s_cselect_b32 s38, s28, s36
	s_cselect_b32 s37, s31, s41
	s_cselect_b32 s36, s30, s40
	s_mov_b32 m0, s52
	v_add_u32_e32 v141, 0, v1
	ds_read_b128 v[176:179], v141
	ds_read_b128 v[180:183], v141 offset:1024
	ds_read_b128 v[184:187], v141 offset:2048
	ds_read_b128 v[188:191], v141 offset:3072
	ds_read_b128 v[192:195], v141 offset:4096
	ds_read_b128 v[196:199], v141 offset:5120
	ds_read_b128 v[200:203], v141 offset:6144
	ds_read_b128 v[204:207], v141 offset:7168
	global_load_lds_dwordx4 v130, s[34:35]
	s_mov_b32 m0, s53
	v_mov_b32_e32 v133, v131
	global_load_lds_dwordx4 v132, s[34:35]
	s_waitcnt vmcnt(8)
	s_waitcnt lgkmcnt(0)
	s_barrier
	s_setprio 1
	s_waitcnt lgkmcnt(0)
	v_mfma_f32_16x16x32_bf16 v[2:5], v[142:145], v[176:179], v[2:5]
	v_mfma_f32_16x16x32_bf16 v[2:5], v[148:151], v[180:183], v[2:5]
	v_mfma_f32_16x16x32_bf16 v[6:9], v[156:159], v[180:183], v[6:9]
	v_mfma_f32_16x16x32_bf16 v[6:9], v[152:155], v[176:179], v[6:9]
	v_mfma_f32_16x16x32_bf16 v[14:17], v[152:155], v[184:187], v[14:17]
	v_mfma_f32_16x16x32_bf16 v[14:17], v[156:159], v[188:191], v[14:17]
	v_mfma_f32_16x16x32_bf16 v[10:13], v[148:151], v[188:191], v[10:13]
	v_mfma_f32_16x16x32_bf16 v[10:13], v[142:145], v[184:187], v[10:13]
	v_mfma_f32_16x16x32_bf16 v[18:21], v[142:145], v[192:195], v[18:21]
	v_mfma_f32_16x16x32_bf16 v[18:21], v[148:151], v[196:199], v[18:21]
	v_mfma_f32_16x16x32_bf16 v[22:25], v[156:159], v[196:199], v[22:25]
	v_mfma_f32_16x16x32_bf16 v[22:25], v[152:155], v[192:195], v[22:25]
	v_mfma_f32_16x16x32_bf16 v[30:33], v[152:155], v[200:203], v[30:33]
	v_mfma_f32_16x16x32_bf16 v[30:33], v[156:159], v[204:207], v[30:33]
	v_mfma_f32_16x16x32_bf16 v[26:29], v[148:151], v[204:207], v[26:29]
	v_mfma_f32_16x16x32_bf16 v[26:29], v[142:145], v[200:203], v[26:29]
	s_setprio 0
	s_setprio 1
	v_mfma_f32_16x16x32_bf16 v[34:37], v[160:163], v[176:179], v[34:37]
	v_mfma_f32_16x16x32_bf16 v[34:37], v[164:167], v[180:183], v[34:37]
	v_mfma_f32_16x16x32_bf16 v[38:41], v[172:175], v[180:183], v[38:41]
	v_mfma_f32_16x16x32_bf16 v[38:41], v[168:171], v[176:179], v[38:41]
	v_mfma_f32_16x16x32_bf16 v[46:49], v[168:171], v[184:187], v[46:49]
	v_mfma_f32_16x16x32_bf16 v[46:49], v[172:175], v[188:191], v[46:49]
	v_mfma_f32_16x16x32_bf16 v[42:45], v[164:167], v[188:191], v[42:45]
	v_mfma_f32_16x16x32_bf16 v[42:45], v[160:163], v[184:187], v[42:45]
	v_mfma_f32_16x16x32_bf16 v[50:53], v[160:163], v[192:195], v[50:53]
	v_mfma_f32_16x16x32_bf16 v[50:53], v[164:167], v[196:199], v[50:53]
	v_mfma_f32_16x16x32_bf16 v[54:57], v[172:175], v[196:199], v[54:57]
	v_mfma_f32_16x16x32_bf16 v[54:57], v[168:171], v[192:195], v[54:57]
	v_mfma_f32_16x16x32_bf16 v[62:65], v[168:171], v[200:203], v[62:65]
	s_setprio 2
	s_barrier
	v_mfma_f32_16x16x32_bf16 v[62:65], v[172:175], v[204:207], v[62:65]
	v_mfma_f32_16x16x32_bf16 v[58:61], v[164:167], v[204:207], v[58:61]
	v_mfma_f32_16x16x32_bf16 v[58:61], v[160:163], v[200:203], v[58:61]
	s_setprio 0
	s_add_i32 s43, s54, s21
	s_mov_b32 m0, s43
	ds_read_b128 v[176:179], v141 offset:16384
	ds_read_b128 v[180:183], v141 offset:17408
	ds_read_b128 v[184:187], v141 offset:18432
	ds_read_b128 v[188:191], v141 offset:19456
	ds_read_b128 v[192:195], v141 offset:20480
	ds_read_b128 v[196:199], v141 offset:21504
	ds_read_b128 v[200:203], v141 offset:22528
	ds_read_b128 v[204:207], v141 offset:23552
	global_load_lds_dwordx4 v136, s[36:37]
	s_add_i32 m0, s43, 0x2000
	s_add_u32 s60, s36, 0x80000
	s_addc_u32 s61, s37, 0
	s_add_i32 s43, s55, s21
	global_load_lds_dwordx4 v134, s[36:37]
	s_mov_b32 m0, s43
	v_mov_b32_e32 v137, v131
	global_load_lds_dwordx4 v136, s[60:61]
	s_add_i32 m0, s43, 0x2000
	v_mov_b32_e32 v135, v131
	global_load_lds_dwordx4 v134, s[60:61]
	s_mov_b32 m0, s33
	v_lshl_add_u64 v[138:139], s[36:37], 0, v[136:137]
	global_load_lds_dwordx4 v130, s[38:39]
	s_mov_b32 m0, s44
	v_lshl_add_u64 v[208:209], s[36:37], 0, v[134:135]
	global_load_lds_dwordx4 v132, s[38:39]
	s_waitcnt vmcnt(8)
	s_waitcnt lgkmcnt(0)
	v_lshl_add_u64 v[210:211], s[38:39], 0, v[130:131]
	v_lshl_add_u64 v[212:213], s[38:39], 0, v[132:133]
	s_barrier
	s_setprio 1
	s_waitcnt lgkmcnt(0)
	v_mfma_f32_16x16x32_bf16 v[66:69], v[142:145], v[176:179], v[66:69]
	v_mfma_f32_16x16x32_bf16 v[66:69], v[148:151], v[180:183], v[66:69]
	v_mfma_f32_16x16x32_bf16 v[70:73], v[156:159], v[180:183], v[70:73]
	v_mfma_f32_16x16x32_bf16 v[70:73], v[152:155], v[176:179], v[70:73]
	v_mfma_f32_16x16x32_bf16 v[78:81], v[152:155], v[184:187], v[78:81]
	v_mfma_f32_16x16x32_bf16 v[78:81], v[156:159], v[188:191], v[78:81]
	v_mfma_f32_16x16x32_bf16 v[74:77], v[148:151], v[188:191], v[74:77]
	v_mfma_f32_16x16x32_bf16 v[74:77], v[142:145], v[184:187], v[74:77]
	v_mfma_f32_16x16x32_bf16 v[82:85], v[142:145], v[192:195], v[82:85]
	v_mfma_f32_16x16x32_bf16 v[82:85], v[148:151], v[196:199], v[82:85]
	v_mfma_f32_16x16x32_bf16 v[86:89], v[156:159], v[196:199], v[86:89]
	v_mfma_f32_16x16x32_bf16 v[86:89], v[152:155], v[192:195], v[86:89]
	v_mfma_f32_16x16x32_bf16 v[94:97], v[152:155], v[200:203], v[94:97]
	v_mfma_f32_16x16x32_bf16 v[94:97], v[156:159], v[204:207], v[94:97]
	v_mfma_f32_16x16x32_bf16 v[90:93], v[148:151], v[204:207], v[90:93]
	v_mfma_f32_16x16x32_bf16 v[90:93], v[142:145], v[200:203], v[90:93]
	s_setprio 0
	s_setprio 1
	v_mfma_f32_16x16x32_bf16 v[98:101], v[160:163], v[176:179], v[98:101]
	v_mfma_f32_16x16x32_bf16 v[98:101], v[164:167], v[180:183], v[98:101]
	v_mfma_f32_16x16x32_bf16 v[102:105], v[172:175], v[180:183], v[102:105]
	v_mfma_f32_16x16x32_bf16 v[102:105], v[168:171], v[176:179], v[102:105]
	v_mfma_f32_16x16x32_bf16 v[110:113], v[168:171], v[184:187], v[110:113]
	v_mfma_f32_16x16x32_bf16 v[110:113], v[172:175], v[188:191], v[110:113]
	v_mfma_f32_16x16x32_bf16 v[106:109], v[164:167], v[188:191], v[106:109]
	v_mfma_f32_16x16x32_bf16 v[106:109], v[160:163], v[184:187], v[106:109]
	v_mfma_f32_16x16x32_bf16 v[114:117], v[160:163], v[192:195], v[114:117]
	v_mfma_f32_16x16x32_bf16 v[114:117], v[164:167], v[196:199], v[114:117]
	v_mfma_f32_16x16x32_bf16 v[118:121], v[172:175], v[196:199], v[118:121]
	v_mfma_f32_16x16x32_bf16 v[118:121], v[168:171], v[192:195], v[118:121]
	v_mfma_f32_16x16x32_bf16 v[126:129], v[168:171], v[200:203], v[126:129]
	s_setprio 2
	s_barrier
	v_mfma_f32_16x16x32_bf16 v[126:129], v[172:175], v[204:207], v[126:129]
	v_mfma_f32_16x16x32_bf16 v[122:125], v[164:167], v[204:207], v[122:125]
	v_mfma_f32_16x16x32_bf16 v[122:125], v[160:163], v[200:203], v[122:125]
	s_setprio 0
	s_add_i32 s43, 0, 0x18000
	v_add_u32_e32 v135, s43, v140
	s_add_i32 s60, 0, 0x1c000
	ds_read_b128 v[142:145], v135
	ds_read_b128 v[148:151], v135 offset:1024
	ds_read_b128 v[152:155], v135 offset:2048
	ds_read_b128 v[156:159], v135 offset:3072
	v_add_u32_e32 v135, s60, v140
	ds_read_b128 v[160:163], v135
	ds_read_b128 v[164:167], v135 offset:1024
	ds_read_b128 v[168:171], v135 offset:2048
	ds_read_b128 v[172:175], v135 offset:3072
	s_add_u32 s38, s38, 0x400000
	s_addc_u32 s39, s39, 0
	s_mov_b32 m0, s45
	ds_read_b128 v[176:179], v141 offset:32768
	ds_read_b128 v[180:183], v141 offset:33792
	ds_read_b128 v[184:187], v141 offset:34816
	ds_read_b128 v[188:191], v141 offset:35840
	ds_read_b128 v[192:195], v141 offset:36864
	ds_read_b128 v[196:199], v141 offset:37888
	ds_read_b128 v[200:203], v141 offset:38912
	ds_read_b128 v[204:207], v141 offset:39936
	global_load_lds_dwordx4 v130, s[38:39]
	s_mov_b32 m0, s46
	s_nop 0
	global_load_lds_dwordx4 v132, s[38:39]
	s_waitcnt vmcnt(8)
	s_waitcnt lgkmcnt(0)
	s_barrier
	s_setprio 1
	s_waitcnt lgkmcnt(0)
	v_mfma_f32_16x16x32_bf16 v[2:5], v[142:145], v[176:179], v[2:5]
	v_mfma_f32_16x16x32_bf16 v[2:5], v[148:151], v[180:183], v[2:5]
	v_mfma_f32_16x16x32_bf16 v[6:9], v[156:159], v[180:183], v[6:9]
	v_mfma_f32_16x16x32_bf16 v[6:9], v[152:155], v[176:179], v[6:9]
	v_mfma_f32_16x16x32_bf16 v[14:17], v[152:155], v[184:187], v[14:17]
	v_mfma_f32_16x16x32_bf16 v[14:17], v[156:159], v[188:191], v[14:17]
	v_mfma_f32_16x16x32_bf16 v[10:13], v[148:151], v[188:191], v[10:13]
	v_mfma_f32_16x16x32_bf16 v[10:13], v[142:145], v[184:187], v[10:13]
	v_mfma_f32_16x16x32_bf16 v[18:21], v[142:145], v[192:195], v[18:21]
	v_mfma_f32_16x16x32_bf16 v[18:21], v[148:151], v[196:199], v[18:21]
	v_mfma_f32_16x16x32_bf16 v[22:25], v[156:159], v[196:199], v[22:25]
	v_mfma_f32_16x16x32_bf16 v[22:25], v[152:155], v[192:195], v[22:25]
	v_mfma_f32_16x16x32_bf16 v[30:33], v[152:155], v[200:203], v[30:33]
	v_mfma_f32_16x16x32_bf16 v[30:33], v[156:159], v[204:207], v[30:33]
	v_mfma_f32_16x16x32_bf16 v[26:29], v[148:151], v[204:207], v[26:29]
	v_mfma_f32_16x16x32_bf16 v[26:29], v[142:145], v[200:203], v[26:29]
	s_setprio 0
	s_setprio 1
	v_mfma_f32_16x16x32_bf16 v[34:37], v[160:163], v[176:179], v[34:37]
	v_mfma_f32_16x16x32_bf16 v[34:37], v[164:167], v[180:183], v[34:37]
	v_mfma_f32_16x16x32_bf16 v[38:41], v[172:175], v[180:183], v[38:41]
	v_mfma_f32_16x16x32_bf16 v[38:41], v[168:171], v[176:179], v[38:41]
	v_mfma_f32_16x16x32_bf16 v[46:49], v[168:171], v[184:187], v[46:49]
	v_mfma_f32_16x16x32_bf16 v[46:49], v[172:175], v[188:191], v[46:49]
	v_mfma_f32_16x16x32_bf16 v[42:45], v[164:167], v[188:191], v[42:45]
	v_mfma_f32_16x16x32_bf16 v[42:45], v[160:163], v[184:187], v[42:45]
	v_mfma_f32_16x16x32_bf16 v[50:53], v[160:163], v[192:195], v[50:53]
	v_mfma_f32_16x16x32_bf16 v[50:53], v[164:167], v[196:199], v[50:53]
	v_mfma_f32_16x16x32_bf16 v[54:57], v[172:175], v[196:199], v[54:57]
	v_mfma_f32_16x16x32_bf16 v[54:57], v[168:171], v[192:195], v[54:57]
	v_mfma_f32_16x16x32_bf16 v[62:65], v[168:171], v[200:203], v[62:65]
	s_setprio 2
	s_barrier
	v_mfma_f32_16x16x32_bf16 v[62:65], v[172:175], v[204:207], v[62:65]
	v_mfma_f32_16x16x32_bf16 v[58:61], v[164:167], v[204:207], v[58:61]
	v_mfma_f32_16x16x32_bf16 v[58:61], v[160:163], v[200:203], v[58:61]
	s_setprio 0
	s_add_i32 s38, s43, s21
	v_lshl_add_u64 v[138:139], v[138:139], 0, s[8:9]
	s_mov_b32 m0, s38
	ds_read_b128 v[176:179], v141 offset:49152
	ds_read_b128 v[180:183], v141 offset:50176
	ds_read_b128 v[184:187], v141 offset:51200
	ds_read_b128 v[188:191], v141 offset:52224
	ds_read_b128 v[192:195], v141 offset:53248
	ds_read_b128 v[196:199], v141 offset:54272
	ds_read_b128 v[200:203], v141 offset:55296
	ds_read_b128 v[204:207], v141 offset:56320
	global_load_lds_dwordx4 v[138:139], off
	s_add_i32 m0, s38, 0x2000
	s_add_u32 s36, s36, 0x80080
	v_lshl_add_u64 v[138:139], v[208:209], 0, s[8:9]
	s_addc_u32 s37, s37, 0
	s_add_i32 s38, s60, s21
	global_load_lds_dwordx4 v[138:139], off
	s_mov_b32 m0, s38
	v_lshl_add_u64 v[138:139], v[210:211], 0, s[8:9]
	global_load_lds_dwordx4 v136, s[36:37]
	s_add_i32 m0, s38, 0x2000
	s_nop 0
	global_load_lds_dwordx4 v134, s[36:37]
	s_mov_b32 m0, s50
	s_nop 0
	global_load_lds_dwordx4 v[138:139], off
	v_lshl_add_u64 v[138:139], v[212:213], 0, s[8:9]
	s_mov_b32 m0, s51
	s_nop 0
	global_load_lds_dwordx4 v[138:139], off
	s_waitcnt vmcnt(8)
	s_waitcnt lgkmcnt(0)
	s_barrier
	s_setprio 1
	s_waitcnt lgkmcnt(0)
	v_mfma_f32_16x16x32_bf16 v[66:69], v[142:145], v[176:179], v[66:69]
	v_mfma_f32_16x16x32_bf16 v[66:69], v[148:151], v[180:183], v[66:69]
	v_mfma_f32_16x16x32_bf16 v[70:73], v[156:159], v[180:183], v[70:73]
	v_mfma_f32_16x16x32_bf16 v[70:73], v[152:155], v[176:179], v[70:73]
	v_mfma_f32_16x16x32_bf16 v[78:81], v[152:155], v[184:187], v[78:81]
	v_mfma_f32_16x16x32_bf16 v[78:81], v[156:159], v[188:191], v[78:81]
	v_mfma_f32_16x16x32_bf16 v[74:77], v[148:151], v[188:191], v[74:77]
	v_mfma_f32_16x16x32_bf16 v[74:77], v[142:145], v[184:187], v[74:77]
	v_mfma_f32_16x16x32_bf16 v[82:85], v[142:145], v[192:195], v[82:85]
	v_mfma_f32_16x16x32_bf16 v[82:85], v[148:151], v[196:199], v[82:85]
	v_mfma_f32_16x16x32_bf16 v[86:89], v[156:159], v[196:199], v[86:89]
	v_mfma_f32_16x16x32_bf16 v[86:89], v[152:155], v[192:195], v[86:89]
	v_mfma_f32_16x16x32_bf16 v[94:97], v[152:155], v[200:203], v[94:97]
	v_mfma_f32_16x16x32_bf16 v[94:97], v[156:159], v[204:207], v[94:97]
	v_mfma_f32_16x16x32_bf16 v[90:93], v[148:151], v[204:207], v[90:93]
	v_mfma_f32_16x16x32_bf16 v[90:93], v[142:145], v[200:203], v[90:93]
	s_setprio 0
	s_setprio 1
	v_mfma_f32_16x16x32_bf16 v[98:101], v[160:163], v[176:179], v[98:101]
	v_mfma_f32_16x16x32_bf16 v[98:101], v[164:167], v[180:183], v[98:101]
	v_mfma_f32_16x16x32_bf16 v[102:105], v[172:175], v[180:183], v[102:105]
	v_mfma_f32_16x16x32_bf16 v[102:105], v[168:171], v[176:179], v[102:105]
	v_mfma_f32_16x16x32_bf16 v[110:113], v[168:171], v[184:187], v[110:113]
	v_mfma_f32_16x16x32_bf16 v[110:113], v[172:175], v[188:191], v[110:113]
	v_mfma_f32_16x16x32_bf16 v[106:109], v[164:167], v[188:191], v[106:109]
	v_mfma_f32_16x16x32_bf16 v[106:109], v[160:163], v[184:187], v[106:109]
	v_mfma_f32_16x16x32_bf16 v[114:117], v[160:163], v[192:195], v[114:117]
	v_mfma_f32_16x16x32_bf16 v[114:117], v[164:167], v[196:199], v[114:117]
	v_mfma_f32_16x16x32_bf16 v[118:121], v[172:175], v[196:199], v[118:121]
	v_mfma_f32_16x16x32_bf16 v[118:121], v[168:171], v[192:195], v[118:121]
	v_mfma_f32_16x16x32_bf16 v[126:129], v[168:171], v[200:203], v[126:129]
	s_setprio 2
	s_barrier
	v_mfma_f32_16x16x32_bf16 v[126:129], v[172:175], v[204:207], v[126:129]
	v_mfma_f32_16x16x32_bf16 v[122:125], v[164:167], v[204:207], v[122:125]
	v_mfma_f32_16x16x32_bf16 v[122:125], v[160:163], v[200:203], v[122:125]
	s_setprio 0
	s_add_i32 s42, s42, 2
	s_add_u32 s34, s34, 0x100
	s_addc_u32 s35, s35, 0
	s_add_u32 s40, s40, 0x100
	s_addc_u32 s41, s41, 0
	s_cmp_gt_u32 s42, 5
	s_cbranch_scc0 .LBB0_466
	s_and_b64 vcc, exec, s[10:11]
	s_cbranch_vccz .LBB0_469
	s_barrier

.LBB0_495:
	v_add_u32_e32 v14, s58, v140
	v_add_u32_e32 v30, s59, v140
	ds_read_b128 v[2:5], v14
	ds_read_b128 v[6:9], v14 offset:1024
	ds_read_b128 v[10:13], v14 offset:2048
	ds_read_b128 v[14:17], v14 offset:3072
	ds_read_b128 v[18:21], v30
	ds_read_b128 v[22:25], v30 offset:1024
	ds_read_b128 v[26:29], v30 offset:2048
	ds_read_b128 v[30:33], v30 offset:3072
	v_add_u32_e32 v141, 0, v1
	ds_read_b128 v[34:37], v141
	ds_read_b128 v[38:41], v141 offset:1024
	ds_read_b128 v[42:45], v141 offset:2048
	ds_read_b128 v[46:49], v141 offset:3072
	ds_read_b128 v[50:53], v141 offset:4096
	ds_read_b128 v[54:57], v141 offset:5120
	ds_read_b128 v[58:61], v141 offset:6144
	ds_read_b128 v[62:65], v141 offset:7168
	s_waitcnt vmcnt(8)
	s_waitcnt lgkmcnt(0)
	s_barrier
	s_setprio 1
	s_waitcnt lgkmcnt(0)
	v_mfma_f32_16x16x32_bf16 v[66:69], v[2:5], v[34:37], 0
	v_mfma_f32_16x16x32_bf16 v[66:69], v[6:9], v[38:41], v[66:69]
	v_mfma_f32_16x16x32_bf16 v[70:73], v[10:13], v[34:37], 0
	v_mfma_f32_16x16x32_bf16 v[70:73], v[14:17], v[38:41], v[70:73]
	v_mfma_f32_16x16x32_bf16 v[78:81], v[10:13], v[42:45], 0
	v_mfma_f32_16x16x32_bf16 v[78:81], v[14:17], v[46:49], v[78:81]
	v_mfma_f32_16x16x32_bf16 v[74:77], v[2:5], v[42:45], 0
	v_mfma_f32_16x16x32_bf16 v[74:77], v[6:9], v[46:49], v[74:77]
	v_mfma_f32_16x16x32_bf16 v[82:85], v[2:5], v[50:53], 0
	v_mfma_f32_16x16x32_bf16 v[82:85], v[6:9], v[54:57], v[82:85]
	v_mfma_f32_16x16x32_bf16 v[86:89], v[10:13], v[50:53], 0
	v_mfma_f32_16x16x32_bf16 v[86:89], v[14:17], v[54:57], v[86:89]
	v_mfma_f32_16x16x32_bf16 v[94:97], v[10:13], v[58:61], 0
	v_mfma_f32_16x16x32_bf16 v[94:97], v[14:17], v[62:65], v[94:97]
	v_mfma_f32_16x16x32_bf16 v[90:93], v[2:5], v[58:61], 0
	v_mfma_f32_16x16x32_bf16 v[90:93], v[6:9], v[62:65], v[90:93]
	s_setprio 0
	s_setprio 1
	v_mfma_f32_16x16x32_bf16 v[98:101], v[18:21], v[34:37], 0
	v_mfma_f32_16x16x32_bf16 v[34:37], v[26:29], v[34:37], 0
	v_mfma_f32_16x16x32_bf16 v[102:105], v[18:21], v[42:45], 0
	v_mfma_f32_16x16x32_bf16 v[42:45], v[26:29], v[42:45], 0
	v_mfma_f32_16x16x32_bf16 v[106:109], v[18:21], v[50:53], 0
	v_mfma_f32_16x16x32_bf16 v[50:53], v[26:29], v[50:53], 0
	v_mfma_f32_16x16x32_bf16 v[110:113], v[18:21], v[58:61], 0
	v_mfma_f32_16x16x32_bf16 v[58:61], v[26:29], v[58:61], 0
	v_mfma_f32_16x16x32_bf16 v[98:101], v[22:25], v[38:41], v[98:101]
	v_mfma_f32_16x16x32_bf16 v[38:41], v[30:33], v[38:41], v[34:37]
	v_mfma_f32_16x16x32_bf16 v[102:105], v[22:25], v[46:49], v[102:105]
	v_mfma_f32_16x16x32_bf16 v[46:49], v[30:33], v[46:49], v[42:45]
	v_mfma_f32_16x16x32_bf16 v[106:109], v[22:25], v[54:57], v[106:109]
	s_setprio 2
	s_barrier
	v_mfma_f32_16x16x32_bf16 v[54:57], v[30:33], v[54:57], v[50:53]
	v_mfma_f32_16x16x32_bf16 v[110:113], v[22:25], v[62:65], v[110:113]
	v_mfma_f32_16x16x32_bf16 v[62:65], v[30:33], v[62:65], v[58:61]
	s_setprio 0
	v_lshl_add_u64 v[136:137], s[38:39], 0, v[130:131]
	s_add_i32 s62, s58, s46
	v_mov_b32_e32 v135, v131
	v_lshl_add_u64 v[142:143], v[136:137], 0, s[10:11]
	s_mov_b32 m0, s62
	v_lshl_add_u64 v[244:245], s[38:39], 0, v[134:135]
	ds_read_b128 v[34:37], v141 offset:16384
	ds_read_b128 v[42:45], v141 offset:17408
	ds_read_b128 v[50:53], v141 offset:18432
	ds_read_b128 v[58:61], v141 offset:19456
	ds_read_b128 v[114:117], v141 offset:20480
	ds_read_b128 v[118:121], v141 offset:21504
	ds_read_b128 v[122:125], v141 offset:22528
	ds_read_b128 v[126:129], v141 offset:23552
	global_load_lds_dwordx4 v[142:143], off
	v_lshl_add_u64 v[142:143], v[244:245], 0, s[10:11]
	s_add_i32 m0, s62, 0x2000
	s_add_i32 s62, s59, s46
	global_load_lds_dwordx4 v[142:143], off
	s_mov_b32 m0, s62
	v_mov_b32_e32 v139, v131
	global_load_lds_dwordx4 v130, s[40:41]
	s_add_i32 m0, s62, 0x2000
	v_lshl_add_u64 v[246:247], s[36:37], 0, v[138:139]
	v_mov_b32_e32 v133, v131
	global_load_lds_dwordx4 v134, s[40:41]
	v_lshl_add_u64 v[142:143], v[246:247], 0, s[10:11]
	s_mov_b32 m0, s47
	v_lshl_add_u64 v[248:249], s[36:37], 0, v[132:133]
	global_load_lds_dwordx4 v[142:143], off
	v_lshl_add_u64 v[142:143], v[248:249], 0, s[10:11]
	s_mov_b32 m0, s48
	s_nop 0
	global_load_lds_dwordx4 v[142:143], off
	s_waitcnt vmcnt(8)
	s_waitcnt lgkmcnt(0)
	s_barrier
	s_setprio 1
	s_waitcnt lgkmcnt(0)
	v_mfma_f32_16x16x32_bf16 v[142:145], v[2:5], v[34:37], 0
	v_mfma_f32_16x16x32_bf16 v[148:151], v[10:13], v[34:37], 0
	v_mfma_f32_16x16x32_bf16 v[152:155], v[2:5], v[50:53], 0
	v_mfma_f32_16x16x32_bf16 v[156:159], v[10:13], v[50:53], 0
	v_mfma_f32_16x16x32_bf16 v[160:163], v[2:5], v[114:117], 0
	v_mfma_f32_16x16x32_bf16 v[164:167], v[10:13], v[114:117], 0
	v_mfma_f32_16x16x32_bf16 v[2:5], v[2:5], v[122:125], 0
	v_mfma_f32_16x16x32_bf16 v[10:13], v[10:13], v[122:125], 0
	v_mfma_f32_16x16x32_bf16 v[142:145], v[6:9], v[42:45], v[142:145]
	v_mfma_f32_16x16x32_bf16 v[148:151], v[14:17], v[42:45], v[148:151]
	v_mfma_f32_16x16x32_bf16 v[152:155], v[6:9], v[58:61], v[152:155]
	v_mfma_f32_16x16x32_bf16 v[156:159], v[14:17], v[58:61], v[156:159]
	v_mfma_f32_16x16x32_bf16 v[160:163], v[6:9], v[118:121], v[160:163]
	v_mfma_f32_16x16x32_bf16 v[164:167], v[14:17], v[118:121], v[164:167]
	v_mfma_f32_16x16x32_bf16 v[168:171], v[6:9], v[126:129], v[2:5]
	v_mfma_f32_16x16x32_bf16 v[172:175], v[14:17], v[126:129], v[10:13]
	s_setprio 0
	s_setprio 1
	v_mfma_f32_16x16x32_bf16 v[2:5], v[18:21], v[34:37], 0
	v_mfma_f32_16x16x32_bf16 v[6:9], v[26:29], v[34:37], 0
	v_mfma_f32_16x16x32_bf16 v[10:13], v[18:21], v[50:53], 0
	v_mfma_f32_16x16x32_bf16 v[14:17], v[26:29], v[50:53], 0
	v_mfma_f32_16x16x32_bf16 v[34:37], v[18:21], v[114:117], 0
	v_mfma_f32_16x16x32_bf16 v[50:53], v[26:29], v[114:117], 0
	v_mfma_f32_16x16x32_bf16 v[18:21], v[18:21], v[122:125], 0
	v_mfma_f32_16x16x32_bf16 v[26:29], v[26:29], v[122:125], 0
	v_mfma_f32_16x16x32_bf16 v[114:117], v[22:25], v[42:45], v[2:5]
	v_mfma_f32_16x16x32_bf16 v[122:125], v[30:33], v[42:45], v[6:9]
	v_mfma_f32_16x16x32_bf16 v[184:187], v[22:25], v[118:121], v[34:37]
	v_mfma_f32_16x16x32_bf16 v[118:121], v[30:33], v[118:121], v[50:53]
	v_mfma_f32_16x16x32_bf16 v[188:191], v[22:25], v[126:129], v[18:21]
	s_setprio 2
	s_barrier
	v_mfma_f32_16x16x32_bf16 v[126:129], v[30:33], v[126:129], v[26:29]
	v_mfma_f32_16x16x32_bf16 v[176:179], v[22:25], v[58:61], v[10:13]
	v_mfma_f32_16x16x32_bf16 v[180:183], v[30:33], v[58:61], v[14:17]
	s_setprio 0
	s_add_i32 s62, 0, 0x18000
	v_add_u32_e32 v2, s62, v140
	s_add_i32 s63, 0, 0x1c000
	ds_read_b128 v[192:195], v2
	ds_read_b128 v[196:199], v2 offset:1024
	ds_read_b128 v[200:203], v2 offset:2048
	ds_read_b128 v[204:207], v2 offset:3072
	v_add_u32_e32 v2, s63, v140
	ds_read_b128 v[208:211], v2
	ds_read_b128 v[212:215], v2 offset:1024
	ds_read_b128 v[216:219], v2 offset:2048
	ds_read_b128 v[220:223], v2 offset:3072
	s_mov_b32 m0, s49
	ds_read_b128 v[42:45], v141 offset:32768
	ds_read_b128 v[50:53], v141 offset:33792
	ds_read_b128 v[58:61], v141 offset:34816
	ds_read_b128 v[224:227], v141 offset:35840
	ds_read_b128 v[228:231], v141 offset:36864
	ds_read_b128 v[232:235], v141 offset:37888
	ds_read_b128 v[236:239], v141 offset:38912
	ds_read_b128 v[240:243], v141 offset:39936
	global_load_lds_dwordx4 v138, s[42:43]
	s_mov_b32 m0, s50
	s_nop 0
	global_load_lds_dwordx4 v132, s[42:43]
	s_waitcnt vmcnt(8)
	s_waitcnt lgkmcnt(0)
	s_barrier
	s_setprio 1
	s_waitcnt lgkmcnt(0)
	v_mfma_f32_16x16x32_bf16 v[2:5], v[192:195], v[42:45], v[66:69]
	v_mfma_f32_16x16x32_bf16 v[6:9], v[200:203], v[42:45], v[70:73]
	v_mfma_f32_16x16x32_bf16 v[10:13], v[192:195], v[58:61], v[74:77]
	v_mfma_f32_16x16x32_bf16 v[14:17], v[200:203], v[58:61], v[78:81]
	v_mfma_f32_16x16x32_bf16 v[18:21], v[192:195], v[228:231], v[82:85]
	v_mfma_f32_16x16x32_bf16 v[22:25], v[200:203], v[228:231], v[86:89]
	v_mfma_f32_16x16x32_bf16 v[26:29], v[192:195], v[236:239], v[90:93]
	v_mfma_f32_16x16x32_bf16 v[30:33], v[200:203], v[236:239], v[94:97]
	v_mfma_f32_16x16x32_bf16 v[2:5], v[196:199], v[50:53], v[2:5]
	v_mfma_f32_16x16x32_bf16 v[6:9], v[204:207], v[50:53], v[6:9]
	v_mfma_f32_16x16x32_bf16 v[10:13], v[196:199], v[224:227], v[10:13]
	v_mfma_f32_16x16x32_bf16 v[14:17], v[204:207], v[224:227], v[14:17]
	v_mfma_f32_16x16x32_bf16 v[18:21], v[196:199], v[232:235], v[18:21]
	v_mfma_f32_16x16x32_bf16 v[22:25], v[204:207], v[232:235], v[22:25]
	v_mfma_f32_16x16x32_bf16 v[26:29], v[196:199], v[240:243], v[26:29]
	v_mfma_f32_16x16x32_bf16 v[30:33], v[204:207], v[240:243], v[30:33]
	s_setprio 0
	s_setprio 1
	v_mfma_f32_16x16x32_bf16 v[34:37], v[208:211], v[42:45], v[98:101]
	v_mfma_f32_16x16x32_bf16 v[38:41], v[216:219], v[42:45], v[38:41]
	v_mfma_f32_16x16x32_bf16 v[34:37], v[212:215], v[50:53], v[34:37]
	v_mfma_f32_16x16x32_bf16 v[38:41], v[220:223], v[50:53], v[38:41]
	v_mfma_f32_16x16x32_bf16 v[42:45], v[208:211], v[58:61], v[102:105]
	v_mfma_f32_16x16x32_bf16 v[46:49], v[216:219], v[58:61], v[46:49]
	v_mfma_f32_16x16x32_bf16 v[50:53], v[208:211], v[228:231], v[106:109]
	v_mfma_f32_16x16x32_bf16 v[54:57], v[216:219], v[228:231], v[54:57]
	v_mfma_f32_16x16x32_bf16 v[58:61], v[208:211], v[236:239], v[110:113]
	v_mfma_f32_16x16x32_bf16 v[62:65], v[216:219], v[236:239], v[62:65]
	v_mfma_f32_16x16x32_bf16 v[42:45], v[212:215], v[224:227], v[42:45]
	v_mfma_f32_16x16x32_bf16 v[46:49], v[220:223], v[224:227], v[46:49]
	v_mfma_f32_16x16x32_bf16 v[50:53], v[212:215], v[232:235], v[50:53]
	s_setprio 2
	s_barrier
	v_mfma_f32_16x16x32_bf16 v[54:57], v[220:223], v[232:235], v[54:57]
	v_mfma_f32_16x16x32_bf16 v[58:61], v[212:215], v[240:243], v[58:61]
	v_mfma_f32_16x16x32_bf16 v[62:65], v[220:223], v[240:243], v[62:65]
	s_setprio 0
	s_add_i32 s62, s62, s46
	v_lshl_add_u64 v[66:67], v[136:137], 0, s[12:13]
	s_mov_b32 m0, s62
	ds_read_b128 v[102:105], v141 offset:49152
	ds_read_b128 v[106:109], v141 offset:50176
	ds_read_b128 v[110:113], v141 offset:51200
	ds_read_b128 v[224:227], v141 offset:52224
	ds_read_b128 v[228:231], v141 offset:53248
	ds_read_b128 v[232:235], v141 offset:54272
	ds_read_b128 v[236:239], v141 offset:55296
	ds_read_b128 v[240:243], v141 offset:56320
	global_load_lds_dwordx4 v[66:67], off
	v_lshl_add_u64 v[66:67], v[244:245], 0, s[12:13]
	s_add_i32 m0, s62, 0x2000
	s_add_i32 s62, s63, s46
	global_load_lds_dwordx4 v[66:67], off
	s_mov_b32 m0, s62
	v_lshl_add_u64 v[66:67], v[246:247], 0, s[12:13]
	global_load_lds_dwordx4 v130, s[44:45]
	s_add_i32 m0, s62, 0x2000
	s_nop 0
	global_load_lds_dwordx4 v134, s[44:45]
	s_mov_b32 m0, s54
	s_nop 0
	global_load_lds_dwordx4 v[66:67], off
	v_lshl_add_u64 v[66:67], v[248:249], 0, s[12:13]
	s_mov_b32 m0, s55
	s_nop 0
	global_load_lds_dwordx4 v[66:67], off
	s_waitcnt vmcnt(8)
	s_waitcnt lgkmcnt(0)
	s_barrier
	s_setprio 1
	s_waitcnt lgkmcnt(0)
	v_mfma_f32_16x16x32_bf16 v[66:69], v[192:195], v[102:105], v[142:145]
	v_mfma_f32_16x16x32_bf16 v[70:73], v[200:203], v[102:105], v[148:151]
	v_mfma_f32_16x16x32_bf16 v[74:77], v[192:195], v[110:113], v[152:155]
	v_mfma_f32_16x16x32_bf16 v[78:81], v[200:203], v[110:113], v[156:159]
	v_mfma_f32_16x16x32_bf16 v[82:85], v[192:195], v[228:231], v[160:163]
	v_mfma_f32_16x16x32_bf16 v[86:89], v[200:203], v[228:231], v[164:167]
	v_mfma_f32_16x16x32_bf16 v[90:93], v[192:195], v[236:239], v[168:171]
	v_mfma_f32_16x16x32_bf16 v[94:97], v[200:203], v[236:239], v[172:175]
	v_mfma_f32_16x16x32_bf16 v[66:69], v[196:199], v[106:109], v[66:69]
	v_mfma_f32_16x16x32_bf16 v[70:73], v[204:207], v[106:109], v[70:73]
	v_mfma_f32_16x16x32_bf16 v[74:77], v[196:199], v[224:227], v[74:77]
	v_mfma_f32_16x16x32_bf16 v[78:81], v[204:207], v[224:227], v[78:81]
	v_mfma_f32_16x16x32_bf16 v[82:85], v[196:199], v[232:235], v[82:85]
	v_mfma_f32_16x16x32_bf16 v[86:89], v[204:207], v[232:235], v[86:89]
	v_mfma_f32_16x16x32_bf16 v[90:93], v[196:199], v[240:243], v[90:93]
	v_mfma_f32_16x16x32_bf16 v[94:97], v[204:207], v[240:243], v[94:97]
	s_setprio 0
	s_setprio 1
	v_mfma_f32_16x16x32_bf16 v[98:101], v[208:211], v[102:105], v[114:117]
	v_mfma_f32_16x16x32_bf16 v[102:105], v[216:219], v[102:105], v[122:125]
	v_mfma_f32_16x16x32_bf16 v[98:101], v[212:215], v[106:109], v[98:101]
	v_mfma_f32_16x16x32_bf16 v[102:105], v[220:223], v[106:109], v[102:105]
	v_mfma_f32_16x16x32_bf16 v[106:109], v[208:211], v[110:113], v[176:179]
	v_mfma_f32_16x16x32_bf16 v[110:113], v[216:219], v[110:113], v[180:183]
	v_mfma_f32_16x16x32_bf16 v[114:117], v[208:211], v[228:231], v[184:187]
	v_mfma_f32_16x16x32_bf16 v[118:121], v[216:219], v[228:231], v[118:121]
	v_mfma_f32_16x16x32_bf16 v[122:125], v[208:211], v[236:239], v[188:191]
	v_mfma_f32_16x16x32_bf16 v[126:129], v[216:219], v[236:239], v[126:129]
	v_mfma_f32_16x16x32_bf16 v[106:109], v[212:215], v[224:227], v[106:109]
	v_mfma_f32_16x16x32_bf16 v[110:113], v[220:223], v[224:227], v[110:113]
	v_mfma_f32_16x16x32_bf16 v[114:117], v[212:215], v[232:235], v[114:117]
	s_setprio 2
	s_barrier
	v_mfma_f32_16x16x32_bf16 v[118:121], v[220:223], v[232:235], v[118:121]
	v_mfma_f32_16x16x32_bf16 v[122:125], v[212:215], v[240:243], v[122:125]
	v_mfma_f32_16x16x32_bf16 v[126:129], v[220:223], v[240:243], v[126:129]
	s_setprio 0
	s_add_i32 s27, s27, 2
	s_cmp_ge_i32 s27, s15
	s_cbranch_scc0 .LBB0_495
	v_mov_b32_e32 v136, v130
	s_branch .LBB0_498

.LBB0_499:
	v_add_u32_e32 v133, s58, v140
	ds_read_b128 v[142:145], v133
	ds_read_b128 v[148:151], v133 offset:1024
	ds_read_b128 v[152:155], v133 offset:2048
	ds_read_b128 v[156:159], v133 offset:3072
	v_add_u32_e32 v133, s59, v140
	ds_read_b128 v[160:163], v133
	ds_read_b128 v[164:167], v133 offset:1024
	ds_read_b128 v[168:171], v133 offset:2048
	ds_read_b128 v[172:175], v133 offset:3072
	s_add_u32 s38, s36, 0xfff80080
	s_addc_u32 s39, s37, -1
	s_cmp_eq_u32 s42, 4
	s_cselect_b32 s41, s31, s39
	s_cselect_b32 s40, s30, s38
	s_cselect_b32 s39, s35, s27
	s_cselect_b32 s38, s34, s15
	s_mov_b32 m0, s56
	v_add_u32_e32 v141, 0, v1
	ds_read_b128 v[176:179], v141
	ds_read_b128 v[180:183], v141 offset:1024
	ds_read_b128 v[184:187], v141 offset:2048
	ds_read_b128 v[188:191], v141 offset:3072
	ds_read_b128 v[192:195], v141 offset:4096
	ds_read_b128 v[196:199], v141 offset:5120
	ds_read_b128 v[200:203], v141 offset:6144
	ds_read_b128 v[204:207], v141 offset:7168
	global_load_lds_dwordx4 v130, s[36:37]
	s_mov_b32 m0, s57
	v_mov_b32_e32 v133, v131
	global_load_lds_dwordx4 v132, s[36:37]
	s_waitcnt vmcnt(8)
	s_waitcnt lgkmcnt(0)
	s_barrier
	s_setprio 1
	s_waitcnt lgkmcnt(0)
	v_mfma_f32_16x16x32_bf16 v[2:5], v[142:145], v[176:179], v[2:5]
	v_mfma_f32_16x16x32_bf16 v[2:5], v[148:151], v[180:183], v[2:5]
	v_mfma_f32_16x16x32_bf16 v[6:9], v[156:159], v[180:183], v[6:9]
	v_mfma_f32_16x16x32_bf16 v[6:9], v[152:155], v[176:179], v[6:9]
	v_mfma_f32_16x16x32_bf16 v[14:17], v[152:155], v[184:187], v[14:17]
	v_mfma_f32_16x16x32_bf16 v[14:17], v[156:159], v[188:191], v[14:17]
	v_mfma_f32_16x16x32_bf16 v[10:13], v[148:151], v[188:191], v[10:13]
	v_mfma_f32_16x16x32_bf16 v[10:13], v[142:145], v[184:187], v[10:13]
	v_mfma_f32_16x16x32_bf16 v[18:21], v[142:145], v[192:195], v[18:21]
	v_mfma_f32_16x16x32_bf16 v[18:21], v[148:151], v[196:199], v[18:21]
	v_mfma_f32_16x16x32_bf16 v[22:25], v[156:159], v[196:199], v[22:25]
	v_mfma_f32_16x16x32_bf16 v[22:25], v[152:155], v[192:195], v[22:25]
	v_mfma_f32_16x16x32_bf16 v[30:33], v[152:155], v[200:203], v[30:33]
	v_mfma_f32_16x16x32_bf16 v[30:33], v[156:159], v[204:207], v[30:33]
	v_mfma_f32_16x16x32_bf16 v[26:29], v[148:151], v[204:207], v[26:29]
	v_mfma_f32_16x16x32_bf16 v[26:29], v[142:145], v[200:203], v[26:29]
	s_setprio 0
	s_setprio 1
	v_mfma_f32_16x16x32_bf16 v[34:37], v[160:163], v[176:179], v[34:37]
	v_mfma_f32_16x16x32_bf16 v[34:37], v[164:167], v[180:183], v[34:37]
	v_mfma_f32_16x16x32_bf16 v[38:41], v[172:175], v[180:183], v[38:41]
	v_mfma_f32_16x16x32_bf16 v[38:41], v[168:171], v[176:179], v[38:41]
	v_mfma_f32_16x16x32_bf16 v[46:49], v[168:171], v[184:187], v[46:49]
	v_mfma_f32_16x16x32_bf16 v[46:49], v[172:175], v[188:191], v[46:49]
	v_mfma_f32_16x16x32_bf16 v[42:45], v[164:167], v[188:191], v[42:45]
	v_mfma_f32_16x16x32_bf16 v[42:45], v[160:163], v[184:187], v[42:45]
	v_mfma_f32_16x16x32_bf16 v[50:53], v[160:163], v[192:195], v[50:53]
	v_mfma_f32_16x16x32_bf16 v[50:53], v[164:167], v[196:199], v[50:53]
	v_mfma_f32_16x16x32_bf16 v[54:57], v[172:175], v[196:199], v[54:57]
	v_mfma_f32_16x16x32_bf16 v[54:57], v[168:171], v[192:195], v[54:57]
	v_mfma_f32_16x16x32_bf16 v[62:65], v[168:171], v[200:203], v[62:65]
	s_setprio 2
	s_barrier
	v_mfma_f32_16x16x32_bf16 v[62:65], v[172:175], v[204:207], v[62:65]
	v_mfma_f32_16x16x32_bf16 v[58:61], v[164:167], v[204:207], v[58:61]
	v_mfma_f32_16x16x32_bf16 v[58:61], v[160:163], v[200:203], v[58:61]
	s_setprio 0
	s_add_i32 s43, s58, s46
	s_mov_b32 m0, s43
	ds_read_b128 v[176:179], v141 offset:16384
	ds_read_b128 v[180:183], v141 offset:17408
	ds_read_b128 v[184:187], v141 offset:18432
	ds_read_b128 v[188:191], v141 offset:19456
	ds_read_b128 v[192:195], v141 offset:20480
	ds_read_b128 v[196:199], v141 offset:21504
	ds_read_b128 v[200:203], v141 offset:22528
	ds_read_b128 v[204:207], v141 offset:23552
	global_load_lds_dwordx4 v136, s[38:39]
	s_add_i32 m0, s43, 0x2000
	s_add_u32 s44, s38, 0x400000
	s_addc_u32 s45, s39, 0
	s_add_i32 s43, s59, s46
	global_load_lds_dwordx4 v134, s[38:39]
	s_mov_b32 m0, s43
	v_mov_b32_e32 v137, v131
	global_load_lds_dwordx4 v136, s[44:45]
	s_add_i32 m0, s43, 0x2000
	v_mov_b32_e32 v135, v131
	global_load_lds_dwordx4 v134, s[44:45]
	s_mov_b32 m0, s47
	v_lshl_add_u64 v[138:139], s[38:39], 0, v[136:137]
	global_load_lds_dwordx4 v130, s[40:41]
	s_mov_b32 m0, s48
	v_lshl_add_u64 v[208:209], s[38:39], 0, v[134:135]
	global_load_lds_dwordx4 v132, s[40:41]
	s_waitcnt vmcnt(8)
	s_waitcnt lgkmcnt(0)
	v_lshl_add_u64 v[210:211], s[40:41], 0, v[130:131]
	v_lshl_add_u64 v[212:213], s[40:41], 0, v[132:133]
	s_barrier
	s_setprio 1
	s_waitcnt lgkmcnt(0)
	v_mfma_f32_16x16x32_bf16 v[66:69], v[142:145], v[176:179], v[66:69]
	v_mfma_f32_16x16x32_bf16 v[66:69], v[148:151], v[180:183], v[66:69]
	v_mfma_f32_16x16x32_bf16 v[70:73], v[156:159], v[180:183], v[70:73]
	v_mfma_f32_16x16x32_bf16 v[70:73], v[152:155], v[176:179], v[70:73]
	v_mfma_f32_16x16x32_bf16 v[78:81], v[152:155], v[184:187], v[78:81]
	v_mfma_f32_16x16x32_bf16 v[78:81], v[156:159], v[188:191], v[78:81]
	v_mfma_f32_16x16x32_bf16 v[74:77], v[148:151], v[188:191], v[74:77]
	v_mfma_f32_16x16x32_bf16 v[74:77], v[142:145], v[184:187], v[74:77]
	v_mfma_f32_16x16x32_bf16 v[82:85], v[142:145], v[192:195], v[82:85]
	v_mfma_f32_16x16x32_bf16 v[82:85], v[148:151], v[196:199], v[82:85]
	v_mfma_f32_16x16x32_bf16 v[86:89], v[156:159], v[196:199], v[86:89]
	v_mfma_f32_16x16x32_bf16 v[86:89], v[152:155], v[192:195], v[86:89]
	v_mfma_f32_16x16x32_bf16 v[94:97], v[152:155], v[200:203], v[94:97]
	v_mfma_f32_16x16x32_bf16 v[94:97], v[156:159], v[204:207], v[94:97]
	v_mfma_f32_16x16x32_bf16 v[90:93], v[148:151], v[204:207], v[90:93]
	v_mfma_f32_16x16x32_bf16 v[90:93], v[142:145], v[200:203], v[90:93]
	s_setprio 0
	s_setprio 1
	v_mfma_f32_16x16x32_bf16 v[98:101], v[160:163], v[176:179], v[98:101]
	v_mfma_f32_16x16x32_bf16 v[98:101], v[164:167], v[180:183], v[98:101]
	v_mfma_f32_16x16x32_bf16 v[102:105], v[172:175], v[180:183], v[102:105]
	v_mfma_f32_16x16x32_bf16 v[102:105], v[168:171], v[176:179], v[102:105]
	v_mfma_f32_16x16x32_bf16 v[110:113], v[168:171], v[184:187], v[110:113]
	v_mfma_f32_16x16x32_bf16 v[110:113], v[172:175], v[188:191], v[110:113]
	v_mfma_f32_16x16x32_bf16 v[106:109], v[164:167], v[188:191], v[106:109]
	v_mfma_f32_16x16x32_bf16 v[106:109], v[160:163], v[184:187], v[106:109]
	v_mfma_f32_16x16x32_bf16 v[114:117], v[160:163], v[192:195], v[114:117]
	v_mfma_f32_16x16x32_bf16 v[114:117], v[164:167], v[196:199], v[114:117]
	v_mfma_f32_16x16x32_bf16 v[118:121], v[172:175], v[196:199], v[118:121]
	v_mfma_f32_16x16x32_bf16 v[118:121], v[168:171], v[192:195], v[118:121]
	v_mfma_f32_16x16x32_bf16 v[126:129], v[168:171], v[200:203], v[126:129]
	s_setprio 2
	s_barrier
	v_mfma_f32_16x16x32_bf16 v[126:129], v[172:175], v[204:207], v[126:129]
	v_mfma_f32_16x16x32_bf16 v[122:125], v[164:167], v[204:207], v[122:125]
	v_mfma_f32_16x16x32_bf16 v[122:125], v[160:163], v[200:203], v[122:125]
	s_setprio 0
	s_add_i32 s43, 0, 0x18000
	v_add_u32_e32 v135, s43, v140
	s_add_i32 s44, 0, 0x1c000
	ds_read_b128 v[142:145], v135
	ds_read_b128 v[148:151], v135 offset:1024
	ds_read_b128 v[152:155], v135 offset:2048
	ds_read_b128 v[156:159], v135 offset:3072
	v_add_u32_e32 v135, s44, v140
	ds_read_b128 v[160:163], v135
	ds_read_b128 v[164:167], v135 offset:1024
	ds_read_b128 v[168:171], v135 offset:2048
	ds_read_b128 v[172:175], v135 offset:3072
	s_add_u32 s40, s40, 0x80000
	s_addc_u32 s41, s41, 0
	s_mov_b32 m0, s49
	ds_read_b128 v[176:179], v141 offset:32768
	ds_read_b128 v[180:183], v141 offset:33792
	ds_read_b128 v[184:187], v141 offset:34816
	ds_read_b128 v[188:191], v141 offset:35840
	ds_read_b128 v[192:195], v141 offset:36864
	ds_read_b128 v[196:199], v141 offset:37888
	ds_read_b128 v[200:203], v141 offset:38912
	ds_read_b128 v[204:207], v141 offset:39936
	global_load_lds_dwordx4 v130, s[40:41]
	s_mov_b32 m0, s50
	s_nop 0
	global_load_lds_dwordx4 v132, s[40:41]
	s_waitcnt vmcnt(8)
	s_waitcnt lgkmcnt(0)
	s_barrier
	s_setprio 1
	s_waitcnt lgkmcnt(0)
	v_mfma_f32_16x16x32_bf16 v[2:5], v[142:145], v[176:179], v[2:5]
	v_mfma_f32_16x16x32_bf16 v[2:5], v[148:151], v[180:183], v[2:5]
	v_mfma_f32_16x16x32_bf16 v[6:9], v[156:159], v[180:183], v[6:9]
	v_mfma_f32_16x16x32_bf16 v[6:9], v[152:155], v[176:179], v[6:9]
	v_mfma_f32_16x16x32_bf16 v[14:17], v[152:155], v[184:187], v[14:17]
	v_mfma_f32_16x16x32_bf16 v[14:17], v[156:159], v[188:191], v[14:17]
	v_mfma_f32_16x16x32_bf16 v[10:13], v[148:151], v[188:191], v[10:13]
	v_mfma_f32_16x16x32_bf16 v[10:13], v[142:145], v[184:187], v[10:13]
	v_mfma_f32_16x16x32_bf16 v[18:21], v[142:145], v[192:195], v[18:21]
	v_mfma_f32_16x16x32_bf16 v[18:21], v[148:151], v[196:199], v[18:21]
	v_mfma_f32_16x16x32_bf16 v[22:25], v[156:159], v[196:199], v[22:25]
	v_mfma_f32_16x16x32_bf16 v[22:25], v[152:155], v[192:195], v[22:25]
	v_mfma_f32_16x16x32_bf16 v[30:33], v[152:155], v[200:203], v[30:33]
	v_mfma_f32_16x16x32_bf16 v[30:33], v[156:159], v[204:207], v[30:33]
	v_mfma_f32_16x16x32_bf16 v[26:29], v[148:151], v[204:207], v[26:29]
	v_mfma_f32_16x16x32_bf16 v[26:29], v[142:145], v[200:203], v[26:29]
	s_setprio 0
	s_setprio 1
	v_mfma_f32_16x16x32_bf16 v[34:37], v[160:163], v[176:179], v[34:37]
	v_mfma_f32_16x16x32_bf16 v[34:37], v[164:167], v[180:183], v[34:37]
	v_mfma_f32_16x16x32_bf16 v[38:41], v[172:175], v[180:183], v[38:41]
	v_mfma_f32_16x16x32_bf16 v[38:41], v[168:171], v[176:179], v[38:41]
	v_mfma_f32_16x16x32_bf16 v[46:49], v[168:171], v[184:187], v[46:49]
	v_mfma_f32_16x16x32_bf16 v[46:49], v[172:175], v[188:191], v[46:49]
	v_mfma_f32_16x16x32_bf16 v[42:45], v[164:167], v[188:191], v[42:45]
	v_mfma_f32_16x16x32_bf16 v[42:45], v[160:163], v[184:187], v[42:45]
	v_mfma_f32_16x16x32_bf16 v[50:53], v[160:163], v[192:195], v[50:53]
	v_mfma_f32_16x16x32_bf16 v[50:53], v[164:167], v[196:199], v[50:53]
	v_mfma_f32_16x16x32_bf16 v[54:57], v[172:175], v[196:199], v[54:57]
	v_mfma_f32_16x16x32_bf16 v[54:57], v[168:171], v[192:195], v[54:57]
	v_mfma_f32_16x16x32_bf16 v[62:65], v[168:171], v[200:203], v[62:65]
	s_setprio 2
	s_barrier
	v_mfma_f32_16x16x32_bf16 v[62:65], v[172:175], v[204:207], v[62:65]
	v_mfma_f32_16x16x32_bf16 v[58:61], v[164:167], v[204:207], v[58:61]
	v_mfma_f32_16x16x32_bf16 v[58:61], v[160:163], v[200:203], v[58:61]
	s_setprio 0
	s_add_i32 s40, s43, s46
	v_lshl_add_u64 v[138:139], v[138:139], 0, s[6:7]
	s_mov_b32 m0, s40
	ds_read_b128 v[176:179], v141 offset:49152
	ds_read_b128 v[180:183], v141 offset:50176
	ds_read_b128 v[184:187], v141 offset:51200
	ds_read_b128 v[188:191], v141 offset:52224
	ds_read_b128 v[192:195], v141 offset:53248
	ds_read_b128 v[196:199], v141 offset:54272
	ds_read_b128 v[200:203], v141 offset:55296
	ds_read_b128 v[204:207], v141 offset:56320
	global_load_lds_dwordx4 v[138:139], off
	s_add_i32 m0, s40, 0x2000
	s_add_u32 s38, s38, 0x400080
	v_lshl_add_u64 v[138:139], v[208:209], 0, s[6:7]
	s_addc_u32 s39, s39, 0
	s_add_i32 s40, s44, s46
	global_load_lds_dwordx4 v[138:139], off
	s_mov_b32 m0, s40
	v_lshl_add_u64 v[138:139], v[210:211], 0, s[6:7]
	global_load_lds_dwordx4 v136, s[38:39]
	s_add_i32 m0, s40, 0x2000
	s_nop 0
	global_load_lds_dwordx4 v134, s[38:39]
	s_mov_b32 m0, s54
	s_nop 0
	global_load_lds_dwordx4 v[138:139], off
	v_lshl_add_u64 v[138:139], v[212:213], 0, s[6:7]
	s_mov_b32 m0, s55
	s_nop 0
	global_load_lds_dwordx4 v[138:139], off
	s_waitcnt vmcnt(8)
	s_waitcnt lgkmcnt(0)
	s_barrier
	s_setprio 1
	s_waitcnt lgkmcnt(0)
	v_mfma_f32_16x16x32_bf16 v[66:69], v[142:145], v[176:179], v[66:69]
	v_mfma_f32_16x16x32_bf16 v[66:69], v[148:151], v[180:183], v[66:69]
	v_mfma_f32_16x16x32_bf16 v[70:73], v[156:159], v[180:183], v[70:73]
	v_mfma_f32_16x16x32_bf16 v[70:73], v[152:155], v[176:179], v[70:73]
	v_mfma_f32_16x16x32_bf16 v[78:81], v[152:155], v[184:187], v[78:81]
	v_mfma_f32_16x16x32_bf16 v[78:81], v[156:159], v[188:191], v[78:81]
	v_mfma_f32_16x16x32_bf16 v[74:77], v[148:151], v[188:191], v[74:77]
	v_mfma_f32_16x16x32_bf16 v[74:77], v[142:145], v[184:187], v[74:77]
	v_mfma_f32_16x16x32_bf16 v[82:85], v[142:145], v[192:195], v[82:85]
	v_mfma_f32_16x16x32_bf16 v[82:85], v[148:151], v[196:199], v[82:85]
	v_mfma_f32_16x16x32_bf16 v[86:89], v[156:159], v[196:199], v[86:89]
	v_mfma_f32_16x16x32_bf16 v[86:89], v[152:155], v[192:195], v[86:89]
	v_mfma_f32_16x16x32_bf16 v[94:97], v[152:155], v[200:203], v[94:97]
	v_mfma_f32_16x16x32_bf16 v[94:97], v[156:159], v[204:207], v[94:97]
	v_mfma_f32_16x16x32_bf16 v[90:93], v[148:151], v[204:207], v[90:93]
	v_mfma_f32_16x16x32_bf16 v[90:93], v[142:145], v[200:203], v[90:93]
	s_setprio 0
	s_setprio 1
	v_mfma_f32_16x16x32_bf16 v[98:101], v[160:163], v[176:179], v[98:101]
	v_mfma_f32_16x16x32_bf16 v[98:101], v[164:167], v[180:183], v[98:101]
	v_mfma_f32_16x16x32_bf16 v[102:105], v[172:175], v[180:183], v[102:105]
	v_mfma_f32_16x16x32_bf16 v[102:105], v[168:171], v[176:179], v[102:105]
	v_mfma_f32_16x16x32_bf16 v[110:113], v[168:171], v[184:187], v[110:113]
	v_mfma_f32_16x16x32_bf16 v[110:113], v[172:175], v[188:191], v[110:113]
	v_mfma_f32_16x16x32_bf16 v[106:109], v[164:167], v[188:191], v[106:109]
	v_mfma_f32_16x16x32_bf16 v[106:109], v[160:163], v[184:187], v[106:109]
	v_mfma_f32_16x16x32_bf16 v[114:117], v[160:163], v[192:195], v[114:117]
	v_mfma_f32_16x16x32_bf16 v[114:117], v[164:167], v[196:199], v[114:117]
	v_mfma_f32_16x16x32_bf16 v[118:121], v[172:175], v[196:199], v[118:121]
	v_mfma_f32_16x16x32_bf16 v[118:121], v[168:171], v[192:195], v[118:121]
	v_mfma_f32_16x16x32_bf16 v[126:129], v[168:171], v[200:203], v[126:129]
	s_setprio 2
	s_barrier
	v_mfma_f32_16x16x32_bf16 v[126:129], v[172:175], v[204:207], v[126:129]
	v_mfma_f32_16x16x32_bf16 v[122:125], v[164:167], v[204:207], v[122:125]
	v_mfma_f32_16x16x32_bf16 v[122:125], v[160:163], v[200:203], v[122:125]
	s_setprio 0
	s_add_i32 s42, s42, 2
	s_add_u32 s36, s36, 0x100
	s_addc_u32 s37, s37, 0
	s_add_u32 s15, s15, 0x100
	s_addc_u32 s27, s27, 0
	s_cmp_gt_u32 s42, 5
	s_cbranch_scc0 .LBB0_499
	s_and_b64 vcc, exec, s[8:9]
	s_cbranch_vccz .LBB0_502
	s_barrier

.LBB0_528:
	s_add_i32 s53, 0, 0x10000
	s_add_i32 s72, 0, 0x14000
	v_add_u32_e32 v16, s53, v147
	v_add_u32_e32 v32, s72, v147
	ds_read_b128 v[4:7], v16
	ds_read_b128 v[8:11], v16 offset:1024
	ds_read_b128 v[12:15], v16 offset:2048
	ds_read_b128 v[16:19], v16 offset:3072
	ds_read_b128 v[20:23], v32
	ds_read_b128 v[24:27], v32 offset:1024
	ds_read_b128 v[28:31], v32 offset:2048
	ds_read_b128 v[32:35], v32 offset:3072
	v_add_u32_e32 v231, 0, v146
	ds_read_b128 v[36:39], v231
	ds_read_b128 v[40:43], v231 offset:1024
	ds_read_b128 v[44:47], v231 offset:2048
	ds_read_b128 v[48:51], v231 offset:3072
	ds_read_b128 v[52:55], v231 offset:4096
	ds_read_b128 v[56:59], v231 offset:5120
	ds_read_b128 v[60:63], v231 offset:6144
	ds_read_b128 v[64:67], v231 offset:7168
	s_waitcnt vmcnt(8)
	s_waitcnt lgkmcnt(0)
	s_barrier
	s_setprio 1
	s_waitcnt lgkmcnt(0)
	v_mfma_f32_16x16x32_f16 v[68:71], v[4:7], v[36:39], 0
	v_mfma_f32_16x16x32_f16 v[68:71], v[8:11], v[40:43], v[68:71]
	v_mfma_f32_16x16x32_f16 v[72:75], v[12:15], v[36:39], 0
	v_mfma_f32_16x16x32_f16 v[72:75], v[16:19], v[40:43], v[72:75]
	v_mfma_f32_16x16x32_f16 v[80:83], v[12:15], v[44:47], 0
	v_mfma_f32_16x16x32_f16 v[80:83], v[16:19], v[48:51], v[80:83]
	v_mfma_f32_16x16x32_f16 v[76:79], v[4:7], v[44:47], 0
	v_mfma_f32_16x16x32_f16 v[76:79], v[8:11], v[48:51], v[76:79]
	v_mfma_f32_16x16x32_f16 v[84:87], v[4:7], v[52:55], 0
	v_mfma_f32_16x16x32_f16 v[84:87], v[8:11], v[56:59], v[84:87]
	v_mfma_f32_16x16x32_f16 v[88:91], v[12:15], v[52:55], 0
	v_mfma_f32_16x16x32_f16 v[88:91], v[16:19], v[56:59], v[88:91]
	v_mfma_f32_16x16x32_f16 v[96:99], v[12:15], v[60:63], 0
	v_mfma_f32_16x16x32_f16 v[96:99], v[16:19], v[64:67], v[96:99]
	v_mfma_f32_16x16x32_f16 v[92:95], v[4:7], v[60:63], 0
	v_mfma_f32_16x16x32_f16 v[92:95], v[8:11], v[64:67], v[92:95]
	s_setprio 0
	s_setprio 1
	v_mfma_f32_16x16x32_f16 v[100:103], v[20:23], v[36:39], 0
	v_mfma_f32_16x16x32_f16 v[36:39], v[28:31], v[36:39], 0
	v_mfma_f32_16x16x32_f16 v[104:107], v[20:23], v[44:47], 0
	v_mfma_f32_16x16x32_f16 v[44:47], v[28:31], v[44:47], 0
	v_mfma_f32_16x16x32_f16 v[108:111], v[20:23], v[52:55], 0
	v_mfma_f32_16x16x32_f16 v[52:55], v[28:31], v[52:55], 0
	v_mfma_f32_16x16x32_f16 v[112:115], v[20:23], v[60:63], 0
	v_mfma_f32_16x16x32_f16 v[60:63], v[28:31], v[60:63], 0
	v_mfma_f32_16x16x32_f16 v[100:103], v[24:27], v[40:43], v[100:103]
	v_mfma_f32_16x16x32_f16 v[40:43], v[32:35], v[40:43], v[36:39]
	v_mfma_f32_16x16x32_f16 v[104:107], v[24:27], v[48:51], v[104:107]
	v_mfma_f32_16x16x32_f16 v[48:51], v[32:35], v[48:51], v[44:47]
	v_mfma_f32_16x16x32_f16 v[108:111], v[24:27], v[56:59], v[108:111]
	s_setprio 2
	s_barrier
	v_mfma_f32_16x16x32_f16 v[56:59], v[32:35], v[56:59], v[52:55]
	v_mfma_f32_16x16x32_f16 v[112:115], v[24:27], v[64:67], v[112:115]
	v_mfma_f32_16x16x32_f16 v[64:67], v[32:35], v[64:67], v[60:63]
	s_setprio 0
	v_lshl_add_u64 v[136:137], s[6:7], 0, v[2:3]
	s_add_i32 s53, s53, s38
	v_mov_b32_e32 v135, v3
	v_lshl_add_u64 v[140:141], v[136:137], 0, s[74:75]
	s_mov_b32 m0, s53
	v_lshl_add_u64 v[144:145], s[6:7], 0, v[134:135]
	ds_read_b128 v[36:39], v231 offset:16384
	ds_read_b128 v[44:47], v231 offset:17408
	ds_read_b128 v[52:55], v231 offset:18432
	ds_read_b128 v[60:63], v231 offset:19456
	ds_read_b128 v[116:119], v231 offset:20480
	ds_read_b128 v[120:123], v231 offset:21504
	ds_read_b128 v[124:127], v231 offset:22528
	ds_read_b128 v[128:131], v231 offset:23552
	global_load_lds_dwordx4 v[140:141], off
	v_lshl_add_u64 v[140:141], v[144:145], 0, s[74:75]
	s_add_i32 m0, s53, 0x2000
	s_add_i32 s53, s72, s38
	global_load_lds_dwordx4 v[140:141], off
	s_mov_b32 m0, s53
	v_mov_b32_e32 v139, v3
	global_load_lds_dwordx4 v2, s[16:17]
	s_add_i32 m0, s53, 0x2000
	v_lshl_add_u64 v[248:249], s[8:9], 0, v[138:139]
	v_mov_b32_e32 v133, v3
	global_load_lds_dwordx4 v134, s[16:17]
	v_lshl_add_u64 v[140:141], v[248:249], 0, s[74:75]
	s_mov_b32 m0, s58
	v_lshl_add_u64 v[250:251], s[8:9], 0, v[132:133]
	global_load_lds_dwordx4 v[140:141], off
	v_lshl_add_u64 v[140:141], v[250:251], 0, s[74:75]
	s_mov_b32 m0, s59
	s_nop 0
	global_load_lds_dwordx4 v[140:141], off
	s_waitcnt vmcnt(8)
	s_waitcnt lgkmcnt(0)
	s_barrier
	s_setprio 1
	s_waitcnt lgkmcnt(0)
	v_mfma_f32_16x16x32_f16 v[140:143], v[4:7], v[36:39], 0
	v_mfma_f32_16x16x32_f16 v[148:151], v[12:15], v[36:39], 0
	v_mfma_f32_16x16x32_f16 v[152:155], v[4:7], v[52:55], 0
	v_mfma_f32_16x16x32_f16 v[156:159], v[12:15], v[52:55], 0
	v_mfma_f32_16x16x32_f16 v[160:163], v[4:7], v[116:119], 0
	v_mfma_f32_16x16x32_f16 v[164:167], v[12:15], v[116:119], 0
	v_mfma_f32_16x16x32_f16 v[4:7], v[4:7], v[124:127], 0
	v_mfma_f32_16x16x32_f16 v[12:15], v[12:15], v[124:127], 0
	v_mfma_f32_16x16x32_f16 v[140:143], v[8:11], v[44:47], v[140:143]
	v_mfma_f32_16x16x32_f16 v[148:151], v[16:19], v[44:47], v[148:151]
	v_mfma_f32_16x16x32_f16 v[152:155], v[8:11], v[60:63], v[152:155]
	v_mfma_f32_16x16x32_f16 v[156:159], v[16:19], v[60:63], v[156:159]
	v_mfma_f32_16x16x32_f16 v[160:163], v[8:11], v[120:123], v[160:163]
	v_mfma_f32_16x16x32_f16 v[164:167], v[16:19], v[120:123], v[164:167]
	v_mfma_f32_16x16x32_f16 v[168:171], v[8:11], v[128:131], v[4:7]
	v_mfma_f32_16x16x32_f16 v[172:175], v[16:19], v[128:131], v[12:15]
	s_setprio 0
	s_setprio 1
	v_mfma_f32_16x16x32_f16 v[4:7], v[20:23], v[36:39], 0
	v_mfma_f32_16x16x32_f16 v[8:11], v[28:31], v[36:39], 0
	v_mfma_f32_16x16x32_f16 v[12:15], v[20:23], v[52:55], 0
	v_mfma_f32_16x16x32_f16 v[16:19], v[28:31], v[52:55], 0
	v_mfma_f32_16x16x32_f16 v[36:39], v[20:23], v[116:119], 0
	v_mfma_f32_16x16x32_f16 v[52:55], v[28:31], v[116:119], 0
	v_mfma_f32_16x16x32_f16 v[20:23], v[20:23], v[124:127], 0
	v_mfma_f32_16x16x32_f16 v[28:31], v[28:31], v[124:127], 0
	v_mfma_f32_16x16x32_f16 v[116:119], v[24:27], v[44:47], v[4:7]
	v_mfma_f32_16x16x32_f16 v[124:127], v[32:35], v[44:47], v[8:11]
	v_mfma_f32_16x16x32_f16 v[184:187], v[24:27], v[120:123], v[36:39]
	v_mfma_f32_16x16x32_f16 v[120:123], v[32:35], v[120:123], v[52:55]
	v_mfma_f32_16x16x32_f16 v[188:191], v[24:27], v[128:131], v[20:23]
	s_setprio 2
	s_barrier
	v_mfma_f32_16x16x32_f16 v[128:131], v[32:35], v[128:131], v[28:31]
	v_mfma_f32_16x16x32_f16 v[176:179], v[24:27], v[60:63], v[12:15]
	v_mfma_f32_16x16x32_f16 v[180:183], v[32:35], v[60:63], v[16:19]
	s_setprio 0
	s_add_i32 s53, 0, 0x18000
	v_add_u32_e32 v4, s53, v147
	s_add_i32 s72, 0, 0x1c000
	ds_read_b128 v[192:195], v4
	ds_read_b128 v[196:199], v4 offset:1024
	ds_read_b128 v[200:203], v4 offset:2048
	ds_read_b128 v[204:207], v4 offset:3072
	v_add_u32_e32 v4, s72, v147
	ds_read_b128 v[208:211], v4
	ds_read_b128 v[212:215], v4 offset:1024
	ds_read_b128 v[216:219], v4 offset:2048
	ds_read_b128 v[220:223], v4 offset:3072
	s_mov_b32 m0, s60
	ds_read_b128 v[44:47], v231 offset:32768
	ds_read_b128 v[52:55], v231 offset:33792
	ds_read_b128 v[60:63], v231 offset:34816
	ds_read_b128 v[224:227], v231 offset:35840
	ds_read_b128 v[232:235], v231 offset:36864
	ds_read_b128 v[236:239], v231 offset:37888
	ds_read_b128 v[240:243], v231 offset:38912
	ds_read_b128 v[244:247], v231 offset:39936
	global_load_lds_dwordx4 v138, s[26:27]
	s_mov_b32 m0, s61
	s_nop 0
	global_load_lds_dwordx4 v132, s[26:27]
	s_waitcnt vmcnt(8)
	s_waitcnt lgkmcnt(0)
	s_barrier
	s_setprio 1
	s_waitcnt lgkmcnt(0)
	v_mfma_f32_16x16x32_f16 v[4:7], v[192:195], v[44:47], v[68:71]
	v_mfma_f32_16x16x32_f16 v[8:11], v[200:203], v[44:47], v[72:75]
	v_mfma_f32_16x16x32_f16 v[12:15], v[192:195], v[60:63], v[76:79]
	v_mfma_f32_16x16x32_f16 v[16:19], v[200:203], v[60:63], v[80:83]
	v_mfma_f32_16x16x32_f16 v[20:23], v[192:195], v[232:235], v[84:87]
	v_mfma_f32_16x16x32_f16 v[24:27], v[200:203], v[232:235], v[88:91]
	v_mfma_f32_16x16x32_f16 v[28:31], v[192:195], v[240:243], v[92:95]
	v_mfma_f32_16x16x32_f16 v[32:35], v[200:203], v[240:243], v[96:99]
	v_mfma_f32_16x16x32_f16 v[4:7], v[196:199], v[52:55], v[4:7]
	v_mfma_f32_16x16x32_f16 v[8:11], v[204:207], v[52:55], v[8:11]
	v_mfma_f32_16x16x32_f16 v[12:15], v[196:199], v[224:227], v[12:15]
	v_mfma_f32_16x16x32_f16 v[16:19], v[204:207], v[224:227], v[16:19]
	v_mfma_f32_16x16x32_f16 v[20:23], v[196:199], v[236:239], v[20:23]
	v_mfma_f32_16x16x32_f16 v[24:27], v[204:207], v[236:239], v[24:27]
	v_mfma_f32_16x16x32_f16 v[28:31], v[196:199], v[244:247], v[28:31]
	v_mfma_f32_16x16x32_f16 v[32:35], v[204:207], v[244:247], v[32:35]
	s_setprio 0
	s_setprio 1
	v_mfma_f32_16x16x32_f16 v[36:39], v[208:211], v[44:47], v[100:103]
	v_mfma_f32_16x16x32_f16 v[40:43], v[216:219], v[44:47], v[40:43]
	v_mfma_f32_16x16x32_f16 v[36:39], v[212:215], v[52:55], v[36:39]
	v_mfma_f32_16x16x32_f16 v[40:43], v[220:223], v[52:55], v[40:43]
	v_mfma_f32_16x16x32_f16 v[44:47], v[208:211], v[60:63], v[104:107]
	v_mfma_f32_16x16x32_f16 v[48:51], v[216:219], v[60:63], v[48:51]
	v_mfma_f32_16x16x32_f16 v[52:55], v[208:211], v[232:235], v[108:111]
	v_mfma_f32_16x16x32_f16 v[56:59], v[216:219], v[232:235], v[56:59]
	v_mfma_f32_16x16x32_f16 v[60:63], v[208:211], v[240:243], v[112:115]
	v_mfma_f32_16x16x32_f16 v[64:67], v[216:219], v[240:243], v[64:67]
	v_mfma_f32_16x16x32_f16 v[44:47], v[212:215], v[224:227], v[44:47]
	v_mfma_f32_16x16x32_f16 v[48:51], v[220:223], v[224:227], v[48:51]
	v_mfma_f32_16x16x32_f16 v[52:55], v[212:215], v[236:239], v[52:55]
	s_setprio 2
	s_barrier
	v_mfma_f32_16x16x32_f16 v[56:59], v[220:223], v[236:239], v[56:59]
	v_mfma_f32_16x16x32_f16 v[60:63], v[212:215], v[244:247], v[60:63]
	v_mfma_f32_16x16x32_f16 v[64:67], v[220:223], v[244:247], v[64:67]
	s_setprio 0
	s_add_i32 s53, s53, s38
	v_lshl_add_u64 v[68:69], v[136:137], 0, s[24:25]
	s_mov_b32 m0, s53
	ds_read_b128 v[104:107], v231 offset:49152
	ds_read_b128 v[108:111], v231 offset:50176
	ds_read_b128 v[112:115], v231 offset:51200
	ds_read_b128 v[224:227], v231 offset:52224
	ds_read_b128 v[232:235], v231 offset:53248
	ds_read_b128 v[236:239], v231 offset:54272
	ds_read_b128 v[240:243], v231 offset:55296
	ds_read_b128 v[244:247], v231 offset:56320
	global_load_lds_dwordx4 v[68:69], off
	v_lshl_add_u64 v[68:69], v[144:145], 0, s[24:25]
	s_add_i32 m0, s53, 0x2000
	s_add_i32 s53, s72, s38
	global_load_lds_dwordx4 v[68:69], off
	s_mov_b32 m0, s53
	v_lshl_add_u64 v[68:69], v[248:249], 0, s[24:25]
	global_load_lds_dwordx4 v2, s[28:29]
	s_add_i32 m0, s53, 0x2000
	s_nop 0
	global_load_lds_dwordx4 v134, s[28:29]
	s_mov_b32 m0, s64
	s_nop 0
	global_load_lds_dwordx4 v[68:69], off
	v_lshl_add_u64 v[68:69], v[250:251], 0, s[24:25]
	s_mov_b32 m0, s65
	s_nop 0
	global_load_lds_dwordx4 v[68:69], off
	s_waitcnt vmcnt(8)
	s_waitcnt lgkmcnt(0)
	s_barrier
	s_setprio 1
	s_waitcnt lgkmcnt(0)
	v_mfma_f32_16x16x32_f16 v[68:71], v[192:195], v[104:107], v[140:143]
	v_mfma_f32_16x16x32_f16 v[72:75], v[200:203], v[104:107], v[148:151]
	v_mfma_f32_16x16x32_f16 v[76:79], v[192:195], v[112:115], v[152:155]
	v_mfma_f32_16x16x32_f16 v[80:83], v[200:203], v[112:115], v[156:159]
	v_mfma_f32_16x16x32_f16 v[84:87], v[192:195], v[232:235], v[160:163]
	v_mfma_f32_16x16x32_f16 v[88:91], v[200:203], v[232:235], v[164:167]
	v_mfma_f32_16x16x32_f16 v[92:95], v[192:195], v[240:243], v[168:171]
	v_mfma_f32_16x16x32_f16 v[96:99], v[200:203], v[240:243], v[172:175]
	v_mfma_f32_16x16x32_f16 v[68:71], v[196:199], v[108:111], v[68:71]
	v_mfma_f32_16x16x32_f16 v[72:75], v[204:207], v[108:111], v[72:75]
	v_mfma_f32_16x16x32_f16 v[76:79], v[196:199], v[224:227], v[76:79]
	v_mfma_f32_16x16x32_f16 v[80:83], v[204:207], v[224:227], v[80:83]
	v_mfma_f32_16x16x32_f16 v[84:87], v[196:199], v[236:239], v[84:87]
	v_mfma_f32_16x16x32_f16 v[88:91], v[204:207], v[236:239], v[88:91]
	v_mfma_f32_16x16x32_f16 v[92:95], v[196:199], v[244:247], v[92:95]
	v_mfma_f32_16x16x32_f16 v[96:99], v[204:207], v[244:247], v[96:99]
	s_setprio 0
	s_setprio 1
	v_mfma_f32_16x16x32_f16 v[100:103], v[208:211], v[104:107], v[116:119]
	v_mfma_f32_16x16x32_f16 v[104:107], v[216:219], v[104:107], v[124:127]
	v_mfma_f32_16x16x32_f16 v[100:103], v[212:215], v[108:111], v[100:103]
	v_mfma_f32_16x16x32_f16 v[104:107], v[220:223], v[108:111], v[104:107]
	v_mfma_f32_16x16x32_f16 v[108:111], v[208:211], v[112:115], v[176:179]
	v_mfma_f32_16x16x32_f16 v[112:115], v[216:219], v[112:115], v[180:183]
	v_mfma_f32_16x16x32_f16 v[116:119], v[208:211], v[232:235], v[184:187]
	v_mfma_f32_16x16x32_f16 v[120:123], v[216:219], v[232:235], v[120:123]
	v_mfma_f32_16x16x32_f16 v[124:127], v[208:211], v[240:243], v[188:191]
	v_mfma_f32_16x16x32_f16 v[128:131], v[216:219], v[240:243], v[128:131]
	v_mfma_f32_16x16x32_f16 v[108:111], v[212:215], v[224:227], v[108:111]
	v_mfma_f32_16x16x32_f16 v[112:115], v[220:223], v[224:227], v[112:115]
	v_mfma_f32_16x16x32_f16 v[116:119], v[212:215], v[236:239], v[116:119]
	s_setprio 2
	s_barrier
	v_mfma_f32_16x16x32_f16 v[120:123], v[220:223], v[236:239], v[120:123]
	v_mfma_f32_16x16x32_f16 v[124:127], v[212:215], v[244:247], v[124:127]
	v_mfma_f32_16x16x32_f16 v[128:131], v[220:223], v[244:247], v[128:131]
	s_setprio 0
	s_add_i32 s41, s41, 2
	s_cmp_ge_i32 s41, s40
	s_cbranch_scc0 .LBB0_528
	v_mov_b32_e32 v136, v2
	s_branch .LBB0_531

.LBB0_532:
	s_add_u32 s6, s8, 0xfff80080
	s_addc_u32 s7, s9, -1
	s_add_i32 s29, 0, 0x10000
	s_cmp_eq_u32 s28, 28
	s_cselect_b32 s17, s13, s7
	s_cselect_b32 s16, s12, s6
	v_add_u32_e32 v133, s29, v147
	s_cselect_b32 s7, s15, s27
	s_cselect_b32 s6, s14, s26
	s_add_i32 s53, 0, 0x14000
	ds_read_b128 v[138:141], v133
	ds_read_b128 v[142:145], v133 offset:1024
	ds_read_b128 v[148:151], v133 offset:2048
	ds_read_b128 v[152:155], v133 offset:3072
	v_add_u32_e32 v133, s53, v147
	ds_read_b128 v[156:159], v133
	ds_read_b128 v[160:163], v133 offset:1024
	ds_read_b128 v[164:167], v133 offset:2048
	ds_read_b128 v[168:171], v133 offset:3072
	s_mov_b32 m0, s66
	v_add_u32_e32 v212, 0, v146
	ds_read_b128 v[172:175], v212
	ds_read_b128 v[176:179], v212 offset:1024
	ds_read_b128 v[180:183], v212 offset:2048
	ds_read_b128 v[184:187], v212 offset:3072
	ds_read_b128 v[188:191], v212 offset:4096
	ds_read_b128 v[192:195], v212 offset:5120
	ds_read_b128 v[196:199], v212 offset:6144
	ds_read_b128 v[200:203], v212 offset:7168
	global_load_lds_dwordx4 v2, s[8:9]
	s_mov_b32 m0, s67
	v_mov_b32_e32 v133, v3
	global_load_lds_dwordx4 v132, s[8:9]
	s_waitcnt vmcnt(8)
	s_waitcnt lgkmcnt(0)
	s_barrier
	s_setprio 1
	s_waitcnt lgkmcnt(0)
	v_mfma_f32_16x16x32_f16 v[4:7], v[138:141], v[172:175], v[4:7]
	v_mfma_f32_16x16x32_f16 v[4:7], v[142:145], v[176:179], v[4:7]
	v_mfma_f32_16x16x32_f16 v[8:11], v[152:155], v[176:179], v[8:11]
	v_mfma_f32_16x16x32_f16 v[8:11], v[148:151], v[172:175], v[8:11]
	v_mfma_f32_16x16x32_f16 v[16:19], v[148:151], v[180:183], v[16:19]
	v_mfma_f32_16x16x32_f16 v[16:19], v[152:155], v[184:187], v[16:19]
	v_mfma_f32_16x16x32_f16 v[12:15], v[142:145], v[184:187], v[12:15]
	v_mfma_f32_16x16x32_f16 v[12:15], v[138:141], v[180:183], v[12:15]
	v_mfma_f32_16x16x32_f16 v[20:23], v[138:141], v[188:191], v[20:23]
	v_mfma_f32_16x16x32_f16 v[20:23], v[142:145], v[192:195], v[20:23]
	v_mfma_f32_16x16x32_f16 v[24:27], v[152:155], v[192:195], v[24:27]
	v_mfma_f32_16x16x32_f16 v[24:27], v[148:151], v[188:191], v[24:27]
	v_mfma_f32_16x16x32_f16 v[32:35], v[148:151], v[196:199], v[32:35]
	v_mfma_f32_16x16x32_f16 v[32:35], v[152:155], v[200:203], v[32:35]
	v_mfma_f32_16x16x32_f16 v[28:31], v[142:145], v[200:203], v[28:31]
	v_mfma_f32_16x16x32_f16 v[28:31], v[138:141], v[196:199], v[28:31]
	s_setprio 0
	s_setprio 1
	v_mfma_f32_16x16x32_f16 v[36:39], v[156:159], v[172:175], v[36:39]
	v_mfma_f32_16x16x32_f16 v[36:39], v[160:163], v[176:179], v[36:39]
	v_mfma_f32_16x16x32_f16 v[40:43], v[168:171], v[176:179], v[40:43]
	v_mfma_f32_16x16x32_f16 v[40:43], v[164:167], v[172:175], v[40:43]
	v_mfma_f32_16x16x32_f16 v[48:51], v[164:167], v[180:183], v[48:51]
	v_mfma_f32_16x16x32_f16 v[48:51], v[168:171], v[184:187], v[48:51]
	v_mfma_f32_16x16x32_f16 v[44:47], v[160:163], v[184:187], v[44:47]
	v_mfma_f32_16x16x32_f16 v[44:47], v[156:159], v[180:183], v[44:47]
	v_mfma_f32_16x16x32_f16 v[52:55], v[156:159], v[188:191], v[52:55]
	v_mfma_f32_16x16x32_f16 v[52:55], v[160:163], v[192:195], v[52:55]
	v_mfma_f32_16x16x32_f16 v[56:59], v[168:171], v[192:195], v[56:59]
	v_mfma_f32_16x16x32_f16 v[56:59], v[164:167], v[188:191], v[56:59]
	v_mfma_f32_16x16x32_f16 v[64:67], v[164:167], v[196:199], v[64:67]
	s_setprio 2
	s_barrier
	v_mfma_f32_16x16x32_f16 v[64:67], v[168:171], v[200:203], v[64:67]
	v_mfma_f32_16x16x32_f16 v[60:63], v[160:163], v[200:203], v[60:63]
	v_mfma_f32_16x16x32_f16 v[60:63], v[156:159], v[196:199], v[60:63]
	s_setprio 0
	s_add_i32 s29, s29, s38
	s_mov_b32 m0, s29
	ds_read_b128 v[172:175], v212 offset:16384
	ds_read_b128 v[176:179], v212 offset:17408
	ds_read_b128 v[180:183], v212 offset:18432
	ds_read_b128 v[184:187], v212 offset:19456
	ds_read_b128 v[188:191], v212 offset:20480
	ds_read_b128 v[192:195], v212 offset:21504
	ds_read_b128 v[196:199], v212 offset:22528
	ds_read_b128 v[200:203], v212 offset:23552
	global_load_lds_dwordx4 v136, s[6:7]
	s_add_i32 m0, s29, 0x2000
	s_add_u32 s40, s6, 0x80000
	s_addc_u32 s41, s7, 0
	s_add_i32 s29, s53, s38
	global_load_lds_dwordx4 v134, s[6:7]
	s_mov_b32 m0, s29
	v_mov_b32_e32 v137, v3
	global_load_lds_dwordx4 v136, s[40:41]
	s_add_i32 m0, s29, 0x2000
	v_mov_b32_e32 v135, v3
	global_load_lds_dwordx4 v134, s[40:41]
	s_mov_b32 m0, s58
	v_lshl_add_u64 v[204:205], s[6:7], 0, v[136:137]
	global_load_lds_dwordx4 v2, s[16:17]
	s_mov_b32 m0, s59
	v_lshl_add_u64 v[206:207], s[6:7], 0, v[134:135]
	global_load_lds_dwordx4 v132, s[16:17]
	s_waitcnt vmcnt(8)
	s_waitcnt lgkmcnt(0)
	v_lshl_add_u64 v[208:209], s[16:17], 0, v[2:3]
	v_lshl_add_u64 v[210:211], s[16:17], 0, v[132:133]
	s_barrier
	s_setprio 1
	s_waitcnt lgkmcnt(0)
	v_mfma_f32_16x16x32_f16 v[68:71], v[138:141], v[172:175], v[68:71]
	v_mfma_f32_16x16x32_f16 v[68:71], v[142:145], v[176:179], v[68:71]
	v_mfma_f32_16x16x32_f16 v[72:75], v[152:155], v[176:179], v[72:75]
	v_mfma_f32_16x16x32_f16 v[72:75], v[148:151], v[172:175], v[72:75]
	v_mfma_f32_16x16x32_f16 v[80:83], v[148:151], v[180:183], v[80:83]
	v_mfma_f32_16x16x32_f16 v[80:83], v[152:155], v[184:187], v[80:83]
	v_mfma_f32_16x16x32_f16 v[76:79], v[142:145], v[184:187], v[76:79]
	v_mfma_f32_16x16x32_f16 v[76:79], v[138:141], v[180:183], v[76:79]
	v_mfma_f32_16x16x32_f16 v[84:87], v[138:141], v[188:191], v[84:87]
	v_mfma_f32_16x16x32_f16 v[84:87], v[142:145], v[192:195], v[84:87]
	v_mfma_f32_16x16x32_f16 v[88:91], v[152:155], v[192:195], v[88:91]
	v_mfma_f32_16x16x32_f16 v[88:91], v[148:151], v[188:191], v[88:91]
	v_mfma_f32_16x16x32_f16 v[96:99], v[148:151], v[196:199], v[96:99]
	v_mfma_f32_16x16x32_f16 v[96:99], v[152:155], v[200:203], v[96:99]
	v_mfma_f32_16x16x32_f16 v[92:95], v[142:145], v[200:203], v[92:95]
	v_mfma_f32_16x16x32_f16 v[92:95], v[138:141], v[196:199], v[92:95]
	s_setprio 0
	s_setprio 1
	v_mfma_f32_16x16x32_f16 v[100:103], v[156:159], v[172:175], v[100:103]
	v_mfma_f32_16x16x32_f16 v[100:103], v[160:163], v[176:179], v[100:103]
	v_mfma_f32_16x16x32_f16 v[104:107], v[168:171], v[176:179], v[104:107]
	v_mfma_f32_16x16x32_f16 v[104:107], v[164:167], v[172:175], v[104:107]
	v_mfma_f32_16x16x32_f16 v[112:115], v[164:167], v[180:183], v[112:115]
	v_mfma_f32_16x16x32_f16 v[112:115], v[168:171], v[184:187], v[112:115]
	v_mfma_f32_16x16x32_f16 v[108:111], v[160:163], v[184:187], v[108:111]
	v_mfma_f32_16x16x32_f16 v[108:111], v[156:159], v[180:183], v[108:111]
	v_mfma_f32_16x16x32_f16 v[116:119], v[156:159], v[188:191], v[116:119]
	v_mfma_f32_16x16x32_f16 v[116:119], v[160:163], v[192:195], v[116:119]
	v_mfma_f32_16x16x32_f16 v[120:123], v[168:171], v[192:195], v[120:123]
	v_mfma_f32_16x16x32_f16 v[120:123], v[164:167], v[188:191], v[120:123]
	v_mfma_f32_16x16x32_f16 v[128:131], v[164:167], v[196:199], v[128:131]
	s_setprio 2
	s_barrier
	v_mfma_f32_16x16x32_f16 v[128:131], v[168:171], v[200:203], v[128:131]
	v_mfma_f32_16x16x32_f16 v[124:127], v[160:163], v[200:203], v[124:127]
	v_mfma_f32_16x16x32_f16 v[124:127], v[156:159], v[196:199], v[124:127]
	s_setprio 0
	s_add_i32 s29, 0, 0x18000
	v_add_u32_e32 v135, s29, v147
	s_add_i32 s40, 0, 0x1c000
	ds_read_b128 v[138:141], v135
	ds_read_b128 v[142:145], v135 offset:1024
	ds_read_b128 v[148:151], v135 offset:2048
	ds_read_b128 v[152:155], v135 offset:3072
	v_add_u32_e32 v135, s40, v147
	ds_read_b128 v[156:159], v135
	ds_read_b128 v[160:163], v135 offset:1024
	ds_read_b128 v[164:167], v135 offset:2048
	ds_read_b128 v[168:171], v135 offset:3072
	s_add_u32 s16, s16, 0x80000
	s_addc_u32 s17, s17, 0
	s_mov_b32 m0, s60
	ds_read_b128 v[172:175], v212 offset:32768
	ds_read_b128 v[176:179], v212 offset:33792
	ds_read_b128 v[180:183], v212 offset:34816
	ds_read_b128 v[184:187], v212 offset:35840
	ds_read_b128 v[188:191], v212 offset:36864
	ds_read_b128 v[192:195], v212 offset:37888
	ds_read_b128 v[196:199], v212 offset:38912
	ds_read_b128 v[200:203], v212 offset:39936
	global_load_lds_dwordx4 v2, s[16:17]
	s_mov_b32 m0, s61
	s_nop 0
	global_load_lds_dwordx4 v132, s[16:17]
	s_waitcnt vmcnt(8)
	s_waitcnt lgkmcnt(0)
	s_barrier
	s_setprio 1
	s_waitcnt lgkmcnt(0)
	v_mfma_f32_16x16x32_f16 v[4:7], v[138:141], v[172:175], v[4:7]
	v_mfma_f32_16x16x32_f16 v[4:7], v[142:145], v[176:179], v[4:7]
	v_mfma_f32_16x16x32_f16 v[8:11], v[152:155], v[176:179], v[8:11]
	v_mfma_f32_16x16x32_f16 v[8:11], v[148:151], v[172:175], v[8:11]
	v_mfma_f32_16x16x32_f16 v[16:19], v[148:151], v[180:183], v[16:19]
	v_mfma_f32_16x16x32_f16 v[16:19], v[152:155], v[184:187], v[16:19]
	v_mfma_f32_16x16x32_f16 v[12:15], v[142:145], v[184:187], v[12:15]
	v_mfma_f32_16x16x32_f16 v[12:15], v[138:141], v[180:183], v[12:15]
	v_mfma_f32_16x16x32_f16 v[20:23], v[138:141], v[188:191], v[20:23]
	v_mfma_f32_16x16x32_f16 v[20:23], v[142:145], v[192:195], v[20:23]
	v_mfma_f32_16x16x32_f16 v[24:27], v[152:155], v[192:195], v[24:27]
	v_mfma_f32_16x16x32_f16 v[24:27], v[148:151], v[188:191], v[24:27]
	v_mfma_f32_16x16x32_f16 v[32:35], v[148:151], v[196:199], v[32:35]
	v_mfma_f32_16x16x32_f16 v[32:35], v[152:155], v[200:203], v[32:35]
	v_mfma_f32_16x16x32_f16 v[28:31], v[142:145], v[200:203], v[28:31]
	v_mfma_f32_16x16x32_f16 v[28:31], v[138:141], v[196:199], v[28:31]
	s_setprio 0
	s_setprio 1
	v_mfma_f32_16x16x32_f16 v[36:39], v[156:159], v[172:175], v[36:39]
	v_mfma_f32_16x16x32_f16 v[36:39], v[160:163], v[176:179], v[36:39]
	v_mfma_f32_16x16x32_f16 v[40:43], v[168:171], v[176:179], v[40:43]
	v_mfma_f32_16x16x32_f16 v[40:43], v[164:167], v[172:175], v[40:43]
	v_mfma_f32_16x16x32_f16 v[48:51], v[164:167], v[180:183], v[48:51]
	v_mfma_f32_16x16x32_f16 v[48:51], v[168:171], v[184:187], v[48:51]
	v_mfma_f32_16x16x32_f16 v[44:47], v[160:163], v[184:187], v[44:47]
	v_mfma_f32_16x16x32_f16 v[44:47], v[156:159], v[180:183], v[44:47]
	v_mfma_f32_16x16x32_f16 v[52:55], v[156:159], v[188:191], v[52:55]
	v_mfma_f32_16x16x32_f16 v[52:55], v[160:163], v[192:195], v[52:55]
	v_mfma_f32_16x16x32_f16 v[56:59], v[168:171], v[192:195], v[56:59]
	v_mfma_f32_16x16x32_f16 v[56:59], v[164:167], v[188:191], v[56:59]
	v_mfma_f32_16x16x32_f16 v[64:67], v[164:167], v[196:199], v[64:67]
	s_setprio 2
	s_barrier
	v_mfma_f32_16x16x32_f16 v[64:67], v[168:171], v[200:203], v[64:67]
	v_mfma_f32_16x16x32_f16 v[60:63], v[160:163], v[200:203], v[60:63]
	v_mfma_f32_16x16x32_f16 v[60:63], v[156:159], v[196:199], v[60:63]
	s_setprio 0
	s_add_i32 s16, s29, s38
	v_lshl_add_u64 v[204:205], v[204:205], 0, s[86:87]
	s_mov_b32 m0, s16
	ds_read_b128 v[172:175], v212 offset:49152
	ds_read_b128 v[176:179], v212 offset:50176
	ds_read_b128 v[180:183], v212 offset:51200
	ds_read_b128 v[184:187], v212 offset:52224
	ds_read_b128 v[188:191], v212 offset:53248
	ds_read_b128 v[192:195], v212 offset:54272
	ds_read_b128 v[196:199], v212 offset:55296
	ds_read_b128 v[200:203], v212 offset:56320
	global_load_lds_dwordx4 v[204:205], off
	s_add_i32 m0, s16, 0x2000
	s_add_u32 s6, s6, 0x80080
	v_lshl_add_u64 v[204:205], v[206:207], 0, s[86:87]
	s_addc_u32 s7, s7, 0
	s_add_i32 s16, s40, s38
	global_load_lds_dwordx4 v[204:205], off
	s_mov_b32 m0, s16
	v_lshl_add_u64 v[204:205], v[208:209], 0, s[86:87]
	global_load_lds_dwordx4 v136, s[6:7]
	s_add_i32 m0, s16, 0x2000
	s_nop 0
	global_load_lds_dwordx4 v134, s[6:7]
	s_mov_b32 m0, s64
	s_nop 0
	global_load_lds_dwordx4 v[204:205], off
	v_lshl_add_u64 v[204:205], v[210:211], 0, s[86:87]
	s_mov_b32 m0, s65
	s_nop 0
	global_load_lds_dwordx4 v[204:205], off
	s_waitcnt vmcnt(8)
	s_waitcnt lgkmcnt(0)
	s_barrier
	s_setprio 1
	s_waitcnt lgkmcnt(0)
	v_mfma_f32_16x16x32_f16 v[68:71], v[138:141], v[172:175], v[68:71]
	v_mfma_f32_16x16x32_f16 v[68:71], v[142:145], v[176:179], v[68:71]
	v_mfma_f32_16x16x32_f16 v[72:75], v[152:155], v[176:179], v[72:75]
	v_mfma_f32_16x16x32_f16 v[72:75], v[148:151], v[172:175], v[72:75]
	v_mfma_f32_16x16x32_f16 v[80:83], v[148:151], v[180:183], v[80:83]
	v_mfma_f32_16x16x32_f16 v[80:83], v[152:155], v[184:187], v[80:83]
	v_mfma_f32_16x16x32_f16 v[76:79], v[142:145], v[184:187], v[76:79]
	v_mfma_f32_16x16x32_f16 v[76:79], v[138:141], v[180:183], v[76:79]
	v_mfma_f32_16x16x32_f16 v[84:87], v[138:141], v[188:191], v[84:87]
	v_mfma_f32_16x16x32_f16 v[84:87], v[142:145], v[192:195], v[84:87]
	v_mfma_f32_16x16x32_f16 v[88:91], v[152:155], v[192:195], v[88:91]
	v_mfma_f32_16x16x32_f16 v[88:91], v[148:151], v[188:191], v[88:91]
	v_mfma_f32_16x16x32_f16 v[96:99], v[148:151], v[196:199], v[96:99]
	v_mfma_f32_16x16x32_f16 v[96:99], v[152:155], v[200:203], v[96:99]
	v_mfma_f32_16x16x32_f16 v[92:95], v[142:145], v[200:203], v[92:95]
	v_mfma_f32_16x16x32_f16 v[92:95], v[138:141], v[196:199], v[92:95]
	s_setprio 0
	s_setprio 1
	v_mfma_f32_16x16x32_f16 v[100:103], v[156:159], v[172:175], v[100:103]
	v_mfma_f32_16x16x32_f16 v[100:103], v[160:163], v[176:179], v[100:103]
	v_mfma_f32_16x16x32_f16 v[104:107], v[168:171], v[176:179], v[104:107]
	v_mfma_f32_16x16x32_f16 v[104:107], v[164:167], v[172:175], v[104:107]
	v_mfma_f32_16x16x32_f16 v[112:115], v[164:167], v[180:183], v[112:115]
	v_mfma_f32_16x16x32_f16 v[112:115], v[168:171], v[184:187], v[112:115]
	v_mfma_f32_16x16x32_f16 v[108:111], v[160:163], v[184:187], v[108:111]
	v_mfma_f32_16x16x32_f16 v[108:111], v[156:159], v[180:183], v[108:111]
	v_mfma_f32_16x16x32_f16 v[116:119], v[156:159], v[188:191], v[116:119]
	v_mfma_f32_16x16x32_f16 v[116:119], v[160:163], v[192:195], v[116:119]
	v_mfma_f32_16x16x32_f16 v[120:123], v[168:171], v[192:195], v[120:123]
	v_mfma_f32_16x16x32_f16 v[120:123], v[164:167], v[188:191], v[120:123]
	v_mfma_f32_16x16x32_f16 v[128:131], v[164:167], v[196:199], v[128:131]
	s_setprio 2
	s_barrier
	v_mfma_f32_16x16x32_f16 v[128:131], v[168:171], v[200:203], v[128:131]
	v_mfma_f32_16x16x32_f16 v[124:127], v[160:163], v[200:203], v[124:127]
	v_mfma_f32_16x16x32_f16 v[124:127], v[156:159], v[196:199], v[124:127]
	s_setprio 0
	s_add_i32 s28, s28, 2
	s_add_u32 s8, s8, 0x100
	s_addc_u32 s9, s9, 0
	s_add_u32 s26, s26, 0x100
	s_addc_u32 s27, s27, 0
	s_cmp_gt_u32 s28, 29
	s_cbranch_scc0 .LBB0_532
	s_and_b64 vcc, exec, s[50:51]
	s_cbranch_vccz .LBB0_535
	s_barrier

.LBB0_641:
	s_add_i32 s43, 0, 0x10000
	s_add_i32 s71, 0, 0x14000
	v_add_u32_e32 v16, s43, v232
	v_add_u32_e32 v32, s71, v232
	ds_read_b128 v[4:7], v16
	ds_read_b128 v[8:11], v16 offset:1024
	ds_read_b128 v[12:15], v16 offset:2048
	ds_read_b128 v[16:19], v16 offset:3072
	ds_read_b128 v[20:23], v32
	ds_read_b128 v[24:27], v32 offset:1024
	ds_read_b128 v[28:31], v32 offset:2048
	ds_read_b128 v[32:35], v32 offset:3072
	v_add_u32_e32 v233, 0, v231
	ds_read_b128 v[36:39], v233
	ds_read_b128 v[40:43], v233 offset:1024
	ds_read_b128 v[44:47], v233 offset:2048
	ds_read_b128 v[48:51], v233 offset:3072
	ds_read_b128 v[52:55], v233 offset:4096
	ds_read_b128 v[56:59], v233 offset:5120
	ds_read_b128 v[60:63], v233 offset:6144
	ds_read_b128 v[64:67], v233 offset:7168
	s_waitcnt vmcnt(8)
	s_waitcnt lgkmcnt(0)
	s_barrier
	s_setprio 1
	s_waitcnt lgkmcnt(0)
	v_mfma_f32_16x16x32_bf16 v[68:71], v[4:7], v[36:39], 0
	v_mfma_f32_16x16x32_bf16 v[68:71], v[8:11], v[40:43], v[68:71]
	v_mfma_f32_16x16x32_bf16 v[72:75], v[12:15], v[36:39], 0
	v_mfma_f32_16x16x32_bf16 v[72:75], v[16:19], v[40:43], v[72:75]
	v_mfma_f32_16x16x32_bf16 v[80:83], v[12:15], v[44:47], 0
	v_mfma_f32_16x16x32_bf16 v[80:83], v[16:19], v[48:51], v[80:83]
	v_mfma_f32_16x16x32_bf16 v[76:79], v[4:7], v[44:47], 0
	v_mfma_f32_16x16x32_bf16 v[76:79], v[8:11], v[48:51], v[76:79]
	v_mfma_f32_16x16x32_bf16 v[84:87], v[4:7], v[52:55], 0
	v_mfma_f32_16x16x32_bf16 v[84:87], v[8:11], v[56:59], v[84:87]
	v_mfma_f32_16x16x32_bf16 v[88:91], v[12:15], v[52:55], 0
	v_mfma_f32_16x16x32_bf16 v[88:91], v[16:19], v[56:59], v[88:91]
	v_mfma_f32_16x16x32_bf16 v[96:99], v[12:15], v[60:63], 0
	v_mfma_f32_16x16x32_bf16 v[96:99], v[16:19], v[64:67], v[96:99]
	v_mfma_f32_16x16x32_bf16 v[92:95], v[4:7], v[60:63], 0
	v_mfma_f32_16x16x32_bf16 v[92:95], v[8:11], v[64:67], v[92:95]
	s_setprio 0
	s_setprio 1
	v_mfma_f32_16x16x32_bf16 v[100:103], v[20:23], v[36:39], 0
	v_mfma_f32_16x16x32_bf16 v[36:39], v[28:31], v[36:39], 0
	v_mfma_f32_16x16x32_bf16 v[104:107], v[20:23], v[44:47], 0
	v_mfma_f32_16x16x32_bf16 v[44:47], v[28:31], v[44:47], 0
	v_mfma_f32_16x16x32_bf16 v[108:111], v[20:23], v[52:55], 0
	v_mfma_f32_16x16x32_bf16 v[52:55], v[28:31], v[52:55], 0
	v_mfma_f32_16x16x32_bf16 v[112:115], v[20:23], v[60:63], 0
	v_mfma_f32_16x16x32_bf16 v[60:63], v[28:31], v[60:63], 0
	v_mfma_f32_16x16x32_bf16 v[100:103], v[24:27], v[40:43], v[100:103]
	v_mfma_f32_16x16x32_bf16 v[40:43], v[32:35], v[40:43], v[36:39]
	v_mfma_f32_16x16x32_bf16 v[104:107], v[24:27], v[48:51], v[104:107]
	v_mfma_f32_16x16x32_bf16 v[48:51], v[32:35], v[48:51], v[44:47]
	v_mfma_f32_16x16x32_bf16 v[108:111], v[24:27], v[56:59], v[108:111]
	s_setprio 2
	s_barrier
	v_mfma_f32_16x16x32_bf16 v[56:59], v[32:35], v[56:59], v[52:55]
	v_mfma_f32_16x16x32_bf16 v[112:115], v[24:27], v[64:67], v[112:115]
	v_mfma_f32_16x16x32_bf16 v[64:67], v[32:35], v[64:67], v[60:63]
	s_setprio 0
	v_lshl_add_u64 v[186:187], s[8:9], 0, v[2:3]
	s_add_i32 s43, s43, s54
	v_mov_b32_e32 v191, v3
	v_lshl_add_u64 v[134:135], v[186:187], 0, s[80:81]
	s_mov_b32 m0, s43
	v_lshl_add_u64 v[246:247], s[8:9], 0, v[190:191]
	ds_read_b128 v[36:39], v233 offset:16384
	ds_read_b128 v[44:47], v233 offset:17408
	ds_read_b128 v[52:55], v233 offset:18432
	ds_read_b128 v[60:63], v233 offset:19456
	ds_read_b128 v[116:119], v233 offset:20480
	ds_read_b128 v[120:123], v233 offset:21504
	ds_read_b128 v[124:127], v233 offset:22528
	ds_read_b128 v[128:131], v233 offset:23552
	global_load_lds_dwordx4 v[134:135], off
	v_lshl_add_u64 v[134:135], v[246:247], 0, s[80:81]
	s_add_i32 m0, s43, 0x2000
	s_add_i32 s43, s71, s54
	global_load_lds_dwordx4 v[134:135], off
	s_mov_b32 m0, s43
	v_mov_b32_e32 v133, v3
	global_load_lds_dwordx4 v2, s[16:17]
	s_add_i32 m0, s43, 0x2000
	v_lshl_add_u64 v[248:249], s[6:7], 0, v[132:133]
	v_mov_b32_e32 v189, v3
	global_load_lds_dwordx4 v190, s[16:17]
	v_lshl_add_u64 v[134:135], v[248:249], 0, s[80:81]
	s_mov_b32 m0, s55
	v_lshl_add_u64 v[250:251], s[6:7], 0, v[188:189]
	global_load_lds_dwordx4 v[134:135], off
	v_lshl_add_u64 v[134:135], v[250:251], 0, s[80:81]
	s_mov_b32 m0, s56
	s_nop 0
	global_load_lds_dwordx4 v[134:135], off
	s_waitcnt vmcnt(8)
	s_waitcnt lgkmcnt(0)
	s_barrier
	s_setprio 1
	s_waitcnt lgkmcnt(0)
	v_mfma_f32_16x16x32_bf16 v[134:137], v[4:7], v[36:39], 0
	v_mfma_f32_16x16x32_bf16 v[138:141], v[12:15], v[36:39], 0
	v_mfma_f32_16x16x32_bf16 v[142:145], v[4:7], v[52:55], 0
	v_mfma_f32_16x16x32_bf16 v[146:149], v[12:15], v[52:55], 0
	v_mfma_f32_16x16x32_bf16 v[150:153], v[4:7], v[116:119], 0
	v_mfma_f32_16x16x32_bf16 v[154:157], v[12:15], v[116:119], 0
	v_mfma_f32_16x16x32_bf16 v[4:7], v[4:7], v[124:127], 0
	v_mfma_f32_16x16x32_bf16 v[12:15], v[12:15], v[124:127], 0
	v_mfma_f32_16x16x32_bf16 v[134:137], v[8:11], v[44:47], v[134:137]
	v_mfma_f32_16x16x32_bf16 v[138:141], v[16:19], v[44:47], v[138:141]
	v_mfma_f32_16x16x32_bf16 v[142:145], v[8:11], v[60:63], v[142:145]
	v_mfma_f32_16x16x32_bf16 v[146:149], v[16:19], v[60:63], v[146:149]
	v_mfma_f32_16x16x32_bf16 v[150:153], v[8:11], v[120:123], v[150:153]
	v_mfma_f32_16x16x32_bf16 v[154:157], v[16:19], v[120:123], v[154:157]
	v_mfma_f32_16x16x32_bf16 v[158:161], v[8:11], v[128:131], v[4:7]
	v_mfma_f32_16x16x32_bf16 v[162:165], v[16:19], v[128:131], v[12:15]
	s_setprio 0
	s_setprio 1
	v_mfma_f32_16x16x32_bf16 v[4:7], v[20:23], v[36:39], 0
	v_mfma_f32_16x16x32_bf16 v[8:11], v[28:31], v[36:39], 0
	v_mfma_f32_16x16x32_bf16 v[12:15], v[20:23], v[52:55], 0
	v_mfma_f32_16x16x32_bf16 v[16:19], v[28:31], v[52:55], 0
	v_mfma_f32_16x16x32_bf16 v[36:39], v[20:23], v[116:119], 0
	v_mfma_f32_16x16x32_bf16 v[52:55], v[28:31], v[116:119], 0
	v_mfma_f32_16x16x32_bf16 v[20:23], v[20:23], v[124:127], 0
	v_mfma_f32_16x16x32_bf16 v[28:31], v[28:31], v[124:127], 0
	v_mfma_f32_16x16x32_bf16 v[116:119], v[24:27], v[44:47], v[4:7]
	v_mfma_f32_16x16x32_bf16 v[124:127], v[32:35], v[44:47], v[8:11]
	v_mfma_f32_16x16x32_bf16 v[174:177], v[24:27], v[120:123], v[36:39]
	v_mfma_f32_16x16x32_bf16 v[120:123], v[32:35], v[120:123], v[52:55]
	v_mfma_f32_16x16x32_bf16 v[178:181], v[24:27], v[128:131], v[20:23]
	s_setprio 2
	s_barrier
	v_mfma_f32_16x16x32_bf16 v[128:131], v[32:35], v[128:131], v[28:31]
	v_mfma_f32_16x16x32_bf16 v[166:169], v[24:27], v[60:63], v[12:15]
	v_mfma_f32_16x16x32_bf16 v[170:173], v[32:35], v[60:63], v[16:19]
	s_setprio 0
	s_add_i32 s43, 0, 0x18000
	v_add_u32_e32 v4, s43, v232
	s_add_i32 s71, 0, 0x1c000
	ds_read_b128 v[182:185], v4
	ds_read_b128 v[192:195], v4 offset:1024
	ds_read_b128 v[196:199], v4 offset:2048
	ds_read_b128 v[200:203], v4 offset:3072
	v_add_u32_e32 v4, s71, v232
	ds_read_b128 v[204:207], v4
	ds_read_b128 v[208:211], v4 offset:1024
	ds_read_b128 v[212:215], v4 offset:2048
	ds_read_b128 v[216:219], v4 offset:3072
	s_mov_b32 m0, s57
	ds_read_b128 v[44:47], v233 offset:32768
	ds_read_b128 v[52:55], v233 offset:33792
	ds_read_b128 v[60:63], v233 offset:34816
	ds_read_b128 v[220:223], v233 offset:35840
	ds_read_b128 v[224:227], v233 offset:36864
	ds_read_b128 v[234:237], v233 offset:37888
	ds_read_b128 v[238:241], v233 offset:38912
	ds_read_b128 v[242:245], v233 offset:39936
	global_load_lds_dwordx4 v132, s[26:27]
	s_mov_b32 m0, s58
	s_nop 0
	global_load_lds_dwordx4 v188, s[26:27]
	s_waitcnt vmcnt(8)
	s_waitcnt lgkmcnt(0)
	s_barrier
	s_setprio 1
	s_waitcnt lgkmcnt(0)
	v_mfma_f32_16x16x32_bf16 v[4:7], v[182:185], v[44:47], v[68:71]
	v_mfma_f32_16x16x32_bf16 v[8:11], v[196:199], v[44:47], v[72:75]
	v_mfma_f32_16x16x32_bf16 v[12:15], v[182:185], v[60:63], v[76:79]
	v_mfma_f32_16x16x32_bf16 v[16:19], v[196:199], v[60:63], v[80:83]
	v_mfma_f32_16x16x32_bf16 v[20:23], v[182:185], v[224:227], v[84:87]
	v_mfma_f32_16x16x32_bf16 v[24:27], v[196:199], v[224:227], v[88:91]
	v_mfma_f32_16x16x32_bf16 v[28:31], v[182:185], v[238:241], v[92:95]
	v_mfma_f32_16x16x32_bf16 v[32:35], v[196:199], v[238:241], v[96:99]
	v_mfma_f32_16x16x32_bf16 v[4:7], v[192:195], v[52:55], v[4:7]
	v_mfma_f32_16x16x32_bf16 v[8:11], v[200:203], v[52:55], v[8:11]
	v_mfma_f32_16x16x32_bf16 v[12:15], v[192:195], v[220:223], v[12:15]
	v_mfma_f32_16x16x32_bf16 v[16:19], v[200:203], v[220:223], v[16:19]
	v_mfma_f32_16x16x32_bf16 v[20:23], v[192:195], v[234:237], v[20:23]
	v_mfma_f32_16x16x32_bf16 v[24:27], v[200:203], v[234:237], v[24:27]
	v_mfma_f32_16x16x32_bf16 v[28:31], v[192:195], v[242:245], v[28:31]
	v_mfma_f32_16x16x32_bf16 v[32:35], v[200:203], v[242:245], v[32:35]
	s_setprio 0
	s_setprio 1
	v_mfma_f32_16x16x32_bf16 v[36:39], v[204:207], v[44:47], v[100:103]
	v_mfma_f32_16x16x32_bf16 v[40:43], v[212:215], v[44:47], v[40:43]
	v_mfma_f32_16x16x32_bf16 v[36:39], v[208:211], v[52:55], v[36:39]
	v_mfma_f32_16x16x32_bf16 v[40:43], v[216:219], v[52:55], v[40:43]
	v_mfma_f32_16x16x32_bf16 v[44:47], v[204:207], v[60:63], v[104:107]
	v_mfma_f32_16x16x32_bf16 v[48:51], v[212:215], v[60:63], v[48:51]
	v_mfma_f32_16x16x32_bf16 v[52:55], v[204:207], v[224:227], v[108:111]
	v_mfma_f32_16x16x32_bf16 v[56:59], v[212:215], v[224:227], v[56:59]
	v_mfma_f32_16x16x32_bf16 v[60:63], v[204:207], v[238:241], v[112:115]
	v_mfma_f32_16x16x32_bf16 v[64:67], v[212:215], v[238:241], v[64:67]
	v_mfma_f32_16x16x32_bf16 v[44:47], v[208:211], v[220:223], v[44:47]
	v_mfma_f32_16x16x32_bf16 v[48:51], v[216:219], v[220:223], v[48:51]
	v_mfma_f32_16x16x32_bf16 v[52:55], v[208:211], v[234:237], v[52:55]
	s_setprio 2
	s_barrier
	v_mfma_f32_16x16x32_bf16 v[56:59], v[216:219], v[234:237], v[56:59]
	v_mfma_f32_16x16x32_bf16 v[60:63], v[208:211], v[242:245], v[60:63]
	v_mfma_f32_16x16x32_bf16 v[64:67], v[216:219], v[242:245], v[64:67]
	s_setprio 0
	s_add_i32 s43, s43, s54
	v_lshl_add_u64 v[68:69], v[186:187], 0, s[0:1]
	s_mov_b32 m0, s43
	ds_read_b128 v[104:107], v233 offset:49152
	ds_read_b128 v[108:111], v233 offset:50176
	ds_read_b128 v[112:115], v233 offset:51200
	ds_read_b128 v[220:223], v233 offset:52224
	ds_read_b128 v[224:227], v233 offset:53248
	ds_read_b128 v[234:237], v233 offset:54272
	ds_read_b128 v[238:241], v233 offset:55296
	ds_read_b128 v[242:245], v233 offset:56320
	global_load_lds_dwordx4 v[68:69], off
	v_lshl_add_u64 v[68:69], v[246:247], 0, s[0:1]
	s_add_i32 m0, s43, 0x2000
	s_add_i32 s43, s71, s54
	global_load_lds_dwordx4 v[68:69], off
	s_mov_b32 m0, s43
	v_lshl_add_u64 v[68:69], v[248:249], 0, s[0:1]
	global_load_lds_dwordx4 v2, s[28:29]
	s_add_i32 m0, s43, 0x2000
	s_nop 0
	global_load_lds_dwordx4 v190, s[28:29]
	s_mov_b32 m0, s62
	s_nop 0
	global_load_lds_dwordx4 v[68:69], off
	v_lshl_add_u64 v[68:69], v[250:251], 0, s[0:1]
	s_mov_b32 m0, s63
	s_nop 0
	global_load_lds_dwordx4 v[68:69], off
	s_waitcnt vmcnt(8)
	s_waitcnt lgkmcnt(0)
	s_barrier
	s_setprio 1
	s_waitcnt lgkmcnt(0)
	v_mfma_f32_16x16x32_bf16 v[68:71], v[182:185], v[104:107], v[134:137]
	v_mfma_f32_16x16x32_bf16 v[72:75], v[196:199], v[104:107], v[138:141]
	v_mfma_f32_16x16x32_bf16 v[76:79], v[182:185], v[112:115], v[142:145]
	v_mfma_f32_16x16x32_bf16 v[80:83], v[196:199], v[112:115], v[146:149]
	v_mfma_f32_16x16x32_bf16 v[84:87], v[182:185], v[224:227], v[150:153]
	v_mfma_f32_16x16x32_bf16 v[88:91], v[196:199], v[224:227], v[154:157]
	v_mfma_f32_16x16x32_bf16 v[92:95], v[182:185], v[238:241], v[158:161]
	v_mfma_f32_16x16x32_bf16 v[96:99], v[196:199], v[238:241], v[162:165]
	v_mfma_f32_16x16x32_bf16 v[68:71], v[192:195], v[108:111], v[68:71]
	v_mfma_f32_16x16x32_bf16 v[72:75], v[200:203], v[108:111], v[72:75]
	v_mfma_f32_16x16x32_bf16 v[76:79], v[192:195], v[220:223], v[76:79]
	v_mfma_f32_16x16x32_bf16 v[80:83], v[200:203], v[220:223], v[80:83]
	v_mfma_f32_16x16x32_bf16 v[84:87], v[192:195], v[234:237], v[84:87]
	v_mfma_f32_16x16x32_bf16 v[88:91], v[200:203], v[234:237], v[88:91]
	v_mfma_f32_16x16x32_bf16 v[92:95], v[192:195], v[242:245], v[92:95]
	v_mfma_f32_16x16x32_bf16 v[96:99], v[200:203], v[242:245], v[96:99]
	s_setprio 0
	s_setprio 1
	v_mfma_f32_16x16x32_bf16 v[100:103], v[204:207], v[104:107], v[116:119]
	v_mfma_f32_16x16x32_bf16 v[104:107], v[212:215], v[104:107], v[124:127]
	v_mfma_f32_16x16x32_bf16 v[100:103], v[208:211], v[108:111], v[100:103]
	v_mfma_f32_16x16x32_bf16 v[104:107], v[216:219], v[108:111], v[104:107]
	v_mfma_f32_16x16x32_bf16 v[108:111], v[204:207], v[112:115], v[166:169]
	v_mfma_f32_16x16x32_bf16 v[112:115], v[212:215], v[112:115], v[170:173]
	v_mfma_f32_16x16x32_bf16 v[116:119], v[204:207], v[224:227], v[174:177]
	v_mfma_f32_16x16x32_bf16 v[120:123], v[212:215], v[224:227], v[120:123]
	v_mfma_f32_16x16x32_bf16 v[124:127], v[204:207], v[238:241], v[178:181]
	v_mfma_f32_16x16x32_bf16 v[128:131], v[212:215], v[238:241], v[128:131]
	v_mfma_f32_16x16x32_bf16 v[108:111], v[208:211], v[220:223], v[108:111]
	v_mfma_f32_16x16x32_bf16 v[112:115], v[216:219], v[220:223], v[112:115]
	v_mfma_f32_16x16x32_bf16 v[116:119], v[208:211], v[234:237], v[116:119]
	s_setprio 2
	s_barrier
	v_mfma_f32_16x16x32_bf16 v[120:123], v[216:219], v[234:237], v[120:123]
	v_mfma_f32_16x16x32_bf16 v[124:127], v[208:211], v[242:245], v[124:127]
	v_mfma_f32_16x16x32_bf16 v[128:131], v[216:219], v[242:245], v[128:131]
	s_setprio 0
	s_add_i32 s42, s42, 2
	s_cmp_ge_i32 s42, s38
	s_cbranch_scc0 .LBB0_641
	v_mov_b32_e32 v192, v2
	s_branch .LBB0_644

.LBB0_649:
	s_or_b32 s38, s28, 1
	s_lshl_b64 s[42:43], s[38:39], 7
	s_sub_u32 s38, 0, s42
	s_subb_u32 s42, 0, s43
	s_add_u32 s38, s6, s38
	s_addc_u32 s43, s7, s42
	s_add_i32 s71, 0, 0x10000
	s_add_i32 s72, 0, 0x14000
	v_add_u32_e32 v144, s71, v232
	v_add_u32_e32 v160, s72, v232
	s_waitcnt lgkmcnt(0)
	ds_read_b128 v[132:135], v144
	ds_read_b128 v[136:139], v144 offset:1024
	ds_read_b128 v[140:143], v144 offset:2048
	ds_read_b128 v[144:147], v144 offset:3072
	ds_read_b128 v[148:151], v160
	ds_read_b128 v[152:155], v160 offset:1024
	ds_read_b128 v[156:159], v160 offset:2048
	ds_read_b128 v[160:163], v160 offset:3072
	s_add_u32 s42, s38, 0x160000
	s_mov_b32 m0, s64
	v_add_u32_e32 v210, 0, v231
	s_addc_u32 s43, s43, 0
	ds_read_b128 v[164:167], v210
	ds_read_b128 v[168:171], v210 offset:1024
	ds_read_b128 v[172:175], v210 offset:2048
	ds_read_b128 v[176:179], v210 offset:3072
	ds_read_b128 v[180:183], v210 offset:4096
	ds_read_b128 v[184:187], v210 offset:5120
	ds_read_b128 v[194:197], v210 offset:6144
	ds_read_b128 v[198:201], v210 offset:7168
	global_load_lds_dwordx4 v2, s[42:43]
	s_mov_b32 m0, s65
	v_mov_b32_e32 v189, v3
	global_load_lds_dwordx4 v188, s[42:43]
	s_waitcnt vmcnt(8)
	s_waitcnt lgkmcnt(0)
	s_barrier
	s_setprio 1
	s_waitcnt lgkmcnt(0)
	v_mfma_f32_16x16x32_bf16 v[4:7], v[132:135], v[164:167], v[4:7]
	v_mfma_f32_16x16x32_bf16 v[4:7], v[136:139], v[168:171], v[4:7]
	v_mfma_f32_16x16x32_bf16 v[8:11], v[144:147], v[168:171], v[8:11]
	v_mfma_f32_16x16x32_bf16 v[8:11], v[140:143], v[164:167], v[8:11]
	v_mfma_f32_16x16x32_bf16 v[16:19], v[140:143], v[172:175], v[16:19]
	v_mfma_f32_16x16x32_bf16 v[16:19], v[144:147], v[176:179], v[16:19]
	v_mfma_f32_16x16x32_bf16 v[12:15], v[136:139], v[176:179], v[12:15]
	v_mfma_f32_16x16x32_bf16 v[12:15], v[132:135], v[172:175], v[12:15]
	v_mfma_f32_16x16x32_bf16 v[20:23], v[132:135], v[180:183], v[20:23]
	v_mfma_f32_16x16x32_bf16 v[20:23], v[136:139], v[184:187], v[20:23]
	v_mfma_f32_16x16x32_bf16 v[24:27], v[144:147], v[184:187], v[24:27]
	v_mfma_f32_16x16x32_bf16 v[24:27], v[140:143], v[180:183], v[24:27]
	v_mfma_f32_16x16x32_bf16 v[32:35], v[140:143], v[194:197], v[32:35]
	v_mfma_f32_16x16x32_bf16 v[32:35], v[144:147], v[198:201], v[32:35]
	v_mfma_f32_16x16x32_bf16 v[28:31], v[136:139], v[198:201], v[28:31]
	v_mfma_f32_16x16x32_bf16 v[28:31], v[132:135], v[194:197], v[28:31]
	s_setprio 0
	s_setprio 1
	v_mfma_f32_16x16x32_bf16 v[36:39], v[148:151], v[164:167], v[36:39]
	v_mfma_f32_16x16x32_bf16 v[36:39], v[152:155], v[168:171], v[36:39]
	v_mfma_f32_16x16x32_bf16 v[40:43], v[160:163], v[168:171], v[40:43]
	v_mfma_f32_16x16x32_bf16 v[40:43], v[156:159], v[164:167], v[40:43]
	v_mfma_f32_16x16x32_bf16 v[48:51], v[156:159], v[172:175], v[48:51]
	v_mfma_f32_16x16x32_bf16 v[48:51], v[160:163], v[176:179], v[48:51]
	v_mfma_f32_16x16x32_bf16 v[44:47], v[152:155], v[176:179], v[44:47]
	v_mfma_f32_16x16x32_bf16 v[44:47], v[148:151], v[172:175], v[44:47]
	v_mfma_f32_16x16x32_bf16 v[52:55], v[148:151], v[180:183], v[52:55]
	v_mfma_f32_16x16x32_bf16 v[52:55], v[152:155], v[184:187], v[52:55]
	v_mfma_f32_16x16x32_bf16 v[56:59], v[160:163], v[184:187], v[56:59]
	v_mfma_f32_16x16x32_bf16 v[56:59], v[156:159], v[180:183], v[56:59]
	v_mfma_f32_16x16x32_bf16 v[64:67], v[156:159], v[194:197], v[64:67]
	s_setprio 2
	s_barrier
	v_mfma_f32_16x16x32_bf16 v[64:67], v[160:163], v[198:201], v[64:67]
	v_mfma_f32_16x16x32_bf16 v[60:63], v[152:155], v[198:201], v[60:63]
	v_mfma_f32_16x16x32_bf16 v[60:63], v[148:151], v[194:197], v[60:63]
	s_setprio 0
	s_add_i32 s38, s71, s54
	s_mov_b32 m0, s38
	ds_read_b128 v[164:167], v210 offset:16384
	ds_read_b128 v[168:171], v210 offset:17408
	ds_read_b128 v[172:175], v210 offset:18432
	ds_read_b128 v[176:179], v210 offset:19456
	ds_read_b128 v[180:183], v210 offset:20480
	ds_read_b128 v[184:187], v210 offset:21504
	ds_read_b128 v[194:197], v210 offset:22528
	ds_read_b128 v[198:201], v210 offset:23552
	global_load_lds_dwordx4 v192, s[16:17]
	s_add_i32 m0, s38, 0x2000
	s_add_u32 s42, s16, 0x160000
	s_addc_u32 s43, s17, 0
	s_add_i32 s38, s72, s54
	global_load_lds_dwordx4 v190, s[16:17]
	s_mov_b32 m0, s38
	v_mov_b32_e32 v193, v3
	global_load_lds_dwordx4 v192, s[42:43]
	s_add_i32 m0, s38, 0x2000
	v_mov_b32_e32 v191, v3
	global_load_lds_dwordx4 v190, s[42:43]
	s_mov_b32 m0, s55
	v_lshl_add_u64 v[202:203], s[16:17], 0, v[192:193]
	global_load_lds_dwordx4 v2, s[26:27]
	s_mov_b32 m0, s56
	v_lshl_add_u64 v[204:205], s[16:17], 0, v[190:191]
	global_load_lds_dwordx4 v188, s[26:27]
	s_waitcnt vmcnt(8)
	s_waitcnt lgkmcnt(0)
	v_lshl_add_u64 v[206:207], s[26:27], 0, v[2:3]
	v_lshl_add_u64 v[208:209], s[26:27], 0, v[188:189]
	s_barrier
	s_setprio 1
	s_waitcnt lgkmcnt(0)
	v_mfma_f32_16x16x32_bf16 v[68:71], v[132:135], v[164:167], v[68:71]
	v_mfma_f32_16x16x32_bf16 v[68:71], v[136:139], v[168:171], v[68:71]
	v_mfma_f32_16x16x32_bf16 v[72:75], v[144:147], v[168:171], v[72:75]
	v_mfma_f32_16x16x32_bf16 v[72:75], v[140:143], v[164:167], v[72:75]
	v_mfma_f32_16x16x32_bf16 v[80:83], v[140:143], v[172:175], v[80:83]
	v_mfma_f32_16x16x32_bf16 v[80:83], v[144:147], v[176:179], v[80:83]
	v_mfma_f32_16x16x32_bf16 v[76:79], v[136:139], v[176:179], v[76:79]
	v_mfma_f32_16x16x32_bf16 v[76:79], v[132:135], v[172:175], v[76:79]
	v_mfma_f32_16x16x32_bf16 v[84:87], v[132:135], v[180:183], v[84:87]
	v_mfma_f32_16x16x32_bf16 v[84:87], v[136:139], v[184:187], v[84:87]
	v_mfma_f32_16x16x32_bf16 v[88:91], v[144:147], v[184:187], v[88:91]
	v_mfma_f32_16x16x32_bf16 v[88:91], v[140:143], v[180:183], v[88:91]
	v_mfma_f32_16x16x32_bf16 v[96:99], v[140:143], v[194:197], v[96:99]
	v_mfma_f32_16x16x32_bf16 v[96:99], v[144:147], v[198:201], v[96:99]
	v_mfma_f32_16x16x32_bf16 v[92:95], v[136:139], v[198:201], v[92:95]
	v_mfma_f32_16x16x32_bf16 v[92:95], v[132:135], v[194:197], v[92:95]
	s_setprio 0
	s_setprio 1
	v_mfma_f32_16x16x32_bf16 v[100:103], v[148:151], v[164:167], v[100:103]
	v_mfma_f32_16x16x32_bf16 v[100:103], v[152:155], v[168:171], v[100:103]
	v_mfma_f32_16x16x32_bf16 v[104:107], v[160:163], v[168:171], v[104:107]
	v_mfma_f32_16x16x32_bf16 v[104:107], v[156:159], v[164:167], v[104:107]
	v_mfma_f32_16x16x32_bf16 v[112:115], v[156:159], v[172:175], v[112:115]
	v_mfma_f32_16x16x32_bf16 v[112:115], v[160:163], v[176:179], v[112:115]
	v_mfma_f32_16x16x32_bf16 v[108:111], v[152:155], v[176:179], v[108:111]
	v_mfma_f32_16x16x32_bf16 v[108:111], v[148:151], v[172:175], v[108:111]
	v_mfma_f32_16x16x32_bf16 v[116:119], v[148:151], v[180:183], v[116:119]
	v_mfma_f32_16x16x32_bf16 v[116:119], v[152:155], v[184:187], v[116:119]
	v_mfma_f32_16x16x32_bf16 v[120:123], v[160:163], v[184:187], v[120:123]
	v_mfma_f32_16x16x32_bf16 v[120:123], v[156:159], v[180:183], v[120:123]
	v_mfma_f32_16x16x32_bf16 v[128:131], v[156:159], v[194:197], v[128:131]
	s_setprio 2
	s_barrier
	v_mfma_f32_16x16x32_bf16 v[128:131], v[160:163], v[198:201], v[128:131]
	v_mfma_f32_16x16x32_bf16 v[124:127], v[152:155], v[198:201], v[124:127]
	v_mfma_f32_16x16x32_bf16 v[124:127], v[148:151], v[194:197], v[124:127]
	s_setprio 0
	s_add_i32 s38, 0, 0x18000
	s_add_i32 s42, 0, 0x1c000
	v_add_u32_e32 v144, s38, v232
	v_add_u32_e32 v160, s42, v232
	ds_read_b128 v[132:135], v144
	ds_read_b128 v[136:139], v144 offset:1024
	ds_read_b128 v[140:143], v144 offset:2048
	ds_read_b128 v[144:147], v144 offset:3072
	ds_read_b128 v[148:151], v160
	ds_read_b128 v[152:155], v160 offset:1024
	ds_read_b128 v[156:159], v160 offset:2048
	ds_read_b128 v[160:163], v160 offset:3072
	s_add_u32 s26, s26, 0x160000
	s_addc_u32 s27, s27, 0
	s_mov_b32 m0, s57
	ds_read_b128 v[164:167], v210 offset:32768
	ds_read_b128 v[168:171], v210 offset:33792
	ds_read_b128 v[172:175], v210 offset:34816
	ds_read_b128 v[176:179], v210 offset:35840
	ds_read_b128 v[180:183], v210 offset:36864
	ds_read_b128 v[184:187], v210 offset:37888
	ds_read_b128 v[194:197], v210 offset:38912
	ds_read_b128 v[198:201], v210 offset:39936
	global_load_lds_dwordx4 v2, s[26:27]
	s_mov_b32 m0, s58
	s_nop 0
	global_load_lds_dwordx4 v188, s[26:27]
	s_waitcnt vmcnt(8)
	s_waitcnt lgkmcnt(0)
	s_barrier
	s_setprio 1
	s_waitcnt lgkmcnt(0)
	v_mfma_f32_16x16x32_bf16 v[4:7], v[132:135], v[164:167], v[4:7]
	v_mfma_f32_16x16x32_bf16 v[4:7], v[136:139], v[168:171], v[4:7]
	v_mfma_f32_16x16x32_bf16 v[8:11], v[144:147], v[168:171], v[8:11]
	v_mfma_f32_16x16x32_bf16 v[8:11], v[140:143], v[164:167], v[8:11]
	v_mfma_f32_16x16x32_bf16 v[16:19], v[140:143], v[172:175], v[16:19]
	v_mfma_f32_16x16x32_bf16 v[16:19], v[144:147], v[176:179], v[16:19]
	v_mfma_f32_16x16x32_bf16 v[12:15], v[136:139], v[176:179], v[12:15]
	v_mfma_f32_16x16x32_bf16 v[12:15], v[132:135], v[172:175], v[12:15]
	v_mfma_f32_16x16x32_bf16 v[20:23], v[132:135], v[180:183], v[20:23]
	v_mfma_f32_16x16x32_bf16 v[20:23], v[136:139], v[184:187], v[20:23]
	v_mfma_f32_16x16x32_bf16 v[24:27], v[144:147], v[184:187], v[24:27]
	v_mfma_f32_16x16x32_bf16 v[24:27], v[140:143], v[180:183], v[24:27]
	v_mfma_f32_16x16x32_bf16 v[32:35], v[140:143], v[194:197], v[32:35]
	v_mfma_f32_16x16x32_bf16 v[32:35], v[144:147], v[198:201], v[32:35]
	v_mfma_f32_16x16x32_bf16 v[28:31], v[136:139], v[198:201], v[28:31]
	v_mfma_f32_16x16x32_bf16 v[28:31], v[132:135], v[194:197], v[28:31]
	s_setprio 0
	s_setprio 1
	v_mfma_f32_16x16x32_bf16 v[36:39], v[148:151], v[164:167], v[36:39]
	v_mfma_f32_16x16x32_bf16 v[36:39], v[152:155], v[168:171], v[36:39]
	v_mfma_f32_16x16x32_bf16 v[40:43], v[160:163], v[168:171], v[40:43]
	v_mfma_f32_16x16x32_bf16 v[40:43], v[156:159], v[164:167], v[40:43]
	v_mfma_f32_16x16x32_bf16 v[48:51], v[156:159], v[172:175], v[48:51]
	v_mfma_f32_16x16x32_bf16 v[48:51], v[160:163], v[176:179], v[48:51]
	v_mfma_f32_16x16x32_bf16 v[44:47], v[152:155], v[176:179], v[44:47]
	v_mfma_f32_16x16x32_bf16 v[44:47], v[148:151], v[172:175], v[44:47]
	v_mfma_f32_16x16x32_bf16 v[52:55], v[148:151], v[180:183], v[52:55]
	v_mfma_f32_16x16x32_bf16 v[52:55], v[152:155], v[184:187], v[52:55]
	v_mfma_f32_16x16x32_bf16 v[56:59], v[160:163], v[184:187], v[56:59]
	v_mfma_f32_16x16x32_bf16 v[56:59], v[156:159], v[180:183], v[56:59]
	v_mfma_f32_16x16x32_bf16 v[64:67], v[156:159], v[194:197], v[64:67]
	s_setprio 2
	s_barrier
	v_mfma_f32_16x16x32_bf16 v[64:67], v[160:163], v[198:201], v[64:67]
	v_mfma_f32_16x16x32_bf16 v[60:63], v[152:155], v[198:201], v[60:63]
	v_mfma_f32_16x16x32_bf16 v[60:63], v[148:151], v[194:197], v[60:63]
	s_setprio 0
	s_add_i32 s26, s38, s54
	v_lshl_add_u64 v[202:203], v[202:203], 0, s[4:5]
	s_mov_b32 m0, s26
	ds_read_b128 v[164:167], v210 offset:49152
	ds_read_b128 v[168:171], v210 offset:50176
	ds_read_b128 v[172:175], v210 offset:51200
	ds_read_b128 v[176:179], v210 offset:52224
	ds_read_b128 v[180:183], v210 offset:53248
	ds_read_b128 v[184:187], v210 offset:54272
	ds_read_b128 v[194:197], v210 offset:55296
	ds_read_b128 v[198:201], v210 offset:56320
	global_load_lds_dwordx4 v[202:203], off
	s_add_i32 m0, s26, 0x2000
	s_add_u32 s16, s16, 0x15ff80
	v_lshl_add_u64 v[202:203], v[204:205], 0, s[4:5]
	s_addc_u32 s17, s17, 0
	s_add_i32 s26, s42, s54
	global_load_lds_dwordx4 v[202:203], off
	s_mov_b32 m0, s26
	v_lshl_add_u64 v[202:203], v[206:207], 0, s[4:5]
	global_load_lds_dwordx4 v192, s[16:17]
	s_add_i32 m0, s26, 0x2000
	s_nop 0
	global_load_lds_dwordx4 v190, s[16:17]
	s_mov_b32 m0, s62
	s_nop 0
	global_load_lds_dwordx4 v[202:203], off
	v_lshl_add_u64 v[202:203], v[208:209], 0, s[4:5]
	s_mov_b32 m0, s63
	s_nop 0
	global_load_lds_dwordx4 v[202:203], off
	s_waitcnt vmcnt(8)
	s_waitcnt lgkmcnt(0)
	s_barrier
	s_setprio 1
	s_waitcnt lgkmcnt(0)
	v_mfma_f32_16x16x32_bf16 v[68:71], v[132:135], v[164:167], v[68:71]
	v_mfma_f32_16x16x32_bf16 v[68:71], v[136:139], v[168:171], v[68:71]
	v_mfma_f32_16x16x32_bf16 v[72:75], v[144:147], v[168:171], v[72:75]
	v_mfma_f32_16x16x32_bf16 v[72:75], v[140:143], v[164:167], v[72:75]
	v_mfma_f32_16x16x32_bf16 v[80:83], v[140:143], v[172:175], v[80:83]
	v_mfma_f32_16x16x32_bf16 v[80:83], v[144:147], v[176:179], v[80:83]
	v_mfma_f32_16x16x32_bf16 v[76:79], v[136:139], v[176:179], v[76:79]
	v_mfma_f32_16x16x32_bf16 v[76:79], v[132:135], v[172:175], v[76:79]
	v_mfma_f32_16x16x32_bf16 v[84:87], v[132:135], v[180:183], v[84:87]
	v_mfma_f32_16x16x32_bf16 v[84:87], v[136:139], v[184:187], v[84:87]
	v_mfma_f32_16x16x32_bf16 v[88:91], v[144:147], v[184:187], v[88:91]
	v_mfma_f32_16x16x32_bf16 v[88:91], v[140:143], v[180:183], v[88:91]
	v_mfma_f32_16x16x32_bf16 v[96:99], v[140:143], v[194:197], v[96:99]
	v_mfma_f32_16x16x32_bf16 v[96:99], v[144:147], v[198:201], v[96:99]
	v_mfma_f32_16x16x32_bf16 v[92:95], v[136:139], v[198:201], v[92:95]
	v_mfma_f32_16x16x32_bf16 v[92:95], v[132:135], v[194:197], v[92:95]
	s_setprio 0
	s_setprio 1
	v_mfma_f32_16x16x32_bf16 v[100:103], v[148:151], v[164:167], v[100:103]
	v_mfma_f32_16x16x32_bf16 v[100:103], v[152:155], v[168:171], v[100:103]
	v_mfma_f32_16x16x32_bf16 v[104:107], v[160:163], v[168:171], v[104:107]
	v_mfma_f32_16x16x32_bf16 v[104:107], v[156:159], v[164:167], v[104:107]
	v_mfma_f32_16x16x32_bf16 v[112:115], v[156:159], v[172:175], v[112:115]
	v_mfma_f32_16x16x32_bf16 v[112:115], v[160:163], v[176:179], v[112:115]
	v_mfma_f32_16x16x32_bf16 v[108:111], v[152:155], v[176:179], v[108:111]
	v_mfma_f32_16x16x32_bf16 v[108:111], v[148:151], v[172:175], v[108:111]
	v_mfma_f32_16x16x32_bf16 v[116:119], v[148:151], v[180:183], v[116:119]
	v_mfma_f32_16x16x32_bf16 v[116:119], v[152:155], v[184:187], v[116:119]
	v_mfma_f32_16x16x32_bf16 v[120:123], v[160:163], v[184:187], v[120:123]
	v_mfma_f32_16x16x32_bf16 v[120:123], v[156:159], v[180:183], v[120:123]
	v_mfma_f32_16x16x32_bf16 v[128:131], v[156:159], v[194:197], v[128:131]
	s_setprio 2
	s_barrier
	v_mfma_f32_16x16x32_bf16 v[128:131], v[160:163], v[198:201], v[128:131]
	v_mfma_f32_16x16x32_bf16 v[124:127], v[152:155], v[198:201], v[124:127]
	v_mfma_f32_16x16x32_bf16 v[124:127], v[148:151], v[194:197], v[124:127]
	s_setprio 0
	s_cmpk_gt_u32 s28, 0x55
	s_cbranch_scc1 .LBB0_651
	s_mov_b32 s28, s29
	s_branch .LBB0_645

.LBB0_749:
	s_add_i32 s47, 0, 0x10000
	s_add_i32 s49, 0, 0x14000
	v_add_u32_e32 v16, s47, v147
	v_add_u32_e32 v32, s49, v147
	ds_read_b128 v[4:7], v16
	ds_read_b128 v[8:11], v16 offset:1024
	ds_read_b128 v[12:15], v16 offset:2048
	ds_read_b128 v[16:19], v16 offset:3072
	ds_read_b128 v[20:23], v32
	ds_read_b128 v[24:27], v32 offset:1024
	ds_read_b128 v[28:31], v32 offset:2048
	ds_read_b128 v[32:35], v32 offset:3072
	v_add_u32_e32 v231, 0, v146
	ds_read_b128 v[36:39], v231
	ds_read_b128 v[40:43], v231 offset:1024
	ds_read_b128 v[44:47], v231 offset:2048
	ds_read_b128 v[48:51], v231 offset:3072
	ds_read_b128 v[52:55], v231 offset:4096
	ds_read_b128 v[56:59], v231 offset:5120
	ds_read_b128 v[60:63], v231 offset:6144
	ds_read_b128 v[64:67], v231 offset:7168
	s_waitcnt vmcnt(8)
	s_waitcnt lgkmcnt(0)
	s_barrier
	s_setprio 1
	s_waitcnt lgkmcnt(0)
	v_mfma_f32_16x16x32_f16 v[68:71], v[4:7], v[36:39], 0
	v_mfma_f32_16x16x32_f16 v[68:71], v[8:11], v[40:43], v[68:71]
	v_mfma_f32_16x16x32_f16 v[72:75], v[12:15], v[36:39], 0
	v_mfma_f32_16x16x32_f16 v[72:75], v[16:19], v[40:43], v[72:75]
	v_mfma_f32_16x16x32_f16 v[80:83], v[12:15], v[44:47], 0
	v_mfma_f32_16x16x32_f16 v[80:83], v[16:19], v[48:51], v[80:83]
	v_mfma_f32_16x16x32_f16 v[76:79], v[4:7], v[44:47], 0
	v_mfma_f32_16x16x32_f16 v[76:79], v[8:11], v[48:51], v[76:79]
	v_mfma_f32_16x16x32_f16 v[84:87], v[4:7], v[52:55], 0
	v_mfma_f32_16x16x32_f16 v[84:87], v[8:11], v[56:59], v[84:87]
	v_mfma_f32_16x16x32_f16 v[88:91], v[12:15], v[52:55], 0
	v_mfma_f32_16x16x32_f16 v[88:91], v[16:19], v[56:59], v[88:91]
	v_mfma_f32_16x16x32_f16 v[96:99], v[12:15], v[60:63], 0
	v_mfma_f32_16x16x32_f16 v[96:99], v[16:19], v[64:67], v[96:99]
	v_mfma_f32_16x16x32_f16 v[92:95], v[4:7], v[60:63], 0
	v_mfma_f32_16x16x32_f16 v[92:95], v[8:11], v[64:67], v[92:95]
	s_setprio 0
	s_setprio 1
	v_mfma_f32_16x16x32_f16 v[100:103], v[20:23], v[36:39], 0
	v_mfma_f32_16x16x32_f16 v[36:39], v[28:31], v[36:39], 0
	v_mfma_f32_16x16x32_f16 v[104:107], v[20:23], v[44:47], 0
	v_mfma_f32_16x16x32_f16 v[44:47], v[28:31], v[44:47], 0
	v_mfma_f32_16x16x32_f16 v[108:111], v[20:23], v[52:55], 0
	v_mfma_f32_16x16x32_f16 v[52:55], v[28:31], v[52:55], 0
	v_mfma_f32_16x16x32_f16 v[112:115], v[20:23], v[60:63], 0
	v_mfma_f32_16x16x32_f16 v[60:63], v[28:31], v[60:63], 0
	v_mfma_f32_16x16x32_f16 v[100:103], v[24:27], v[40:43], v[100:103]
	v_mfma_f32_16x16x32_f16 v[40:43], v[32:35], v[40:43], v[36:39]
	v_mfma_f32_16x16x32_f16 v[104:107], v[24:27], v[48:51], v[104:107]
	v_mfma_f32_16x16x32_f16 v[48:51], v[32:35], v[48:51], v[44:47]
	v_mfma_f32_16x16x32_f16 v[108:111], v[24:27], v[56:59], v[108:111]
	s_setprio 2
	s_barrier
	v_mfma_f32_16x16x32_f16 v[56:59], v[32:35], v[56:59], v[52:55]
	v_mfma_f32_16x16x32_f16 v[112:115], v[24:27], v[64:67], v[112:115]
	v_mfma_f32_16x16x32_f16 v[64:67], v[32:35], v[64:67], v[60:63]
	s_setprio 0
	v_lshl_add_u64 v[136:137], s[6:7], 0, v[2:3]
	s_add_i32 s47, s47, s62
	v_mov_b32_e32 v135, v3
	v_lshl_add_u64 v[140:141], v[136:137], 0, s[74:75]
	s_mov_b32 m0, s47
	v_lshl_add_u64 v[144:145], s[6:7], 0, v[134:135]
	ds_read_b128 v[36:39], v231 offset:16384
	ds_read_b128 v[44:47], v231 offset:17408
	ds_read_b128 v[52:55], v231 offset:18432
	ds_read_b128 v[60:63], v231 offset:19456
	ds_read_b128 v[116:119], v231 offset:20480
	ds_read_b128 v[120:123], v231 offset:21504
	ds_read_b128 v[124:127], v231 offset:22528
	ds_read_b128 v[128:131], v231 offset:23552
	global_load_lds_dwordx4 v[140:141], off
	v_lshl_add_u64 v[140:141], v[144:145], 0, s[74:75]
	s_add_i32 m0, s47, 0x2000
	s_add_i32 s47, s49, s62
	global_load_lds_dwordx4 v[140:141], off
	s_mov_b32 m0, s47
	v_mov_b32_e32 v139, v3
	global_load_lds_dwordx4 v2, s[16:17]
	s_add_i32 m0, s47, 0x2000
	v_lshl_add_u64 v[248:249], s[8:9], 0, v[138:139]
	v_mov_b32_e32 v133, v3
	global_load_lds_dwordx4 v134, s[16:17]
	v_lshl_add_u64 v[140:141], v[248:249], 0, s[74:75]
	s_mov_b32 m0, s63
	v_lshl_add_u64 v[250:251], s[8:9], 0, v[132:133]
	global_load_lds_dwordx4 v[140:141], off
	v_lshl_add_u64 v[140:141], v[250:251], 0, s[74:75]
	s_mov_b32 m0, s64
	s_nop 0
	global_load_lds_dwordx4 v[140:141], off
	s_waitcnt vmcnt(8)
	s_waitcnt lgkmcnt(0)
	s_barrier
	s_setprio 1
	s_waitcnt lgkmcnt(0)
	v_mfma_f32_16x16x32_f16 v[140:143], v[4:7], v[36:39], 0
	v_mfma_f32_16x16x32_f16 v[148:151], v[12:15], v[36:39], 0
	v_mfma_f32_16x16x32_f16 v[152:155], v[4:7], v[52:55], 0
	v_mfma_f32_16x16x32_f16 v[156:159], v[12:15], v[52:55], 0
	v_mfma_f32_16x16x32_f16 v[160:163], v[4:7], v[116:119], 0
	v_mfma_f32_16x16x32_f16 v[164:167], v[12:15], v[116:119], 0
	v_mfma_f32_16x16x32_f16 v[4:7], v[4:7], v[124:127], 0
	v_mfma_f32_16x16x32_f16 v[12:15], v[12:15], v[124:127], 0
	v_mfma_f32_16x16x32_f16 v[140:143], v[8:11], v[44:47], v[140:143]
	v_mfma_f32_16x16x32_f16 v[148:151], v[16:19], v[44:47], v[148:151]
	v_mfma_f32_16x16x32_f16 v[152:155], v[8:11], v[60:63], v[152:155]
	v_mfma_f32_16x16x32_f16 v[156:159], v[16:19], v[60:63], v[156:159]
	v_mfma_f32_16x16x32_f16 v[160:163], v[8:11], v[120:123], v[160:163]
	v_mfma_f32_16x16x32_f16 v[164:167], v[16:19], v[120:123], v[164:167]
	v_mfma_f32_16x16x32_f16 v[168:171], v[8:11], v[128:131], v[4:7]
	v_mfma_f32_16x16x32_f16 v[172:175], v[16:19], v[128:131], v[12:15]
	s_setprio 0
	s_setprio 1
	v_mfma_f32_16x16x32_f16 v[4:7], v[20:23], v[36:39], 0
	v_mfma_f32_16x16x32_f16 v[8:11], v[28:31], v[36:39], 0
	v_mfma_f32_16x16x32_f16 v[12:15], v[20:23], v[52:55], 0
	v_mfma_f32_16x16x32_f16 v[16:19], v[28:31], v[52:55], 0
	v_mfma_f32_16x16x32_f16 v[36:39], v[20:23], v[116:119], 0
	v_mfma_f32_16x16x32_f16 v[52:55], v[28:31], v[116:119], 0
	v_mfma_f32_16x16x32_f16 v[20:23], v[20:23], v[124:127], 0
	v_mfma_f32_16x16x32_f16 v[28:31], v[28:31], v[124:127], 0
	v_mfma_f32_16x16x32_f16 v[116:119], v[24:27], v[44:47], v[4:7]
	v_mfma_f32_16x16x32_f16 v[124:127], v[32:35], v[44:47], v[8:11]
	v_mfma_f32_16x16x32_f16 v[184:187], v[24:27], v[120:123], v[36:39]
	v_mfma_f32_16x16x32_f16 v[120:123], v[32:35], v[120:123], v[52:55]
	v_mfma_f32_16x16x32_f16 v[188:191], v[24:27], v[128:131], v[20:23]
	s_setprio 2
	s_barrier
	v_mfma_f32_16x16x32_f16 v[128:131], v[32:35], v[128:131], v[28:31]
	v_mfma_f32_16x16x32_f16 v[176:179], v[24:27], v[60:63], v[12:15]
	v_mfma_f32_16x16x32_f16 v[180:183], v[32:35], v[60:63], v[16:19]
	s_setprio 0
	s_add_i32 s47, 0, 0x18000
	v_add_u32_e32 v4, s47, v147
	s_add_i32 s49, 0, 0x1c000
	ds_read_b128 v[192:195], v4
	ds_read_b128 v[196:199], v4 offset:1024
	ds_read_b128 v[200:203], v4 offset:2048
	ds_read_b128 v[204:207], v4 offset:3072
	v_add_u32_e32 v4, s49, v147
	ds_read_b128 v[208:211], v4
	ds_read_b128 v[212:215], v4 offset:1024
	ds_read_b128 v[216:219], v4 offset:2048
	ds_read_b128 v[220:223], v4 offset:3072
	s_mov_b32 m0, s65
	ds_read_b128 v[44:47], v231 offset:32768
	ds_read_b128 v[52:55], v231 offset:33792
	ds_read_b128 v[60:63], v231 offset:34816
	ds_read_b128 v[224:227], v231 offset:35840
	ds_read_b128 v[232:235], v231 offset:36864
	ds_read_b128 v[236:239], v231 offset:37888
	ds_read_b128 v[240:243], v231 offset:38912
	ds_read_b128 v[244:247], v231 offset:39936
	global_load_lds_dwordx4 v138, s[26:27]
	s_mov_b32 m0, s66
	s_nop 0
	global_load_lds_dwordx4 v132, s[26:27]
	s_waitcnt vmcnt(8)
	s_waitcnt lgkmcnt(0)
	s_barrier
	s_setprio 1
	s_waitcnt lgkmcnt(0)
	v_mfma_f32_16x16x32_f16 v[4:7], v[192:195], v[44:47], v[68:71]
	v_mfma_f32_16x16x32_f16 v[8:11], v[200:203], v[44:47], v[72:75]
	v_mfma_f32_16x16x32_f16 v[12:15], v[192:195], v[60:63], v[76:79]
	v_mfma_f32_16x16x32_f16 v[16:19], v[200:203], v[60:63], v[80:83]
	v_mfma_f32_16x16x32_f16 v[20:23], v[192:195], v[232:235], v[84:87]
	v_mfma_f32_16x16x32_f16 v[24:27], v[200:203], v[232:235], v[88:91]
	v_mfma_f32_16x16x32_f16 v[28:31], v[192:195], v[240:243], v[92:95]
	v_mfma_f32_16x16x32_f16 v[32:35], v[200:203], v[240:243], v[96:99]
	v_mfma_f32_16x16x32_f16 v[4:7], v[196:199], v[52:55], v[4:7]
	v_mfma_f32_16x16x32_f16 v[8:11], v[204:207], v[52:55], v[8:11]
	v_mfma_f32_16x16x32_f16 v[12:15], v[196:199], v[224:227], v[12:15]
	v_mfma_f32_16x16x32_f16 v[16:19], v[204:207], v[224:227], v[16:19]
	v_mfma_f32_16x16x32_f16 v[20:23], v[196:199], v[236:239], v[20:23]
	v_mfma_f32_16x16x32_f16 v[24:27], v[204:207], v[236:239], v[24:27]
	v_mfma_f32_16x16x32_f16 v[28:31], v[196:199], v[244:247], v[28:31]
	v_mfma_f32_16x16x32_f16 v[32:35], v[204:207], v[244:247], v[32:35]
	s_setprio 0
	s_setprio 1
	v_mfma_f32_16x16x32_f16 v[36:39], v[208:211], v[44:47], v[100:103]
	v_mfma_f32_16x16x32_f16 v[40:43], v[216:219], v[44:47], v[40:43]
	v_mfma_f32_16x16x32_f16 v[36:39], v[212:215], v[52:55], v[36:39]
	v_mfma_f32_16x16x32_f16 v[40:43], v[220:223], v[52:55], v[40:43]
	v_mfma_f32_16x16x32_f16 v[44:47], v[208:211], v[60:63], v[104:107]
	v_mfma_f32_16x16x32_f16 v[48:51], v[216:219], v[60:63], v[48:51]
	v_mfma_f32_16x16x32_f16 v[52:55], v[208:211], v[232:235], v[108:111]
	v_mfma_f32_16x16x32_f16 v[56:59], v[216:219], v[232:235], v[56:59]
	v_mfma_f32_16x16x32_f16 v[60:63], v[208:211], v[240:243], v[112:115]
	v_mfma_f32_16x16x32_f16 v[64:67], v[216:219], v[240:243], v[64:67]
	v_mfma_f32_16x16x32_f16 v[44:47], v[212:215], v[224:227], v[44:47]
	v_mfma_f32_16x16x32_f16 v[48:51], v[220:223], v[224:227], v[48:51]
	v_mfma_f32_16x16x32_f16 v[52:55], v[212:215], v[236:239], v[52:55]
	s_setprio 2
	s_barrier
	v_mfma_f32_16x16x32_f16 v[56:59], v[220:223], v[236:239], v[56:59]
	v_mfma_f32_16x16x32_f16 v[60:63], v[212:215], v[244:247], v[60:63]
	v_mfma_f32_16x16x32_f16 v[64:67], v[220:223], v[244:247], v[64:67]
	s_setprio 0
	s_add_i32 s47, s47, s62
	v_lshl_add_u64 v[68:69], v[136:137], 0, s[24:25]
	s_mov_b32 m0, s47
	ds_read_b128 v[104:107], v231 offset:49152
	ds_read_b128 v[108:111], v231 offset:50176
	ds_read_b128 v[112:115], v231 offset:51200
	ds_read_b128 v[224:227], v231 offset:52224
	ds_read_b128 v[232:235], v231 offset:53248
	ds_read_b128 v[236:239], v231 offset:54272
	ds_read_b128 v[240:243], v231 offset:55296
	ds_read_b128 v[244:247], v231 offset:56320
	global_load_lds_dwordx4 v[68:69], off
	v_lshl_add_u64 v[68:69], v[144:145], 0, s[24:25]
	s_add_i32 m0, s47, 0x2000
	s_add_i32 s47, s49, s62
	global_load_lds_dwordx4 v[68:69], off
	s_mov_b32 m0, s47
	v_lshl_add_u64 v[68:69], v[248:249], 0, s[24:25]
	global_load_lds_dwordx4 v2, s[28:29]
	s_add_i32 m0, s47, 0x2000
	s_nop 0
	global_load_lds_dwordx4 v134, s[28:29]
	s_mov_b32 m0, s69
	s_nop 0
	global_load_lds_dwordx4 v[68:69], off
	v_lshl_add_u64 v[68:69], v[250:251], 0, s[24:25]
	s_mov_b32 m0, s70
	s_nop 0
	global_load_lds_dwordx4 v[68:69], off
	s_waitcnt vmcnt(8)
	s_waitcnt lgkmcnt(0)
	s_barrier
	s_setprio 1
	s_waitcnt lgkmcnt(0)
	v_mfma_f32_16x16x32_f16 v[68:71], v[192:195], v[104:107], v[140:143]
	v_mfma_f32_16x16x32_f16 v[72:75], v[200:203], v[104:107], v[148:151]
	v_mfma_f32_16x16x32_f16 v[76:79], v[192:195], v[112:115], v[152:155]
	v_mfma_f32_16x16x32_f16 v[80:83], v[200:203], v[112:115], v[156:159]
	v_mfma_f32_16x16x32_f16 v[84:87], v[192:195], v[232:235], v[160:163]
	v_mfma_f32_16x16x32_f16 v[88:91], v[200:203], v[232:235], v[164:167]
	v_mfma_f32_16x16x32_f16 v[92:95], v[192:195], v[240:243], v[168:171]
	v_mfma_f32_16x16x32_f16 v[96:99], v[200:203], v[240:243], v[172:175]
	v_mfma_f32_16x16x32_f16 v[68:71], v[196:199], v[108:111], v[68:71]
	v_mfma_f32_16x16x32_f16 v[72:75], v[204:207], v[108:111], v[72:75]
	v_mfma_f32_16x16x32_f16 v[76:79], v[196:199], v[224:227], v[76:79]
	v_mfma_f32_16x16x32_f16 v[80:83], v[204:207], v[224:227], v[80:83]
	v_mfma_f32_16x16x32_f16 v[84:87], v[196:199], v[236:239], v[84:87]
	v_mfma_f32_16x16x32_f16 v[88:91], v[204:207], v[236:239], v[88:91]
	v_mfma_f32_16x16x32_f16 v[92:95], v[196:199], v[244:247], v[92:95]
	v_mfma_f32_16x16x32_f16 v[96:99], v[204:207], v[244:247], v[96:99]
	s_setprio 0
	s_setprio 1
	v_mfma_f32_16x16x32_f16 v[100:103], v[208:211], v[104:107], v[116:119]
	v_mfma_f32_16x16x32_f16 v[104:107], v[216:219], v[104:107], v[124:127]
	v_mfma_f32_16x16x32_f16 v[100:103], v[212:215], v[108:111], v[100:103]
	v_mfma_f32_16x16x32_f16 v[104:107], v[220:223], v[108:111], v[104:107]
	v_mfma_f32_16x16x32_f16 v[108:111], v[208:211], v[112:115], v[176:179]
	v_mfma_f32_16x16x32_f16 v[112:115], v[216:219], v[112:115], v[180:183]
	v_mfma_f32_16x16x32_f16 v[116:119], v[208:211], v[232:235], v[184:187]
	v_mfma_f32_16x16x32_f16 v[120:123], v[216:219], v[232:235], v[120:123]
	v_mfma_f32_16x16x32_f16 v[124:127], v[208:211], v[240:243], v[188:191]
	v_mfma_f32_16x16x32_f16 v[128:131], v[216:219], v[240:243], v[128:131]
	v_mfma_f32_16x16x32_f16 v[108:111], v[212:215], v[224:227], v[108:111]
	v_mfma_f32_16x16x32_f16 v[112:115], v[220:223], v[224:227], v[112:115]
	v_mfma_f32_16x16x32_f16 v[116:119], v[212:215], v[236:239], v[116:119]
	s_setprio 2
	s_barrier
	v_mfma_f32_16x16x32_f16 v[120:123], v[220:223], v[236:239], v[120:123]
	v_mfma_f32_16x16x32_f16 v[124:127], v[212:215], v[244:247], v[124:127]
	v_mfma_f32_16x16x32_f16 v[128:131], v[220:223], v[244:247], v[128:131]
	s_setprio 0
	s_add_i32 s45, s45, 2
	s_cmp_ge_i32 s45, s44
	s_cbranch_scc0 .LBB0_749
	v_mov_b32_e32 v136, v2
	s_branch .LBB0_752

.LBB0_753:
	s_add_u32 s6, s8, 0xfff80080
	s_addc_u32 s7, s9, -1
	s_add_i32 s29, 0, 0x10000
	s_cmp_eq_u32 s28, 28
	s_cselect_b32 s17, s13, s7
	s_cselect_b32 s16, s12, s6
	v_add_u32_e32 v133, s29, v147
	s_cselect_b32 s7, s15, s27
	s_cselect_b32 s6, s14, s26
	s_add_i32 s47, 0, 0x14000
	ds_read_b128 v[138:141], v133
	ds_read_b128 v[142:145], v133 offset:1024
	ds_read_b128 v[148:151], v133 offset:2048
	ds_read_b128 v[152:155], v133 offset:3072
	v_add_u32_e32 v133, s47, v147
	ds_read_b128 v[156:159], v133
	ds_read_b128 v[160:163], v133 offset:1024
	ds_read_b128 v[164:167], v133 offset:2048
	ds_read_b128 v[168:171], v133 offset:3072
	s_mov_b32 m0, s71
	v_add_u32_e32 v212, 0, v146
	ds_read_b128 v[172:175], v212
	ds_read_b128 v[176:179], v212 offset:1024
	ds_read_b128 v[180:183], v212 offset:2048
	ds_read_b128 v[184:187], v212 offset:3072
	ds_read_b128 v[188:191], v212 offset:4096
	ds_read_b128 v[192:195], v212 offset:5120
	ds_read_b128 v[196:199], v212 offset:6144
	ds_read_b128 v[200:203], v212 offset:7168
	global_load_lds_dwordx4 v2, s[8:9]
	s_mov_b32 m0, s72
	v_mov_b32_e32 v133, v3
	global_load_lds_dwordx4 v132, s[8:9]
	s_waitcnt vmcnt(8)
	s_waitcnt lgkmcnt(0)
	s_barrier
	s_setprio 1
	s_waitcnt lgkmcnt(0)
	v_mfma_f32_16x16x32_f16 v[4:7], v[138:141], v[172:175], v[4:7]
	v_mfma_f32_16x16x32_f16 v[4:7], v[142:145], v[176:179], v[4:7]
	v_mfma_f32_16x16x32_f16 v[8:11], v[152:155], v[176:179], v[8:11]
	v_mfma_f32_16x16x32_f16 v[8:11], v[148:151], v[172:175], v[8:11]
	v_mfma_f32_16x16x32_f16 v[16:19], v[148:151], v[180:183], v[16:19]
	v_mfma_f32_16x16x32_f16 v[16:19], v[152:155], v[184:187], v[16:19]
	v_mfma_f32_16x16x32_f16 v[12:15], v[142:145], v[184:187], v[12:15]
	v_mfma_f32_16x16x32_f16 v[12:15], v[138:141], v[180:183], v[12:15]
	v_mfma_f32_16x16x32_f16 v[20:23], v[138:141], v[188:191], v[20:23]
	v_mfma_f32_16x16x32_f16 v[20:23], v[142:145], v[192:195], v[20:23]
	v_mfma_f32_16x16x32_f16 v[24:27], v[152:155], v[192:195], v[24:27]
	v_mfma_f32_16x16x32_f16 v[24:27], v[148:151], v[188:191], v[24:27]
	v_mfma_f32_16x16x32_f16 v[32:35], v[148:151], v[196:199], v[32:35]
	v_mfma_f32_16x16x32_f16 v[32:35], v[152:155], v[200:203], v[32:35]
	v_mfma_f32_16x16x32_f16 v[28:31], v[142:145], v[200:203], v[28:31]
	v_mfma_f32_16x16x32_f16 v[28:31], v[138:141], v[196:199], v[28:31]
	s_setprio 0
	s_setprio 1
	v_mfma_f32_16x16x32_f16 v[36:39], v[156:159], v[172:175], v[36:39]
	v_mfma_f32_16x16x32_f16 v[36:39], v[160:163], v[176:179], v[36:39]
	v_mfma_f32_16x16x32_f16 v[40:43], v[168:171], v[176:179], v[40:43]
	v_mfma_f32_16x16x32_f16 v[40:43], v[164:167], v[172:175], v[40:43]
	v_mfma_f32_16x16x32_f16 v[48:51], v[164:167], v[180:183], v[48:51]
	v_mfma_f32_16x16x32_f16 v[48:51], v[168:171], v[184:187], v[48:51]
	v_mfma_f32_16x16x32_f16 v[44:47], v[160:163], v[184:187], v[44:47]
	v_mfma_f32_16x16x32_f16 v[44:47], v[156:159], v[180:183], v[44:47]
	v_mfma_f32_16x16x32_f16 v[52:55], v[156:159], v[188:191], v[52:55]
	v_mfma_f32_16x16x32_f16 v[52:55], v[160:163], v[192:195], v[52:55]
	v_mfma_f32_16x16x32_f16 v[56:59], v[168:171], v[192:195], v[56:59]
	v_mfma_f32_16x16x32_f16 v[56:59], v[164:167], v[188:191], v[56:59]
	v_mfma_f32_16x16x32_f16 v[64:67], v[164:167], v[196:199], v[64:67]
	s_setprio 2
	s_barrier
	v_mfma_f32_16x16x32_f16 v[64:67], v[168:171], v[200:203], v[64:67]
	v_mfma_f32_16x16x32_f16 v[60:63], v[160:163], v[200:203], v[60:63]
	v_mfma_f32_16x16x32_f16 v[60:63], v[156:159], v[196:199], v[60:63]
	s_setprio 0
	s_add_i32 s29, s29, s62
	s_mov_b32 m0, s29
	ds_read_b128 v[172:175], v212 offset:16384
	ds_read_b128 v[176:179], v212 offset:17408
	ds_read_b128 v[180:183], v212 offset:18432
	ds_read_b128 v[184:187], v212 offset:19456
	ds_read_b128 v[188:191], v212 offset:20480
	ds_read_b128 v[192:195], v212 offset:21504
	ds_read_b128 v[196:199], v212 offset:22528
	ds_read_b128 v[200:203], v212 offset:23552
	global_load_lds_dwordx4 v136, s[6:7]
	s_add_i32 m0, s29, 0x2000
	s_add_u32 s44, s6, 0x80000
	s_addc_u32 s45, s7, 0
	s_add_i32 s29, s47, s62
	global_load_lds_dwordx4 v134, s[6:7]
	s_mov_b32 m0, s29
	v_mov_b32_e32 v137, v3
	global_load_lds_dwordx4 v136, s[44:45]
	s_add_i32 m0, s29, 0x2000
	v_mov_b32_e32 v135, v3
	global_load_lds_dwordx4 v134, s[44:45]
	s_mov_b32 m0, s63
	v_lshl_add_u64 v[204:205], s[6:7], 0, v[136:137]
	global_load_lds_dwordx4 v2, s[16:17]
	s_mov_b32 m0, s64
	v_lshl_add_u64 v[206:207], s[6:7], 0, v[134:135]
	global_load_lds_dwordx4 v132, s[16:17]
	s_waitcnt vmcnt(8)
	s_waitcnt lgkmcnt(0)
	v_lshl_add_u64 v[208:209], s[16:17], 0, v[2:3]
	v_lshl_add_u64 v[210:211], s[16:17], 0, v[132:133]
	s_barrier
	s_setprio 1
	s_waitcnt lgkmcnt(0)
	v_mfma_f32_16x16x32_f16 v[68:71], v[138:141], v[172:175], v[68:71]
	v_mfma_f32_16x16x32_f16 v[68:71], v[142:145], v[176:179], v[68:71]
	v_mfma_f32_16x16x32_f16 v[72:75], v[152:155], v[176:179], v[72:75]
	v_mfma_f32_16x16x32_f16 v[72:75], v[148:151], v[172:175], v[72:75]
	v_mfma_f32_16x16x32_f16 v[80:83], v[148:151], v[180:183], v[80:83]
	v_mfma_f32_16x16x32_f16 v[80:83], v[152:155], v[184:187], v[80:83]
	v_mfma_f32_16x16x32_f16 v[76:79], v[142:145], v[184:187], v[76:79]
	v_mfma_f32_16x16x32_f16 v[76:79], v[138:141], v[180:183], v[76:79]
	v_mfma_f32_16x16x32_f16 v[84:87], v[138:141], v[188:191], v[84:87]
	v_mfma_f32_16x16x32_f16 v[84:87], v[142:145], v[192:195], v[84:87]
	v_mfma_f32_16x16x32_f16 v[88:91], v[152:155], v[192:195], v[88:91]
	v_mfma_f32_16x16x32_f16 v[88:91], v[148:151], v[188:191], v[88:91]
	v_mfma_f32_16x16x32_f16 v[96:99], v[148:151], v[196:199], v[96:99]
	v_mfma_f32_16x16x32_f16 v[96:99], v[152:155], v[200:203], v[96:99]
	v_mfma_f32_16x16x32_f16 v[92:95], v[142:145], v[200:203], v[92:95]
	v_mfma_f32_16x16x32_f16 v[92:95], v[138:141], v[196:199], v[92:95]
	s_setprio 0
	s_setprio 1
	v_mfma_f32_16x16x32_f16 v[100:103], v[156:159], v[172:175], v[100:103]
	v_mfma_f32_16x16x32_f16 v[100:103], v[160:163], v[176:179], v[100:103]
	v_mfma_f32_16x16x32_f16 v[104:107], v[168:171], v[176:179], v[104:107]
	v_mfma_f32_16x16x32_f16 v[104:107], v[164:167], v[172:175], v[104:107]
	v_mfma_f32_16x16x32_f16 v[112:115], v[164:167], v[180:183], v[112:115]
	v_mfma_f32_16x16x32_f16 v[112:115], v[168:171], v[184:187], v[112:115]
	v_mfma_f32_16x16x32_f16 v[108:111], v[160:163], v[184:187], v[108:111]
	v_mfma_f32_16x16x32_f16 v[108:111], v[156:159], v[180:183], v[108:111]
	v_mfma_f32_16x16x32_f16 v[116:119], v[156:159], v[188:191], v[116:119]
	v_mfma_f32_16x16x32_f16 v[116:119], v[160:163], v[192:195], v[116:119]
	v_mfma_f32_16x16x32_f16 v[120:123], v[168:171], v[192:195], v[120:123]
	v_mfma_f32_16x16x32_f16 v[120:123], v[164:167], v[188:191], v[120:123]
	v_mfma_f32_16x16x32_f16 v[128:131], v[164:167], v[196:199], v[128:131]
	s_setprio 2
	s_barrier
	v_mfma_f32_16x16x32_f16 v[128:131], v[168:171], v[200:203], v[128:131]
	v_mfma_f32_16x16x32_f16 v[124:127], v[160:163], v[200:203], v[124:127]
	v_mfma_f32_16x16x32_f16 v[124:127], v[156:159], v[196:199], v[124:127]
	s_setprio 0
	s_add_i32 s29, 0, 0x18000
	v_add_u32_e32 v135, s29, v147
	s_add_i32 s44, 0, 0x1c000
	ds_read_b128 v[138:141], v135
	ds_read_b128 v[142:145], v135 offset:1024
	ds_read_b128 v[148:151], v135 offset:2048
	ds_read_b128 v[152:155], v135 offset:3072
	v_add_u32_e32 v135, s44, v147
	ds_read_b128 v[156:159], v135
	ds_read_b128 v[160:163], v135 offset:1024
	ds_read_b128 v[164:167], v135 offset:2048
	ds_read_b128 v[168:171], v135 offset:3072
	s_add_u32 s16, s16, 0x80000
	s_addc_u32 s17, s17, 0
	s_mov_b32 m0, s65
	ds_read_b128 v[172:175], v212 offset:32768
	ds_read_b128 v[176:179], v212 offset:33792
	ds_read_b128 v[180:183], v212 offset:34816
	ds_read_b128 v[184:187], v212 offset:35840
	ds_read_b128 v[188:191], v212 offset:36864
	ds_read_b128 v[192:195], v212 offset:37888
	ds_read_b128 v[196:199], v212 offset:38912
	ds_read_b128 v[200:203], v212 offset:39936
	global_load_lds_dwordx4 v2, s[16:17]
	s_mov_b32 m0, s66
	s_nop 0
	global_load_lds_dwordx4 v132, s[16:17]
	s_waitcnt vmcnt(8)
	s_waitcnt lgkmcnt(0)
	s_barrier
	s_setprio 1
	s_waitcnt lgkmcnt(0)
	v_mfma_f32_16x16x32_f16 v[4:7], v[138:141], v[172:175], v[4:7]
	v_mfma_f32_16x16x32_f16 v[4:7], v[142:145], v[176:179], v[4:7]
	v_mfma_f32_16x16x32_f16 v[8:11], v[152:155], v[176:179], v[8:11]
	v_mfma_f32_16x16x32_f16 v[8:11], v[148:151], v[172:175], v[8:11]
	v_mfma_f32_16x16x32_f16 v[16:19], v[148:151], v[180:183], v[16:19]
	v_mfma_f32_16x16x32_f16 v[16:19], v[152:155], v[184:187], v[16:19]
	v_mfma_f32_16x16x32_f16 v[12:15], v[142:145], v[184:187], v[12:15]
	v_mfma_f32_16x16x32_f16 v[12:15], v[138:141], v[180:183], v[12:15]
	v_mfma_f32_16x16x32_f16 v[20:23], v[138:141], v[188:191], v[20:23]
	v_mfma_f32_16x16x32_f16 v[20:23], v[142:145], v[192:195], v[20:23]
	v_mfma_f32_16x16x32_f16 v[24:27], v[152:155], v[192:195], v[24:27]
	v_mfma_f32_16x16x32_f16 v[24:27], v[148:151], v[188:191], v[24:27]
	v_mfma_f32_16x16x32_f16 v[32:35], v[148:151], v[196:199], v[32:35]
	v_mfma_f32_16x16x32_f16 v[32:35], v[152:155], v[200:203], v[32:35]
	v_mfma_f32_16x16x32_f16 v[28:31], v[142:145], v[200:203], v[28:31]
	v_mfma_f32_16x16x32_f16 v[28:31], v[138:141], v[196:199], v[28:31]
	s_setprio 0
	s_setprio 1
	v_mfma_f32_16x16x32_f16 v[36:39], v[156:159], v[172:175], v[36:39]
	v_mfma_f32_16x16x32_f16 v[36:39], v[160:163], v[176:179], v[36:39]
	v_mfma_f32_16x16x32_f16 v[40:43], v[168:171], v[176:179], v[40:43]
	v_mfma_f32_16x16x32_f16 v[40:43], v[164:167], v[172:175], v[40:43]
	v_mfma_f32_16x16x32_f16 v[48:51], v[164:167], v[180:183], v[48:51]
	v_mfma_f32_16x16x32_f16 v[48:51], v[168:171], v[184:187], v[48:51]
	v_mfma_f32_16x16x32_f16 v[44:47], v[160:163], v[184:187], v[44:47]
	v_mfma_f32_16x16x32_f16 v[44:47], v[156:159], v[180:183], v[44:47]
	v_mfma_f32_16x16x32_f16 v[52:55], v[156:159], v[188:191], v[52:55]
	v_mfma_f32_16x16x32_f16 v[52:55], v[160:163], v[192:195], v[52:55]
	v_mfma_f32_16x16x32_f16 v[56:59], v[168:171], v[192:195], v[56:59]
	v_mfma_f32_16x16x32_f16 v[56:59], v[164:167], v[188:191], v[56:59]
	v_mfma_f32_16x16x32_f16 v[64:67], v[164:167], v[196:199], v[64:67]
	s_setprio 2
	s_barrier
	v_mfma_f32_16x16x32_f16 v[64:67], v[168:171], v[200:203], v[64:67]
	v_mfma_f32_16x16x32_f16 v[60:63], v[160:163], v[200:203], v[60:63]
	v_mfma_f32_16x16x32_f16 v[60:63], v[156:159], v[196:199], v[60:63]
	s_setprio 0
	s_add_i32 s16, s29, s62
	v_lshl_add_u64 v[204:205], v[204:205], 0, s[86:87]
	s_mov_b32 m0, s16
	ds_read_b128 v[172:175], v212 offset:49152
	ds_read_b128 v[176:179], v212 offset:50176
	ds_read_b128 v[180:183], v212 offset:51200
	ds_read_b128 v[184:187], v212 offset:52224
	ds_read_b128 v[188:191], v212 offset:53248
	ds_read_b128 v[192:195], v212 offset:54272
	ds_read_b128 v[196:199], v212 offset:55296
	ds_read_b128 v[200:203], v212 offset:56320
	global_load_lds_dwordx4 v[204:205], off
	s_add_i32 m0, s16, 0x2000
	s_add_u32 s6, s6, 0x80080
	v_lshl_add_u64 v[204:205], v[206:207], 0, s[86:87]
	s_addc_u32 s7, s7, 0
	s_add_i32 s16, s44, s62
	global_load_lds_dwordx4 v[204:205], off
	s_mov_b32 m0, s16
	v_lshl_add_u64 v[204:205], v[208:209], 0, s[86:87]
	global_load_lds_dwordx4 v136, s[6:7]
	s_add_i32 m0, s16, 0x2000
	s_nop 0
	global_load_lds_dwordx4 v134, s[6:7]
	s_mov_b32 m0, s69
	s_nop 0
	global_load_lds_dwordx4 v[204:205], off
	v_lshl_add_u64 v[204:205], v[210:211], 0, s[86:87]
	s_mov_b32 m0, s70
	s_nop 0
	global_load_lds_dwordx4 v[204:205], off
	s_waitcnt vmcnt(8)
	s_waitcnt lgkmcnt(0)
	s_barrier
	s_setprio 1
	s_waitcnt lgkmcnt(0)
	v_mfma_f32_16x16x32_f16 v[68:71], v[138:141], v[172:175], v[68:71]
	v_mfma_f32_16x16x32_f16 v[68:71], v[142:145], v[176:179], v[68:71]
	v_mfma_f32_16x16x32_f16 v[72:75], v[152:155], v[176:179], v[72:75]
	v_mfma_f32_16x16x32_f16 v[72:75], v[148:151], v[172:175], v[72:75]
	v_mfma_f32_16x16x32_f16 v[80:83], v[148:151], v[180:183], v[80:83]
	v_mfma_f32_16x16x32_f16 v[80:83], v[152:155], v[184:187], v[80:83]
	v_mfma_f32_16x16x32_f16 v[76:79], v[142:145], v[184:187], v[76:79]
	v_mfma_f32_16x16x32_f16 v[76:79], v[138:141], v[180:183], v[76:79]
	v_mfma_f32_16x16x32_f16 v[84:87], v[138:141], v[188:191], v[84:87]
	v_mfma_f32_16x16x32_f16 v[84:87], v[142:145], v[192:195], v[84:87]
	v_mfma_f32_16x16x32_f16 v[88:91], v[152:155], v[192:195], v[88:91]
	v_mfma_f32_16x16x32_f16 v[88:91], v[148:151], v[188:191], v[88:91]
	v_mfma_f32_16x16x32_f16 v[96:99], v[148:151], v[196:199], v[96:99]
	v_mfma_f32_16x16x32_f16 v[96:99], v[152:155], v[200:203], v[96:99]
	v_mfma_f32_16x16x32_f16 v[92:95], v[142:145], v[200:203], v[92:95]
	v_mfma_f32_16x16x32_f16 v[92:95], v[138:141], v[196:199], v[92:95]
	s_setprio 0
	s_setprio 1
	v_mfma_f32_16x16x32_f16 v[100:103], v[156:159], v[172:175], v[100:103]
	v_mfma_f32_16x16x32_f16 v[100:103], v[160:163], v[176:179], v[100:103]
	v_mfma_f32_16x16x32_f16 v[104:107], v[168:171], v[176:179], v[104:107]
	v_mfma_f32_16x16x32_f16 v[104:107], v[164:167], v[172:175], v[104:107]
	v_mfma_f32_16x16x32_f16 v[112:115], v[164:167], v[180:183], v[112:115]
	v_mfma_f32_16x16x32_f16 v[112:115], v[168:171], v[184:187], v[112:115]
	v_mfma_f32_16x16x32_f16 v[108:111], v[160:163], v[184:187], v[108:111]
	v_mfma_f32_16x16x32_f16 v[108:111], v[156:159], v[180:183], v[108:111]
	v_mfma_f32_16x16x32_f16 v[116:119], v[156:159], v[188:191], v[116:119]
	v_mfma_f32_16x16x32_f16 v[116:119], v[160:163], v[192:195], v[116:119]
	v_mfma_f32_16x16x32_f16 v[120:123], v[168:171], v[192:195], v[120:123]
	v_mfma_f32_16x16x32_f16 v[120:123], v[164:167], v[188:191], v[120:123]
	v_mfma_f32_16x16x32_f16 v[128:131], v[164:167], v[196:199], v[128:131]
	s_setprio 2
	s_barrier
	v_mfma_f32_16x16x32_f16 v[128:131], v[168:171], v[200:203], v[128:131]
	v_mfma_f32_16x16x32_f16 v[124:127], v[160:163], v[200:203], v[124:127]
	v_mfma_f32_16x16x32_f16 v[124:127], v[156:159], v[196:199], v[124:127]
	s_setprio 0
	s_add_i32 s28, s28, 2
	s_add_u32 s8, s8, 0x100
	s_addc_u32 s9, s9, 0
	s_add_u32 s26, s26, 0x100
	s_addc_u32 s27, s27, 0
	s_cmp_gt_u32 s28, 29
	s_cbranch_scc0 .LBB0_753
	s_and_b64 vcc, exec, s[52:53]
	s_cbranch_vccz .LBB0_756
	s_barrier

.LBB0_1175:
	s_add_i32 s61, 0, 0x10000
	s_add_i32 s79, 0, 0x14000
	v_add_u32_e32 v16, s61, v209
	v_add_u32_e32 v32, s79, v209
	ds_read_b128 v[4:7], v16
	ds_read_b128 v[8:11], v16 offset:1024
	ds_read_b128 v[12:15], v16 offset:2048
	ds_read_b128 v[16:19], v16 offset:3072
	ds_read_b128 v[20:23], v32
	ds_read_b128 v[24:27], v32 offset:1024
	ds_read_b128 v[28:31], v32 offset:2048
	ds_read_b128 v[32:35], v32 offset:3072
	v_add_u32_e32 v231, 0, v208
	ds_read_b128 v[36:39], v231
	ds_read_b128 v[40:43], v231 offset:1024
	ds_read_b128 v[44:47], v231 offset:2048
	ds_read_b128 v[48:51], v231 offset:3072
	ds_read_b128 v[52:55], v231 offset:4096
	ds_read_b128 v[56:59], v231 offset:5120
	ds_read_b128 v[60:63], v231 offset:6144
	ds_read_b128 v[64:67], v231 offset:7168
	s_waitcnt vmcnt(8)
	s_waitcnt lgkmcnt(0)
	s_barrier
	s_setprio 1
	s_waitcnt lgkmcnt(0)
	v_mfma_f32_16x16x32_bf16 v[68:71], v[4:7], v[36:39], 0
	v_mfma_f32_16x16x32_bf16 v[68:71], v[8:11], v[40:43], v[68:71]
	v_mfma_f32_16x16x32_bf16 v[72:75], v[12:15], v[36:39], 0
	v_mfma_f32_16x16x32_bf16 v[72:75], v[16:19], v[40:43], v[72:75]
	v_mfma_f32_16x16x32_bf16 v[80:83], v[12:15], v[44:47], 0
	v_mfma_f32_16x16x32_bf16 v[80:83], v[16:19], v[48:51], v[80:83]
	v_mfma_f32_16x16x32_bf16 v[76:79], v[4:7], v[44:47], 0
	v_mfma_f32_16x16x32_bf16 v[76:79], v[8:11], v[48:51], v[76:79]
	v_mfma_f32_16x16x32_bf16 v[84:87], v[4:7], v[52:55], 0
	v_mfma_f32_16x16x32_bf16 v[84:87], v[8:11], v[56:59], v[84:87]
	v_mfma_f32_16x16x32_bf16 v[88:91], v[12:15], v[52:55], 0
	v_mfma_f32_16x16x32_bf16 v[88:91], v[16:19], v[56:59], v[88:91]
	v_mfma_f32_16x16x32_bf16 v[96:99], v[12:15], v[60:63], 0
	v_mfma_f32_16x16x32_bf16 v[96:99], v[16:19], v[64:67], v[96:99]
	v_mfma_f32_16x16x32_bf16 v[92:95], v[4:7], v[60:63], 0
	v_mfma_f32_16x16x32_bf16 v[92:95], v[8:11], v[64:67], v[92:95]
	s_setprio 0
	s_setprio 1
	v_mfma_f32_16x16x32_bf16 v[100:103], v[20:23], v[36:39], 0
	v_mfma_f32_16x16x32_bf16 v[36:39], v[28:31], v[36:39], 0
	v_mfma_f32_16x16x32_bf16 v[104:107], v[20:23], v[44:47], 0
	v_mfma_f32_16x16x32_bf16 v[44:47], v[28:31], v[44:47], 0
	v_mfma_f32_16x16x32_bf16 v[108:111], v[20:23], v[52:55], 0
	v_mfma_f32_16x16x32_bf16 v[52:55], v[28:31], v[52:55], 0
	v_mfma_f32_16x16x32_bf16 v[112:115], v[20:23], v[60:63], 0
	v_mfma_f32_16x16x32_bf16 v[60:63], v[28:31], v[60:63], 0
	v_mfma_f32_16x16x32_bf16 v[100:103], v[24:27], v[40:43], v[100:103]
	v_mfma_f32_16x16x32_bf16 v[40:43], v[32:35], v[40:43], v[36:39]
	v_mfma_f32_16x16x32_bf16 v[104:107], v[24:27], v[48:51], v[104:107]
	v_mfma_f32_16x16x32_bf16 v[48:51], v[32:35], v[48:51], v[44:47]
	v_mfma_f32_16x16x32_bf16 v[108:111], v[24:27], v[56:59], v[108:111]
	s_setprio 2
	s_barrier
	v_mfma_f32_16x16x32_bf16 v[56:59], v[32:35], v[56:59], v[52:55]
	v_mfma_f32_16x16x32_bf16 v[112:115], v[24:27], v[64:67], v[112:115]
	v_mfma_f32_16x16x32_bf16 v[64:67], v[32:35], v[64:67], v[60:63]
	s_setprio 0
	v_lshl_add_u64 v[186:187], s[12:13], 0, v[2:3]
	s_add_i32 s61, s61, s36
	v_mov_b32_e32 v191, v3
	v_lshl_add_u64 v[134:135], v[186:187], 0, s[74:75]
	s_mov_b32 m0, s61
	v_lshl_add_u64 v[226:227], s[12:13], 0, v[190:191]
	ds_read_b128 v[36:39], v231 offset:16384
	ds_read_b128 v[44:47], v231 offset:17408
	ds_read_b128 v[52:55], v231 offset:18432
	ds_read_b128 v[60:63], v231 offset:19456
	ds_read_b128 v[116:119], v231 offset:20480
	ds_read_b128 v[120:123], v231 offset:21504
	ds_read_b128 v[124:127], v231 offset:22528
	ds_read_b128 v[128:131], v231 offset:23552
	global_load_lds_dwordx4 v[134:135], off
	v_lshl_add_u64 v[134:135], v[226:227], 0, s[74:75]
	s_add_i32 m0, s61, 0x2000
	s_add_i32 s61, s79, s36
	global_load_lds_dwordx4 v[134:135], off
	s_mov_b32 m0, s61
	v_mov_b32_e32 v133, v3
	global_load_lds_dwordx4 v2, s[16:17]
	s_add_i32 m0, s61, 0x2000
	v_lshl_add_u64 v[248:249], s[6:7], 0, v[132:133]
	v_mov_b32_e32 v189, v3
	global_load_lds_dwordx4 v190, s[16:17]
	v_lshl_add_u64 v[134:135], v[248:249], 0, s[74:75]
	s_mov_b32 m0, s37
	v_lshl_add_u64 v[250:251], s[6:7], 0, v[188:189]
	global_load_lds_dwordx4 v[134:135], off
	v_lshl_add_u64 v[134:135], v[250:251], 0, s[74:75]
	s_mov_b32 m0, s66
	s_nop 0
	global_load_lds_dwordx4 v[134:135], off
	s_waitcnt vmcnt(8)
	s_waitcnt lgkmcnt(0)
	s_barrier
	s_setprio 1
	s_waitcnt lgkmcnt(0)
	v_mfma_f32_16x16x32_bf16 v[134:137], v[4:7], v[36:39], 0
	v_mfma_f32_16x16x32_bf16 v[138:141], v[12:15], v[36:39], 0
	v_mfma_f32_16x16x32_bf16 v[142:145], v[4:7], v[52:55], 0
	v_mfma_f32_16x16x32_bf16 v[146:149], v[12:15], v[52:55], 0
	v_mfma_f32_16x16x32_bf16 v[150:153], v[4:7], v[116:119], 0
	v_mfma_f32_16x16x32_bf16 v[154:157], v[12:15], v[116:119], 0
	v_mfma_f32_16x16x32_bf16 v[4:7], v[4:7], v[124:127], 0
	v_mfma_f32_16x16x32_bf16 v[12:15], v[12:15], v[124:127], 0
	v_mfma_f32_16x16x32_bf16 v[134:137], v[8:11], v[44:47], v[134:137]
	v_mfma_f32_16x16x32_bf16 v[138:141], v[16:19], v[44:47], v[138:141]
	v_mfma_f32_16x16x32_bf16 v[142:145], v[8:11], v[60:63], v[142:145]
	v_mfma_f32_16x16x32_bf16 v[146:149], v[16:19], v[60:63], v[146:149]
	v_mfma_f32_16x16x32_bf16 v[150:153], v[8:11], v[120:123], v[150:153]
	v_mfma_f32_16x16x32_bf16 v[154:157], v[16:19], v[120:123], v[154:157]
	v_mfma_f32_16x16x32_bf16 v[158:161], v[8:11], v[128:131], v[4:7]
	v_mfma_f32_16x16x32_bf16 v[162:165], v[16:19], v[128:131], v[12:15]
	s_setprio 0
	s_setprio 1
	v_mfma_f32_16x16x32_bf16 v[4:7], v[20:23], v[36:39], 0
	v_mfma_f32_16x16x32_bf16 v[8:11], v[28:31], v[36:39], 0
	v_mfma_f32_16x16x32_bf16 v[12:15], v[20:23], v[52:55], 0
	v_mfma_f32_16x16x32_bf16 v[16:19], v[28:31], v[52:55], 0
	v_mfma_f32_16x16x32_bf16 v[36:39], v[20:23], v[116:119], 0
	v_mfma_f32_16x16x32_bf16 v[52:55], v[28:31], v[116:119], 0
	v_mfma_f32_16x16x32_bf16 v[20:23], v[20:23], v[124:127], 0
	v_mfma_f32_16x16x32_bf16 v[28:31], v[28:31], v[124:127], 0
	v_mfma_f32_16x16x32_bf16 v[116:119], v[24:27], v[44:47], v[4:7]
	v_mfma_f32_16x16x32_bf16 v[124:127], v[32:35], v[44:47], v[8:11]
	v_mfma_f32_16x16x32_bf16 v[174:177], v[24:27], v[120:123], v[36:39]
	v_mfma_f32_16x16x32_bf16 v[120:123], v[32:35], v[120:123], v[52:55]
	v_mfma_f32_16x16x32_bf16 v[178:181], v[24:27], v[128:131], v[20:23]
	s_setprio 2
	s_barrier
	v_mfma_f32_16x16x32_bf16 v[128:131], v[32:35], v[128:131], v[28:31]
	v_mfma_f32_16x16x32_bf16 v[166:169], v[24:27], v[60:63], v[12:15]
	v_mfma_f32_16x16x32_bf16 v[170:173], v[32:35], v[60:63], v[16:19]
	s_setprio 0
	s_add_i32 s61, 0, 0x18000
	v_add_u32_e32 v4, s61, v209
	s_add_i32 s79, 0, 0x1c000
	ds_read_b128 v[182:185], v4
	ds_read_b128 v[192:195], v4 offset:1024
	ds_read_b128 v[196:199], v4 offset:2048
	ds_read_b128 v[200:203], v4 offset:3072
	v_add_u32_e32 v4, s79, v209
	ds_read_b128 v[204:207], v4
	ds_read_b128 v[210:213], v4 offset:1024
	ds_read_b128 v[214:217], v4 offset:2048
	ds_read_b128 v[218:221], v4 offset:3072
	s_mov_b32 m0, s67
	ds_read_b128 v[44:47], v231 offset:32768
	ds_read_b128 v[52:55], v231 offset:33792
	ds_read_b128 v[60:63], v231 offset:34816
	ds_read_b128 v[222:225], v231 offset:35840
	ds_read_b128 v[232:235], v231 offset:36864
	ds_read_b128 v[236:239], v231 offset:37888
	ds_read_b128 v[240:243], v231 offset:38912
	ds_read_b128 v[244:247], v231 offset:39936
	global_load_lds_dwordx4 v132, s[26:27]
	s_mov_b32 m0, s68
	s_nop 0
	global_load_lds_dwordx4 v188, s[26:27]
	s_waitcnt vmcnt(8)
	s_waitcnt lgkmcnt(0)
	s_barrier
	s_setprio 1
	s_waitcnt lgkmcnt(0)
	v_mfma_f32_16x16x32_bf16 v[4:7], v[182:185], v[44:47], v[68:71]
	v_mfma_f32_16x16x32_bf16 v[8:11], v[196:199], v[44:47], v[72:75]
	v_mfma_f32_16x16x32_bf16 v[12:15], v[182:185], v[60:63], v[76:79]
	v_mfma_f32_16x16x32_bf16 v[16:19], v[196:199], v[60:63], v[80:83]
	v_mfma_f32_16x16x32_bf16 v[20:23], v[182:185], v[232:235], v[84:87]
	v_mfma_f32_16x16x32_bf16 v[24:27], v[196:199], v[232:235], v[88:91]
	v_mfma_f32_16x16x32_bf16 v[28:31], v[182:185], v[240:243], v[92:95]
	v_mfma_f32_16x16x32_bf16 v[32:35], v[196:199], v[240:243], v[96:99]
	v_mfma_f32_16x16x32_bf16 v[4:7], v[192:195], v[52:55], v[4:7]
	v_mfma_f32_16x16x32_bf16 v[8:11], v[200:203], v[52:55], v[8:11]
	v_mfma_f32_16x16x32_bf16 v[12:15], v[192:195], v[222:225], v[12:15]
	v_mfma_f32_16x16x32_bf16 v[16:19], v[200:203], v[222:225], v[16:19]
	v_mfma_f32_16x16x32_bf16 v[20:23], v[192:195], v[236:239], v[20:23]
	v_mfma_f32_16x16x32_bf16 v[24:27], v[200:203], v[236:239], v[24:27]
	v_mfma_f32_16x16x32_bf16 v[28:31], v[192:195], v[244:247], v[28:31]
	v_mfma_f32_16x16x32_bf16 v[32:35], v[200:203], v[244:247], v[32:35]
	s_setprio 0
	s_setprio 1
	v_mfma_f32_16x16x32_bf16 v[36:39], v[204:207], v[44:47], v[100:103]
	v_mfma_f32_16x16x32_bf16 v[40:43], v[214:217], v[44:47], v[40:43]
	v_mfma_f32_16x16x32_bf16 v[36:39], v[210:213], v[52:55], v[36:39]
	v_mfma_f32_16x16x32_bf16 v[40:43], v[218:221], v[52:55], v[40:43]
	v_mfma_f32_16x16x32_bf16 v[44:47], v[204:207], v[60:63], v[104:107]
	v_mfma_f32_16x16x32_bf16 v[48:51], v[214:217], v[60:63], v[48:51]
	v_mfma_f32_16x16x32_bf16 v[52:55], v[204:207], v[232:235], v[108:111]
	v_mfma_f32_16x16x32_bf16 v[56:59], v[214:217], v[232:235], v[56:59]
	v_mfma_f32_16x16x32_bf16 v[60:63], v[204:207], v[240:243], v[112:115]
	v_mfma_f32_16x16x32_bf16 v[64:67], v[214:217], v[240:243], v[64:67]
	v_mfma_f32_16x16x32_bf16 v[44:47], v[210:213], v[222:225], v[44:47]
	v_mfma_f32_16x16x32_bf16 v[48:51], v[218:221], v[222:225], v[48:51]
	v_mfma_f32_16x16x32_bf16 v[52:55], v[210:213], v[236:239], v[52:55]
	s_setprio 2
	s_barrier
	v_mfma_f32_16x16x32_bf16 v[56:59], v[218:221], v[236:239], v[56:59]
	v_mfma_f32_16x16x32_bf16 v[60:63], v[210:213], v[244:247], v[60:63]
	v_mfma_f32_16x16x32_bf16 v[64:67], v[218:221], v[244:247], v[64:67]
	s_setprio 0
	s_add_i32 s61, s61, s36
	v_lshl_add_u64 v[68:69], v[186:187], 0, s[24:25]
	s_mov_b32 m0, s61
	ds_read_b128 v[104:107], v231 offset:49152
	ds_read_b128 v[108:111], v231 offset:50176
	ds_read_b128 v[112:115], v231 offset:51200
	ds_read_b128 v[222:225], v231 offset:52224
	ds_read_b128 v[232:235], v231 offset:53248
	ds_read_b128 v[236:239], v231 offset:54272
	ds_read_b128 v[240:243], v231 offset:55296
	ds_read_b128 v[244:247], v231 offset:56320
	global_load_lds_dwordx4 v[68:69], off
	v_lshl_add_u64 v[68:69], v[226:227], 0, s[24:25]
	s_add_i32 m0, s61, 0x2000
	s_add_i32 s61, s79, s36
	global_load_lds_dwordx4 v[68:69], off
	s_mov_b32 m0, s61
	v_lshl_add_u64 v[68:69], v[248:249], 0, s[24:25]
	global_load_lds_dwordx4 v2, s[28:29]
	s_add_i32 m0, s61, 0x2000
	s_nop 0
	global_load_lds_dwordx4 v190, s[28:29]
	s_mov_b32 m0, s71
	s_nop 0
	global_load_lds_dwordx4 v[68:69], off
	v_lshl_add_u64 v[68:69], v[250:251], 0, s[24:25]
	s_mov_b32 m0, s72
	s_nop 0
	global_load_lds_dwordx4 v[68:69], off
	s_waitcnt vmcnt(8)
	s_waitcnt lgkmcnt(0)
	s_barrier
	s_setprio 1
	s_waitcnt lgkmcnt(0)
	v_mfma_f32_16x16x32_bf16 v[68:71], v[182:185], v[104:107], v[134:137]
	v_mfma_f32_16x16x32_bf16 v[72:75], v[196:199], v[104:107], v[138:141]
	v_mfma_f32_16x16x32_bf16 v[76:79], v[182:185], v[112:115], v[142:145]
	v_mfma_f32_16x16x32_bf16 v[80:83], v[196:199], v[112:115], v[146:149]
	v_mfma_f32_16x16x32_bf16 v[84:87], v[182:185], v[232:235], v[150:153]
	v_mfma_f32_16x16x32_bf16 v[88:91], v[196:199], v[232:235], v[154:157]
	v_mfma_f32_16x16x32_bf16 v[92:95], v[182:185], v[240:243], v[158:161]
	v_mfma_f32_16x16x32_bf16 v[96:99], v[196:199], v[240:243], v[162:165]
	v_mfma_f32_16x16x32_bf16 v[68:71], v[192:195], v[108:111], v[68:71]
	v_mfma_f32_16x16x32_bf16 v[72:75], v[200:203], v[108:111], v[72:75]
	v_mfma_f32_16x16x32_bf16 v[76:79], v[192:195], v[222:225], v[76:79]
	v_mfma_f32_16x16x32_bf16 v[80:83], v[200:203], v[222:225], v[80:83]
	v_mfma_f32_16x16x32_bf16 v[84:87], v[192:195], v[236:239], v[84:87]
	v_mfma_f32_16x16x32_bf16 v[88:91], v[200:203], v[236:239], v[88:91]
	v_mfma_f32_16x16x32_bf16 v[92:95], v[192:195], v[244:247], v[92:95]
	v_mfma_f32_16x16x32_bf16 v[96:99], v[200:203], v[244:247], v[96:99]
	s_setprio 0
	s_setprio 1
	v_mfma_f32_16x16x32_bf16 v[100:103], v[204:207], v[104:107], v[116:119]
	v_mfma_f32_16x16x32_bf16 v[104:107], v[214:217], v[104:107], v[124:127]
	v_mfma_f32_16x16x32_bf16 v[100:103], v[210:213], v[108:111], v[100:103]
	v_mfma_f32_16x16x32_bf16 v[104:107], v[218:221], v[108:111], v[104:107]
	v_mfma_f32_16x16x32_bf16 v[108:111], v[204:207], v[112:115], v[166:169]
	v_mfma_f32_16x16x32_bf16 v[112:115], v[214:217], v[112:115], v[170:173]
	v_mfma_f32_16x16x32_bf16 v[116:119], v[204:207], v[232:235], v[174:177]
	v_mfma_f32_16x16x32_bf16 v[120:123], v[214:217], v[232:235], v[120:123]
	v_mfma_f32_16x16x32_bf16 v[124:127], v[204:207], v[240:243], v[178:181]
	v_mfma_f32_16x16x32_bf16 v[128:131], v[214:217], v[240:243], v[128:131]
	v_mfma_f32_16x16x32_bf16 v[108:111], v[210:213], v[222:225], v[108:111]
	v_mfma_f32_16x16x32_bf16 v[112:115], v[218:221], v[222:225], v[112:115]
	v_mfma_f32_16x16x32_bf16 v[116:119], v[210:213], v[236:239], v[116:119]
	s_setprio 2
	s_barrier
	v_mfma_f32_16x16x32_bf16 v[120:123], v[218:221], v[236:239], v[120:123]
	v_mfma_f32_16x16x32_bf16 v[124:127], v[210:213], v[244:247], v[124:127]
	v_mfma_f32_16x16x32_bf16 v[128:131], v[218:221], v[244:247], v[128:131]
	s_setprio 0
	s_add_i32 s43, s43, 2
	s_cmp_ge_i32 s43, s42
	s_cbranch_scc0 .LBB0_1175
.LBB0_1176:
	s_add_i32 s12, 0, 0x10000
	s_add_i32 s13, 0, 0x14000
	v_mov_b32_e32 v192, v2
	v_mov_b32_e32 v2, v132
	v_add_u32_e32 v144, s12, v209
	v_add_u32_e32 v160, s13, v209
	ds_read_b128 v[132:135], v144
	ds_read_b128 v[136:139], v144 offset:1024
	ds_read_b128 v[140:143], v144 offset:2048
	ds_read_b128 v[144:147], v144 offset:3072
	ds_read_b128 v[148:151], v160
	ds_read_b128 v[152:155], v160 offset:1024
	ds_read_b128 v[156:159], v160 offset:2048
	ds_read_b128 v[160:163], v160 offset:3072
	s_add_u32 s6, s6, 0x80180
	s_mov_b32 m0, s73
	v_add_u32_e32 v212, 0, v208
	s_addc_u32 s7, s7, 0
	ds_read_b128 v[164:167], v212
	ds_read_b128 v[168:171], v212 offset:1024
	ds_read_b128 v[172:175], v212 offset:2048
	ds_read_b128 v[176:179], v212 offset:3072
	ds_read_b128 v[180:183], v212 offset:4096
	ds_read_b128 v[184:187], v212 offset:5120
	ds_read_b128 v[194:197], v212 offset:6144
	ds_read_b128 v[198:201], v212 offset:7168
	global_load_lds_dwordx4 v2, s[6:7]
	s_mov_b32 m0, s76
	v_mov_b32_e32 v189, v3
	global_load_lds_dwordx4 v188, s[6:7]
	s_waitcnt vmcnt(8)
	s_waitcnt lgkmcnt(0)
	s_barrier
	s_setprio 1
	s_waitcnt lgkmcnt(0)
	v_mfma_f32_16x16x32_bf16 v[4:7], v[132:135], v[164:167], v[4:7]
	v_mfma_f32_16x16x32_bf16 v[4:7], v[136:139], v[168:171], v[4:7]
	v_mfma_f32_16x16x32_bf16 v[8:11], v[144:147], v[168:171], v[8:11]
	v_mfma_f32_16x16x32_bf16 v[8:11], v[140:143], v[164:167], v[8:11]
	v_mfma_f32_16x16x32_bf16 v[16:19], v[140:143], v[172:175], v[16:19]
	v_mfma_f32_16x16x32_bf16 v[16:19], v[144:147], v[176:179], v[16:19]
	v_mfma_f32_16x16x32_bf16 v[12:15], v[136:139], v[176:179], v[12:15]
	v_mfma_f32_16x16x32_bf16 v[12:15], v[132:135], v[172:175], v[12:15]
	v_mfma_f32_16x16x32_bf16 v[20:23], v[132:135], v[180:183], v[20:23]
	v_mfma_f32_16x16x32_bf16 v[20:23], v[136:139], v[184:187], v[20:23]
	v_mfma_f32_16x16x32_bf16 v[24:27], v[144:147], v[184:187], v[24:27]
	v_mfma_f32_16x16x32_bf16 v[24:27], v[140:143], v[180:183], v[24:27]
	v_mfma_f32_16x16x32_bf16 v[32:35], v[140:143], v[194:197], v[32:35]
	v_mfma_f32_16x16x32_bf16 v[32:35], v[144:147], v[198:201], v[32:35]
	v_mfma_f32_16x16x32_bf16 v[28:31], v[136:139], v[198:201], v[28:31]
	v_mfma_f32_16x16x32_bf16 v[28:31], v[132:135], v[194:197], v[28:31]
	s_setprio 0
	s_setprio 1
	v_mfma_f32_16x16x32_bf16 v[36:39], v[148:151], v[164:167], v[36:39]
	v_mfma_f32_16x16x32_bf16 v[36:39], v[152:155], v[168:171], v[36:39]
	v_mfma_f32_16x16x32_bf16 v[40:43], v[160:163], v[168:171], v[40:43]
	v_mfma_f32_16x16x32_bf16 v[40:43], v[156:159], v[164:167], v[40:43]
	v_mfma_f32_16x16x32_bf16 v[48:51], v[156:159], v[172:175], v[48:51]
	v_mfma_f32_16x16x32_bf16 v[48:51], v[160:163], v[176:179], v[48:51]
	v_mfma_f32_16x16x32_bf16 v[44:47], v[152:155], v[176:179], v[44:47]
	v_mfma_f32_16x16x32_bf16 v[44:47], v[148:151], v[172:175], v[44:47]
	v_mfma_f32_16x16x32_bf16 v[52:55], v[148:151], v[180:183], v[52:55]
	v_mfma_f32_16x16x32_bf16 v[52:55], v[152:155], v[184:187], v[52:55]
	v_mfma_f32_16x16x32_bf16 v[56:59], v[160:163], v[184:187], v[56:59]
	v_mfma_f32_16x16x32_bf16 v[56:59], v[156:159], v[180:183], v[56:59]
	v_mfma_f32_16x16x32_bf16 v[64:67], v[156:159], v[194:197], v[64:67]
	s_setprio 2
	s_barrier
	v_mfma_f32_16x16x32_bf16 v[64:67], v[160:163], v[198:201], v[64:67]
	v_mfma_f32_16x16x32_bf16 v[60:63], v[152:155], v[198:201], v[60:63]
	v_mfma_f32_16x16x32_bf16 v[60:63], v[148:151], v[194:197], v[60:63]
	s_setprio 0
	s_add_i32 s6, s12, s36
	s_mov_b32 m0, s6
	ds_read_b128 v[164:167], v212 offset:16384
	ds_read_b128 v[168:171], v212 offset:17408
	ds_read_b128 v[172:175], v212 offset:18432
	ds_read_b128 v[176:179], v212 offset:19456
	ds_read_b128 v[180:183], v212 offset:20480
	ds_read_b128 v[184:187], v212 offset:21504
	ds_read_b128 v[194:197], v212 offset:22528
	ds_read_b128 v[198:201], v212 offset:23552
	global_load_lds_dwordx4 v192, s[14:15]
	s_add_i32 m0, s6, 0x2000
	s_add_u32 s6, s14, 0x10000
	s_addc_u32 s7, s15, 0
	s_add_i32 s12, s13, s36
	global_load_lds_dwordx4 v190, s[14:15]
	s_mov_b32 m0, s12
	v_mov_b32_e32 v193, v3
	global_load_lds_dwordx4 v192, s[6:7]
	s_add_i32 m0, s12, 0x2000
	v_mov_b32_e32 v191, v3
	global_load_lds_dwordx4 v190, s[6:7]
	s_mov_b32 m0, s37
	v_lshl_add_u64 v[202:203], s[14:15], 0, v[192:193]
	global_load_lds_dwordx4 v2, s[10:11]
	s_mov_b32 m0, s66
	v_lshl_add_u64 v[204:205], s[14:15], 0, v[190:191]
	global_load_lds_dwordx4 v188, s[10:11]
	s_waitcnt vmcnt(8)
	s_waitcnt lgkmcnt(0)
	v_lshl_add_u64 v[206:207], s[10:11], 0, v[2:3]
	v_lshl_add_u64 v[210:211], s[10:11], 0, v[188:189]
	s_barrier
	s_setprio 1
	s_waitcnt lgkmcnt(0)
	v_mfma_f32_16x16x32_bf16 v[68:71], v[132:135], v[164:167], v[68:71]
	v_mfma_f32_16x16x32_bf16 v[68:71], v[136:139], v[168:171], v[68:71]
	v_mfma_f32_16x16x32_bf16 v[72:75], v[144:147], v[168:171], v[72:75]
	v_mfma_f32_16x16x32_bf16 v[72:75], v[140:143], v[164:167], v[72:75]
	v_mfma_f32_16x16x32_bf16 v[80:83], v[140:143], v[172:175], v[80:83]
	v_mfma_f32_16x16x32_bf16 v[80:83], v[144:147], v[176:179], v[80:83]
	v_mfma_f32_16x16x32_bf16 v[76:79], v[136:139], v[176:179], v[76:79]
	v_mfma_f32_16x16x32_bf16 v[76:79], v[132:135], v[172:175], v[76:79]
	v_mfma_f32_16x16x32_bf16 v[84:87], v[132:135], v[180:183], v[84:87]
	v_mfma_f32_16x16x32_bf16 v[84:87], v[136:139], v[184:187], v[84:87]
	v_mfma_f32_16x16x32_bf16 v[88:91], v[144:147], v[184:187], v[88:91]
	v_mfma_f32_16x16x32_bf16 v[88:91], v[140:143], v[180:183], v[88:91]
	v_mfma_f32_16x16x32_bf16 v[96:99], v[140:143], v[194:197], v[96:99]
	v_mfma_f32_16x16x32_bf16 v[96:99], v[144:147], v[198:201], v[96:99]
	v_mfma_f32_16x16x32_bf16 v[92:95], v[136:139], v[198:201], v[92:95]
	v_mfma_f32_16x16x32_bf16 v[92:95], v[132:135], v[194:197], v[92:95]
	s_setprio 0
	s_setprio 1
	v_mfma_f32_16x16x32_bf16 v[100:103], v[148:151], v[164:167], v[100:103]
	v_mfma_f32_16x16x32_bf16 v[100:103], v[152:155], v[168:171], v[100:103]
	v_mfma_f32_16x16x32_bf16 v[104:107], v[160:163], v[168:171], v[104:107]
	v_mfma_f32_16x16x32_bf16 v[104:107], v[156:159], v[164:167], v[104:107]
	v_mfma_f32_16x16x32_bf16 v[112:115], v[156:159], v[172:175], v[112:115]
	v_mfma_f32_16x16x32_bf16 v[112:115], v[160:163], v[176:179], v[112:115]
	v_mfma_f32_16x16x32_bf16 v[108:111], v[152:155], v[176:179], v[108:111]
	v_mfma_f32_16x16x32_bf16 v[108:111], v[148:151], v[172:175], v[108:111]
	v_mfma_f32_16x16x32_bf16 v[116:119], v[148:151], v[180:183], v[116:119]
	v_mfma_f32_16x16x32_bf16 v[116:119], v[152:155], v[184:187], v[116:119]
	v_mfma_f32_16x16x32_bf16 v[120:123], v[160:163], v[184:187], v[120:123]
	v_mfma_f32_16x16x32_bf16 v[120:123], v[156:159], v[180:183], v[120:123]
	v_mfma_f32_16x16x32_bf16 v[128:131], v[156:159], v[194:197], v[128:131]
	s_setprio 2
	s_barrier
	v_mfma_f32_16x16x32_bf16 v[128:131], v[160:163], v[198:201], v[128:131]
	v_mfma_f32_16x16x32_bf16 v[124:127], v[152:155], v[198:201], v[124:127]
	v_mfma_f32_16x16x32_bf16 v[124:127], v[148:151], v[194:197], v[124:127]
	s_setprio 0
	s_add_i32 s12, 0, 0x18000
	s_add_i32 s13, 0, 0x1c000
	v_add_u32_e32 v144, s12, v209
	v_add_u32_e32 v160, s13, v209
	ds_read_b128 v[132:135], v144
	ds_read_b128 v[136:139], v144 offset:1024
	ds_read_b128 v[140:143], v144 offset:2048
	ds_read_b128 v[144:147], v144 offset:3072
	ds_read_b128 v[148:151], v160
	ds_read_b128 v[152:155], v160 offset:1024
	ds_read_b128 v[156:159], v160 offset:2048
	ds_read_b128 v[160:163], v160 offset:3072
	s_add_u32 s6, s10, 0x80000
	s_addc_u32 s7, s11, 0
	s_mov_b32 m0, s67
	ds_read_b128 v[164:167], v212 offset:32768
	ds_read_b128 v[168:171], v212 offset:33792
	ds_read_b128 v[172:175], v212 offset:34816
	ds_read_b128 v[176:179], v212 offset:35840
	ds_read_b128 v[180:183], v212 offset:36864
	ds_read_b128 v[184:187], v212 offset:37888
	ds_read_b128 v[194:197], v212 offset:38912
	ds_read_b128 v[198:201], v212 offset:39936
	global_load_lds_dwordx4 v2, s[6:7]
	s_mov_b32 m0, s68
	s_nop 0
	global_load_lds_dwordx4 v188, s[6:7]
	s_waitcnt vmcnt(8)
	s_waitcnt lgkmcnt(0)
	s_barrier
	s_setprio 1
	s_waitcnt lgkmcnt(0)
	v_mfma_f32_16x16x32_bf16 v[4:7], v[132:135], v[164:167], v[4:7]
	v_mfma_f32_16x16x32_bf16 v[4:7], v[136:139], v[168:171], v[4:7]
	v_mfma_f32_16x16x32_bf16 v[8:11], v[144:147], v[168:171], v[8:11]
	v_mfma_f32_16x16x32_bf16 v[8:11], v[140:143], v[164:167], v[8:11]
	v_mfma_f32_16x16x32_bf16 v[16:19], v[140:143], v[172:175], v[16:19]
	v_mfma_f32_16x16x32_bf16 v[16:19], v[144:147], v[176:179], v[16:19]
	v_mfma_f32_16x16x32_bf16 v[12:15], v[136:139], v[176:179], v[12:15]
	v_mfma_f32_16x16x32_bf16 v[12:15], v[132:135], v[172:175], v[12:15]
	v_mfma_f32_16x16x32_bf16 v[20:23], v[132:135], v[180:183], v[20:23]
	v_mfma_f32_16x16x32_bf16 v[20:23], v[136:139], v[184:187], v[20:23]
	v_mfma_f32_16x16x32_bf16 v[24:27], v[144:147], v[184:187], v[24:27]
	v_mfma_f32_16x16x32_bf16 v[24:27], v[140:143], v[180:183], v[24:27]
	v_mfma_f32_16x16x32_bf16 v[32:35], v[140:143], v[194:197], v[32:35]
	v_mfma_f32_16x16x32_bf16 v[32:35], v[144:147], v[198:201], v[32:35]
	v_mfma_f32_16x16x32_bf16 v[28:31], v[136:139], v[198:201], v[28:31]
	v_mfma_f32_16x16x32_bf16 v[28:31], v[132:135], v[194:197], v[28:31]
	s_setprio 0
	s_setprio 1
	v_mfma_f32_16x16x32_bf16 v[36:39], v[148:151], v[164:167], v[36:39]
	v_mfma_f32_16x16x32_bf16 v[36:39], v[152:155], v[168:171], v[36:39]
	v_mfma_f32_16x16x32_bf16 v[40:43], v[160:163], v[168:171], v[40:43]
	v_mfma_f32_16x16x32_bf16 v[40:43], v[156:159], v[164:167], v[40:43]
	v_mfma_f32_16x16x32_bf16 v[48:51], v[156:159], v[172:175], v[48:51]
	v_mfma_f32_16x16x32_bf16 v[48:51], v[160:163], v[176:179], v[48:51]
	v_mfma_f32_16x16x32_bf16 v[44:47], v[152:155], v[176:179], v[44:47]
	v_mfma_f32_16x16x32_bf16 v[44:47], v[148:151], v[172:175], v[44:47]
	v_mfma_f32_16x16x32_bf16 v[52:55], v[148:151], v[180:183], v[52:55]
	v_mfma_f32_16x16x32_bf16 v[52:55], v[152:155], v[184:187], v[52:55]
	v_mfma_f32_16x16x32_bf16 v[56:59], v[160:163], v[184:187], v[56:59]
	v_mfma_f32_16x16x32_bf16 v[56:59], v[156:159], v[180:183], v[56:59]
	v_mfma_f32_16x16x32_bf16 v[64:67], v[156:159], v[194:197], v[64:67]
	s_setprio 2
	s_barrier
	v_mfma_f32_16x16x32_bf16 v[64:67], v[160:163], v[198:201], v[64:67]
	v_mfma_f32_16x16x32_bf16 v[60:63], v[152:155], v[198:201], v[60:63]
	v_mfma_f32_16x16x32_bf16 v[60:63], v[148:151], v[194:197], v[60:63]
	s_setprio 0
	s_add_i32 s6, s12, s36
	v_lshl_add_u64 v[202:203], v[202:203], 0, s[86:87]
	s_mov_b32 m0, s6
	ds_read_b128 v[164:167], v212 offset:49152
	ds_read_b128 v[168:171], v212 offset:50176
	ds_read_b128 v[172:175], v212 offset:51200
	ds_read_b128 v[176:179], v212 offset:52224
	ds_read_b128 v[180:183], v212 offset:53248
	ds_read_b128 v[184:187], v212 offset:54272
	ds_read_b128 v[194:197], v212 offset:55296
	ds_read_b128 v[198:201], v212 offset:56320
	global_load_lds_dwordx4 v[202:203], off
	s_add_i32 m0, s6, 0x2000
	s_add_u32 s6, s14, 0x10080
	v_lshl_add_u64 v[202:203], v[204:205], 0, s[86:87]
	s_addc_u32 s7, s15, 0
	s_add_i32 s12, s13, s36
	global_load_lds_dwordx4 v[202:203], off
	s_mov_b32 m0, s12
	v_lshl_add_u64 v[202:203], v[206:207], 0, s[86:87]
	global_load_lds_dwordx4 v192, s[6:7]
	s_add_i32 m0, s12, 0x2000
	s_nop 0
	global_load_lds_dwordx4 v190, s[6:7]
	s_mov_b32 m0, s71
	s_nop 0
	global_load_lds_dwordx4 v[202:203], off
	v_lshl_add_u64 v[202:203], v[210:211], 0, s[86:87]
	s_mov_b32 m0, s72
	s_nop 0
	global_load_lds_dwordx4 v[202:203], off
	s_waitcnt vmcnt(8)
	s_waitcnt lgkmcnt(0)
	s_barrier
	s_setprio 1
	s_waitcnt lgkmcnt(0)
	v_mfma_f32_16x16x32_bf16 v[68:71], v[132:135], v[164:167], v[68:71]
	v_mfma_f32_16x16x32_bf16 v[68:71], v[136:139], v[168:171], v[68:71]
	v_mfma_f32_16x16x32_bf16 v[72:75], v[144:147], v[168:171], v[72:75]
	v_mfma_f32_16x16x32_bf16 v[72:75], v[140:143], v[164:167], v[72:75]
	v_mfma_f32_16x16x32_bf16 v[80:83], v[140:143], v[172:175], v[80:83]
	v_mfma_f32_16x16x32_bf16 v[80:83], v[144:147], v[176:179], v[80:83]
	v_mfma_f32_16x16x32_bf16 v[76:79], v[136:139], v[176:179], v[76:79]
	v_mfma_f32_16x16x32_bf16 v[76:79], v[132:135], v[172:175], v[76:79]
	v_mfma_f32_16x16x32_bf16 v[84:87], v[132:135], v[180:183], v[84:87]
	v_mfma_f32_16x16x32_bf16 v[84:87], v[136:139], v[184:187], v[84:87]
	v_mfma_f32_16x16x32_bf16 v[88:91], v[144:147], v[184:187], v[88:91]
	v_mfma_f32_16x16x32_bf16 v[88:91], v[140:143], v[180:183], v[88:91]
	v_mfma_f32_16x16x32_bf16 v[96:99], v[140:143], v[194:197], v[96:99]
	v_mfma_f32_16x16x32_bf16 v[96:99], v[144:147], v[198:201], v[96:99]
	v_mfma_f32_16x16x32_bf16 v[92:95], v[136:139], v[198:201], v[92:95]
	v_mfma_f32_16x16x32_bf16 v[92:95], v[132:135], v[194:197], v[92:95]
	s_setprio 0
	s_setprio 1
	v_mfma_f32_16x16x32_bf16 v[100:103], v[148:151], v[164:167], v[100:103]
	v_mfma_f32_16x16x32_bf16 v[100:103], v[152:155], v[168:171], v[100:103]
	v_mfma_f32_16x16x32_bf16 v[104:107], v[160:163], v[168:171], v[104:107]
	v_mfma_f32_16x16x32_bf16 v[104:107], v[156:159], v[164:167], v[104:107]
	v_mfma_f32_16x16x32_bf16 v[112:115], v[156:159], v[172:175], v[112:115]
	v_mfma_f32_16x16x32_bf16 v[112:115], v[160:163], v[176:179], v[112:115]
	v_mfma_f32_16x16x32_bf16 v[108:111], v[152:155], v[176:179], v[108:111]
	v_mfma_f32_16x16x32_bf16 v[108:111], v[148:151], v[172:175], v[108:111]
	v_mfma_f32_16x16x32_bf16 v[116:119], v[148:151], v[180:183], v[116:119]
	v_mfma_f32_16x16x32_bf16 v[116:119], v[152:155], v[184:187], v[116:119]
	v_mfma_f32_16x16x32_bf16 v[120:123], v[160:163], v[184:187], v[120:123]
	v_mfma_f32_16x16x32_bf16 v[120:123], v[156:159], v[180:183], v[120:123]
	v_mfma_f32_16x16x32_bf16 v[128:131], v[156:159], v[194:197], v[128:131]
	s_setprio 2
	s_barrier
	v_mfma_f32_16x16x32_bf16 v[128:131], v[160:163], v[198:201], v[128:131]
	v_mfma_f32_16x16x32_bf16 v[124:127], v[152:155], v[198:201], v[124:127]
	v_mfma_f32_16x16x32_bf16 v[124:127], v[148:151], v[194:197], v[124:127]
	s_setprio 0
	s_and_b64 vcc, exec, s[58:59]
	s_cbranch_vccz .LBB0_1178
	s_barrier

.LBB0_1625:
	s_add_i32 s51, 0, 0x10000
	s_add_i32 s72, 0, 0x14000
	v_add_u32_e32 v16, s51, v232
	v_add_u32_e32 v32, s72, v232
	ds_read_b128 v[4:7], v16
	ds_read_b128 v[8:11], v16 offset:1024
	ds_read_b128 v[12:15], v16 offset:2048
	ds_read_b128 v[16:19], v16 offset:3072
	ds_read_b128 v[20:23], v32
	ds_read_b128 v[24:27], v32 offset:1024
	ds_read_b128 v[28:31], v32 offset:2048
	ds_read_b128 v[32:35], v32 offset:3072
	v_add_u32_e32 v233, 0, v231
	ds_read_b128 v[36:39], v233
	ds_read_b128 v[40:43], v233 offset:1024
	ds_read_b128 v[44:47], v233 offset:2048
	ds_read_b128 v[48:51], v233 offset:3072
	ds_read_b128 v[52:55], v233 offset:4096
	ds_read_b128 v[56:59], v233 offset:5120
	ds_read_b128 v[60:63], v233 offset:6144
	ds_read_b128 v[64:67], v233 offset:7168
	s_waitcnt vmcnt(8)
	s_waitcnt lgkmcnt(0)
	s_barrier
	s_setprio 1
	s_waitcnt lgkmcnt(0)
	v_mfma_f32_16x16x32_bf16 v[68:71], v[4:7], v[36:39], 0
	v_mfma_f32_16x16x32_bf16 v[68:71], v[8:11], v[40:43], v[68:71]
	v_mfma_f32_16x16x32_bf16 v[72:75], v[12:15], v[36:39], 0
	v_mfma_f32_16x16x32_bf16 v[72:75], v[16:19], v[40:43], v[72:75]
	v_mfma_f32_16x16x32_bf16 v[80:83], v[12:15], v[44:47], 0
	v_mfma_f32_16x16x32_bf16 v[80:83], v[16:19], v[48:51], v[80:83]
	v_mfma_f32_16x16x32_bf16 v[76:79], v[4:7], v[44:47], 0
	v_mfma_f32_16x16x32_bf16 v[76:79], v[8:11], v[48:51], v[76:79]
	v_mfma_f32_16x16x32_bf16 v[84:87], v[4:7], v[52:55], 0
	v_mfma_f32_16x16x32_bf16 v[84:87], v[8:11], v[56:59], v[84:87]
	v_mfma_f32_16x16x32_bf16 v[88:91], v[12:15], v[52:55], 0
	v_mfma_f32_16x16x32_bf16 v[88:91], v[16:19], v[56:59], v[88:91]
	v_mfma_f32_16x16x32_bf16 v[96:99], v[12:15], v[60:63], 0
	v_mfma_f32_16x16x32_bf16 v[96:99], v[16:19], v[64:67], v[96:99]
	v_mfma_f32_16x16x32_bf16 v[92:95], v[4:7], v[60:63], 0
	v_mfma_f32_16x16x32_bf16 v[92:95], v[8:11], v[64:67], v[92:95]
	s_setprio 0
	s_setprio 1
	v_mfma_f32_16x16x32_bf16 v[100:103], v[20:23], v[36:39], 0
	v_mfma_f32_16x16x32_bf16 v[36:39], v[28:31], v[36:39], 0
	v_mfma_f32_16x16x32_bf16 v[104:107], v[20:23], v[44:47], 0
	v_mfma_f32_16x16x32_bf16 v[44:47], v[28:31], v[44:47], 0
	v_mfma_f32_16x16x32_bf16 v[108:111], v[20:23], v[52:55], 0
	v_mfma_f32_16x16x32_bf16 v[52:55], v[28:31], v[52:55], 0
	v_mfma_f32_16x16x32_bf16 v[112:115], v[20:23], v[60:63], 0
	v_mfma_f32_16x16x32_bf16 v[60:63], v[28:31], v[60:63], 0
	v_mfma_f32_16x16x32_bf16 v[100:103], v[24:27], v[40:43], v[100:103]
	v_mfma_f32_16x16x32_bf16 v[40:43], v[32:35], v[40:43], v[36:39]
	v_mfma_f32_16x16x32_bf16 v[104:107], v[24:27], v[48:51], v[104:107]
	v_mfma_f32_16x16x32_bf16 v[48:51], v[32:35], v[48:51], v[44:47]
	v_mfma_f32_16x16x32_bf16 v[108:111], v[24:27], v[56:59], v[108:111]
	s_setprio 2
	s_barrier
	v_mfma_f32_16x16x32_bf16 v[56:59], v[32:35], v[56:59], v[52:55]
	v_mfma_f32_16x16x32_bf16 v[112:115], v[24:27], v[64:67], v[112:115]
	v_mfma_f32_16x16x32_bf16 v[64:67], v[32:35], v[64:67], v[60:63]
	s_setprio 0
	v_lshl_add_u64 v[186:187], s[12:13], 0, v[2:3]
	s_add_i32 s51, s51, s56
	v_mov_b32_e32 v191, v3
	v_lshl_add_u64 v[134:135], v[186:187], 0, s[74:75]
	s_mov_b32 m0, s51
	v_lshl_add_u64 v[246:247], s[12:13], 0, v[190:191]
	ds_read_b128 v[36:39], v233 offset:16384
	ds_read_b128 v[44:47], v233 offset:17408
	ds_read_b128 v[52:55], v233 offset:18432
	ds_read_b128 v[60:63], v233 offset:19456
	ds_read_b128 v[116:119], v233 offset:20480
	ds_read_b128 v[120:123], v233 offset:21504
	ds_read_b128 v[124:127], v233 offset:22528
	ds_read_b128 v[128:131], v233 offset:23552
	global_load_lds_dwordx4 v[134:135], off
	v_lshl_add_u64 v[134:135], v[246:247], 0, s[74:75]
	s_add_i32 m0, s51, 0x2000
	s_add_i32 s51, s72, s56
	global_load_lds_dwordx4 v[134:135], off
	s_mov_b32 m0, s51
	v_mov_b32_e32 v133, v3
	global_load_lds_dwordx4 v2, s[16:17]
	s_add_i32 m0, s51, 0x2000
	v_lshl_add_u64 v[248:249], s[14:15], 0, v[132:133]
	v_mov_b32_e32 v189, v3
	global_load_lds_dwordx4 v190, s[16:17]
	v_lshl_add_u64 v[134:135], v[248:249], 0, s[74:75]
	s_mov_b32 m0, s57
	v_lshl_add_u64 v[250:251], s[14:15], 0, v[188:189]
	global_load_lds_dwordx4 v[134:135], off
	v_lshl_add_u64 v[134:135], v[250:251], 0, s[74:75]
	s_mov_b32 m0, s58
	s_nop 0
	global_load_lds_dwordx4 v[134:135], off
	s_waitcnt vmcnt(8)
	s_waitcnt lgkmcnt(0)
	s_barrier
	s_setprio 1
	s_waitcnt lgkmcnt(0)
	v_mfma_f32_16x16x32_bf16 v[134:137], v[4:7], v[36:39], 0
	v_mfma_f32_16x16x32_bf16 v[138:141], v[12:15], v[36:39], 0
	v_mfma_f32_16x16x32_bf16 v[142:145], v[4:7], v[52:55], 0
	v_mfma_f32_16x16x32_bf16 v[146:149], v[12:15], v[52:55], 0
	v_mfma_f32_16x16x32_bf16 v[150:153], v[4:7], v[116:119], 0
	v_mfma_f32_16x16x32_bf16 v[154:157], v[12:15], v[116:119], 0
	v_mfma_f32_16x16x32_bf16 v[4:7], v[4:7], v[124:127], 0
	v_mfma_f32_16x16x32_bf16 v[12:15], v[12:15], v[124:127], 0
	v_mfma_f32_16x16x32_bf16 v[134:137], v[8:11], v[44:47], v[134:137]
	v_mfma_f32_16x16x32_bf16 v[138:141], v[16:19], v[44:47], v[138:141]
	v_mfma_f32_16x16x32_bf16 v[142:145], v[8:11], v[60:63], v[142:145]
	v_mfma_f32_16x16x32_bf16 v[146:149], v[16:19], v[60:63], v[146:149]
	v_mfma_f32_16x16x32_bf16 v[150:153], v[8:11], v[120:123], v[150:153]
	v_mfma_f32_16x16x32_bf16 v[154:157], v[16:19], v[120:123], v[154:157]
	v_mfma_f32_16x16x32_bf16 v[158:161], v[8:11], v[128:131], v[4:7]
	v_mfma_f32_16x16x32_bf16 v[162:165], v[16:19], v[128:131], v[12:15]
	s_setprio 0
	s_setprio 1
	v_mfma_f32_16x16x32_bf16 v[4:7], v[20:23], v[36:39], 0
	v_mfma_f32_16x16x32_bf16 v[8:11], v[28:31], v[36:39], 0
	v_mfma_f32_16x16x32_bf16 v[12:15], v[20:23], v[52:55], 0
	v_mfma_f32_16x16x32_bf16 v[16:19], v[28:31], v[52:55], 0
	v_mfma_f32_16x16x32_bf16 v[36:39], v[20:23], v[116:119], 0
	v_mfma_f32_16x16x32_bf16 v[52:55], v[28:31], v[116:119], 0
	v_mfma_f32_16x16x32_bf16 v[20:23], v[20:23], v[124:127], 0
	v_mfma_f32_16x16x32_bf16 v[28:31], v[28:31], v[124:127], 0
	v_mfma_f32_16x16x32_bf16 v[116:119], v[24:27], v[44:47], v[4:7]
	v_mfma_f32_16x16x32_bf16 v[124:127], v[32:35], v[44:47], v[8:11]
	v_mfma_f32_16x16x32_bf16 v[174:177], v[24:27], v[120:123], v[36:39]
	v_mfma_f32_16x16x32_bf16 v[120:123], v[32:35], v[120:123], v[52:55]
	v_mfma_f32_16x16x32_bf16 v[178:181], v[24:27], v[128:131], v[20:23]
	s_setprio 2
	s_barrier
	v_mfma_f32_16x16x32_bf16 v[128:131], v[32:35], v[128:131], v[28:31]
	v_mfma_f32_16x16x32_bf16 v[166:169], v[24:27], v[60:63], v[12:15]
	v_mfma_f32_16x16x32_bf16 v[170:173], v[32:35], v[60:63], v[16:19]
	s_setprio 0
	s_add_i32 s51, 0, 0x18000
	v_add_u32_e32 v4, s51, v232
	s_add_i32 s72, 0, 0x1c000
	ds_read_b128 v[182:185], v4
	ds_read_b128 v[192:195], v4 offset:1024
	ds_read_b128 v[196:199], v4 offset:2048
	ds_read_b128 v[200:203], v4 offset:3072
	v_add_u32_e32 v4, s72, v232
	ds_read_b128 v[204:207], v4
	ds_read_b128 v[208:211], v4 offset:1024
	ds_read_b128 v[212:215], v4 offset:2048
	ds_read_b128 v[216:219], v4 offset:3072
	s_mov_b32 m0, s59
	ds_read_b128 v[44:47], v233 offset:32768
	ds_read_b128 v[52:55], v233 offset:33792
	ds_read_b128 v[60:63], v233 offset:34816
	ds_read_b128 v[220:223], v233 offset:35840
	ds_read_b128 v[224:227], v233 offset:36864
	ds_read_b128 v[234:237], v233 offset:37888
	ds_read_b128 v[238:241], v233 offset:38912
	ds_read_b128 v[242:245], v233 offset:39936
	global_load_lds_dwordx4 v132, s[26:27]
	s_mov_b32 m0, s60
	s_nop 0
	global_load_lds_dwordx4 v188, s[26:27]
	s_waitcnt vmcnt(8)
	s_waitcnt lgkmcnt(0)
	s_barrier
	s_setprio 1
	s_waitcnt lgkmcnt(0)
	v_mfma_f32_16x16x32_bf16 v[4:7], v[182:185], v[44:47], v[68:71]
	v_mfma_f32_16x16x32_bf16 v[8:11], v[196:199], v[44:47], v[72:75]
	v_mfma_f32_16x16x32_bf16 v[12:15], v[182:185], v[60:63], v[76:79]
	v_mfma_f32_16x16x32_bf16 v[16:19], v[196:199], v[60:63], v[80:83]
	v_mfma_f32_16x16x32_bf16 v[20:23], v[182:185], v[224:227], v[84:87]
	v_mfma_f32_16x16x32_bf16 v[24:27], v[196:199], v[224:227], v[88:91]
	v_mfma_f32_16x16x32_bf16 v[28:31], v[182:185], v[238:241], v[92:95]
	v_mfma_f32_16x16x32_bf16 v[32:35], v[196:199], v[238:241], v[96:99]
	v_mfma_f32_16x16x32_bf16 v[4:7], v[192:195], v[52:55], v[4:7]
	v_mfma_f32_16x16x32_bf16 v[8:11], v[200:203], v[52:55], v[8:11]
	v_mfma_f32_16x16x32_bf16 v[12:15], v[192:195], v[220:223], v[12:15]
	v_mfma_f32_16x16x32_bf16 v[16:19], v[200:203], v[220:223], v[16:19]
	v_mfma_f32_16x16x32_bf16 v[20:23], v[192:195], v[234:237], v[20:23]
	v_mfma_f32_16x16x32_bf16 v[24:27], v[200:203], v[234:237], v[24:27]
	v_mfma_f32_16x16x32_bf16 v[28:31], v[192:195], v[242:245], v[28:31]
	v_mfma_f32_16x16x32_bf16 v[32:35], v[200:203], v[242:245], v[32:35]
	s_setprio 0
	s_setprio 1
	v_mfma_f32_16x16x32_bf16 v[36:39], v[204:207], v[44:47], v[100:103]
	v_mfma_f32_16x16x32_bf16 v[40:43], v[212:215], v[44:47], v[40:43]
	v_mfma_f32_16x16x32_bf16 v[36:39], v[208:211], v[52:55], v[36:39]
	v_mfma_f32_16x16x32_bf16 v[40:43], v[216:219], v[52:55], v[40:43]
	v_mfma_f32_16x16x32_bf16 v[44:47], v[204:207], v[60:63], v[104:107]
	v_mfma_f32_16x16x32_bf16 v[48:51], v[212:215], v[60:63], v[48:51]
	v_mfma_f32_16x16x32_bf16 v[52:55], v[204:207], v[224:227], v[108:111]
	v_mfma_f32_16x16x32_bf16 v[56:59], v[212:215], v[224:227], v[56:59]
	v_mfma_f32_16x16x32_bf16 v[60:63], v[204:207], v[238:241], v[112:115]
	v_mfma_f32_16x16x32_bf16 v[64:67], v[212:215], v[238:241], v[64:67]
	v_mfma_f32_16x16x32_bf16 v[44:47], v[208:211], v[220:223], v[44:47]
	v_mfma_f32_16x16x32_bf16 v[48:51], v[216:219], v[220:223], v[48:51]
	v_mfma_f32_16x16x32_bf16 v[52:55], v[208:211], v[234:237], v[52:55]
	s_setprio 2
	s_barrier
	v_mfma_f32_16x16x32_bf16 v[56:59], v[216:219], v[234:237], v[56:59]
	v_mfma_f32_16x16x32_bf16 v[60:63], v[208:211], v[242:245], v[60:63]
	v_mfma_f32_16x16x32_bf16 v[64:67], v[216:219], v[242:245], v[64:67]
	s_setprio 0
	s_add_i32 s51, s51, s56
	v_lshl_add_u64 v[68:69], v[186:187], 0, s[24:25]
	s_mov_b32 m0, s51
	ds_read_b128 v[104:107], v233 offset:49152
	ds_read_b128 v[108:111], v233 offset:50176
	ds_read_b128 v[112:115], v233 offset:51200
	ds_read_b128 v[220:223], v233 offset:52224
	ds_read_b128 v[224:227], v233 offset:53248
	ds_read_b128 v[234:237], v233 offset:54272
	ds_read_b128 v[238:241], v233 offset:55296
	ds_read_b128 v[242:245], v233 offset:56320
	global_load_lds_dwordx4 v[68:69], off
	v_lshl_add_u64 v[68:69], v[246:247], 0, s[24:25]
	s_add_i32 m0, s51, 0x2000
	s_add_i32 s51, s72, s56
	global_load_lds_dwordx4 v[68:69], off
	s_mov_b32 m0, s51
	v_lshl_add_u64 v[68:69], v[248:249], 0, s[24:25]
	global_load_lds_dwordx4 v2, s[28:29]
	s_add_i32 m0, s51, 0x2000
	s_nop 0
	global_load_lds_dwordx4 v190, s[28:29]
	s_mov_b32 m0, s64
	s_nop 0
	global_load_lds_dwordx4 v[68:69], off
	v_lshl_add_u64 v[68:69], v[250:251], 0, s[24:25]
	s_mov_b32 m0, s65
	s_nop 0
	global_load_lds_dwordx4 v[68:69], off
	s_waitcnt vmcnt(8)
	s_waitcnt lgkmcnt(0)
	s_barrier
	s_setprio 1
	s_waitcnt lgkmcnt(0)
	v_mfma_f32_16x16x32_bf16 v[68:71], v[182:185], v[104:107], v[134:137]
	v_mfma_f32_16x16x32_bf16 v[72:75], v[196:199], v[104:107], v[138:141]
	v_mfma_f32_16x16x32_bf16 v[76:79], v[182:185], v[112:115], v[142:145]
	v_mfma_f32_16x16x32_bf16 v[80:83], v[196:199], v[112:115], v[146:149]
	v_mfma_f32_16x16x32_bf16 v[84:87], v[182:185], v[224:227], v[150:153]
	v_mfma_f32_16x16x32_bf16 v[88:91], v[196:199], v[224:227], v[154:157]
	v_mfma_f32_16x16x32_bf16 v[92:95], v[182:185], v[238:241], v[158:161]
	v_mfma_f32_16x16x32_bf16 v[96:99], v[196:199], v[238:241], v[162:165]
	v_mfma_f32_16x16x32_bf16 v[68:71], v[192:195], v[108:111], v[68:71]
	v_mfma_f32_16x16x32_bf16 v[72:75], v[200:203], v[108:111], v[72:75]
	v_mfma_f32_16x16x32_bf16 v[76:79], v[192:195], v[220:223], v[76:79]
	v_mfma_f32_16x16x32_bf16 v[80:83], v[200:203], v[220:223], v[80:83]
	v_mfma_f32_16x16x32_bf16 v[84:87], v[192:195], v[234:237], v[84:87]
	v_mfma_f32_16x16x32_bf16 v[88:91], v[200:203], v[234:237], v[88:91]
	v_mfma_f32_16x16x32_bf16 v[92:95], v[192:195], v[242:245], v[92:95]
	v_mfma_f32_16x16x32_bf16 v[96:99], v[200:203], v[242:245], v[96:99]
	s_setprio 0
	s_setprio 1
	v_mfma_f32_16x16x32_bf16 v[100:103], v[204:207], v[104:107], v[116:119]
	v_mfma_f32_16x16x32_bf16 v[104:107], v[212:215], v[104:107], v[124:127]
	v_mfma_f32_16x16x32_bf16 v[100:103], v[208:211], v[108:111], v[100:103]
	v_mfma_f32_16x16x32_bf16 v[104:107], v[216:219], v[108:111], v[104:107]
	v_mfma_f32_16x16x32_bf16 v[108:111], v[204:207], v[112:115], v[166:169]
	v_mfma_f32_16x16x32_bf16 v[112:115], v[212:215], v[112:115], v[170:173]
	v_mfma_f32_16x16x32_bf16 v[116:119], v[204:207], v[224:227], v[174:177]
	v_mfma_f32_16x16x32_bf16 v[120:123], v[212:215], v[224:227], v[120:123]
	v_mfma_f32_16x16x32_bf16 v[124:127], v[204:207], v[238:241], v[178:181]
	v_mfma_f32_16x16x32_bf16 v[128:131], v[212:215], v[238:241], v[128:131]
	v_mfma_f32_16x16x32_bf16 v[108:111], v[208:211], v[220:223], v[108:111]
	v_mfma_f32_16x16x32_bf16 v[112:115], v[216:219], v[220:223], v[112:115]
	v_mfma_f32_16x16x32_bf16 v[116:119], v[208:211], v[234:237], v[116:119]
	s_setprio 2
	s_barrier
	v_mfma_f32_16x16x32_bf16 v[120:123], v[216:219], v[234:237], v[120:123]
	v_mfma_f32_16x16x32_bf16 v[124:127], v[208:211], v[242:245], v[124:127]
	v_mfma_f32_16x16x32_bf16 v[128:131], v[216:219], v[242:245], v[128:131]
	s_setprio 0
	s_add_i32 s43, s43, 2
	s_cmp_ge_i32 s43, s42
	s_cbranch_scc0 .LBB0_1625
	v_mov_b32_e32 v192, v2
	s_branch .LBB0_1628

.LBB0_1629:
	s_add_u32 s12, s14, 0xfff80080
	s_addc_u32 s13, s15, -1
	s_add_i32 s29, 0, 0x10000
	s_cmp_eq_u32 s28, 28
	s_cselect_b32 s17, s9, s13
	s_cselect_b32 s16, s8, s12
	s_cselect_b32 s13, s11, s27
	s_cselect_b32 s12, s10, s26
	s_add_i32 s51, 0, 0x14000
	v_add_u32_e32 v144, s29, v232
	v_add_u32_e32 v160, s51, v232
	s_waitcnt lgkmcnt(0)
	ds_read_b128 v[132:135], v144
	ds_read_b128 v[136:139], v144 offset:1024
	ds_read_b128 v[140:143], v144 offset:2048
	ds_read_b128 v[144:147], v144 offset:3072
	ds_read_b128 v[148:151], v160
	ds_read_b128 v[152:155], v160 offset:1024
	ds_read_b128 v[156:159], v160 offset:2048
	ds_read_b128 v[160:163], v160 offset:3072
	s_mov_b32 m0, s66
	v_add_u32_e32 v210, 0, v231
	ds_read_b128 v[164:167], v210
	ds_read_b128 v[168:171], v210 offset:1024
	ds_read_b128 v[172:175], v210 offset:2048
	ds_read_b128 v[176:179], v210 offset:3072
	ds_read_b128 v[180:183], v210 offset:4096
	ds_read_b128 v[184:187], v210 offset:5120
	ds_read_b128 v[194:197], v210 offset:6144
	ds_read_b128 v[198:201], v210 offset:7168
	global_load_lds_dwordx4 v2, s[14:15]
	s_mov_b32 m0, s67
	v_mov_b32_e32 v189, v3
	global_load_lds_dwordx4 v188, s[14:15]
	s_waitcnt vmcnt(8)
	s_waitcnt lgkmcnt(0)
	s_barrier
	s_setprio 1
	s_waitcnt lgkmcnt(0)
	v_mfma_f32_16x16x32_bf16 v[4:7], v[132:135], v[164:167], v[4:7]
	v_mfma_f32_16x16x32_bf16 v[4:7], v[136:139], v[168:171], v[4:7]
	v_mfma_f32_16x16x32_bf16 v[8:11], v[144:147], v[168:171], v[8:11]
	v_mfma_f32_16x16x32_bf16 v[8:11], v[140:143], v[164:167], v[8:11]
	v_mfma_f32_16x16x32_bf16 v[16:19], v[140:143], v[172:175], v[16:19]
	v_mfma_f32_16x16x32_bf16 v[16:19], v[144:147], v[176:179], v[16:19]
	v_mfma_f32_16x16x32_bf16 v[12:15], v[136:139], v[176:179], v[12:15]
	v_mfma_f32_16x16x32_bf16 v[12:15], v[132:135], v[172:175], v[12:15]
	v_mfma_f32_16x16x32_bf16 v[20:23], v[132:135], v[180:183], v[20:23]
	v_mfma_f32_16x16x32_bf16 v[20:23], v[136:139], v[184:187], v[20:23]
	v_mfma_f32_16x16x32_bf16 v[24:27], v[144:147], v[184:187], v[24:27]
	v_mfma_f32_16x16x32_bf16 v[24:27], v[140:143], v[180:183], v[24:27]
	v_mfma_f32_16x16x32_bf16 v[32:35], v[140:143], v[194:197], v[32:35]
	v_mfma_f32_16x16x32_bf16 v[32:35], v[144:147], v[198:201], v[32:35]
	v_mfma_f32_16x16x32_bf16 v[28:31], v[136:139], v[198:201], v[28:31]
	v_mfma_f32_16x16x32_bf16 v[28:31], v[132:135], v[194:197], v[28:31]
	s_setprio 0
	s_setprio 1
	v_mfma_f32_16x16x32_bf16 v[36:39], v[148:151], v[164:167], v[36:39]
	v_mfma_f32_16x16x32_bf16 v[36:39], v[152:155], v[168:171], v[36:39]
	v_mfma_f32_16x16x32_bf16 v[40:43], v[160:163], v[168:171], v[40:43]
	v_mfma_f32_16x16x32_bf16 v[40:43], v[156:159], v[164:167], v[40:43]
	v_mfma_f32_16x16x32_bf16 v[48:51], v[156:159], v[172:175], v[48:51]
	v_mfma_f32_16x16x32_bf16 v[48:51], v[160:163], v[176:179], v[48:51]
	v_mfma_f32_16x16x32_bf16 v[44:47], v[152:155], v[176:179], v[44:47]
	v_mfma_f32_16x16x32_bf16 v[44:47], v[148:151], v[172:175], v[44:47]
	v_mfma_f32_16x16x32_bf16 v[52:55], v[148:151], v[180:183], v[52:55]
	v_mfma_f32_16x16x32_bf16 v[52:55], v[152:155], v[184:187], v[52:55]
	v_mfma_f32_16x16x32_bf16 v[56:59], v[160:163], v[184:187], v[56:59]
	v_mfma_f32_16x16x32_bf16 v[56:59], v[156:159], v[180:183], v[56:59]
	v_mfma_f32_16x16x32_bf16 v[64:67], v[156:159], v[194:197], v[64:67]
	s_setprio 2
	s_barrier
	v_mfma_f32_16x16x32_bf16 v[64:67], v[160:163], v[198:201], v[64:67]
	v_mfma_f32_16x16x32_bf16 v[60:63], v[152:155], v[198:201], v[60:63]
	v_mfma_f32_16x16x32_bf16 v[60:63], v[148:151], v[194:197], v[60:63]
	s_setprio 0
	s_add_i32 s29, s29, s56
	s_mov_b32 m0, s29
	ds_read_b128 v[164:167], v210 offset:16384
	ds_read_b128 v[168:171], v210 offset:17408
	ds_read_b128 v[172:175], v210 offset:18432
	ds_read_b128 v[176:179], v210 offset:19456
	ds_read_b128 v[180:183], v210 offset:20480
	ds_read_b128 v[184:187], v210 offset:21504
	ds_read_b128 v[194:197], v210 offset:22528
	ds_read_b128 v[198:201], v210 offset:23552
	global_load_lds_dwordx4 v192, s[12:13]
	s_add_i32 m0, s29, 0x2000
	s_add_u32 s42, s12, 0x80000
	s_addc_u32 s43, s13, 0
	s_add_i32 s29, s51, s56
	global_load_lds_dwordx4 v190, s[12:13]
	s_mov_b32 m0, s29
	v_mov_b32_e32 v193, v3
	global_load_lds_dwordx4 v192, s[42:43]
	s_add_i32 m0, s29, 0x2000
	v_mov_b32_e32 v191, v3
	global_load_lds_dwordx4 v190, s[42:43]
	s_mov_b32 m0, s57
	v_lshl_add_u64 v[202:203], s[12:13], 0, v[192:193]
	global_load_lds_dwordx4 v2, s[16:17]
	s_mov_b32 m0, s58
	v_lshl_add_u64 v[204:205], s[12:13], 0, v[190:191]
	global_load_lds_dwordx4 v188, s[16:17]
	s_waitcnt vmcnt(8)
	s_waitcnt lgkmcnt(0)
	v_lshl_add_u64 v[206:207], s[16:17], 0, v[2:3]
	v_lshl_add_u64 v[208:209], s[16:17], 0, v[188:189]
	s_barrier
	s_setprio 1
	s_waitcnt lgkmcnt(0)
	v_mfma_f32_16x16x32_bf16 v[68:71], v[132:135], v[164:167], v[68:71]
	v_mfma_f32_16x16x32_bf16 v[68:71], v[136:139], v[168:171], v[68:71]
	v_mfma_f32_16x16x32_bf16 v[72:75], v[144:147], v[168:171], v[72:75]
	v_mfma_f32_16x16x32_bf16 v[72:75], v[140:143], v[164:167], v[72:75]
	v_mfma_f32_16x16x32_bf16 v[80:83], v[140:143], v[172:175], v[80:83]
	v_mfma_f32_16x16x32_bf16 v[80:83], v[144:147], v[176:179], v[80:83]
	v_mfma_f32_16x16x32_bf16 v[76:79], v[136:139], v[176:179], v[76:79]
	v_mfma_f32_16x16x32_bf16 v[76:79], v[132:135], v[172:175], v[76:79]
	v_mfma_f32_16x16x32_bf16 v[84:87], v[132:135], v[180:183], v[84:87]
	v_mfma_f32_16x16x32_bf16 v[84:87], v[136:139], v[184:187], v[84:87]
	v_mfma_f32_16x16x32_bf16 v[88:91], v[144:147], v[184:187], v[88:91]
	v_mfma_f32_16x16x32_bf16 v[88:91], v[140:143], v[180:183], v[88:91]
	v_mfma_f32_16x16x32_bf16 v[96:99], v[140:143], v[194:197], v[96:99]
	v_mfma_f32_16x16x32_bf16 v[96:99], v[144:147], v[198:201], v[96:99]
	v_mfma_f32_16x16x32_bf16 v[92:95], v[136:139], v[198:201], v[92:95]
	v_mfma_f32_16x16x32_bf16 v[92:95], v[132:135], v[194:197], v[92:95]
	s_setprio 0
	s_setprio 1
	v_mfma_f32_16x16x32_bf16 v[100:103], v[148:151], v[164:167], v[100:103]
	v_mfma_f32_16x16x32_bf16 v[100:103], v[152:155], v[168:171], v[100:103]
	v_mfma_f32_16x16x32_bf16 v[104:107], v[160:163], v[168:171], v[104:107]
	v_mfma_f32_16x16x32_bf16 v[104:107], v[156:159], v[164:167], v[104:107]
	v_mfma_f32_16x16x32_bf16 v[112:115], v[156:159], v[172:175], v[112:115]
	v_mfma_f32_16x16x32_bf16 v[112:115], v[160:163], v[176:179], v[112:115]
	v_mfma_f32_16x16x32_bf16 v[108:111], v[152:155], v[176:179], v[108:111]
	v_mfma_f32_16x16x32_bf16 v[108:111], v[148:151], v[172:175], v[108:111]
	v_mfma_f32_16x16x32_bf16 v[116:119], v[148:151], v[180:183], v[116:119]
	v_mfma_f32_16x16x32_bf16 v[116:119], v[152:155], v[184:187], v[116:119]
	v_mfma_f32_16x16x32_bf16 v[120:123], v[160:163], v[184:187], v[120:123]
	v_mfma_f32_16x16x32_bf16 v[120:123], v[156:159], v[180:183], v[120:123]
	v_mfma_f32_16x16x32_bf16 v[128:131], v[156:159], v[194:197], v[128:131]
	s_setprio 2
	s_barrier
	v_mfma_f32_16x16x32_bf16 v[128:131], v[160:163], v[198:201], v[128:131]
	v_mfma_f32_16x16x32_bf16 v[124:127], v[152:155], v[198:201], v[124:127]
	v_mfma_f32_16x16x32_bf16 v[124:127], v[148:151], v[194:197], v[124:127]
	s_setprio 0
	s_add_i32 s29, 0, 0x18000
	s_add_i32 s42, 0, 0x1c000
	v_add_u32_e32 v144, s29, v232
	v_add_u32_e32 v160, s42, v232
	ds_read_b128 v[132:135], v144
	ds_read_b128 v[136:139], v144 offset:1024
	ds_read_b128 v[140:143], v144 offset:2048
	ds_read_b128 v[144:147], v144 offset:3072
	ds_read_b128 v[148:151], v160
	ds_read_b128 v[152:155], v160 offset:1024
	ds_read_b128 v[156:159], v160 offset:2048
	ds_read_b128 v[160:163], v160 offset:3072
	s_add_u32 s16, s16, 0x80000
	s_addc_u32 s17, s17, 0
	s_mov_b32 m0, s59
	ds_read_b128 v[164:167], v210 offset:32768
	ds_read_b128 v[168:171], v210 offset:33792
	ds_read_b128 v[172:175], v210 offset:34816
	ds_read_b128 v[176:179], v210 offset:35840
	ds_read_b128 v[180:183], v210 offset:36864
	ds_read_b128 v[184:187], v210 offset:37888
	ds_read_b128 v[194:197], v210 offset:38912
	ds_read_b128 v[198:201], v210 offset:39936
	global_load_lds_dwordx4 v2, s[16:17]
	s_mov_b32 m0, s60
	s_nop 0
	global_load_lds_dwordx4 v188, s[16:17]
	s_waitcnt vmcnt(8)
	s_waitcnt lgkmcnt(0)
	s_barrier
	s_setprio 1
	s_waitcnt lgkmcnt(0)
	v_mfma_f32_16x16x32_bf16 v[4:7], v[132:135], v[164:167], v[4:7]
	v_mfma_f32_16x16x32_bf16 v[4:7], v[136:139], v[168:171], v[4:7]
	v_mfma_f32_16x16x32_bf16 v[8:11], v[144:147], v[168:171], v[8:11]
	v_mfma_f32_16x16x32_bf16 v[8:11], v[140:143], v[164:167], v[8:11]
	v_mfma_f32_16x16x32_bf16 v[16:19], v[140:143], v[172:175], v[16:19]
	v_mfma_f32_16x16x32_bf16 v[16:19], v[144:147], v[176:179], v[16:19]
	v_mfma_f32_16x16x32_bf16 v[12:15], v[136:139], v[176:179], v[12:15]
	v_mfma_f32_16x16x32_bf16 v[12:15], v[132:135], v[172:175], v[12:15]
	v_mfma_f32_16x16x32_bf16 v[20:23], v[132:135], v[180:183], v[20:23]
	v_mfma_f32_16x16x32_bf16 v[20:23], v[136:139], v[184:187], v[20:23]
	v_mfma_f32_16x16x32_bf16 v[24:27], v[144:147], v[184:187], v[24:27]
	v_mfma_f32_16x16x32_bf16 v[24:27], v[140:143], v[180:183], v[24:27]
	v_mfma_f32_16x16x32_bf16 v[32:35], v[140:143], v[194:197], v[32:35]
	v_mfma_f32_16x16x32_bf16 v[32:35], v[144:147], v[198:201], v[32:35]
	v_mfma_f32_16x16x32_bf16 v[28:31], v[136:139], v[198:201], v[28:31]
	v_mfma_f32_16x16x32_bf16 v[28:31], v[132:135], v[194:197], v[28:31]
	s_setprio 0
	s_setprio 1
	v_mfma_f32_16x16x32_bf16 v[36:39], v[148:151], v[164:167], v[36:39]
	v_mfma_f32_16x16x32_bf16 v[36:39], v[152:155], v[168:171], v[36:39]
	v_mfma_f32_16x16x32_bf16 v[40:43], v[160:163], v[168:171], v[40:43]
	v_mfma_f32_16x16x32_bf16 v[40:43], v[156:159], v[164:167], v[40:43]
	v_mfma_f32_16x16x32_bf16 v[48:51], v[156:159], v[172:175], v[48:51]
	v_mfma_f32_16x16x32_bf16 v[48:51], v[160:163], v[176:179], v[48:51]
	v_mfma_f32_16x16x32_bf16 v[44:47], v[152:155], v[176:179], v[44:47]
	v_mfma_f32_16x16x32_bf16 v[44:47], v[148:151], v[172:175], v[44:47]
	v_mfma_f32_16x16x32_bf16 v[52:55], v[148:151], v[180:183], v[52:55]
	v_mfma_f32_16x16x32_bf16 v[52:55], v[152:155], v[184:187], v[52:55]
	v_mfma_f32_16x16x32_bf16 v[56:59], v[160:163], v[184:187], v[56:59]
	v_mfma_f32_16x16x32_bf16 v[56:59], v[156:159], v[180:183], v[56:59]
	v_mfma_f32_16x16x32_bf16 v[64:67], v[156:159], v[194:197], v[64:67]
	s_setprio 2
	s_barrier
	v_mfma_f32_16x16x32_bf16 v[64:67], v[160:163], v[198:201], v[64:67]
	v_mfma_f32_16x16x32_bf16 v[60:63], v[152:155], v[198:201], v[60:63]
	v_mfma_f32_16x16x32_bf16 v[60:63], v[148:151], v[194:197], v[60:63]
	s_setprio 0
	s_add_i32 s16, s29, s56
	v_lshl_add_u64 v[202:203], v[202:203], 0, s[86:87]
	s_mov_b32 m0, s16
	ds_read_b128 v[164:167], v210 offset:49152
	ds_read_b128 v[168:171], v210 offset:50176
	ds_read_b128 v[172:175], v210 offset:51200
	ds_read_b128 v[176:179], v210 offset:52224
	ds_read_b128 v[180:183], v210 offset:53248
	ds_read_b128 v[184:187], v210 offset:54272
	ds_read_b128 v[194:197], v210 offset:55296
	ds_read_b128 v[198:201], v210 offset:56320
	global_load_lds_dwordx4 v[202:203], off
	s_add_i32 m0, s16, 0x2000
	s_add_u32 s12, s12, 0x80080
	v_lshl_add_u64 v[202:203], v[204:205], 0, s[86:87]
	s_addc_u32 s13, s13, 0
	s_add_i32 s16, s42, s56
	global_load_lds_dwordx4 v[202:203], off
	s_mov_b32 m0, s16
	v_lshl_add_u64 v[202:203], v[206:207], 0, s[86:87]
	global_load_lds_dwordx4 v192, s[12:13]
	s_add_i32 m0, s16, 0x2000
	s_nop 0
	global_load_lds_dwordx4 v190, s[12:13]
	s_mov_b32 m0, s64
	s_nop 0
	global_load_lds_dwordx4 v[202:203], off
	v_lshl_add_u64 v[202:203], v[208:209], 0, s[86:87]
	s_mov_b32 m0, s65
	s_nop 0
	global_load_lds_dwordx4 v[202:203], off
	s_waitcnt vmcnt(8)
	s_waitcnt lgkmcnt(0)
	s_barrier
	s_setprio 1
	s_waitcnt lgkmcnt(0)
	v_mfma_f32_16x16x32_bf16 v[68:71], v[132:135], v[164:167], v[68:71]
	v_mfma_f32_16x16x32_bf16 v[68:71], v[136:139], v[168:171], v[68:71]
	v_mfma_f32_16x16x32_bf16 v[72:75], v[144:147], v[168:171], v[72:75]
	v_mfma_f32_16x16x32_bf16 v[72:75], v[140:143], v[164:167], v[72:75]
	v_mfma_f32_16x16x32_bf16 v[80:83], v[140:143], v[172:175], v[80:83]
	v_mfma_f32_16x16x32_bf16 v[80:83], v[144:147], v[176:179], v[80:83]
	v_mfma_f32_16x16x32_bf16 v[76:79], v[136:139], v[176:179], v[76:79]
	v_mfma_f32_16x16x32_bf16 v[76:79], v[132:135], v[172:175], v[76:79]
	v_mfma_f32_16x16x32_bf16 v[84:87], v[132:135], v[180:183], v[84:87]
	v_mfma_f32_16x16x32_bf16 v[84:87], v[136:139], v[184:187], v[84:87]
	v_mfma_f32_16x16x32_bf16 v[88:91], v[144:147], v[184:187], v[88:91]
	v_mfma_f32_16x16x32_bf16 v[88:91], v[140:143], v[180:183], v[88:91]
	v_mfma_f32_16x16x32_bf16 v[96:99], v[140:143], v[194:197], v[96:99]
	v_mfma_f32_16x16x32_bf16 v[96:99], v[144:147], v[198:201], v[96:99]
	v_mfma_f32_16x16x32_bf16 v[92:95], v[136:139], v[198:201], v[92:95]
	v_mfma_f32_16x16x32_bf16 v[92:95], v[132:135], v[194:197], v[92:95]
	s_setprio 0
	s_setprio 1
	v_mfma_f32_16x16x32_bf16 v[100:103], v[148:151], v[164:167], v[100:103]
	v_mfma_f32_16x16x32_bf16 v[100:103], v[152:155], v[168:171], v[100:103]
	v_mfma_f32_16x16x32_bf16 v[104:107], v[160:163], v[168:171], v[104:107]
	v_mfma_f32_16x16x32_bf16 v[104:107], v[156:159], v[164:167], v[104:107]
	v_mfma_f32_16x16x32_bf16 v[112:115], v[156:159], v[172:175], v[112:115]
	v_mfma_f32_16x16x32_bf16 v[112:115], v[160:163], v[176:179], v[112:115]
	v_mfma_f32_16x16x32_bf16 v[108:111], v[152:155], v[176:179], v[108:111]
	v_mfma_f32_16x16x32_bf16 v[108:111], v[148:151], v[172:175], v[108:111]
	v_mfma_f32_16x16x32_bf16 v[116:119], v[148:151], v[180:183], v[116:119]
	v_mfma_f32_16x16x32_bf16 v[116:119], v[152:155], v[184:187], v[116:119]
	v_mfma_f32_16x16x32_bf16 v[120:123], v[160:163], v[184:187], v[120:123]
	v_mfma_f32_16x16x32_bf16 v[120:123], v[156:159], v[180:183], v[120:123]
	v_mfma_f32_16x16x32_bf16 v[128:131], v[156:159], v[194:197], v[128:131]
	s_setprio 2
	s_barrier
	v_mfma_f32_16x16x32_bf16 v[128:131], v[160:163], v[198:201], v[128:131]
	v_mfma_f32_16x16x32_bf16 v[124:127], v[152:155], v[198:201], v[124:127]
	v_mfma_f32_16x16x32_bf16 v[124:127], v[148:151], v[194:197], v[124:127]
	s_setprio 0
	s_add_i32 s28, s28, 2
	s_add_u32 s14, s14, 0x100
	s_addc_u32 s15, s15, 0
	s_add_u32 s26, s26, 0x100
	s_addc_u32 s27, s27, 0
	s_cmp_gt_u32 s28, 29
	s_cbranch_scc0 .LBB0_1629
	s_and_b64 vcc, exec, s[48:49]
	s_cbranch_vccz .LBB0_1632
	s_barrier

.LBB0_2065:
	s_add_i32 s51, 0, 0x10000
	s_add_i32 s71, 0, 0x14000
	v_add_u32_e32 v16, s51, v232
	v_add_u32_e32 v32, s71, v232
	ds_read_b128 v[4:7], v16
	ds_read_b128 v[8:11], v16 offset:1024
	ds_read_b128 v[12:15], v16 offset:2048
	ds_read_b128 v[16:19], v16 offset:3072
	ds_read_b128 v[20:23], v32
	ds_read_b128 v[24:27], v32 offset:1024
	ds_read_b128 v[28:31], v32 offset:2048
	ds_read_b128 v[32:35], v32 offset:3072
	v_add_u32_e32 v233, 0, v231
	ds_read_b128 v[36:39], v233
	ds_read_b128 v[40:43], v233 offset:1024
	ds_read_b128 v[44:47], v233 offset:2048
	ds_read_b128 v[48:51], v233 offset:3072
	ds_read_b128 v[52:55], v233 offset:4096
	ds_read_b128 v[56:59], v233 offset:5120
	ds_read_b128 v[60:63], v233 offset:6144
	ds_read_b128 v[64:67], v233 offset:7168
	s_waitcnt vmcnt(8)
	s_waitcnt lgkmcnt(0)
	s_barrier
	s_setprio 1
	s_waitcnt lgkmcnt(0)
	v_mfma_f32_16x16x32_bf16 v[68:71], v[4:7], v[36:39], 0
	v_mfma_f32_16x16x32_bf16 v[68:71], v[8:11], v[40:43], v[68:71]
	v_mfma_f32_16x16x32_bf16 v[72:75], v[12:15], v[36:39], 0
	v_mfma_f32_16x16x32_bf16 v[72:75], v[16:19], v[40:43], v[72:75]
	v_mfma_f32_16x16x32_bf16 v[80:83], v[12:15], v[44:47], 0
	v_mfma_f32_16x16x32_bf16 v[80:83], v[16:19], v[48:51], v[80:83]
	v_mfma_f32_16x16x32_bf16 v[76:79], v[4:7], v[44:47], 0
	v_mfma_f32_16x16x32_bf16 v[76:79], v[8:11], v[48:51], v[76:79]
	v_mfma_f32_16x16x32_bf16 v[84:87], v[4:7], v[52:55], 0
	v_mfma_f32_16x16x32_bf16 v[84:87], v[8:11], v[56:59], v[84:87]
	v_mfma_f32_16x16x32_bf16 v[88:91], v[12:15], v[52:55], 0
	v_mfma_f32_16x16x32_bf16 v[88:91], v[16:19], v[56:59], v[88:91]
	v_mfma_f32_16x16x32_bf16 v[96:99], v[12:15], v[60:63], 0
	v_mfma_f32_16x16x32_bf16 v[96:99], v[16:19], v[64:67], v[96:99]
	v_mfma_f32_16x16x32_bf16 v[92:95], v[4:7], v[60:63], 0
	v_mfma_f32_16x16x32_bf16 v[92:95], v[8:11], v[64:67], v[92:95]
	s_setprio 0
	s_setprio 1
	v_mfma_f32_16x16x32_bf16 v[100:103], v[20:23], v[36:39], 0
	v_mfma_f32_16x16x32_bf16 v[36:39], v[28:31], v[36:39], 0
	v_mfma_f32_16x16x32_bf16 v[104:107], v[20:23], v[44:47], 0
	v_mfma_f32_16x16x32_bf16 v[44:47], v[28:31], v[44:47], 0
	v_mfma_f32_16x16x32_bf16 v[108:111], v[20:23], v[52:55], 0
	v_mfma_f32_16x16x32_bf16 v[52:55], v[28:31], v[52:55], 0
	v_mfma_f32_16x16x32_bf16 v[112:115], v[20:23], v[60:63], 0
	v_mfma_f32_16x16x32_bf16 v[60:63], v[28:31], v[60:63], 0
	v_mfma_f32_16x16x32_bf16 v[100:103], v[24:27], v[40:43], v[100:103]
	v_mfma_f32_16x16x32_bf16 v[40:43], v[32:35], v[40:43], v[36:39]
	v_mfma_f32_16x16x32_bf16 v[104:107], v[24:27], v[48:51], v[104:107]
	v_mfma_f32_16x16x32_bf16 v[48:51], v[32:35], v[48:51], v[44:47]
	v_mfma_f32_16x16x32_bf16 v[108:111], v[24:27], v[56:59], v[108:111]
	s_setprio 2
	s_barrier
	v_mfma_f32_16x16x32_bf16 v[56:59], v[32:35], v[56:59], v[52:55]
	v_mfma_f32_16x16x32_bf16 v[112:115], v[24:27], v[64:67], v[112:115]
	v_mfma_f32_16x16x32_bf16 v[64:67], v[32:35], v[64:67], v[60:63]
	s_setprio 0
	v_lshl_add_u64 v[186:187], s[12:13], 0, v[2:3]
	s_add_i32 s51, s51, s38
	v_mov_b32_e32 v191, v3
	v_lshl_add_u64 v[134:135], v[186:187], 0, s[74:75]
	s_mov_b32 m0, s51
	v_lshl_add_u64 v[246:247], s[12:13], 0, v[190:191]
	ds_read_b128 v[36:39], v233 offset:16384
	ds_read_b128 v[44:47], v233 offset:17408
	ds_read_b128 v[52:55], v233 offset:18432
	ds_read_b128 v[60:63], v233 offset:19456
	ds_read_b128 v[116:119], v233 offset:20480
	ds_read_b128 v[120:123], v233 offset:21504
	ds_read_b128 v[124:127], v233 offset:22528
	ds_read_b128 v[128:131], v233 offset:23552
	global_load_lds_dwordx4 v[134:135], off
	v_lshl_add_u64 v[134:135], v[246:247], 0, s[74:75]
	s_add_i32 m0, s51, 0x2000
	s_add_i32 s51, s71, s38
	global_load_lds_dwordx4 v[134:135], off
	s_mov_b32 m0, s51
	v_mov_b32_e32 v133, v3
	global_load_lds_dwordx4 v2, s[16:17]
	s_add_i32 m0, s51, 0x2000
	v_lshl_add_u64 v[248:249], s[14:15], 0, v[132:133]
	v_mov_b32_e32 v189, v3
	global_load_lds_dwordx4 v190, s[16:17]
	v_lshl_add_u64 v[134:135], v[248:249], 0, s[74:75]
	s_mov_b32 m0, s56
	v_lshl_add_u64 v[250:251], s[14:15], 0, v[188:189]
	global_load_lds_dwordx4 v[134:135], off
	v_lshl_add_u64 v[134:135], v[250:251], 0, s[74:75]
	s_mov_b32 m0, s57
	s_nop 0
	global_load_lds_dwordx4 v[134:135], off
	s_waitcnt vmcnt(8)
	s_waitcnt lgkmcnt(0)
	s_barrier
	s_setprio 1
	s_waitcnt lgkmcnt(0)
	v_mfma_f32_16x16x32_bf16 v[134:137], v[4:7], v[36:39], 0
	v_mfma_f32_16x16x32_bf16 v[138:141], v[12:15], v[36:39], 0
	v_mfma_f32_16x16x32_bf16 v[142:145], v[4:7], v[52:55], 0
	v_mfma_f32_16x16x32_bf16 v[146:149], v[12:15], v[52:55], 0
	v_mfma_f32_16x16x32_bf16 v[150:153], v[4:7], v[116:119], 0
	v_mfma_f32_16x16x32_bf16 v[154:157], v[12:15], v[116:119], 0
	v_mfma_f32_16x16x32_bf16 v[4:7], v[4:7], v[124:127], 0
	v_mfma_f32_16x16x32_bf16 v[12:15], v[12:15], v[124:127], 0
	v_mfma_f32_16x16x32_bf16 v[134:137], v[8:11], v[44:47], v[134:137]
	v_mfma_f32_16x16x32_bf16 v[138:141], v[16:19], v[44:47], v[138:141]
	v_mfma_f32_16x16x32_bf16 v[142:145], v[8:11], v[60:63], v[142:145]
	v_mfma_f32_16x16x32_bf16 v[146:149], v[16:19], v[60:63], v[146:149]
	v_mfma_f32_16x16x32_bf16 v[150:153], v[8:11], v[120:123], v[150:153]
	v_mfma_f32_16x16x32_bf16 v[154:157], v[16:19], v[120:123], v[154:157]
	v_mfma_f32_16x16x32_bf16 v[158:161], v[8:11], v[128:131], v[4:7]
	v_mfma_f32_16x16x32_bf16 v[162:165], v[16:19], v[128:131], v[12:15]
	s_setprio 0
	s_setprio 1
	v_mfma_f32_16x16x32_bf16 v[4:7], v[20:23], v[36:39], 0
	v_mfma_f32_16x16x32_bf16 v[8:11], v[28:31], v[36:39], 0
	v_mfma_f32_16x16x32_bf16 v[12:15], v[20:23], v[52:55], 0
	v_mfma_f32_16x16x32_bf16 v[16:19], v[28:31], v[52:55], 0
	v_mfma_f32_16x16x32_bf16 v[36:39], v[20:23], v[116:119], 0
	v_mfma_f32_16x16x32_bf16 v[52:55], v[28:31], v[116:119], 0
	v_mfma_f32_16x16x32_bf16 v[20:23], v[20:23], v[124:127], 0
	v_mfma_f32_16x16x32_bf16 v[28:31], v[28:31], v[124:127], 0
	v_mfma_f32_16x16x32_bf16 v[116:119], v[24:27], v[44:47], v[4:7]
	v_mfma_f32_16x16x32_bf16 v[124:127], v[32:35], v[44:47], v[8:11]
	v_mfma_f32_16x16x32_bf16 v[174:177], v[24:27], v[120:123], v[36:39]
	v_mfma_f32_16x16x32_bf16 v[120:123], v[32:35], v[120:123], v[52:55]
	v_mfma_f32_16x16x32_bf16 v[178:181], v[24:27], v[128:131], v[20:23]
	s_setprio 2
	s_barrier
	v_mfma_f32_16x16x32_bf16 v[128:131], v[32:35], v[128:131], v[28:31]
	v_mfma_f32_16x16x32_bf16 v[166:169], v[24:27], v[60:63], v[12:15]
	v_mfma_f32_16x16x32_bf16 v[170:173], v[32:35], v[60:63], v[16:19]
	s_setprio 0
	s_add_i32 s51, 0, 0x18000
	v_add_u32_e32 v4, s51, v232
	s_add_i32 s71, 0, 0x1c000
	ds_read_b128 v[182:185], v4
	ds_read_b128 v[192:195], v4 offset:1024
	ds_read_b128 v[196:199], v4 offset:2048
	ds_read_b128 v[200:203], v4 offset:3072
	v_add_u32_e32 v4, s71, v232
	ds_read_b128 v[204:207], v4
	ds_read_b128 v[208:211], v4 offset:1024
	ds_read_b128 v[212:215], v4 offset:2048
	ds_read_b128 v[216:219], v4 offset:3072
	s_mov_b32 m0, s58
	ds_read_b128 v[44:47], v233 offset:32768
	ds_read_b128 v[52:55], v233 offset:33792
	ds_read_b128 v[60:63], v233 offset:34816
	ds_read_b128 v[220:223], v233 offset:35840
	ds_read_b128 v[224:227], v233 offset:36864
	ds_read_b128 v[234:237], v233 offset:37888
	ds_read_b128 v[238:241], v233 offset:38912
	ds_read_b128 v[242:245], v233 offset:39936
	global_load_lds_dwordx4 v132, s[26:27]
	s_mov_b32 m0, s59
	s_nop 0
	global_load_lds_dwordx4 v188, s[26:27]
	s_waitcnt vmcnt(8)
	s_waitcnt lgkmcnt(0)
	s_barrier
	s_setprio 1
	s_waitcnt lgkmcnt(0)
	v_mfma_f32_16x16x32_bf16 v[4:7], v[182:185], v[44:47], v[68:71]
	v_mfma_f32_16x16x32_bf16 v[8:11], v[196:199], v[44:47], v[72:75]
	v_mfma_f32_16x16x32_bf16 v[12:15], v[182:185], v[60:63], v[76:79]
	v_mfma_f32_16x16x32_bf16 v[16:19], v[196:199], v[60:63], v[80:83]
	v_mfma_f32_16x16x32_bf16 v[20:23], v[182:185], v[224:227], v[84:87]
	v_mfma_f32_16x16x32_bf16 v[24:27], v[196:199], v[224:227], v[88:91]
	v_mfma_f32_16x16x32_bf16 v[28:31], v[182:185], v[238:241], v[92:95]
	v_mfma_f32_16x16x32_bf16 v[32:35], v[196:199], v[238:241], v[96:99]
	v_mfma_f32_16x16x32_bf16 v[4:7], v[192:195], v[52:55], v[4:7]
	v_mfma_f32_16x16x32_bf16 v[8:11], v[200:203], v[52:55], v[8:11]
	v_mfma_f32_16x16x32_bf16 v[12:15], v[192:195], v[220:223], v[12:15]
	v_mfma_f32_16x16x32_bf16 v[16:19], v[200:203], v[220:223], v[16:19]
	v_mfma_f32_16x16x32_bf16 v[20:23], v[192:195], v[234:237], v[20:23]
	v_mfma_f32_16x16x32_bf16 v[24:27], v[200:203], v[234:237], v[24:27]
	v_mfma_f32_16x16x32_bf16 v[28:31], v[192:195], v[242:245], v[28:31]
	v_mfma_f32_16x16x32_bf16 v[32:35], v[200:203], v[242:245], v[32:35]
	s_setprio 0
	s_setprio 1
	v_mfma_f32_16x16x32_bf16 v[36:39], v[204:207], v[44:47], v[100:103]
	v_mfma_f32_16x16x32_bf16 v[40:43], v[212:215], v[44:47], v[40:43]
	v_mfma_f32_16x16x32_bf16 v[36:39], v[208:211], v[52:55], v[36:39]
	v_mfma_f32_16x16x32_bf16 v[40:43], v[216:219], v[52:55], v[40:43]
	v_mfma_f32_16x16x32_bf16 v[44:47], v[204:207], v[60:63], v[104:107]
	v_mfma_f32_16x16x32_bf16 v[48:51], v[212:215], v[60:63], v[48:51]
	v_mfma_f32_16x16x32_bf16 v[52:55], v[204:207], v[224:227], v[108:111]
	v_mfma_f32_16x16x32_bf16 v[56:59], v[212:215], v[224:227], v[56:59]
	v_mfma_f32_16x16x32_bf16 v[60:63], v[204:207], v[238:241], v[112:115]
	v_mfma_f32_16x16x32_bf16 v[64:67], v[212:215], v[238:241], v[64:67]
	v_mfma_f32_16x16x32_bf16 v[44:47], v[208:211], v[220:223], v[44:47]
	v_mfma_f32_16x16x32_bf16 v[48:51], v[216:219], v[220:223], v[48:51]
	v_mfma_f32_16x16x32_bf16 v[52:55], v[208:211], v[234:237], v[52:55]
	s_setprio 2
	s_barrier
	v_mfma_f32_16x16x32_bf16 v[56:59], v[216:219], v[234:237], v[56:59]
	v_mfma_f32_16x16x32_bf16 v[60:63], v[208:211], v[242:245], v[60:63]
	v_mfma_f32_16x16x32_bf16 v[64:67], v[216:219], v[242:245], v[64:67]
	s_setprio 0
	s_add_i32 s51, s51, s38
	v_lshl_add_u64 v[68:69], v[186:187], 0, s[24:25]
	s_mov_b32 m0, s51
	ds_read_b128 v[104:107], v233 offset:49152
	ds_read_b128 v[108:111], v233 offset:50176
	ds_read_b128 v[112:115], v233 offset:51200
	ds_read_b128 v[220:223], v233 offset:52224
	ds_read_b128 v[224:227], v233 offset:53248
	ds_read_b128 v[234:237], v233 offset:54272
	ds_read_b128 v[238:241], v233 offset:55296
	ds_read_b128 v[242:245], v233 offset:56320
	global_load_lds_dwordx4 v[68:69], off
	v_lshl_add_u64 v[68:69], v[246:247], 0, s[24:25]
	s_add_i32 m0, s51, 0x2000
	s_add_i32 s51, s71, s38
	global_load_lds_dwordx4 v[68:69], off
	s_mov_b32 m0, s51
	v_lshl_add_u64 v[68:69], v[248:249], 0, s[24:25]
	global_load_lds_dwordx4 v2, s[28:29]
	s_add_i32 m0, s51, 0x2000
	s_nop 0
	global_load_lds_dwordx4 v190, s[28:29]
	s_mov_b32 m0, s63
	s_nop 0
	global_load_lds_dwordx4 v[68:69], off
	v_lshl_add_u64 v[68:69], v[250:251], 0, s[24:25]
	s_mov_b32 m0, s64
	s_nop 0
	global_load_lds_dwordx4 v[68:69], off
	s_waitcnt vmcnt(8)
	s_waitcnt lgkmcnt(0)
	s_barrier
	s_setprio 1
	s_waitcnt lgkmcnt(0)
	v_mfma_f32_16x16x32_bf16 v[68:71], v[182:185], v[104:107], v[134:137]
	v_mfma_f32_16x16x32_bf16 v[72:75], v[196:199], v[104:107], v[138:141]
	v_mfma_f32_16x16x32_bf16 v[76:79], v[182:185], v[112:115], v[142:145]
	v_mfma_f32_16x16x32_bf16 v[80:83], v[196:199], v[112:115], v[146:149]
	v_mfma_f32_16x16x32_bf16 v[84:87], v[182:185], v[224:227], v[150:153]
	v_mfma_f32_16x16x32_bf16 v[88:91], v[196:199], v[224:227], v[154:157]
	v_mfma_f32_16x16x32_bf16 v[92:95], v[182:185], v[238:241], v[158:161]
	v_mfma_f32_16x16x32_bf16 v[96:99], v[196:199], v[238:241], v[162:165]
	v_mfma_f32_16x16x32_bf16 v[68:71], v[192:195], v[108:111], v[68:71]
	v_mfma_f32_16x16x32_bf16 v[72:75], v[200:203], v[108:111], v[72:75]
	v_mfma_f32_16x16x32_bf16 v[76:79], v[192:195], v[220:223], v[76:79]
	v_mfma_f32_16x16x32_bf16 v[80:83], v[200:203], v[220:223], v[80:83]
	v_mfma_f32_16x16x32_bf16 v[84:87], v[192:195], v[234:237], v[84:87]
	v_mfma_f32_16x16x32_bf16 v[88:91], v[200:203], v[234:237], v[88:91]
	v_mfma_f32_16x16x32_bf16 v[92:95], v[192:195], v[242:245], v[92:95]
	v_mfma_f32_16x16x32_bf16 v[96:99], v[200:203], v[242:245], v[96:99]
	s_setprio 0
	s_setprio 1
	v_mfma_f32_16x16x32_bf16 v[100:103], v[204:207], v[104:107], v[116:119]
	v_mfma_f32_16x16x32_bf16 v[104:107], v[212:215], v[104:107], v[124:127]
	v_mfma_f32_16x16x32_bf16 v[100:103], v[208:211], v[108:111], v[100:103]
	v_mfma_f32_16x16x32_bf16 v[104:107], v[216:219], v[108:111], v[104:107]
	v_mfma_f32_16x16x32_bf16 v[108:111], v[204:207], v[112:115], v[166:169]
	v_mfma_f32_16x16x32_bf16 v[112:115], v[212:215], v[112:115], v[170:173]
	v_mfma_f32_16x16x32_bf16 v[116:119], v[204:207], v[224:227], v[174:177]
	v_mfma_f32_16x16x32_bf16 v[120:123], v[212:215], v[224:227], v[120:123]
	v_mfma_f32_16x16x32_bf16 v[124:127], v[204:207], v[238:241], v[178:181]
	v_mfma_f32_16x16x32_bf16 v[128:131], v[212:215], v[238:241], v[128:131]
	v_mfma_f32_16x16x32_bf16 v[108:111], v[208:211], v[220:223], v[108:111]
	v_mfma_f32_16x16x32_bf16 v[112:115], v[216:219], v[220:223], v[112:115]
	v_mfma_f32_16x16x32_bf16 v[116:119], v[208:211], v[234:237], v[116:119]
	s_setprio 2
	s_barrier
	v_mfma_f32_16x16x32_bf16 v[120:123], v[216:219], v[234:237], v[120:123]
	v_mfma_f32_16x16x32_bf16 v[124:127], v[208:211], v[242:245], v[124:127]
	v_mfma_f32_16x16x32_bf16 v[128:131], v[216:219], v[242:245], v[128:131]
	s_setprio 0
	s_add_i32 s45, s45, 2
	s_cmp_ge_i32 s45, s44
	s_cbranch_scc0 .LBB0_2065
	v_mov_b32_e32 v192, v2
	s_branch .LBB0_2068

.LBB0_2069:
	s_add_u32 s12, s14, 0xfff80080
	s_addc_u32 s13, s15, -1
	s_add_i32 s29, 0, 0x10000
	s_cmp_eq_u32 s28, 4
	s_cselect_b32 s17, s9, s13
	s_cselect_b32 s16, s8, s12
	s_cselect_b32 s13, s11, s27
	s_cselect_b32 s12, s10, s26
	s_add_i32 s51, 0, 0x14000
	v_add_u32_e32 v144, s29, v232
	v_add_u32_e32 v160, s51, v232
	s_waitcnt lgkmcnt(0)
	ds_read_b128 v[132:135], v144
	ds_read_b128 v[136:139], v144 offset:1024
	ds_read_b128 v[140:143], v144 offset:2048
	ds_read_b128 v[144:147], v144 offset:3072
	ds_read_b128 v[148:151], v160
	ds_read_b128 v[152:155], v160 offset:1024
	ds_read_b128 v[156:159], v160 offset:2048
	ds_read_b128 v[160:163], v160 offset:3072
	s_mov_b32 m0, s65
	v_add_u32_e32 v210, 0, v231
	ds_read_b128 v[164:167], v210
	ds_read_b128 v[168:171], v210 offset:1024
	ds_read_b128 v[172:175], v210 offset:2048
	ds_read_b128 v[176:179], v210 offset:3072
	ds_read_b128 v[180:183], v210 offset:4096
	ds_read_b128 v[184:187], v210 offset:5120
	ds_read_b128 v[194:197], v210 offset:6144
	ds_read_b128 v[198:201], v210 offset:7168
	global_load_lds_dwordx4 v2, s[14:15]
	s_mov_b32 m0, s66
	v_mov_b32_e32 v189, v3
	global_load_lds_dwordx4 v188, s[14:15]
	s_waitcnt vmcnt(8)
	s_waitcnt lgkmcnt(0)
	s_barrier
	s_setprio 1
	s_waitcnt lgkmcnt(0)
	v_mfma_f32_16x16x32_bf16 v[4:7], v[132:135], v[164:167], v[4:7]
	v_mfma_f32_16x16x32_bf16 v[4:7], v[136:139], v[168:171], v[4:7]
	v_mfma_f32_16x16x32_bf16 v[8:11], v[144:147], v[168:171], v[8:11]
	v_mfma_f32_16x16x32_bf16 v[8:11], v[140:143], v[164:167], v[8:11]
	v_mfma_f32_16x16x32_bf16 v[16:19], v[140:143], v[172:175], v[16:19]
	v_mfma_f32_16x16x32_bf16 v[16:19], v[144:147], v[176:179], v[16:19]
	v_mfma_f32_16x16x32_bf16 v[12:15], v[136:139], v[176:179], v[12:15]
	v_mfma_f32_16x16x32_bf16 v[12:15], v[132:135], v[172:175], v[12:15]
	v_mfma_f32_16x16x32_bf16 v[20:23], v[132:135], v[180:183], v[20:23]
	v_mfma_f32_16x16x32_bf16 v[20:23], v[136:139], v[184:187], v[20:23]
	v_mfma_f32_16x16x32_bf16 v[24:27], v[144:147], v[184:187], v[24:27]
	v_mfma_f32_16x16x32_bf16 v[24:27], v[140:143], v[180:183], v[24:27]
	v_mfma_f32_16x16x32_bf16 v[32:35], v[140:143], v[194:197], v[32:35]
	v_mfma_f32_16x16x32_bf16 v[32:35], v[144:147], v[198:201], v[32:35]
	v_mfma_f32_16x16x32_bf16 v[28:31], v[136:139], v[198:201], v[28:31]
	v_mfma_f32_16x16x32_bf16 v[28:31], v[132:135], v[194:197], v[28:31]
	s_setprio 0
	s_setprio 1
	v_mfma_f32_16x16x32_bf16 v[36:39], v[148:151], v[164:167], v[36:39]
	v_mfma_f32_16x16x32_bf16 v[36:39], v[152:155], v[168:171], v[36:39]
	v_mfma_f32_16x16x32_bf16 v[40:43], v[160:163], v[168:171], v[40:43]
	v_mfma_f32_16x16x32_bf16 v[40:43], v[156:159], v[164:167], v[40:43]
	v_mfma_f32_16x16x32_bf16 v[48:51], v[156:159], v[172:175], v[48:51]
	v_mfma_f32_16x16x32_bf16 v[48:51], v[160:163], v[176:179], v[48:51]
	v_mfma_f32_16x16x32_bf16 v[44:47], v[152:155], v[176:179], v[44:47]
	v_mfma_f32_16x16x32_bf16 v[44:47], v[148:151], v[172:175], v[44:47]
	v_mfma_f32_16x16x32_bf16 v[52:55], v[148:151], v[180:183], v[52:55]
	v_mfma_f32_16x16x32_bf16 v[52:55], v[152:155], v[184:187], v[52:55]
	v_mfma_f32_16x16x32_bf16 v[56:59], v[160:163], v[184:187], v[56:59]
	v_mfma_f32_16x16x32_bf16 v[56:59], v[156:159], v[180:183], v[56:59]
	v_mfma_f32_16x16x32_bf16 v[64:67], v[156:159], v[194:197], v[64:67]
	s_setprio 2
	s_barrier
	v_mfma_f32_16x16x32_bf16 v[64:67], v[160:163], v[198:201], v[64:67]
	v_mfma_f32_16x16x32_bf16 v[60:63], v[152:155], v[198:201], v[60:63]
	v_mfma_f32_16x16x32_bf16 v[60:63], v[148:151], v[194:197], v[60:63]
	s_setprio 0
	s_add_i32 s29, s29, s38
	s_mov_b32 m0, s29
	ds_read_b128 v[164:167], v210 offset:16384
	ds_read_b128 v[168:171], v210 offset:17408
	ds_read_b128 v[172:175], v210 offset:18432
	ds_read_b128 v[176:179], v210 offset:19456
	ds_read_b128 v[180:183], v210 offset:20480
	ds_read_b128 v[184:187], v210 offset:21504
	ds_read_b128 v[194:197], v210 offset:22528
	ds_read_b128 v[198:201], v210 offset:23552
	global_load_lds_dwordx4 v192, s[12:13]
	s_add_i32 m0, s29, 0x2000
	s_add_u32 s44, s12, 0x20000
	s_addc_u32 s45, s13, 0
	s_add_i32 s29, s51, s38
	global_load_lds_dwordx4 v190, s[12:13]
	s_mov_b32 m0, s29
	v_mov_b32_e32 v193, v3
	global_load_lds_dwordx4 v192, s[44:45]
	s_add_i32 m0, s29, 0x2000
	v_mov_b32_e32 v191, v3
	global_load_lds_dwordx4 v190, s[44:45]
	s_mov_b32 m0, s56
	v_lshl_add_u64 v[202:203], s[12:13], 0, v[192:193]
	global_load_lds_dwordx4 v2, s[16:17]
	s_mov_b32 m0, s57
	v_lshl_add_u64 v[204:205], s[12:13], 0, v[190:191]
	global_load_lds_dwordx4 v188, s[16:17]
	s_waitcnt vmcnt(8)
	s_waitcnt lgkmcnt(0)
	v_lshl_add_u64 v[206:207], s[16:17], 0, v[2:3]
	v_lshl_add_u64 v[208:209], s[16:17], 0, v[188:189]
	s_barrier
	s_setprio 1
	s_waitcnt lgkmcnt(0)
	v_mfma_f32_16x16x32_bf16 v[68:71], v[132:135], v[164:167], v[68:71]
	v_mfma_f32_16x16x32_bf16 v[68:71], v[136:139], v[168:171], v[68:71]
	v_mfma_f32_16x16x32_bf16 v[72:75], v[144:147], v[168:171], v[72:75]
	v_mfma_f32_16x16x32_bf16 v[72:75], v[140:143], v[164:167], v[72:75]
	v_mfma_f32_16x16x32_bf16 v[80:83], v[140:143], v[172:175], v[80:83]
	v_mfma_f32_16x16x32_bf16 v[80:83], v[144:147], v[176:179], v[80:83]
	v_mfma_f32_16x16x32_bf16 v[76:79], v[136:139], v[176:179], v[76:79]
	v_mfma_f32_16x16x32_bf16 v[76:79], v[132:135], v[172:175], v[76:79]
	v_mfma_f32_16x16x32_bf16 v[84:87], v[132:135], v[180:183], v[84:87]
	v_mfma_f32_16x16x32_bf16 v[84:87], v[136:139], v[184:187], v[84:87]
	v_mfma_f32_16x16x32_bf16 v[88:91], v[144:147], v[184:187], v[88:91]
	v_mfma_f32_16x16x32_bf16 v[88:91], v[140:143], v[180:183], v[88:91]
	v_mfma_f32_16x16x32_bf16 v[96:99], v[140:143], v[194:197], v[96:99]
	v_mfma_f32_16x16x32_bf16 v[96:99], v[144:147], v[198:201], v[96:99]
	v_mfma_f32_16x16x32_bf16 v[92:95], v[136:139], v[198:201], v[92:95]
	v_mfma_f32_16x16x32_bf16 v[92:95], v[132:135], v[194:197], v[92:95]
	s_setprio 0
	s_setprio 1
	v_mfma_f32_16x16x32_bf16 v[100:103], v[148:151], v[164:167], v[100:103]
	v_mfma_f32_16x16x32_bf16 v[100:103], v[152:155], v[168:171], v[100:103]
	v_mfma_f32_16x16x32_bf16 v[104:107], v[160:163], v[168:171], v[104:107]
	v_mfma_f32_16x16x32_bf16 v[104:107], v[156:159], v[164:167], v[104:107]
	v_mfma_f32_16x16x32_bf16 v[112:115], v[156:159], v[172:175], v[112:115]
	v_mfma_f32_16x16x32_bf16 v[112:115], v[160:163], v[176:179], v[112:115]
	v_mfma_f32_16x16x32_bf16 v[108:111], v[152:155], v[176:179], v[108:111]
	v_mfma_f32_16x16x32_bf16 v[108:111], v[148:151], v[172:175], v[108:111]
	v_mfma_f32_16x16x32_bf16 v[116:119], v[148:151], v[180:183], v[116:119]
	v_mfma_f32_16x16x32_bf16 v[116:119], v[152:155], v[184:187], v[116:119]
	v_mfma_f32_16x16x32_bf16 v[120:123], v[160:163], v[184:187], v[120:123]
	v_mfma_f32_16x16x32_bf16 v[120:123], v[156:159], v[180:183], v[120:123]
	v_mfma_f32_16x16x32_bf16 v[128:131], v[156:159], v[194:197], v[128:131]
	s_setprio 2
	s_barrier
	v_mfma_f32_16x16x32_bf16 v[128:131], v[160:163], v[198:201], v[128:131]
	v_mfma_f32_16x16x32_bf16 v[124:127], v[152:155], v[198:201], v[124:127]
	v_mfma_f32_16x16x32_bf16 v[124:127], v[148:151], v[194:197], v[124:127]
	s_setprio 0
	s_add_i32 s29, 0, 0x18000
	s_add_i32 s44, 0, 0x1c000
	v_add_u32_e32 v144, s29, v232
	v_add_u32_e32 v160, s44, v232
	ds_read_b128 v[132:135], v144
	ds_read_b128 v[136:139], v144 offset:1024
	ds_read_b128 v[140:143], v144 offset:2048
	ds_read_b128 v[144:147], v144 offset:3072
	ds_read_b128 v[148:151], v160
	ds_read_b128 v[152:155], v160 offset:1024
	ds_read_b128 v[156:159], v160 offset:2048
	ds_read_b128 v[160:163], v160 offset:3072
	s_add_u32 s16, s16, 0x80000
	s_addc_u32 s17, s17, 0
	s_mov_b32 m0, s58
	ds_read_b128 v[164:167], v210 offset:32768
	ds_read_b128 v[168:171], v210 offset:33792
	ds_read_b128 v[172:175], v210 offset:34816
	ds_read_b128 v[176:179], v210 offset:35840
	ds_read_b128 v[180:183], v210 offset:36864
	ds_read_b128 v[184:187], v210 offset:37888
	ds_read_b128 v[194:197], v210 offset:38912
	ds_read_b128 v[198:201], v210 offset:39936
	global_load_lds_dwordx4 v2, s[16:17]
	s_mov_b32 m0, s59
	s_nop 0
	global_load_lds_dwordx4 v188, s[16:17]
	s_waitcnt vmcnt(8)
	s_waitcnt lgkmcnt(0)
	s_barrier
	s_setprio 1
	s_waitcnt lgkmcnt(0)
	v_mfma_f32_16x16x32_bf16 v[4:7], v[132:135], v[164:167], v[4:7]
	v_mfma_f32_16x16x32_bf16 v[4:7], v[136:139], v[168:171], v[4:7]
	v_mfma_f32_16x16x32_bf16 v[8:11], v[144:147], v[168:171], v[8:11]
	v_mfma_f32_16x16x32_bf16 v[8:11], v[140:143], v[164:167], v[8:11]
	v_mfma_f32_16x16x32_bf16 v[16:19], v[140:143], v[172:175], v[16:19]
	v_mfma_f32_16x16x32_bf16 v[16:19], v[144:147], v[176:179], v[16:19]
	v_mfma_f32_16x16x32_bf16 v[12:15], v[136:139], v[176:179], v[12:15]
	v_mfma_f32_16x16x32_bf16 v[12:15], v[132:135], v[172:175], v[12:15]
	v_mfma_f32_16x16x32_bf16 v[20:23], v[132:135], v[180:183], v[20:23]
	v_mfma_f32_16x16x32_bf16 v[20:23], v[136:139], v[184:187], v[20:23]
	v_mfma_f32_16x16x32_bf16 v[24:27], v[144:147], v[184:187], v[24:27]
	v_mfma_f32_16x16x32_bf16 v[24:27], v[140:143], v[180:183], v[24:27]
	v_mfma_f32_16x16x32_bf16 v[32:35], v[140:143], v[194:197], v[32:35]
	v_mfma_f32_16x16x32_bf16 v[32:35], v[144:147], v[198:201], v[32:35]
	v_mfma_f32_16x16x32_bf16 v[28:31], v[136:139], v[198:201], v[28:31]
	v_mfma_f32_16x16x32_bf16 v[28:31], v[132:135], v[194:197], v[28:31]
	s_setprio 0
	s_setprio 1
	v_mfma_f32_16x16x32_bf16 v[36:39], v[148:151], v[164:167], v[36:39]
	v_mfma_f32_16x16x32_bf16 v[36:39], v[152:155], v[168:171], v[36:39]
	v_mfma_f32_16x16x32_bf16 v[40:43], v[160:163], v[168:171], v[40:43]
	v_mfma_f32_16x16x32_bf16 v[40:43], v[156:159], v[164:167], v[40:43]
	v_mfma_f32_16x16x32_bf16 v[48:51], v[156:159], v[172:175], v[48:51]
	v_mfma_f32_16x16x32_bf16 v[48:51], v[160:163], v[176:179], v[48:51]
	v_mfma_f32_16x16x32_bf16 v[44:47], v[152:155], v[176:179], v[44:47]
	v_mfma_f32_16x16x32_bf16 v[44:47], v[148:151], v[172:175], v[44:47]
	v_mfma_f32_16x16x32_bf16 v[52:55], v[148:151], v[180:183], v[52:55]
	v_mfma_f32_16x16x32_bf16 v[52:55], v[152:155], v[184:187], v[52:55]
	v_mfma_f32_16x16x32_bf16 v[56:59], v[160:163], v[184:187], v[56:59]
	v_mfma_f32_16x16x32_bf16 v[56:59], v[156:159], v[180:183], v[56:59]
	v_mfma_f32_16x16x32_bf16 v[64:67], v[156:159], v[194:197], v[64:67]
	s_setprio 2
	s_barrier
	v_mfma_f32_16x16x32_bf16 v[64:67], v[160:163], v[198:201], v[64:67]
	v_mfma_f32_16x16x32_bf16 v[60:63], v[152:155], v[198:201], v[60:63]
	v_mfma_f32_16x16x32_bf16 v[60:63], v[148:151], v[194:197], v[60:63]
	s_setprio 0
	s_add_i32 s16, s29, s38
	v_lshl_add_u64 v[202:203], v[202:203], 0, s[86:87]
	s_mov_b32 m0, s16
	ds_read_b128 v[164:167], v210 offset:49152
	ds_read_b128 v[168:171], v210 offset:50176
	ds_read_b128 v[172:175], v210 offset:51200
	ds_read_b128 v[176:179], v210 offset:52224
	ds_read_b128 v[180:183], v210 offset:53248
	ds_read_b128 v[184:187], v210 offset:54272
	ds_read_b128 v[194:197], v210 offset:55296
	ds_read_b128 v[198:201], v210 offset:56320
	global_load_lds_dwordx4 v[202:203], off
	s_add_i32 m0, s16, 0x2000
	s_add_u32 s12, s12, 0x20080
	v_lshl_add_u64 v[202:203], v[204:205], 0, s[86:87]
	s_addc_u32 s13, s13, 0
	s_add_i32 s16, s44, s38
	global_load_lds_dwordx4 v[202:203], off
	s_mov_b32 m0, s16
	v_lshl_add_u64 v[202:203], v[206:207], 0, s[86:87]
	global_load_lds_dwordx4 v192, s[12:13]
	s_add_i32 m0, s16, 0x2000
	s_nop 0
	global_load_lds_dwordx4 v190, s[12:13]
	s_mov_b32 m0, s63
	s_nop 0
	global_load_lds_dwordx4 v[202:203], off
	v_lshl_add_u64 v[202:203], v[208:209], 0, s[86:87]
	s_mov_b32 m0, s64
	s_nop 0
	global_load_lds_dwordx4 v[202:203], off
	s_waitcnt vmcnt(8)
	s_waitcnt lgkmcnt(0)
	s_barrier
	s_setprio 1
	s_waitcnt lgkmcnt(0)
	v_mfma_f32_16x16x32_bf16 v[68:71], v[132:135], v[164:167], v[68:71]
	v_mfma_f32_16x16x32_bf16 v[68:71], v[136:139], v[168:171], v[68:71]
	v_mfma_f32_16x16x32_bf16 v[72:75], v[144:147], v[168:171], v[72:75]
	v_mfma_f32_16x16x32_bf16 v[72:75], v[140:143], v[164:167], v[72:75]
	v_mfma_f32_16x16x32_bf16 v[80:83], v[140:143], v[172:175], v[80:83]
	v_mfma_f32_16x16x32_bf16 v[80:83], v[144:147], v[176:179], v[80:83]
	v_mfma_f32_16x16x32_bf16 v[76:79], v[136:139], v[176:179], v[76:79]
	v_mfma_f32_16x16x32_bf16 v[76:79], v[132:135], v[172:175], v[76:79]
	v_mfma_f32_16x16x32_bf16 v[84:87], v[132:135], v[180:183], v[84:87]
	v_mfma_f32_16x16x32_bf16 v[84:87], v[136:139], v[184:187], v[84:87]
	v_mfma_f32_16x16x32_bf16 v[88:91], v[144:147], v[184:187], v[88:91]
	v_mfma_f32_16x16x32_bf16 v[88:91], v[140:143], v[180:183], v[88:91]
	v_mfma_f32_16x16x32_bf16 v[96:99], v[140:143], v[194:197], v[96:99]
	v_mfma_f32_16x16x32_bf16 v[96:99], v[144:147], v[198:201], v[96:99]
	v_mfma_f32_16x16x32_bf16 v[92:95], v[136:139], v[198:201], v[92:95]
	v_mfma_f32_16x16x32_bf16 v[92:95], v[132:135], v[194:197], v[92:95]
	s_setprio 0
	s_setprio 1
	v_mfma_f32_16x16x32_bf16 v[100:103], v[148:151], v[164:167], v[100:103]
	v_mfma_f32_16x16x32_bf16 v[100:103], v[152:155], v[168:171], v[100:103]
	v_mfma_f32_16x16x32_bf16 v[104:107], v[160:163], v[168:171], v[104:107]
	v_mfma_f32_16x16x32_bf16 v[104:107], v[156:159], v[164:167], v[104:107]
	v_mfma_f32_16x16x32_bf16 v[112:115], v[156:159], v[172:175], v[112:115]
	v_mfma_f32_16x16x32_bf16 v[112:115], v[160:163], v[176:179], v[112:115]
	v_mfma_f32_16x16x32_bf16 v[108:111], v[152:155], v[176:179], v[108:111]
	v_mfma_f32_16x16x32_bf16 v[108:111], v[148:151], v[172:175], v[108:111]
	v_mfma_f32_16x16x32_bf16 v[116:119], v[148:151], v[180:183], v[116:119]
	v_mfma_f32_16x16x32_bf16 v[116:119], v[152:155], v[184:187], v[116:119]
	v_mfma_f32_16x16x32_bf16 v[120:123], v[160:163], v[184:187], v[120:123]
	v_mfma_f32_16x16x32_bf16 v[120:123], v[156:159], v[180:183], v[120:123]
	v_mfma_f32_16x16x32_bf16 v[128:131], v[156:159], v[194:197], v[128:131]
	s_setprio 2
	s_barrier
	v_mfma_f32_16x16x32_bf16 v[128:131], v[160:163], v[198:201], v[128:131]
	v_mfma_f32_16x16x32_bf16 v[124:127], v[152:155], v[198:201], v[124:127]
	v_mfma_f32_16x16x32_bf16 v[124:127], v[148:151], v[194:197], v[124:127]
	s_setprio 0
	s_add_i32 s28, s28, 2
	s_add_u32 s14, s14, 0x100
	s_addc_u32 s15, s15, 0
	s_add_u32 s26, s26, 0x100
	s_addc_u32 s27, s27, 0
	s_cmp_gt_u32 s28, 5
	s_cbranch_scc0 .LBB0_2069
	s_and_b64 vcc, exec, s[48:49]
	s_cbranch_vccz .LBB0_2072
	s_barrier

.LBB0_2159:
	s_add_i32 s68, 0, 0x10000
	s_add_i32 s69, 0, 0x14000
	v_add_u32_e32 v16, s68, v143
	v_add_u32_e32 v32, s69, v143
	ds_read_b128 v[4:7], v16
	ds_read_b128 v[8:11], v16 offset:1024
	ds_read_b128 v[12:15], v16 offset:2048
	ds_read_b128 v[16:19], v16 offset:3072
	ds_read_b128 v[20:23], v32
	ds_read_b128 v[24:27], v32 offset:1024
	ds_read_b128 v[28:31], v32 offset:2048
	ds_read_b128 v[32:35], v32 offset:3072
	v_add_u32_e32 v231, 0, v142
	ds_read_b128 v[36:39], v231
	ds_read_b128 v[40:43], v231 offset:1024
	ds_read_b128 v[44:47], v231 offset:2048
	ds_read_b128 v[48:51], v231 offset:3072
	ds_read_b128 v[52:55], v231 offset:4096
	ds_read_b128 v[56:59], v231 offset:5120
	ds_read_b128 v[60:63], v231 offset:6144
	ds_read_b128 v[64:67], v231 offset:7168
	s_waitcnt vmcnt(8)
	s_waitcnt lgkmcnt(0)
	s_barrier
	s_setprio 1
	s_waitcnt lgkmcnt(0)
	v_mfma_f32_16x16x32_f16 v[68:71], v[4:7], v[36:39], 0
	v_mfma_f32_16x16x32_f16 v[72:75], v[12:15], v[36:39], 0
	v_mfma_f32_16x16x32_f16 v[76:79], v[4:7], v[44:47], 0
	v_mfma_f32_16x16x32_f16 v[80:83], v[12:15], v[44:47], 0
	v_mfma_f32_16x16x32_f16 v[84:87], v[4:7], v[52:55], 0
	v_mfma_f32_16x16x32_f16 v[88:91], v[12:15], v[52:55], 0
	v_mfma_f32_16x16x32_f16 v[92:95], v[4:7], v[60:63], 0
	v_mfma_f32_16x16x32_f16 v[96:99], v[12:15], v[60:63], 0
	v_mfma_f32_16x16x32_f16 v[68:71], v[8:11], v[40:43], v[68:71]
	v_mfma_f32_16x16x32_f16 v[72:75], v[16:19], v[40:43], v[72:75]
	v_mfma_f32_16x16x32_f16 v[76:79], v[8:11], v[48:51], v[76:79]
	v_mfma_f32_16x16x32_f16 v[80:83], v[16:19], v[48:51], v[80:83]
	v_mfma_f32_16x16x32_f16 v[84:87], v[8:11], v[56:59], v[84:87]
	v_mfma_f32_16x16x32_f16 v[88:91], v[16:19], v[56:59], v[88:91]
	v_mfma_f32_16x16x32_f16 v[92:95], v[8:11], v[64:67], v[92:95]
	v_mfma_f32_16x16x32_f16 v[100:103], v[16:19], v[64:67], v[96:99]
	s_setprio 0
	s_setprio 1
	v_mfma_f32_16x16x32_f16 v[96:99], v[20:23], v[36:39], 0
	v_mfma_f32_16x16x32_f16 v[36:39], v[28:31], v[36:39], 0
	v_mfma_f32_16x16x32_f16 v[104:107], v[20:23], v[44:47], 0
	v_mfma_f32_16x16x32_f16 v[44:47], v[28:31], v[44:47], 0
	v_mfma_f32_16x16x32_f16 v[108:111], v[20:23], v[52:55], 0
	v_mfma_f32_16x16x32_f16 v[52:55], v[28:31], v[52:55], 0
	v_mfma_f32_16x16x32_f16 v[112:115], v[20:23], v[60:63], 0
	v_mfma_f32_16x16x32_f16 v[60:63], v[28:31], v[60:63], 0
	v_mfma_f32_16x16x32_f16 v[116:119], v[24:27], v[40:43], v[96:99]
	v_mfma_f32_16x16x32_f16 v[36:39], v[32:35], v[40:43], v[36:39]
	v_mfma_f32_16x16x32_f16 v[40:43], v[24:27], v[48:51], v[104:107]
	v_mfma_f32_16x16x32_f16 v[44:47], v[32:35], v[48:51], v[44:47]
	v_mfma_f32_16x16x32_f16 v[48:51], v[24:27], v[56:59], v[108:111]
	s_setprio 2
	s_barrier
	v_mfma_f32_16x16x32_f16 v[52:55], v[32:35], v[56:59], v[52:55]
	v_mfma_f32_16x16x32_f16 v[56:59], v[24:27], v[64:67], v[112:115]
	v_mfma_f32_16x16x32_f16 v[60:63], v[32:35], v[64:67], v[60:63]
	s_setprio 0
	v_lshl_add_u64 v[138:139], s[8:9], 0, v[2:3]
	s_add_i32 s68, s68, s53
	v_mov_b32_e32 v135, v3
	v_lshl_add_u64 v[144:145], v[138:139], 0, s[74:75]
	s_mov_b32 m0, s68
	v_lshl_add_u64 v[192:193], s[8:9], 0, v[134:135]
	ds_read_b128 v[64:67], v231 offset:16384
	ds_read_b128 v[96:99], v231 offset:17408
	ds_read_b128 v[104:107], v231 offset:18432
	ds_read_b128 v[108:111], v231 offset:19456
	ds_read_b128 v[112:115], v231 offset:20480
	ds_read_b128 v[120:123], v231 offset:21504
	ds_read_b128 v[124:127], v231 offset:22528
	ds_read_b128 v[128:131], v231 offset:23552
	global_load_lds_dwordx4 v[144:145], off
	v_lshl_add_u64 v[144:145], v[192:193], 0, s[74:75]
	s_add_i32 m0, s68, 0x2000
	s_add_i32 s68, s69, s53
	global_load_lds_dwordx4 v[144:145], off
	s_mov_b32 m0, s68
	v_mov_b32_e32 v137, v3
	global_load_lds_dwordx4 v2, s[40:41]
	s_add_i32 m0, s68, 0x2000
	v_lshl_add_u64 v[248:249], s[6:7], 0, v[136:137]
	v_mov_b32_e32 v133, v3
	global_load_lds_dwordx4 v134, s[40:41]
	v_lshl_add_u64 v[144:145], v[248:249], 0, s[74:75]
	s_mov_b32 m0, s54
	v_lshl_add_u64 v[250:251], s[6:7], 0, v[132:133]
	global_load_lds_dwordx4 v[144:145], off
	v_lshl_add_u64 v[144:145], v[250:251], 0, s[74:75]
	s_mov_b32 m0, s55
	s_nop 0
	global_load_lds_dwordx4 v[144:145], off
	s_waitcnt vmcnt(8)
	s_waitcnt lgkmcnt(0)
	s_barrier
	s_setprio 1
	s_waitcnt lgkmcnt(0)
	v_mfma_f32_16x16x32_f16 v[144:147], v[4:7], v[64:67], 0
	v_mfma_f32_16x16x32_f16 v[148:151], v[12:15], v[64:67], 0
	v_mfma_f32_16x16x32_f16 v[152:155], v[4:7], v[104:107], 0
	v_mfma_f32_16x16x32_f16 v[156:159], v[12:15], v[104:107], 0
	v_mfma_f32_16x16x32_f16 v[160:163], v[4:7], v[112:115], 0
	v_mfma_f32_16x16x32_f16 v[164:167], v[12:15], v[112:115], 0
	v_mfma_f32_16x16x32_f16 v[4:7], v[4:7], v[124:127], 0
	v_mfma_f32_16x16x32_f16 v[12:15], v[12:15], v[124:127], 0
	v_mfma_f32_16x16x32_f16 v[144:147], v[8:11], v[96:99], v[144:147]
	v_mfma_f32_16x16x32_f16 v[152:155], v[8:11], v[108:111], v[152:155]
	v_mfma_f32_16x16x32_f16 v[160:163], v[8:11], v[120:123], v[160:163]
	v_mfma_f32_16x16x32_f16 v[4:7], v[8:11], v[128:131], v[4:7]
	v_mfma_f32_16x16x32_f16 v[8:11], v[16:19], v[128:131], v[12:15]
	v_mfma_f32_16x16x32_f16 v[148:151], v[16:19], v[96:99], v[148:151]
	v_mfma_f32_16x16x32_f16 v[156:159], v[16:19], v[108:111], v[156:159]
	v_mfma_f32_16x16x32_f16 v[164:167], v[16:19], v[120:123], v[164:167]
	s_setprio 0
	s_setprio 1
	v_mfma_f32_16x16x32_f16 v[12:15], v[20:23], v[64:67], 0
	v_mfma_f32_16x16x32_f16 v[16:19], v[28:31], v[64:67], 0
	v_mfma_f32_16x16x32_f16 v[64:67], v[20:23], v[104:107], 0
	v_mfma_f32_16x16x32_f16 v[104:107], v[28:31], v[104:107], 0
	v_mfma_f32_16x16x32_f16 v[168:171], v[20:23], v[112:115], 0
	v_mfma_f32_16x16x32_f16 v[112:115], v[28:31], v[112:115], 0
	v_mfma_f32_16x16x32_f16 v[20:23], v[20:23], v[124:127], 0
	v_mfma_f32_16x16x32_f16 v[28:31], v[28:31], v[124:127], 0
	v_mfma_f32_16x16x32_f16 v[12:15], v[24:27], v[96:99], v[12:15]
	v_mfma_f32_16x16x32_f16 v[172:175], v[32:35], v[96:99], v[16:19]
	v_mfma_f32_16x16x32_f16 v[176:179], v[24:27], v[108:111], v[64:67]
	v_mfma_f32_16x16x32_f16 v[180:183], v[32:35], v[108:111], v[104:107]
	v_mfma_f32_16x16x32_f16 v[168:171], v[24:27], v[120:123], v[168:171]
	s_setprio 2
	s_barrier
	v_mfma_f32_16x16x32_f16 v[184:187], v[32:35], v[120:123], v[112:115]
	v_mfma_f32_16x16x32_f16 v[188:191], v[24:27], v[128:131], v[20:23]
	v_mfma_f32_16x16x32_f16 v[196:199], v[32:35], v[128:131], v[28:31]
	s_setprio 0
	s_add_i32 s68, 0, 0x18000
	v_add_u32_e32 v24, s68, v143
	s_add_i32 s69, 0, 0x1c000
	ds_read_b128 v[16:19], v24
	ds_read_b128 v[20:23], v24 offset:1024
	ds_read_b128 v[28:31], v24 offset:2048
	ds_read_b128 v[200:203], v24 offset:3072
	v_add_u32_e32 v24, s69, v143
	ds_read_b128 v[204:207], v24
	ds_read_b128 v[208:211], v24 offset:1024
	ds_read_b128 v[212:215], v24 offset:2048
	ds_read_b128 v[216:219], v24 offset:3072
	s_mov_b32 m0, s56
	ds_read_b128 v[24:27], v231 offset:32768
	ds_read_b128 v[32:35], v231 offset:33792
	ds_read_b128 v[64:67], v231 offset:34816
	ds_read_b128 v[220:223], v231 offset:35840
	ds_read_b128 v[224:227], v231 offset:36864
	ds_read_b128 v[232:235], v231 offset:37888
	ds_read_b128 v[236:239], v231 offset:38912
	ds_read_b128 v[240:243], v231 offset:39936
	global_load_lds_dwordx4 v136, s[42:43]
	s_mov_b32 m0, s57
	s_nop 0
	global_load_lds_dwordx4 v132, s[42:43]
	s_waitcnt vmcnt(8)
	s_waitcnt lgkmcnt(0)
	s_barrier
	s_setprio 1
	s_waitcnt lgkmcnt(0)
	v_mfma_f32_16x16x32_f16 v[68:71], v[16:19], v[24:27], v[68:71]
	v_mfma_f32_16x16x32_f16 v[128:131], v[20:23], v[32:35], v[68:71]
	v_mfma_f32_16x16x32_f16 v[68:71], v[28:31], v[24:27], v[72:75]
	v_mfma_f32_16x16x32_f16 v[120:123], v[200:203], v[32:35], v[68:71]
	v_mfma_f32_16x16x32_f16 v[68:71], v[16:19], v[64:67], v[76:79]
	v_mfma_f32_16x16x32_f16 v[112:115], v[20:23], v[220:223], v[68:71]
	v_mfma_f32_16x16x32_f16 v[68:71], v[28:31], v[64:67], v[80:83]
	v_mfma_f32_16x16x32_f16 v[104:107], v[200:203], v[220:223], v[68:71]
	v_mfma_f32_16x16x32_f16 v[68:71], v[16:19], v[224:227], v[84:87]
	v_mfma_f32_16x16x32_f16 v[96:99], v[20:23], v[232:235], v[68:71]
	v_mfma_f32_16x16x32_f16 v[68:71], v[28:31], v[224:227], v[88:91]
	v_mfma_f32_16x16x32_f16 v[88:91], v[200:203], v[232:235], v[68:71]
	v_mfma_f32_16x16x32_f16 v[68:71], v[16:19], v[236:239], v[92:95]
	v_mfma_f32_16x16x32_f16 v[80:83], v[20:23], v[240:243], v[68:71]
	v_mfma_f32_16x16x32_f16 v[68:71], v[28:31], v[236:239], v[100:103]
	v_mfma_f32_16x16x32_f16 v[72:75], v[200:203], v[240:243], v[68:71]
	s_setprio 0
	s_setprio 1
	v_mfma_f32_16x16x32_f16 v[68:71], v[204:207], v[24:27], v[116:119]
	v_mfma_f32_16x16x32_f16 v[24:27], v[212:215], v[24:27], v[36:39]
	v_mfma_f32_16x16x32_f16 v[116:119], v[216:219], v[32:35], v[24:27]
	v_mfma_f32_16x16x32_f16 v[24:27], v[204:207], v[64:67], v[40:43]
	v_mfma_f32_16x16x32_f16 v[108:111], v[208:211], v[220:223], v[24:27]
	v_mfma_f32_16x16x32_f16 v[24:27], v[212:215], v[64:67], v[44:47]
	v_mfma_f32_16x16x32_f16 v[100:103], v[216:219], v[220:223], v[24:27]
	v_mfma_f32_16x16x32_f16 v[24:27], v[204:207], v[224:227], v[48:51]
	v_mfma_f32_16x16x32_f16 v[92:95], v[208:211], v[232:235], v[24:27]
	v_mfma_f32_16x16x32_f16 v[24:27], v[212:215], v[224:227], v[52:55]
	v_mfma_f32_16x16x32_f16 v[84:87], v[216:219], v[232:235], v[24:27]
	v_mfma_f32_16x16x32_f16 v[24:27], v[204:207], v[236:239], v[56:59]
	v_mfma_f32_16x16x32_f16 v[76:79], v[208:211], v[240:243], v[24:27]
	s_setprio 2
	s_barrier
	v_mfma_f32_16x16x32_f16 v[24:27], v[212:215], v[236:239], v[60:63]
	v_mfma_f32_16x16x32_f16 v[124:127], v[208:211], v[32:35], v[68:71]
	v_mfma_f32_16x16x32_f16 v[68:71], v[216:219], v[240:243], v[24:27]
	s_setprio 0
	s_add_i32 s68, s68, s53
	s_nop 2
	v_lshl_add_u64 v[24:25], v[138:139], 0, s[24:25]
	s_mov_b32 m0, s68
	ds_read_b128 v[36:39], v231 offset:49152
	ds_read_b128 v[44:47], v231 offset:50176
	ds_read_b128 v[220:223], v231 offset:51200
	ds_read_b128 v[224:227], v231 offset:52224
	ds_read_b128 v[232:235], v231 offset:53248
	ds_read_b128 v[236:239], v231 offset:54272
	ds_read_b128 v[240:243], v231 offset:55296
	ds_read_b128 v[244:247], v231 offset:56320
	global_load_lds_dwordx4 v[24:25], off
	v_lshl_add_u64 v[24:25], v[192:193], 0, s[24:25]
	s_add_i32 m0, s68, 0x2000
	s_add_i32 s68, s69, s53
	global_load_lds_dwordx4 v[24:25], off
	s_mov_b32 m0, s68
	v_lshl_add_u64 v[24:25], v[248:249], 0, s[24:25]
	global_load_lds_dwordx4 v2, s[44:45]
	s_add_i32 m0, s68, 0x2000
	s_nop 0
	global_load_lds_dwordx4 v134, s[44:45]
	s_mov_b32 m0, s59
	s_nop 0
	global_load_lds_dwordx4 v[24:25], off
	v_lshl_add_u64 v[24:25], v[250:251], 0, s[24:25]
	s_mov_b32 m0, s60
	s_nop 0
	global_load_lds_dwordx4 v[24:25], off
	s_waitcnt vmcnt(8)
	s_waitcnt lgkmcnt(0)
	s_barrier
	s_setprio 1
	s_waitcnt lgkmcnt(0)
	v_mfma_f32_16x16x32_f16 v[24:27], v[16:19], v[36:39], v[144:147]
	v_mfma_f32_16x16x32_f16 v[64:67], v[20:23], v[44:47], v[24:27]
	v_mfma_f32_16x16x32_f16 v[24:27], v[28:31], v[36:39], v[148:151]
	v_mfma_f32_16x16x32_f16 v[56:59], v[200:203], v[44:47], v[24:27]
	v_mfma_f32_16x16x32_f16 v[24:27], v[16:19], v[220:223], v[152:155]
	v_mfma_f32_16x16x32_f16 v[48:51], v[20:23], v[224:227], v[24:27]
	v_mfma_f32_16x16x32_f16 v[24:27], v[28:31], v[220:223], v[156:159]
	v_mfma_f32_16x16x32_f16 v[40:43], v[200:203], v[224:227], v[24:27]
	v_mfma_f32_16x16x32_f16 v[24:27], v[16:19], v[232:235], v[160:163]
	v_mfma_f32_16x16x32_f16 v[4:7], v[16:19], v[240:243], v[4:7]
	v_mfma_f32_16x16x32_f16 v[32:35], v[20:23], v[236:239], v[24:27]
	v_mfma_f32_16x16x32_f16 v[24:27], v[28:31], v[232:235], v[164:167]
	v_mfma_f32_16x16x32_f16 v[16:19], v[20:23], v[244:247], v[4:7]
	v_mfma_f32_16x16x32_f16 v[4:7], v[28:31], v[240:243], v[8:11]
	v_mfma_f32_16x16x32_f16 v[24:27], v[200:203], v[236:239], v[24:27]
	v_mfma_f32_16x16x32_f16 v[8:11], v[200:203], v[244:247], v[4:7]
	s_setprio 0
	s_setprio 1
	v_mfma_f32_16x16x32_f16 v[4:7], v[204:207], v[36:39], v[12:15]
	v_mfma_f32_16x16x32_f16 v[60:63], v[208:211], v[44:47], v[4:7]
	v_mfma_f32_16x16x32_f16 v[4:7], v[212:215], v[36:39], v[172:175]
	v_mfma_f32_16x16x32_f16 v[52:55], v[216:219], v[44:47], v[4:7]
	v_mfma_f32_16x16x32_f16 v[4:7], v[204:207], v[220:223], v[176:179]
	v_mfma_f32_16x16x32_f16 v[44:47], v[208:211], v[224:227], v[4:7]
	v_mfma_f32_16x16x32_f16 v[4:7], v[212:215], v[220:223], v[180:183]
	v_mfma_f32_16x16x32_f16 v[36:39], v[216:219], v[224:227], v[4:7]
	v_mfma_f32_16x16x32_f16 v[4:7], v[204:207], v[232:235], v[168:171]
	v_mfma_f32_16x16x32_f16 v[28:31], v[208:211], v[236:239], v[4:7]
	v_mfma_f32_16x16x32_f16 v[4:7], v[212:215], v[232:235], v[184:187]
	v_mfma_f32_16x16x32_f16 v[20:23], v[216:219], v[236:239], v[4:7]
	v_mfma_f32_16x16x32_f16 v[4:7], v[204:207], v[240:243], v[188:191]
	s_setprio 2
	s_barrier
	v_mfma_f32_16x16x32_f16 v[12:15], v[208:211], v[244:247], v[4:7]
	v_mfma_f32_16x16x32_f16 v[4:7], v[212:215], v[240:243], v[196:199]
	v_mfma_f32_16x16x32_f16 v[4:7], v[216:219], v[244:247], v[4:7]
	s_setprio 0
	s_add_i32 s67, s67, 2
	s_cmp_ge_i32 s67, s11
	s_cbranch_scc0 .LBB0_2159

.LBB0_2161:
	s_add_u32 s68, s6, s40
	s_addc_u32 s69, s7, s41
	s_add_u32 s42, s68, 0x200
	s_addc_u32 s43, s69, 0
	s_add_u32 s44, s8, s40
	s_addc_u32 s45, s9, s41
	s_add_u32 s67, s44, 0x200
	s_addc_u32 s70, s45, 0
	s_add_i32 s71, 0, 0x10000
	s_cmp_eq_u32 s11, 28
	s_cselect_b32 s45, s29, s43
	s_cselect_b32 s44, s28, s42
	v_add_u32_e32 v133, s71, v143
	s_cselect_b32 s43, s37, s70
	s_cselect_b32 s42, s36, s67
	s_add_i32 s67, 0, 0x14000
	ds_read_b128 v[144:147], v133
	ds_read_b128 v[148:151], v133 offset:1024
	ds_read_b128 v[152:155], v133 offset:2048
	ds_read_b128 v[156:159], v133 offset:3072
	v_add_u32_e32 v133, s67, v143
	ds_read_b128 v[160:163], v133
	ds_read_b128 v[164:167], v133 offset:1024
	ds_read_b128 v[168:171], v133 offset:2048
	ds_read_b128 v[172:175], v133 offset:3072
	v_lshl_add_u64 v[136:137], s[68:69], 0, v[2:3]
	s_mov_b32 m0, s61
	v_add_u32_e32 v216, 0, v142
	v_lshl_add_u64 v[136:137], v[136:137], 0, s[34:35]
	v_mov_b32_e32 v133, v3
	ds_read_b128 v[176:179], v216
	ds_read_b128 v[180:183], v216 offset:1024
	ds_read_b128 v[184:187], v216 offset:2048
	ds_read_b128 v[188:191], v216 offset:3072
	ds_read_b128 v[196:199], v216 offset:4096
	ds_read_b128 v[200:203], v216 offset:5120
	ds_read_b128 v[204:207], v216 offset:6144
	ds_read_b128 v[208:211], v216 offset:7168
	global_load_lds_dwordx4 v[136:137], off
	v_lshl_add_u64 v[136:137], s[68:69], 0, v[132:133]
	v_lshl_add_u64 v[136:137], v[136:137], 0, s[34:35]
	s_mov_b32 m0, s62
	s_nop 0
	global_load_lds_dwordx4 v[136:137], off
	s_waitcnt vmcnt(8)
	s_waitcnt lgkmcnt(0)
	s_barrier
	s_setprio 1
	s_waitcnt lgkmcnt(0)
	v_mfma_f32_16x16x32_f16 v[128:131], v[144:147], v[176:179], v[128:131]
	v_mfma_f32_16x16x32_f16 v[128:131], v[148:151], v[180:183], v[128:131]
	v_mfma_f32_16x16x32_f16 v[120:123], v[156:159], v[180:183], v[120:123]
	v_mfma_f32_16x16x32_f16 v[120:123], v[152:155], v[176:179], v[120:123]
	v_mfma_f32_16x16x32_f16 v[104:107], v[152:155], v[184:187], v[104:107]
	v_mfma_f32_16x16x32_f16 v[104:107], v[156:159], v[188:191], v[104:107]
	v_mfma_f32_16x16x32_f16 v[112:115], v[148:151], v[188:191], v[112:115]
	v_mfma_f32_16x16x32_f16 v[112:115], v[144:147], v[184:187], v[112:115]
	v_mfma_f32_16x16x32_f16 v[96:99], v[144:147], v[196:199], v[96:99]
	v_mfma_f32_16x16x32_f16 v[96:99], v[148:151], v[200:203], v[96:99]
	v_mfma_f32_16x16x32_f16 v[88:91], v[156:159], v[200:203], v[88:91]
	v_mfma_f32_16x16x32_f16 v[88:91], v[152:155], v[196:199], v[88:91]
	v_mfma_f32_16x16x32_f16 v[72:75], v[152:155], v[204:207], v[72:75]
	v_mfma_f32_16x16x32_f16 v[72:75], v[156:159], v[208:211], v[72:75]
	v_mfma_f32_16x16x32_f16 v[80:83], v[148:151], v[208:211], v[80:83]
	v_mfma_f32_16x16x32_f16 v[80:83], v[144:147], v[204:207], v[80:83]
	s_setprio 0
	s_setprio 1
	v_mfma_f32_16x16x32_f16 v[124:127], v[160:163], v[176:179], v[124:127]
	v_mfma_f32_16x16x32_f16 v[124:127], v[164:167], v[180:183], v[124:127]
	v_mfma_f32_16x16x32_f16 v[116:119], v[172:175], v[180:183], v[116:119]
	v_mfma_f32_16x16x32_f16 v[116:119], v[168:171], v[176:179], v[116:119]
	v_mfma_f32_16x16x32_f16 v[100:103], v[168:171], v[184:187], v[100:103]
	v_mfma_f32_16x16x32_f16 v[100:103], v[172:175], v[188:191], v[100:103]
	v_mfma_f32_16x16x32_f16 v[108:111], v[164:167], v[188:191], v[108:111]
	v_mfma_f32_16x16x32_f16 v[108:111], v[160:163], v[184:187], v[108:111]
	v_mfma_f32_16x16x32_f16 v[92:95], v[160:163], v[196:199], v[92:95]
	v_mfma_f32_16x16x32_f16 v[92:95], v[164:167], v[200:203], v[92:95]
	v_mfma_f32_16x16x32_f16 v[84:87], v[172:175], v[200:203], v[84:87]
	v_mfma_f32_16x16x32_f16 v[84:87], v[168:171], v[196:199], v[84:87]
	v_mfma_f32_16x16x32_f16 v[68:71], v[168:171], v[204:207], v[68:71]
	s_setprio 2
	s_barrier
	v_mfma_f32_16x16x32_f16 v[68:71], v[172:175], v[208:211], v[68:71]
	v_mfma_f32_16x16x32_f16 v[76:79], v[164:167], v[208:211], v[76:79]
	v_mfma_f32_16x16x32_f16 v[76:79], v[160:163], v[204:207], v[76:79]
	s_setprio 0
	s_add_i32 s68, s71, s53
	s_mov_b32 m0, s68
	ds_read_b128 v[176:179], v216 offset:16384
	ds_read_b128 v[180:183], v216 offset:17408
	ds_read_b128 v[184:187], v216 offset:18432
	ds_read_b128 v[188:191], v216 offset:19456
	ds_read_b128 v[196:199], v216 offset:20480
	ds_read_b128 v[200:203], v216 offset:21504
	ds_read_b128 v[204:207], v216 offset:22528
	ds_read_b128 v[208:211], v216 offset:23552
	global_load_lds_dwordx4 v138, s[42:43]
	s_add_i32 m0, s68, 0x2000
	s_add_u32 s68, s42, 0x80000
	s_addc_u32 s69, s43, 0
	s_add_i32 s67, s67, s53
	global_load_lds_dwordx4 v134, s[42:43]
	s_mov_b32 m0, s67
	v_mov_b32_e32 v139, v3
	global_load_lds_dwordx4 v138, s[68:69]
	s_add_i32 m0, s67, 0x2000
	v_mov_b32_e32 v135, v3
	global_load_lds_dwordx4 v134, s[68:69]
	s_mov_b32 m0, s54
	v_lshl_add_u64 v[136:137], s[42:43], 0, v[138:139]
	global_load_lds_dwordx4 v2, s[44:45]
	s_mov_b32 m0, s55
	v_lshl_add_u64 v[192:193], s[42:43], 0, v[134:135]
	global_load_lds_dwordx4 v132, s[44:45]
	s_waitcnt vmcnt(8)
	s_waitcnt lgkmcnt(0)
	v_lshl_add_u64 v[212:213], s[44:45], 0, v[2:3]
	v_lshl_add_u64 v[214:215], s[44:45], 0, v[132:133]
	s_barrier
	s_setprio 1
	s_waitcnt lgkmcnt(0)
	v_mfma_f32_16x16x32_f16 v[64:67], v[144:147], v[176:179], v[64:67]
	v_mfma_f32_16x16x32_f16 v[64:67], v[148:151], v[180:183], v[64:67]
	v_mfma_f32_16x16x32_f16 v[56:59], v[156:159], v[180:183], v[56:59]
	v_mfma_f32_16x16x32_f16 v[56:59], v[152:155], v[176:179], v[56:59]
	v_mfma_f32_16x16x32_f16 v[40:43], v[152:155], v[184:187], v[40:43]
	v_mfma_f32_16x16x32_f16 v[40:43], v[156:159], v[188:191], v[40:43]
	v_mfma_f32_16x16x32_f16 v[48:51], v[148:151], v[188:191], v[48:51]
	v_mfma_f32_16x16x32_f16 v[48:51], v[144:147], v[184:187], v[48:51]
	v_mfma_f32_16x16x32_f16 v[32:35], v[144:147], v[196:199], v[32:35]
	v_mfma_f32_16x16x32_f16 v[32:35], v[148:151], v[200:203], v[32:35]
	v_mfma_f32_16x16x32_f16 v[24:27], v[156:159], v[200:203], v[24:27]
	v_mfma_f32_16x16x32_f16 v[24:27], v[152:155], v[196:199], v[24:27]
	v_mfma_f32_16x16x32_f16 v[8:11], v[152:155], v[204:207], v[8:11]
	v_mfma_f32_16x16x32_f16 v[8:11], v[156:159], v[208:211], v[8:11]
	v_mfma_f32_16x16x32_f16 v[16:19], v[148:151], v[208:211], v[16:19]
	v_mfma_f32_16x16x32_f16 v[16:19], v[144:147], v[204:207], v[16:19]
	s_setprio 0
	s_setprio 1
	v_mfma_f32_16x16x32_f16 v[60:63], v[160:163], v[176:179], v[60:63]
	v_mfma_f32_16x16x32_f16 v[60:63], v[164:167], v[180:183], v[60:63]
	v_mfma_f32_16x16x32_f16 v[52:55], v[172:175], v[180:183], v[52:55]
	v_mfma_f32_16x16x32_f16 v[52:55], v[168:171], v[176:179], v[52:55]
	v_mfma_f32_16x16x32_f16 v[36:39], v[168:171], v[184:187], v[36:39]
	v_mfma_f32_16x16x32_f16 v[36:39], v[172:175], v[188:191], v[36:39]
	v_mfma_f32_16x16x32_f16 v[44:47], v[164:167], v[188:191], v[44:47]
	v_mfma_f32_16x16x32_f16 v[44:47], v[160:163], v[184:187], v[44:47]
	v_mfma_f32_16x16x32_f16 v[28:31], v[160:163], v[196:199], v[28:31]
	v_mfma_f32_16x16x32_f16 v[28:31], v[164:167], v[200:203], v[28:31]
	v_mfma_f32_16x16x32_f16 v[20:23], v[172:175], v[200:203], v[20:23]
	v_mfma_f32_16x16x32_f16 v[20:23], v[168:171], v[196:199], v[20:23]
	v_mfma_f32_16x16x32_f16 v[4:7], v[168:171], v[204:207], v[4:7]
	s_setprio 2
	s_barrier
	v_mfma_f32_16x16x32_f16 v[4:7], v[172:175], v[208:211], v[4:7]
	v_mfma_f32_16x16x32_f16 v[12:15], v[164:167], v[208:211], v[12:15]
	v_mfma_f32_16x16x32_f16 v[12:15], v[160:163], v[204:207], v[12:15]
	s_setprio 0
	s_add_i32 s67, 0, 0x18000
	v_add_u32_e32 v135, s67, v143
	s_add_i32 s68, 0, 0x1c000
	ds_read_b128 v[144:147], v135
	ds_read_b128 v[148:151], v135 offset:1024
	ds_read_b128 v[152:155], v135 offset:2048
	ds_read_b128 v[156:159], v135 offset:3072
	v_add_u32_e32 v135, s68, v143
	ds_read_b128 v[160:163], v135
	ds_read_b128 v[164:167], v135 offset:1024
	ds_read_b128 v[168:171], v135 offset:2048
	ds_read_b128 v[172:175], v135 offset:3072
	s_add_u32 s44, s44, 0x80000
	s_addc_u32 s45, s45, 0
	s_mov_b32 m0, s56
	ds_read_b128 v[176:179], v216 offset:32768
	ds_read_b128 v[180:183], v216 offset:33792
	ds_read_b128 v[184:187], v216 offset:34816
	ds_read_b128 v[188:191], v216 offset:35840
	ds_read_b128 v[196:199], v216 offset:36864
	ds_read_b128 v[200:203], v216 offset:37888
	ds_read_b128 v[204:207], v216 offset:38912
	ds_read_b128 v[208:211], v216 offset:39936
	global_load_lds_dwordx4 v2, s[44:45]
	s_mov_b32 m0, s57
	s_nop 0
	global_load_lds_dwordx4 v132, s[44:45]
	s_waitcnt vmcnt(8)
	s_waitcnt lgkmcnt(0)
	s_barrier
	s_setprio 1
	s_waitcnt lgkmcnt(0)
	v_mfma_f32_16x16x32_f16 v[128:131], v[144:147], v[176:179], v[128:131]
	v_mfma_f32_16x16x32_f16 v[128:131], v[148:151], v[180:183], v[128:131]
	v_mfma_f32_16x16x32_f16 v[120:123], v[156:159], v[180:183], v[120:123]
	v_mfma_f32_16x16x32_f16 v[120:123], v[152:155], v[176:179], v[120:123]
	v_mfma_f32_16x16x32_f16 v[104:107], v[152:155], v[184:187], v[104:107]
	v_mfma_f32_16x16x32_f16 v[104:107], v[156:159], v[188:191], v[104:107]
	v_mfma_f32_16x16x32_f16 v[112:115], v[148:151], v[188:191], v[112:115]
	v_mfma_f32_16x16x32_f16 v[112:115], v[144:147], v[184:187], v[112:115]
	v_mfma_f32_16x16x32_f16 v[96:99], v[144:147], v[196:199], v[96:99]
	v_mfma_f32_16x16x32_f16 v[96:99], v[148:151], v[200:203], v[96:99]
	v_mfma_f32_16x16x32_f16 v[88:91], v[156:159], v[200:203], v[88:91]
	v_mfma_f32_16x16x32_f16 v[88:91], v[152:155], v[196:199], v[88:91]
	v_mfma_f32_16x16x32_f16 v[72:75], v[152:155], v[204:207], v[72:75]
	v_mfma_f32_16x16x32_f16 v[72:75], v[156:159], v[208:211], v[72:75]
	v_mfma_f32_16x16x32_f16 v[80:83], v[148:151], v[208:211], v[80:83]
	v_mfma_f32_16x16x32_f16 v[80:83], v[144:147], v[204:207], v[80:83]
	s_setprio 0
	s_setprio 1
	v_mfma_f32_16x16x32_f16 v[124:127], v[160:163], v[176:179], v[124:127]
	v_mfma_f32_16x16x32_f16 v[124:127], v[164:167], v[180:183], v[124:127]
	v_mfma_f32_16x16x32_f16 v[116:119], v[172:175], v[180:183], v[116:119]
	v_mfma_f32_16x16x32_f16 v[116:119], v[168:171], v[176:179], v[116:119]
	v_mfma_f32_16x16x32_f16 v[100:103], v[168:171], v[184:187], v[100:103]
	v_mfma_f32_16x16x32_f16 v[100:103], v[172:175], v[188:191], v[100:103]
	v_mfma_f32_16x16x32_f16 v[108:111], v[164:167], v[188:191], v[108:111]
	v_mfma_f32_16x16x32_f16 v[108:111], v[160:163], v[184:187], v[108:111]
	v_mfma_f32_16x16x32_f16 v[92:95], v[160:163], v[196:199], v[92:95]
	v_mfma_f32_16x16x32_f16 v[92:95], v[164:167], v[200:203], v[92:95]
	v_mfma_f32_16x16x32_f16 v[84:87], v[172:175], v[200:203], v[84:87]
	v_mfma_f32_16x16x32_f16 v[84:87], v[168:171], v[196:199], v[84:87]
	v_mfma_f32_16x16x32_f16 v[68:71], v[168:171], v[204:207], v[68:71]
	s_setprio 2
	s_barrier
	v_mfma_f32_16x16x32_f16 v[68:71], v[172:175], v[208:211], v[68:71]
	v_mfma_f32_16x16x32_f16 v[76:79], v[164:167], v[208:211], v[76:79]
	v_mfma_f32_16x16x32_f16 v[76:79], v[160:163], v[204:207], v[76:79]
	s_setprio 0
	s_add_i32 s44, s67, s53
	v_lshl_add_u64 v[136:137], v[136:137], 0, s[86:87]
	s_mov_b32 m0, s44
	ds_read_b128 v[176:179], v216 offset:49152
	ds_read_b128 v[180:183], v216 offset:50176
	ds_read_b128 v[184:187], v216 offset:51200
	ds_read_b128 v[188:191], v216 offset:52224
	ds_read_b128 v[196:199], v216 offset:53248
	ds_read_b128 v[200:203], v216 offset:54272
	ds_read_b128 v[204:207], v216 offset:55296
	ds_read_b128 v[208:211], v216 offset:56320
	global_load_lds_dwordx4 v[136:137], off
	s_add_i32 m0, s44, 0x2000
	s_add_u32 s42, s42, 0x80080
	v_lshl_add_u64 v[136:137], v[192:193], 0, s[86:87]
	s_addc_u32 s43, s43, 0
	s_add_i32 s44, s68, s53
	global_load_lds_dwordx4 v[136:137], off
	s_mov_b32 m0, s44
	v_lshl_add_u64 v[136:137], v[212:213], 0, s[86:87]
	global_load_lds_dwordx4 v138, s[42:43]
	s_add_i32 m0, s44, 0x2000
	s_nop 0
	global_load_lds_dwordx4 v134, s[42:43]
	s_mov_b32 m0, s59
	s_nop 0
	global_load_lds_dwordx4 v[136:137], off
	v_lshl_add_u64 v[136:137], v[214:215], 0, s[86:87]
	s_mov_b32 m0, s60
	s_nop 0
	global_load_lds_dwordx4 v[136:137], off
	s_waitcnt vmcnt(8)
	s_waitcnt lgkmcnt(0)
	s_barrier
	s_setprio 1
	s_waitcnt lgkmcnt(0)
	v_mfma_f32_16x16x32_f16 v[64:67], v[144:147], v[176:179], v[64:67]
	v_mfma_f32_16x16x32_f16 v[64:67], v[148:151], v[180:183], v[64:67]
	v_mfma_f32_16x16x32_f16 v[56:59], v[156:159], v[180:183], v[56:59]
	v_mfma_f32_16x16x32_f16 v[56:59], v[152:155], v[176:179], v[56:59]
	v_mfma_f32_16x16x32_f16 v[40:43], v[152:155], v[184:187], v[40:43]
	v_mfma_f32_16x16x32_f16 v[40:43], v[156:159], v[188:191], v[40:43]
	v_mfma_f32_16x16x32_f16 v[48:51], v[148:151], v[188:191], v[48:51]
	v_mfma_f32_16x16x32_f16 v[48:51], v[144:147], v[184:187], v[48:51]
	v_mfma_f32_16x16x32_f16 v[32:35], v[144:147], v[196:199], v[32:35]
	v_mfma_f32_16x16x32_f16 v[32:35], v[148:151], v[200:203], v[32:35]
	v_mfma_f32_16x16x32_f16 v[24:27], v[156:159], v[200:203], v[24:27]
	v_mfma_f32_16x16x32_f16 v[24:27], v[152:155], v[196:199], v[24:27]
	v_mfma_f32_16x16x32_f16 v[8:11], v[152:155], v[204:207], v[8:11]
	v_mfma_f32_16x16x32_f16 v[8:11], v[156:159], v[208:211], v[8:11]
	v_mfma_f32_16x16x32_f16 v[16:19], v[148:151], v[208:211], v[16:19]
	v_mfma_f32_16x16x32_f16 v[16:19], v[144:147], v[204:207], v[16:19]
	s_setprio 0
	s_setprio 1
	v_mfma_f32_16x16x32_f16 v[60:63], v[160:163], v[176:179], v[60:63]
	v_mfma_f32_16x16x32_f16 v[60:63], v[164:167], v[180:183], v[60:63]
	v_mfma_f32_16x16x32_f16 v[52:55], v[172:175], v[180:183], v[52:55]
	v_mfma_f32_16x16x32_f16 v[52:55], v[168:171], v[176:179], v[52:55]
	v_mfma_f32_16x16x32_f16 v[36:39], v[168:171], v[184:187], v[36:39]
	v_mfma_f32_16x16x32_f16 v[36:39], v[172:175], v[188:191], v[36:39]
	v_mfma_f32_16x16x32_f16 v[44:47], v[164:167], v[188:191], v[44:47]
	v_mfma_f32_16x16x32_f16 v[44:47], v[160:163], v[184:187], v[44:47]
	v_mfma_f32_16x16x32_f16 v[28:31], v[160:163], v[196:199], v[28:31]
	v_mfma_f32_16x16x32_f16 v[28:31], v[164:167], v[200:203], v[28:31]
	v_mfma_f32_16x16x32_f16 v[20:23], v[172:175], v[200:203], v[20:23]
	v_mfma_f32_16x16x32_f16 v[20:23], v[168:171], v[196:199], v[20:23]
	v_mfma_f32_16x16x32_f16 v[4:7], v[168:171], v[204:207], v[4:7]
	s_setprio 2
	s_barrier
	v_mfma_f32_16x16x32_f16 v[4:7], v[172:175], v[208:211], v[4:7]
	v_mfma_f32_16x16x32_f16 v[12:15], v[164:167], v[208:211], v[12:15]
	v_mfma_f32_16x16x32_f16 v[12:15], v[160:163], v[204:207], v[12:15]
	s_setprio 0
	s_add_i32 s11, s11, 2
	s_add_u32 s40, s40, 0x100
	s_addc_u32 s41, s41, 0
	s_cmp_gt_u32 s11, 29
	s_cbranch_scc0 .LBB0_2161
	s_andn2_b64 vcc, exec, s[26:27]
	s_cbranch_vccnz .LBB0_2164
	s_add_u32 s6, s28, 0x80080
	s_addc_u32 s7, s29, 0
	s_mov_b32 m0, s61
	v_lshl_add_u64 v[144:145], s[6:7], 0, v[2:3]
	v_lshl_add_u64 v[136:137], s[6:7], 0, v[132:133]
	global_load_lds_dwordx4 v[144:145], off
	s_mov_b32 m0, s62
	s_mov_b32 s47, s65
	global_load_lds_dwordx4 v[136:137], off
	s_mov_b32 s64, s10
	s_mov_b64 s[8:9], s[14:15]
	s_mov_b64 s[6:7], s[12:13]
	s_mov_b32 s63, s66

.LBB0_2269:
	s_add_i32 s51, 0, 0x10000
	s_add_i32 s71, 0, 0x14000
	v_add_u32_e32 v16, s51, v232
	v_add_u32_e32 v32, s71, v232
	ds_read_b128 v[4:7], v16
	ds_read_b128 v[8:11], v16 offset:1024
	ds_read_b128 v[12:15], v16 offset:2048
	ds_read_b128 v[16:19], v16 offset:3072
	ds_read_b128 v[20:23], v32
	ds_read_b128 v[24:27], v32 offset:1024
	ds_read_b128 v[28:31], v32 offset:2048
	ds_read_b128 v[32:35], v32 offset:3072
	v_add_u32_e32 v233, 0, v231
	ds_read_b128 v[36:39], v233
	ds_read_b128 v[40:43], v233 offset:1024
	ds_read_b128 v[44:47], v233 offset:2048
	ds_read_b128 v[48:51], v233 offset:3072
	ds_read_b128 v[52:55], v233 offset:4096
	ds_read_b128 v[56:59], v233 offset:5120
	ds_read_b128 v[60:63], v233 offset:6144
	ds_read_b128 v[64:67], v233 offset:7168
	s_waitcnt vmcnt(8)
	s_waitcnt lgkmcnt(0)
	s_barrier
	s_setprio 1
	s_waitcnt lgkmcnt(0)
	v_mfma_f32_16x16x32_bf16 v[68:71], v[4:7], v[36:39], 0
	v_mfma_f32_16x16x32_bf16 v[68:71], v[8:11], v[40:43], v[68:71]
	v_mfma_f32_16x16x32_bf16 v[72:75], v[12:15], v[36:39], 0
	v_mfma_f32_16x16x32_bf16 v[72:75], v[16:19], v[40:43], v[72:75]
	v_mfma_f32_16x16x32_bf16 v[80:83], v[12:15], v[44:47], 0
	v_mfma_f32_16x16x32_bf16 v[80:83], v[16:19], v[48:51], v[80:83]
	v_mfma_f32_16x16x32_bf16 v[76:79], v[4:7], v[44:47], 0
	v_mfma_f32_16x16x32_bf16 v[76:79], v[8:11], v[48:51], v[76:79]
	v_mfma_f32_16x16x32_bf16 v[84:87], v[4:7], v[52:55], 0
	v_mfma_f32_16x16x32_bf16 v[84:87], v[8:11], v[56:59], v[84:87]
	v_mfma_f32_16x16x32_bf16 v[88:91], v[12:15], v[52:55], 0
	v_mfma_f32_16x16x32_bf16 v[88:91], v[16:19], v[56:59], v[88:91]
	v_mfma_f32_16x16x32_bf16 v[96:99], v[12:15], v[60:63], 0
	v_mfma_f32_16x16x32_bf16 v[96:99], v[16:19], v[64:67], v[96:99]
	v_mfma_f32_16x16x32_bf16 v[92:95], v[4:7], v[60:63], 0
	v_mfma_f32_16x16x32_bf16 v[92:95], v[8:11], v[64:67], v[92:95]
	s_setprio 0
	s_setprio 1
	v_mfma_f32_16x16x32_bf16 v[100:103], v[20:23], v[36:39], 0
	v_mfma_f32_16x16x32_bf16 v[36:39], v[28:31], v[36:39], 0
	v_mfma_f32_16x16x32_bf16 v[104:107], v[20:23], v[44:47], 0
	v_mfma_f32_16x16x32_bf16 v[44:47], v[28:31], v[44:47], 0
	v_mfma_f32_16x16x32_bf16 v[108:111], v[20:23], v[52:55], 0
	v_mfma_f32_16x16x32_bf16 v[52:55], v[28:31], v[52:55], 0
	v_mfma_f32_16x16x32_bf16 v[112:115], v[20:23], v[60:63], 0
	v_mfma_f32_16x16x32_bf16 v[60:63], v[28:31], v[60:63], 0
	v_mfma_f32_16x16x32_bf16 v[100:103], v[24:27], v[40:43], v[100:103]
	v_mfma_f32_16x16x32_bf16 v[40:43], v[32:35], v[40:43], v[36:39]
	v_mfma_f32_16x16x32_bf16 v[104:107], v[24:27], v[48:51], v[104:107]
	v_mfma_f32_16x16x32_bf16 v[48:51], v[32:35], v[48:51], v[44:47]
	v_mfma_f32_16x16x32_bf16 v[108:111], v[24:27], v[56:59], v[108:111]
	s_setprio 2
	s_barrier
	v_mfma_f32_16x16x32_bf16 v[56:59], v[32:35], v[56:59], v[52:55]
	v_mfma_f32_16x16x32_bf16 v[112:115], v[24:27], v[64:67], v[112:115]
	v_mfma_f32_16x16x32_bf16 v[64:67], v[32:35], v[64:67], v[60:63]
	s_setprio 0
	v_lshl_add_u64 v[186:187], s[12:13], 0, v[2:3]
	s_add_i32 s51, s51, s38
	v_mov_b32_e32 v191, v3
	v_lshl_add_u64 v[134:135], v[186:187], 0, s[74:75]
	s_mov_b32 m0, s51
	v_lshl_add_u64 v[246:247], s[12:13], 0, v[190:191]
	ds_read_b128 v[36:39], v233 offset:16384
	ds_read_b128 v[44:47], v233 offset:17408
	ds_read_b128 v[52:55], v233 offset:18432
	ds_read_b128 v[60:63], v233 offset:19456
	ds_read_b128 v[116:119], v233 offset:20480
	ds_read_b128 v[120:123], v233 offset:21504
	ds_read_b128 v[124:127], v233 offset:22528
	ds_read_b128 v[128:131], v233 offset:23552
	global_load_lds_dwordx4 v[134:135], off
	v_lshl_add_u64 v[134:135], v[246:247], 0, s[74:75]
	s_add_i32 m0, s51, 0x2000
	s_add_i32 s51, s71, s38
	global_load_lds_dwordx4 v[134:135], off
	s_mov_b32 m0, s51
	v_mov_b32_e32 v133, v3
	global_load_lds_dwordx4 v2, s[16:17]
	s_add_i32 m0, s51, 0x2000
	v_lshl_add_u64 v[248:249], s[14:15], 0, v[132:133]
	v_mov_b32_e32 v189, v3
	global_load_lds_dwordx4 v190, s[16:17]
	v_lshl_add_u64 v[134:135], v[248:249], 0, s[74:75]
	s_mov_b32 m0, s56
	v_lshl_add_u64 v[250:251], s[14:15], 0, v[188:189]
	global_load_lds_dwordx4 v[134:135], off
	v_lshl_add_u64 v[134:135], v[250:251], 0, s[74:75]
	s_mov_b32 m0, s57
	s_nop 0
	global_load_lds_dwordx4 v[134:135], off
	s_waitcnt vmcnt(8)
	s_waitcnt lgkmcnt(0)
	s_barrier
	s_setprio 1
	s_waitcnt lgkmcnt(0)
	v_mfma_f32_16x16x32_bf16 v[134:137], v[4:7], v[36:39], 0
	v_mfma_f32_16x16x32_bf16 v[138:141], v[12:15], v[36:39], 0
	v_mfma_f32_16x16x32_bf16 v[142:145], v[4:7], v[52:55], 0
	v_mfma_f32_16x16x32_bf16 v[146:149], v[12:15], v[52:55], 0
	v_mfma_f32_16x16x32_bf16 v[150:153], v[4:7], v[116:119], 0
	v_mfma_f32_16x16x32_bf16 v[154:157], v[12:15], v[116:119], 0
	v_mfma_f32_16x16x32_bf16 v[4:7], v[4:7], v[124:127], 0
	v_mfma_f32_16x16x32_bf16 v[12:15], v[12:15], v[124:127], 0
	v_mfma_f32_16x16x32_bf16 v[134:137], v[8:11], v[44:47], v[134:137]
	v_mfma_f32_16x16x32_bf16 v[138:141], v[16:19], v[44:47], v[138:141]
	v_mfma_f32_16x16x32_bf16 v[142:145], v[8:11], v[60:63], v[142:145]
	v_mfma_f32_16x16x32_bf16 v[146:149], v[16:19], v[60:63], v[146:149]
	v_mfma_f32_16x16x32_bf16 v[150:153], v[8:11], v[120:123], v[150:153]
	v_mfma_f32_16x16x32_bf16 v[154:157], v[16:19], v[120:123], v[154:157]
	v_mfma_f32_16x16x32_bf16 v[158:161], v[8:11], v[128:131], v[4:7]
	v_mfma_f32_16x16x32_bf16 v[162:165], v[16:19], v[128:131], v[12:15]
	s_setprio 0
	s_setprio 1
	v_mfma_f32_16x16x32_bf16 v[4:7], v[20:23], v[36:39], 0
	v_mfma_f32_16x16x32_bf16 v[8:11], v[28:31], v[36:39], 0
	v_mfma_f32_16x16x32_bf16 v[12:15], v[20:23], v[52:55], 0
	v_mfma_f32_16x16x32_bf16 v[16:19], v[28:31], v[52:55], 0
	v_mfma_f32_16x16x32_bf16 v[36:39], v[20:23], v[116:119], 0
	v_mfma_f32_16x16x32_bf16 v[52:55], v[28:31], v[116:119], 0
	v_mfma_f32_16x16x32_bf16 v[20:23], v[20:23], v[124:127], 0
	v_mfma_f32_16x16x32_bf16 v[28:31], v[28:31], v[124:127], 0
	v_mfma_f32_16x16x32_bf16 v[116:119], v[24:27], v[44:47], v[4:7]
	v_mfma_f32_16x16x32_bf16 v[124:127], v[32:35], v[44:47], v[8:11]
	v_mfma_f32_16x16x32_bf16 v[174:177], v[24:27], v[120:123], v[36:39]
	v_mfma_f32_16x16x32_bf16 v[120:123], v[32:35], v[120:123], v[52:55]
	v_mfma_f32_16x16x32_bf16 v[178:181], v[24:27], v[128:131], v[20:23]
	s_setprio 2
	s_barrier
	v_mfma_f32_16x16x32_bf16 v[128:131], v[32:35], v[128:131], v[28:31]
	v_mfma_f32_16x16x32_bf16 v[166:169], v[24:27], v[60:63], v[12:15]
	v_mfma_f32_16x16x32_bf16 v[170:173], v[32:35], v[60:63], v[16:19]
	s_setprio 0
	s_add_i32 s51, 0, 0x18000
	v_add_u32_e32 v4, s51, v232
	s_add_i32 s71, 0, 0x1c000
	ds_read_b128 v[182:185], v4
	ds_read_b128 v[192:195], v4 offset:1024
	ds_read_b128 v[196:199], v4 offset:2048
	ds_read_b128 v[200:203], v4 offset:3072
	v_add_u32_e32 v4, s71, v232
	ds_read_b128 v[204:207], v4
	ds_read_b128 v[208:211], v4 offset:1024
	ds_read_b128 v[212:215], v4 offset:2048
	ds_read_b128 v[216:219], v4 offset:3072
	s_mov_b32 m0, s58
	ds_read_b128 v[44:47], v233 offset:32768
	ds_read_b128 v[52:55], v233 offset:33792
	ds_read_b128 v[60:63], v233 offset:34816
	ds_read_b128 v[220:223], v233 offset:35840
	ds_read_b128 v[224:227], v233 offset:36864
	ds_read_b128 v[234:237], v233 offset:37888
	ds_read_b128 v[238:241], v233 offset:38912
	ds_read_b128 v[242:245], v233 offset:39936
	global_load_lds_dwordx4 v132, s[26:27]
	s_mov_b32 m0, s59
	s_nop 0
	global_load_lds_dwordx4 v188, s[26:27]
	s_waitcnt vmcnt(8)
	s_waitcnt lgkmcnt(0)
	s_barrier
	s_setprio 1
	s_waitcnt lgkmcnt(0)
	v_mfma_f32_16x16x32_bf16 v[4:7], v[182:185], v[44:47], v[68:71]
	v_mfma_f32_16x16x32_bf16 v[8:11], v[196:199], v[44:47], v[72:75]
	v_mfma_f32_16x16x32_bf16 v[12:15], v[182:185], v[60:63], v[76:79]
	v_mfma_f32_16x16x32_bf16 v[16:19], v[196:199], v[60:63], v[80:83]
	v_mfma_f32_16x16x32_bf16 v[20:23], v[182:185], v[224:227], v[84:87]
	v_mfma_f32_16x16x32_bf16 v[24:27], v[196:199], v[224:227], v[88:91]
	v_mfma_f32_16x16x32_bf16 v[28:31], v[182:185], v[238:241], v[92:95]
	v_mfma_f32_16x16x32_bf16 v[32:35], v[196:199], v[238:241], v[96:99]
	v_mfma_f32_16x16x32_bf16 v[4:7], v[192:195], v[52:55], v[4:7]
	v_mfma_f32_16x16x32_bf16 v[8:11], v[200:203], v[52:55], v[8:11]
	v_mfma_f32_16x16x32_bf16 v[12:15], v[192:195], v[220:223], v[12:15]
	v_mfma_f32_16x16x32_bf16 v[16:19], v[200:203], v[220:223], v[16:19]
	v_mfma_f32_16x16x32_bf16 v[20:23], v[192:195], v[234:237], v[20:23]
	v_mfma_f32_16x16x32_bf16 v[24:27], v[200:203], v[234:237], v[24:27]
	v_mfma_f32_16x16x32_bf16 v[28:31], v[192:195], v[242:245], v[28:31]
	v_mfma_f32_16x16x32_bf16 v[32:35], v[200:203], v[242:245], v[32:35]
	s_setprio 0
	s_setprio 1
	v_mfma_f32_16x16x32_bf16 v[36:39], v[204:207], v[44:47], v[100:103]
	v_mfma_f32_16x16x32_bf16 v[40:43], v[212:215], v[44:47], v[40:43]
	v_mfma_f32_16x16x32_bf16 v[36:39], v[208:211], v[52:55], v[36:39]
	v_mfma_f32_16x16x32_bf16 v[40:43], v[216:219], v[52:55], v[40:43]
	v_mfma_f32_16x16x32_bf16 v[44:47], v[204:207], v[60:63], v[104:107]
	v_mfma_f32_16x16x32_bf16 v[48:51], v[212:215], v[60:63], v[48:51]
	v_mfma_f32_16x16x32_bf16 v[52:55], v[204:207], v[224:227], v[108:111]
	v_mfma_f32_16x16x32_bf16 v[56:59], v[212:215], v[224:227], v[56:59]
	v_mfma_f32_16x16x32_bf16 v[60:63], v[204:207], v[238:241], v[112:115]
	v_mfma_f32_16x16x32_bf16 v[64:67], v[212:215], v[238:241], v[64:67]
	v_mfma_f32_16x16x32_bf16 v[44:47], v[208:211], v[220:223], v[44:47]
	v_mfma_f32_16x16x32_bf16 v[48:51], v[216:219], v[220:223], v[48:51]
	v_mfma_f32_16x16x32_bf16 v[52:55], v[208:211], v[234:237], v[52:55]
	s_setprio 2
	s_barrier
	v_mfma_f32_16x16x32_bf16 v[56:59], v[216:219], v[234:237], v[56:59]
	v_mfma_f32_16x16x32_bf16 v[60:63], v[208:211], v[242:245], v[60:63]
	v_mfma_f32_16x16x32_bf16 v[64:67], v[216:219], v[242:245], v[64:67]
	s_setprio 0
	s_add_i32 s51, s51, s38
	v_lshl_add_u64 v[68:69], v[186:187], 0, s[24:25]
	s_mov_b32 m0, s51
	ds_read_b128 v[104:107], v233 offset:49152
	ds_read_b128 v[108:111], v233 offset:50176
	ds_read_b128 v[112:115], v233 offset:51200
	ds_read_b128 v[220:223], v233 offset:52224
	ds_read_b128 v[224:227], v233 offset:53248
	ds_read_b128 v[234:237], v233 offset:54272
	ds_read_b128 v[238:241], v233 offset:55296
	ds_read_b128 v[242:245], v233 offset:56320
	global_load_lds_dwordx4 v[68:69], off
	v_lshl_add_u64 v[68:69], v[246:247], 0, s[24:25]
	s_add_i32 m0, s51, 0x2000
	s_add_i32 s51, s71, s38
	global_load_lds_dwordx4 v[68:69], off
	s_mov_b32 m0, s51
	v_lshl_add_u64 v[68:69], v[248:249], 0, s[24:25]
	global_load_lds_dwordx4 v2, s[28:29]
	s_add_i32 m0, s51, 0x2000
	s_nop 0
	global_load_lds_dwordx4 v190, s[28:29]
	s_mov_b32 m0, s63
	s_nop 0
	global_load_lds_dwordx4 v[68:69], off
	v_lshl_add_u64 v[68:69], v[250:251], 0, s[24:25]
	s_mov_b32 m0, s64
	s_nop 0
	global_load_lds_dwordx4 v[68:69], off
	s_waitcnt vmcnt(8)
	s_waitcnt lgkmcnt(0)
	s_barrier
	s_setprio 1
	s_waitcnt lgkmcnt(0)
	v_mfma_f32_16x16x32_bf16 v[68:71], v[182:185], v[104:107], v[134:137]
	v_mfma_f32_16x16x32_bf16 v[72:75], v[196:199], v[104:107], v[138:141]
	v_mfma_f32_16x16x32_bf16 v[76:79], v[182:185], v[112:115], v[142:145]
	v_mfma_f32_16x16x32_bf16 v[80:83], v[196:199], v[112:115], v[146:149]
	v_mfma_f32_16x16x32_bf16 v[84:87], v[182:185], v[224:227], v[150:153]
	v_mfma_f32_16x16x32_bf16 v[88:91], v[196:199], v[224:227], v[154:157]
	v_mfma_f32_16x16x32_bf16 v[92:95], v[182:185], v[238:241], v[158:161]
	v_mfma_f32_16x16x32_bf16 v[96:99], v[196:199], v[238:241], v[162:165]
	v_mfma_f32_16x16x32_bf16 v[68:71], v[192:195], v[108:111], v[68:71]
	v_mfma_f32_16x16x32_bf16 v[72:75], v[200:203], v[108:111], v[72:75]
	v_mfma_f32_16x16x32_bf16 v[76:79], v[192:195], v[220:223], v[76:79]
	v_mfma_f32_16x16x32_bf16 v[80:83], v[200:203], v[220:223], v[80:83]
	v_mfma_f32_16x16x32_bf16 v[84:87], v[192:195], v[234:237], v[84:87]
	v_mfma_f32_16x16x32_bf16 v[88:91], v[200:203], v[234:237], v[88:91]
	v_mfma_f32_16x16x32_bf16 v[92:95], v[192:195], v[242:245], v[92:95]
	v_mfma_f32_16x16x32_bf16 v[96:99], v[200:203], v[242:245], v[96:99]
	s_setprio 0
	s_setprio 1
	v_mfma_f32_16x16x32_bf16 v[100:103], v[204:207], v[104:107], v[116:119]
	v_mfma_f32_16x16x32_bf16 v[104:107], v[212:215], v[104:107], v[124:127]
	v_mfma_f32_16x16x32_bf16 v[100:103], v[208:211], v[108:111], v[100:103]
	v_mfma_f32_16x16x32_bf16 v[104:107], v[216:219], v[108:111], v[104:107]
	v_mfma_f32_16x16x32_bf16 v[108:111], v[204:207], v[112:115], v[166:169]
	v_mfma_f32_16x16x32_bf16 v[112:115], v[212:215], v[112:115], v[170:173]
	v_mfma_f32_16x16x32_bf16 v[116:119], v[204:207], v[224:227], v[174:177]
	v_mfma_f32_16x16x32_bf16 v[120:123], v[212:215], v[224:227], v[120:123]
	v_mfma_f32_16x16x32_bf16 v[124:127], v[204:207], v[238:241], v[178:181]
	v_mfma_f32_16x16x32_bf16 v[128:131], v[212:215], v[238:241], v[128:131]
	v_mfma_f32_16x16x32_bf16 v[108:111], v[208:211], v[220:223], v[108:111]
	v_mfma_f32_16x16x32_bf16 v[112:115], v[216:219], v[220:223], v[112:115]
	v_mfma_f32_16x16x32_bf16 v[116:119], v[208:211], v[234:237], v[116:119]
	s_setprio 2
	s_barrier
	v_mfma_f32_16x16x32_bf16 v[120:123], v[216:219], v[234:237], v[120:123]
	v_mfma_f32_16x16x32_bf16 v[124:127], v[208:211], v[242:245], v[124:127]
	v_mfma_f32_16x16x32_bf16 v[128:131], v[216:219], v[242:245], v[128:131]
	s_setprio 0
	s_add_i32 s41, s41, 2
	s_cmp_ge_i32 s41, s40
	s_cbranch_scc0 .LBB0_2269
	v_mov_b32_e32 v192, v2
	s_branch .LBB0_2272

.LBB0_2273:
	s_add_u32 s12, s14, 0xfffc0080
	s_addc_u32 s13, s15, -1
	s_add_i32 s29, 0, 0x10000
	s_cmp_eq_u32 s28, 12
	s_cselect_b32 s17, s9, s13
	s_cselect_b32 s16, s8, s12
	s_cselect_b32 s13, s11, s27
	s_cselect_b32 s12, s10, s26
	s_add_i32 s51, 0, 0x14000
	v_add_u32_e32 v144, s29, v232
	v_add_u32_e32 v160, s51, v232
	s_waitcnt lgkmcnt(0)
	ds_read_b128 v[132:135], v144
	ds_read_b128 v[136:139], v144 offset:1024
	ds_read_b128 v[140:143], v144 offset:2048
	ds_read_b128 v[144:147], v144 offset:3072
	ds_read_b128 v[148:151], v160
	ds_read_b128 v[152:155], v160 offset:1024
	ds_read_b128 v[156:159], v160 offset:2048
	ds_read_b128 v[160:163], v160 offset:3072
	s_mov_b32 m0, s65
	v_add_u32_e32 v210, 0, v231
	ds_read_b128 v[164:167], v210
	ds_read_b128 v[168:171], v210 offset:1024
	ds_read_b128 v[172:175], v210 offset:2048
	ds_read_b128 v[176:179], v210 offset:3072
	ds_read_b128 v[180:183], v210 offset:4096
	ds_read_b128 v[184:187], v210 offset:5120
	ds_read_b128 v[194:197], v210 offset:6144
	ds_read_b128 v[198:201], v210 offset:7168
	global_load_lds_dwordx4 v2, s[14:15]
	s_mov_b32 m0, s66
	v_mov_b32_e32 v189, v3
	global_load_lds_dwordx4 v188, s[14:15]
	s_waitcnt vmcnt(8)
	s_waitcnt lgkmcnt(0)
	s_barrier
	s_setprio 1
	s_waitcnt lgkmcnt(0)
	v_mfma_f32_16x16x32_bf16 v[4:7], v[132:135], v[164:167], v[4:7]
	v_mfma_f32_16x16x32_bf16 v[4:7], v[136:139], v[168:171], v[4:7]
	v_mfma_f32_16x16x32_bf16 v[8:11], v[144:147], v[168:171], v[8:11]
	v_mfma_f32_16x16x32_bf16 v[8:11], v[140:143], v[164:167], v[8:11]
	v_mfma_f32_16x16x32_bf16 v[16:19], v[140:143], v[172:175], v[16:19]
	v_mfma_f32_16x16x32_bf16 v[16:19], v[144:147], v[176:179], v[16:19]
	v_mfma_f32_16x16x32_bf16 v[12:15], v[136:139], v[176:179], v[12:15]
	v_mfma_f32_16x16x32_bf16 v[12:15], v[132:135], v[172:175], v[12:15]
	v_mfma_f32_16x16x32_bf16 v[20:23], v[132:135], v[180:183], v[20:23]
	v_mfma_f32_16x16x32_bf16 v[20:23], v[136:139], v[184:187], v[20:23]
	v_mfma_f32_16x16x32_bf16 v[24:27], v[144:147], v[184:187], v[24:27]
	v_mfma_f32_16x16x32_bf16 v[24:27], v[140:143], v[180:183], v[24:27]
	v_mfma_f32_16x16x32_bf16 v[32:35], v[140:143], v[194:197], v[32:35]
	v_mfma_f32_16x16x32_bf16 v[32:35], v[144:147], v[198:201], v[32:35]
	v_mfma_f32_16x16x32_bf16 v[28:31], v[136:139], v[198:201], v[28:31]
	v_mfma_f32_16x16x32_bf16 v[28:31], v[132:135], v[194:197], v[28:31]
	s_setprio 0
	s_setprio 1
	v_mfma_f32_16x16x32_bf16 v[36:39], v[148:151], v[164:167], v[36:39]
	v_mfma_f32_16x16x32_bf16 v[36:39], v[152:155], v[168:171], v[36:39]
	v_mfma_f32_16x16x32_bf16 v[40:43], v[160:163], v[168:171], v[40:43]
	v_mfma_f32_16x16x32_bf16 v[40:43], v[156:159], v[164:167], v[40:43]
	v_mfma_f32_16x16x32_bf16 v[48:51], v[156:159], v[172:175], v[48:51]
	v_mfma_f32_16x16x32_bf16 v[48:51], v[160:163], v[176:179], v[48:51]
	v_mfma_f32_16x16x32_bf16 v[44:47], v[152:155], v[176:179], v[44:47]
	v_mfma_f32_16x16x32_bf16 v[44:47], v[148:151], v[172:175], v[44:47]
	v_mfma_f32_16x16x32_bf16 v[52:55], v[148:151], v[180:183], v[52:55]
	v_mfma_f32_16x16x32_bf16 v[52:55], v[152:155], v[184:187], v[52:55]
	v_mfma_f32_16x16x32_bf16 v[56:59], v[160:163], v[184:187], v[56:59]
	v_mfma_f32_16x16x32_bf16 v[56:59], v[156:159], v[180:183], v[56:59]
	v_mfma_f32_16x16x32_bf16 v[64:67], v[156:159], v[194:197], v[64:67]
	s_setprio 2
	s_barrier
	v_mfma_f32_16x16x32_bf16 v[64:67], v[160:163], v[198:201], v[64:67]
	v_mfma_f32_16x16x32_bf16 v[60:63], v[152:155], v[198:201], v[60:63]
	v_mfma_f32_16x16x32_bf16 v[60:63], v[148:151], v[194:197], v[60:63]
	s_setprio 0
	s_add_i32 s29, s29, s38
	s_mov_b32 m0, s29
	ds_read_b128 v[164:167], v210 offset:16384
	ds_read_b128 v[168:171], v210 offset:17408
	ds_read_b128 v[172:175], v210 offset:18432
	ds_read_b128 v[176:179], v210 offset:19456
	ds_read_b128 v[180:183], v210 offset:20480
	ds_read_b128 v[184:187], v210 offset:21504
	ds_read_b128 v[194:197], v210 offset:22528
	ds_read_b128 v[198:201], v210 offset:23552
	global_load_lds_dwordx4 v192, s[12:13]
	s_add_i32 m0, s29, 0x2000
	s_add_u32 s40, s12, 0x100000
	s_addc_u32 s41, s13, 0
	s_add_i32 s29, s51, s38
	global_load_lds_dwordx4 v190, s[12:13]
	s_mov_b32 m0, s29
	v_mov_b32_e32 v193, v3
	global_load_lds_dwordx4 v192, s[40:41]
	s_add_i32 m0, s29, 0x2000
	v_mov_b32_e32 v191, v3
	global_load_lds_dwordx4 v190, s[40:41]
	s_mov_b32 m0, s56
	v_lshl_add_u64 v[202:203], s[12:13], 0, v[192:193]
	global_load_lds_dwordx4 v2, s[16:17]
	s_mov_b32 m0, s57
	v_lshl_add_u64 v[204:205], s[12:13], 0, v[190:191]
	global_load_lds_dwordx4 v188, s[16:17]
	s_waitcnt vmcnt(8)
	s_waitcnt lgkmcnt(0)
	v_lshl_add_u64 v[206:207], s[16:17], 0, v[2:3]
	v_lshl_add_u64 v[208:209], s[16:17], 0, v[188:189]
	s_barrier
	s_setprio 1
	s_waitcnt lgkmcnt(0)
	v_mfma_f32_16x16x32_bf16 v[68:71], v[132:135], v[164:167], v[68:71]
	v_mfma_f32_16x16x32_bf16 v[68:71], v[136:139], v[168:171], v[68:71]
	v_mfma_f32_16x16x32_bf16 v[72:75], v[144:147], v[168:171], v[72:75]
	v_mfma_f32_16x16x32_bf16 v[72:75], v[140:143], v[164:167], v[72:75]
	v_mfma_f32_16x16x32_bf16 v[80:83], v[140:143], v[172:175], v[80:83]
	v_mfma_f32_16x16x32_bf16 v[80:83], v[144:147], v[176:179], v[80:83]
	v_mfma_f32_16x16x32_bf16 v[76:79], v[136:139], v[176:179], v[76:79]
	v_mfma_f32_16x16x32_bf16 v[76:79], v[132:135], v[172:175], v[76:79]
	v_mfma_f32_16x16x32_bf16 v[84:87], v[132:135], v[180:183], v[84:87]
	v_mfma_f32_16x16x32_bf16 v[84:87], v[136:139], v[184:187], v[84:87]
	v_mfma_f32_16x16x32_bf16 v[88:91], v[144:147], v[184:187], v[88:91]
	v_mfma_f32_16x16x32_bf16 v[88:91], v[140:143], v[180:183], v[88:91]
	v_mfma_f32_16x16x32_bf16 v[96:99], v[140:143], v[194:197], v[96:99]
	v_mfma_f32_16x16x32_bf16 v[96:99], v[144:147], v[198:201], v[96:99]
	v_mfma_f32_16x16x32_bf16 v[92:95], v[136:139], v[198:201], v[92:95]
	v_mfma_f32_16x16x32_bf16 v[92:95], v[132:135], v[194:197], v[92:95]
	s_setprio 0
	s_setprio 1
	v_mfma_f32_16x16x32_bf16 v[100:103], v[148:151], v[164:167], v[100:103]
	v_mfma_f32_16x16x32_bf16 v[100:103], v[152:155], v[168:171], v[100:103]
	v_mfma_f32_16x16x32_bf16 v[104:107], v[160:163], v[168:171], v[104:107]
	v_mfma_f32_16x16x32_bf16 v[104:107], v[156:159], v[164:167], v[104:107]
	v_mfma_f32_16x16x32_bf16 v[112:115], v[156:159], v[172:175], v[112:115]
	v_mfma_f32_16x16x32_bf16 v[112:115], v[160:163], v[176:179], v[112:115]
	v_mfma_f32_16x16x32_bf16 v[108:111], v[152:155], v[176:179], v[108:111]
	v_mfma_f32_16x16x32_bf16 v[108:111], v[148:151], v[172:175], v[108:111]
	v_mfma_f32_16x16x32_bf16 v[116:119], v[148:151], v[180:183], v[116:119]
	v_mfma_f32_16x16x32_bf16 v[116:119], v[152:155], v[184:187], v[116:119]
	v_mfma_f32_16x16x32_bf16 v[120:123], v[160:163], v[184:187], v[120:123]
	v_mfma_f32_16x16x32_bf16 v[120:123], v[156:159], v[180:183], v[120:123]
	v_mfma_f32_16x16x32_bf16 v[128:131], v[156:159], v[194:197], v[128:131]
	s_setprio 2
	s_barrier
	v_mfma_f32_16x16x32_bf16 v[128:131], v[160:163], v[198:201], v[128:131]
	v_mfma_f32_16x16x32_bf16 v[124:127], v[152:155], v[198:201], v[124:127]
	v_mfma_f32_16x16x32_bf16 v[124:127], v[148:151], v[194:197], v[124:127]
	s_setprio 0
	s_add_i32 s29, 0, 0x18000
	s_add_i32 s40, 0, 0x1c000
	v_add_u32_e32 v144, s29, v232
	v_add_u32_e32 v160, s40, v232
	ds_read_b128 v[132:135], v144
	ds_read_b128 v[136:139], v144 offset:1024
	ds_read_b128 v[140:143], v144 offset:2048
	ds_read_b128 v[144:147], v144 offset:3072
	ds_read_b128 v[148:151], v160
	ds_read_b128 v[152:155], v160 offset:1024
	ds_read_b128 v[156:159], v160 offset:2048
	ds_read_b128 v[160:163], v160 offset:3072
	s_add_u32 s16, s16, 0x40000
	s_addc_u32 s17, s17, 0
	s_mov_b32 m0, s58
	ds_read_b128 v[164:167], v210 offset:32768
	ds_read_b128 v[168:171], v210 offset:33792
	ds_read_b128 v[172:175], v210 offset:34816
	ds_read_b128 v[176:179], v210 offset:35840
	ds_read_b128 v[180:183], v210 offset:36864
	ds_read_b128 v[184:187], v210 offset:37888
	ds_read_b128 v[194:197], v210 offset:38912
	ds_read_b128 v[198:201], v210 offset:39936
	global_load_lds_dwordx4 v2, s[16:17]
	s_mov_b32 m0, s59
	s_nop 0
	global_load_lds_dwordx4 v188, s[16:17]
	s_waitcnt vmcnt(8)
	s_waitcnt lgkmcnt(0)
	s_barrier
	s_setprio 1
	s_waitcnt lgkmcnt(0)
	v_mfma_f32_16x16x32_bf16 v[4:7], v[132:135], v[164:167], v[4:7]
	v_mfma_f32_16x16x32_bf16 v[4:7], v[136:139], v[168:171], v[4:7]
	v_mfma_f32_16x16x32_bf16 v[8:11], v[144:147], v[168:171], v[8:11]
	v_mfma_f32_16x16x32_bf16 v[8:11], v[140:143], v[164:167], v[8:11]
	v_mfma_f32_16x16x32_bf16 v[16:19], v[140:143], v[172:175], v[16:19]
	v_mfma_f32_16x16x32_bf16 v[16:19], v[144:147], v[176:179], v[16:19]
	v_mfma_f32_16x16x32_bf16 v[12:15], v[136:139], v[176:179], v[12:15]
	v_mfma_f32_16x16x32_bf16 v[12:15], v[132:135], v[172:175], v[12:15]
	v_mfma_f32_16x16x32_bf16 v[20:23], v[132:135], v[180:183], v[20:23]
	v_mfma_f32_16x16x32_bf16 v[20:23], v[136:139], v[184:187], v[20:23]
	v_mfma_f32_16x16x32_bf16 v[24:27], v[144:147], v[184:187], v[24:27]
	v_mfma_f32_16x16x32_bf16 v[24:27], v[140:143], v[180:183], v[24:27]
	v_mfma_f32_16x16x32_bf16 v[32:35], v[140:143], v[194:197], v[32:35]
	v_mfma_f32_16x16x32_bf16 v[32:35], v[144:147], v[198:201], v[32:35]
	v_mfma_f32_16x16x32_bf16 v[28:31], v[136:139], v[198:201], v[28:31]
	v_mfma_f32_16x16x32_bf16 v[28:31], v[132:135], v[194:197], v[28:31]
	s_setprio 0
	s_setprio 1
	v_mfma_f32_16x16x32_bf16 v[36:39], v[148:151], v[164:167], v[36:39]
	v_mfma_f32_16x16x32_bf16 v[36:39], v[152:155], v[168:171], v[36:39]
	v_mfma_f32_16x16x32_bf16 v[40:43], v[160:163], v[168:171], v[40:43]
	v_mfma_f32_16x16x32_bf16 v[40:43], v[156:159], v[164:167], v[40:43]
	v_mfma_f32_16x16x32_bf16 v[48:51], v[156:159], v[172:175], v[48:51]
	v_mfma_f32_16x16x32_bf16 v[48:51], v[160:163], v[176:179], v[48:51]
	v_mfma_f32_16x16x32_bf16 v[44:47], v[152:155], v[176:179], v[44:47]
	v_mfma_f32_16x16x32_bf16 v[44:47], v[148:151], v[172:175], v[44:47]
	v_mfma_f32_16x16x32_bf16 v[52:55], v[148:151], v[180:183], v[52:55]
	v_mfma_f32_16x16x32_bf16 v[52:55], v[152:155], v[184:187], v[52:55]
	v_mfma_f32_16x16x32_bf16 v[56:59], v[160:163], v[184:187], v[56:59]
	v_mfma_f32_16x16x32_bf16 v[56:59], v[156:159], v[180:183], v[56:59]
	v_mfma_f32_16x16x32_bf16 v[64:67], v[156:159], v[194:197], v[64:67]
	s_setprio 2
	s_barrier
	v_mfma_f32_16x16x32_bf16 v[64:67], v[160:163], v[198:201], v[64:67]
	v_mfma_f32_16x16x32_bf16 v[60:63], v[152:155], v[198:201], v[60:63]
	v_mfma_f32_16x16x32_bf16 v[60:63], v[148:151], v[194:197], v[60:63]
	s_setprio 0
	s_add_i32 s16, s29, s38
	v_lshl_add_u64 v[202:203], v[202:203], 0, s[86:87]
	s_mov_b32 m0, s16
	ds_read_b128 v[164:167], v210 offset:49152
	ds_read_b128 v[168:171], v210 offset:50176
	ds_read_b128 v[172:175], v210 offset:51200
	ds_read_b128 v[176:179], v210 offset:52224
	ds_read_b128 v[180:183], v210 offset:53248
	ds_read_b128 v[184:187], v210 offset:54272
	ds_read_b128 v[194:197], v210 offset:55296
	ds_read_b128 v[198:201], v210 offset:56320
	global_load_lds_dwordx4 v[202:203], off
	s_add_i32 m0, s16, 0x2000
	s_add_u32 s12, s12, 0x100080
	v_lshl_add_u64 v[202:203], v[204:205], 0, s[86:87]
	s_addc_u32 s13, s13, 0
	s_add_i32 s16, s40, s38
	global_load_lds_dwordx4 v[202:203], off
	s_mov_b32 m0, s16
	v_lshl_add_u64 v[202:203], v[206:207], 0, s[86:87]
	global_load_lds_dwordx4 v192, s[12:13]
	s_add_i32 m0, s16, 0x2000
	s_nop 0
	global_load_lds_dwordx4 v190, s[12:13]
	s_mov_b32 m0, s63
	s_nop 0
	global_load_lds_dwordx4 v[202:203], off
	v_lshl_add_u64 v[202:203], v[208:209], 0, s[86:87]
	s_mov_b32 m0, s64
	s_nop 0
	global_load_lds_dwordx4 v[202:203], off
	s_waitcnt vmcnt(8)
	s_waitcnt lgkmcnt(0)
	s_barrier
	s_setprio 1
	s_waitcnt lgkmcnt(0)
	v_mfma_f32_16x16x32_bf16 v[68:71], v[132:135], v[164:167], v[68:71]
	v_mfma_f32_16x16x32_bf16 v[68:71], v[136:139], v[168:171], v[68:71]
	v_mfma_f32_16x16x32_bf16 v[72:75], v[144:147], v[168:171], v[72:75]
	v_mfma_f32_16x16x32_bf16 v[72:75], v[140:143], v[164:167], v[72:75]
	v_mfma_f32_16x16x32_bf16 v[80:83], v[140:143], v[172:175], v[80:83]
	v_mfma_f32_16x16x32_bf16 v[80:83], v[144:147], v[176:179], v[80:83]
	v_mfma_f32_16x16x32_bf16 v[76:79], v[136:139], v[176:179], v[76:79]
	v_mfma_f32_16x16x32_bf16 v[76:79], v[132:135], v[172:175], v[76:79]
	v_mfma_f32_16x16x32_bf16 v[84:87], v[132:135], v[180:183], v[84:87]
	v_mfma_f32_16x16x32_bf16 v[84:87], v[136:139], v[184:187], v[84:87]
	v_mfma_f32_16x16x32_bf16 v[88:91], v[144:147], v[184:187], v[88:91]
	v_mfma_f32_16x16x32_bf16 v[88:91], v[140:143], v[180:183], v[88:91]
	v_mfma_f32_16x16x32_bf16 v[96:99], v[140:143], v[194:197], v[96:99]
	v_mfma_f32_16x16x32_bf16 v[96:99], v[144:147], v[198:201], v[96:99]
	v_mfma_f32_16x16x32_bf16 v[92:95], v[136:139], v[198:201], v[92:95]
	v_mfma_f32_16x16x32_bf16 v[92:95], v[132:135], v[194:197], v[92:95]
	s_setprio 0
	s_setprio 1
	v_mfma_f32_16x16x32_bf16 v[100:103], v[148:151], v[164:167], v[100:103]
	v_mfma_f32_16x16x32_bf16 v[100:103], v[152:155], v[168:171], v[100:103]
	v_mfma_f32_16x16x32_bf16 v[104:107], v[160:163], v[168:171], v[104:107]
	v_mfma_f32_16x16x32_bf16 v[104:107], v[156:159], v[164:167], v[104:107]
	v_mfma_f32_16x16x32_bf16 v[112:115], v[156:159], v[172:175], v[112:115]
	v_mfma_f32_16x16x32_bf16 v[112:115], v[160:163], v[176:179], v[112:115]
	v_mfma_f32_16x16x32_bf16 v[108:111], v[152:155], v[176:179], v[108:111]
	v_mfma_f32_16x16x32_bf16 v[108:111], v[148:151], v[172:175], v[108:111]
	v_mfma_f32_16x16x32_bf16 v[116:119], v[148:151], v[180:183], v[116:119]
	v_mfma_f32_16x16x32_bf16 v[116:119], v[152:155], v[184:187], v[116:119]
	v_mfma_f32_16x16x32_bf16 v[120:123], v[160:163], v[184:187], v[120:123]
	v_mfma_f32_16x16x32_bf16 v[120:123], v[156:159], v[180:183], v[120:123]
	v_mfma_f32_16x16x32_bf16 v[128:131], v[156:159], v[194:197], v[128:131]
	s_setprio 2
	s_barrier
	v_mfma_f32_16x16x32_bf16 v[128:131], v[160:163], v[198:201], v[128:131]
	v_mfma_f32_16x16x32_bf16 v[124:127], v[152:155], v[198:201], v[124:127]
	v_mfma_f32_16x16x32_bf16 v[124:127], v[148:151], v[194:197], v[124:127]
	s_setprio 0
	s_add_i32 s28, s28, 2
	s_add_u32 s14, s14, 0x100
	s_addc_u32 s15, s15, 0
	s_add_u32 s26, s26, 0x100
	s_addc_u32 s27, s27, 0
	s_cmp_gt_u32 s28, 13
	s_cbranch_scc0 .LBB0_2273
	s_and_b64 vcc, exec, s[48:49]
	s_cbranch_vccz .LBB0_2276
	s_barrier
